# second routing task's q fragments prefetched; out-proj tile counter read early in the act sub-phase; P9's second counter read overlapped with the panel poll
# speedup vs baseline: 1.0177x; 1.0177x over previous
; __device__ __forceinline__ unsigned xb_ld(unsigned* p)              { return __hip_atomic_load(p, __ATOMIC_RELAXED, __HIP_MEMORY_SCOPE_AGENT); }
; #define XB_SPIN(cond, bar) do { unsigned _sp = 0; while (cond) { __builtin_amdgcn_s_sleep(1); \
;     if ((++_sp & 255u) == 0u) { if (xb_ld(&(bar)[XB_TMO])) break; if (_sp > XB_SPIN_CAP) { atomicAdd(&(bar)[XB_TMO], 1u); break; } } } } while (0)
; #define PHASE_VARS() int tid = tid0; asm volatile("" : "+v"(tid)); const int lane = tid & 63, gtid = bid * NTHR + tid, gwave = gtid >> 6; (void)lane; (void)gtid; (void)gwave
; __global__ void __launch_bounds__(NTHR, 2) k_main(Args a) {
;     ...
;     if (IN(9)) {
;         PHASE_VARS();
;         pg8::Gemm g{XNB, WQT, T, D, D}; pg8::StaticOrder S; S.init(T, D, nb, bid);
;         { __syncthreads();
;           if (tid == 0) { pg8::Unit u; for (int i = 0; S.next(i, u); ++i) { unsigned* cw = &((unsigned*)ws)[6144 + 16 * u.pm]; XB_SPIN(xb_ld(cw) < 4u, (unsigned*)ws); }
;               XB_SPIN(xb_ld(&((unsigned*)ws)[14336]) < 256u, (unsigned*)ws);
;               __builtin_amdgcn_fence(__ATOMIC_ACQUIRE, "agent"); asm volatile("s_waitcnt vmcnt(0)" ::: "memory"); }
;           __syncthreads(); }
.LBB0_572:
	s_cmp_lt_i32 s84, 10
	s_cselect_b64 s[0:1], -1, 0
	s_cmp_gt_i32 s85, 9
	s_cselect_b64 s[4:5], -1, 0
	s_and_b64 s[0:1], s[0:1], s[4:5]
	s_andn2_b64 vcc, exec, s[0:1]
	s_cbranch_vccnz .LBB0_645
	v_mov_b32_e32 v1, v0
	s_mov_b32 s3, 0
	v_cmp_eq_u32_e64 s[0:1], 0, v1
	s_barrier
	s_and_saveexec_b64 s[4:5], s[0:1]
	v_readlane_b32 s54, v235, 34
	v_readlane_b32 s55, v235, 35
	s_cbranch_execz .LBB0_611
	v_mov_b32_e32 v9, 0xe000
	global_load_dword v8, v9, s[90:91] sc1
	s_ashr_i32 s14, s33, 31
	s_ashr_i32 s15, s2, 31
	v_mov_b64_e32 v[2:3], 0x100
	v_mov_b64_e32 v[4:5], 0xff
	v_mov_b32_e32 v1, 0x6000
	v_mov_b32_e32 v6, 0
	s_branch .LBB0_578

; __device__ __forceinline__ unsigned xb_ld(unsigned* p)              { return __hip_atomic_load(p, __ATOMIC_RELAXED, __HIP_MEMORY_SCOPE_AGENT); }
; #define XB_SPIN(cond, bar) do { unsigned _sp = 0; while (cond) { __builtin_amdgcn_s_sleep(1); \
;     if ((++_sp & 255u) == 0u) { if (xb_ld(&(bar)[XB_TMO])) break; if (_sp > XB_SPIN_CAP) { atomicAdd(&(bar)[XB_TMO], 1u); break; } } } } while (0)
; __global__ void __launch_bounds__(NTHR, 2) k_main(Args a) {
;     ...
;               XB_SPIN(xb_ld(&((unsigned*)ws)[14336]) < 256u, (unsigned*)ws);
.LBB0_597:
	v_mov_b32_e32 v1, v8
	s_movk_i32 s3, 0xff
	s_add_u32 s6, s90, 0xe000
	s_addc_u32 s7, s91, 0
	s_waitcnt vmcnt(0)
	v_cmp_lt_u32_e32 vcc, s3, v1
	s_cbranch_vccnz .LBB0_610
	s_mov_b32 s14, 1
	v_mov_b32_e32 v1, 0
	s_branch .LBB0_600

; #define LAS __attribute__((address_space(3)))
; #define MFMA32(a, b, c) __builtin_amdgcn_mfma_f32_32x32x16_bf16((a), (b), (c), 0, 0, 0)
; #define CE_(a, b) ce_desc(v[a], v[b])
; __device__ __forceinline__ void sort16_desc(int (&v)[16]) {
;     ...
;     CE_(0,13); CE_(1,12); CE_(2,15); CE_(3,14); CE_(4,8); CE_(5,6); CE_(7,11); CE_(9,10);
;     CE_(0,5); CE_(1,7); CE_(2,9); CE_(3,4); CE_(6,13); CE_(8,14); CE_(10,15); CE_(11,12);
;     CE_(0,1); CE_(2,3); CE_(4,5); CE_(6,8); CE_(7,9); CE_(10,11); CE_(12,13); CE_(14,15);
;     CE_(0,2); CE_(1,3); CE_(4,10); CE_(5,11); CE_(6,7); CE_(8,9); CE_(12,14); CE_(13,15);
;     CE_(1,2); CE_(3,12); CE_(4,6); CE_(5,7); CE_(8,10); CE_(9,11); CE_(13,14);
;     CE_(1,4); CE_(2,6); CE_(5,8); CE_(7,10); CE_(9,13); CE_(11,14);
;     CE_(2,4); CE_(3,6); CE_(9,12); CE_(11,13);
;     CE_(3,5); CE_(6,8); CE_(7,9); CE_(10,12);
;     CE_(3,4); CE_(5,6); CE_(7,8); CE_(9,10); CE_(11,12);
;     CE_(6,7); CE_(8,9);
;     ...
; }
; __device__ __forceinline__ void route_task(int task, int tl0, const bf16* QP  , const LAS bf16* KHL, LAS unsigned short* EL, LAS float* GL, int lane) {
;     ...
;     { unsigned qo = (unsigned)t * (unsigned)D + (unsigned)(head * 128 + 8 * hi); asm volatile("" : "+v"(qo)); const bf16* qp = QP + qo;
; #pragma unroll
;       for (int hf = 0; hf < 2; ++hf)
; #pragma unroll
;         for (int ks = 0; ks < 4; ++ks) qa[hf][ks] = ldg8(qp + 64 * hf + 16 * ks); }
; #pragma unroll
;     for (int half = 0; half < 2; ++half) {
;         int cur[16];
; #pragma unroll
;         for (int kt = 0; kt < 4; ++kt) {
;             f32x16 X;
; #pragma unroll
;             for (int i = 0; i < 16; ++i) X[i] = 8.f;
;             const LAS bf16* khp = KHL + (half * 128 + 32 * kt + r) * 72 + 8 * hi;
; #pragma unroll
;             for (int ks = 0; ks < 4; ++ks) {
;                 const bf16x8 kh = lds8(khp + 16 * ks);
;                 X = MFMA32(kh, qa[half][ks], X);
;             }
;             int grp[16];
; #pragma unroll
;             for (int i = 0; i < 16; ++i) grp[i] = (int)((__float_as_uint(X[i]) | 127u) - (unsigned)(32 * kt + (i & 3) + 8 * (i >> 2)));
;             sort16_desc(grp);
;             if (kt == 0) {
; #pragma unroll
;                 for (int i = 0; i < 16; ++i) cur[i] = grp[i];
;             } else merge16_desc(cur, grp);
.LBB0_666:
	s_or_b64 exec, exec, s[10:11]
	s_lshl_b32 s10, s2, 4
	s_add_i32 s10, s10, s95
	s_lshl_b32 s10, s10, 12
	v_or_b32_e32 v82, s10, v88
	s_waitcnt lgkmcnt(0)
	s_barrier
	s_add_i32 s11, 0, 0x12000
	v_lshl_add_u64 v[70:71], v[82:83], 1, s[80:81]
	global_load_dwordx4 v[62:65], v[70:71], off
	global_load_dwordx4 v[54:57], v[70:71], off offset:32
	global_load_dwordx4 v[58:61], v[70:71], off offset:64
	global_load_dwordx4 v[50:53], v[70:71], off offset:96
	ds_read_b128 v[34:37], v94
	ds_read_b128 v[38:41], v94 offset:32
	s_add_i32 s10, s10, 0x8000
	s_mov_b32 s41, 0
	s_waitcnt vmcnt(3) lgkmcnt(1)
	v_mfma_f32_32x32x16_bf16 v[18:33], v[34:37], v[62:65], v[2:17]
	ds_read_b128 v[34:37], v94 offset:64
	ds_read_b128 v[66:69], v94 offset:96
	s_waitcnt vmcnt(2) lgkmcnt(2)
	v_mfma_f32_32x32x16_bf16 v[18:33], v[38:41], v[54:57], v[18:33]
	v_and_b32_e32 v38, 64, v112
	v_add_u32_e32 v122, 64, v38
	v_cmp_lt_i32_e32 vcc, v113, v122
	s_waitcnt vmcnt(1) lgkmcnt(1)
	v_mfma_f32_32x32x16_bf16 v[18:33], v[34:37], v[58:61], v[18:33]
	v_cndmask_b32_e32 v34, v112, v113, vcc
	v_lshlrev_b32_e32 v123, 2, v34
	global_load_dwordx4 v[46:49], v[70:71], off offset:128
	global_load_dwordx4 v[42:45], v[70:71], off offset:160
	global_load_dwordx4 v[38:41], v[70:71], off offset:192
	global_load_dwordx4 v[34:37], v[70:71], off offset:224
	s_waitcnt vmcnt(4) lgkmcnt(0)
	v_mfma_f32_32x32x16_bf16 v[18:33], v[66:69], v[50:53], v[18:33]
	s_nop 11
	s_movk_i32 s42, 0x7f
	s_movk_i32 s43, 0xff80
	v_bitop3_b32 v21, v21, s42, 3 bitop3:0x56
	v_bitop3_b32 v32, v32, s42, 26 bitop3:0x56
	v_bitop3_b32 v22, v22, s42, 8 bitop3:0x56
	v_bitop3_b32 v26, v26, s42, 16 bitop3:0x56
	v_bitop3_b32 v31, v31, s42, 25 bitop3:0x56
	v_bitop3_b32 v23, v23, s42, 9 bitop3:0x56
	v_bitop3_b32 v24, v24, s42, 10 bitop3:0x56
	v_bitop3_b32 v27, v27, s42, 17 bitop3:0x56
	v_bitop3_b32 v28, v28, s42, 18 bitop3:0x56
	v_bitop3_b32 v20, v20, s42, 2 bitop3:0x56
	v_bitop3_b32 v33, v33, s42, 27 bitop3:0x56
	v_bitop3_b32 v25, v25, s42, 11 bitop3:0x56
	v_bitop3_b32 v29, v29, s42, 19 bitop3:0x56
	v_bitop3_b32 v19, v19, s42, 1 bitop3:0x56
	v_bitop3_b32 v30, v30, s42, 24 bitop3:0x56
	v_or_b32_e32 v18, 0x7f, v18
	v_max_i32_e32 v66, v21, v32
	v_max_i32_e32 v67, v22, v26
	v_max_i32_e32 v68, v18, v31
	v_max_i32_e32 v69, v23, v24
	v_min_i32_e32 v70, v27, v28
	v_min_i32_e32 v71, v20, v33
	v_min_i32_e32 v72, v25, v29
	v_min_i32_e32 v73, v19, v30
	v_min_i32_e32 v23, v23, v24
	v_min_i32_e32 v18, v18, v31
	v_min_i32_e32 v22, v22, v26
	v_min_i32_e32 v21, v21, v32
	v_max_i32_e32 v19, v19, v30
	v_max_i32_e32 v24, v25, v29
	v_max_i32_e32 v20, v20, v33
	v_max_i32_e32 v25, v27, v28
	v_min_i32_e32 v26, v66, v67
	v_min_i32_e32 v27, v68, v69
	v_max_i32_e32 v28, v70, v71
	v_max_i32_e32 v29, v72, v73
	v_max_i32_e32 v30, v23, v18
	v_max_i32_e32 v31, v22, v21
	v_min_i32_e32 v32, v19, v24
	v_min_i32_e32 v33, v20, v25
	v_min_i32_e32 v18, v23, v18
	v_min_i32_e32 v21, v22, v21
	v_min_i32_e32 v22, v70, v71
	v_max_i32_e32 v23, v68, v69
	v_max_i32_e32 v19, v19, v24
	v_max_i32_e32 v20, v20, v25
	v_max_i32_e32 v24, v66, v67
	v_min_i32_e32 v25, v26, v27
	v_max_i32_e32 v67, v30, v31
	v_min_i32_e32 v30, v30, v31
	v_min_i32_e32 v31, v32, v33
	v_max_i32_e32 v26, v26, v27
	v_max_i32_e32 v27, v28, v29
	v_min_i32_e32 v66, v28, v29
	v_max_i32_e32 v68, v32, v33
	v_min_i32_e32 v75, v21, v22
	v_max_i32_e32 v21, v21, v22
	v_min_i32_e32 v22, v23, v19
	v_min_i32_e32 v28, v20, v24
	v_max_i32_e32 v33, v30, v31
	v_min_i32_e32 v69, v26, v27
	v_max_i32_e32 v29, v25, v66
	v_min_i32_e32 v32, v67, v68
	v_min_i32_e32 v77, v25, v66
	v_min_i32_e32 v25, v22, v28
	v_max_i32_e32 v80, v22, v28
	v_min_i32_e32 v22, v33, v69
	v_max_i32_e32 v125, v20, v24
	v_max_i32_e32 v129, v67, v68
	v_max_i32_e32 v24, v33, v69
	ds_read_b128 v[66:69], v95
	v_min_i32_e32 v72, v72, v73
	v_min_i32_e32 v74, v72, v18
	v_max_i32_e32 v18, v72, v18
	v_max_i32_e32 v124, v23, v19
	v_min_i32_e32 v76, v30, v31
	v_max_i32_e32 v78, v74, v75
	v_min_i32_e32 v79, v18, v21
	v_min_i32_e32 v126, v124, v125
	v_max_i32_e32 v128, v26, v27
	v_max_i32_e32 v18, v18, v21
	v_max_i32_e32 v81, v76, v77
	v_max_i32_e32 v82, v78, v79
	v_min_i32_e32 v127, v80, v126
	v_min_i32_e32 v130, v128, v129
	v_min_i32_e32 v21, v29, v32
	v_min_i32_e32 v28, v25, v18
	v_max_i32_e32 v18, v25, v18
	v_max_i32_e32 v30, v81, v82
	v_min_i32_e32 v19, v127, v130
	v_max_i32_e32 v23, v29, v32
	v_max_i32_e32 v25, v21, v22
	v_max_i32_e32 v31, v30, v28
	v_min_i32_e32 v20, v18, v19
	v_min_i32_e32 v26, v23, v24
	v_max_i32_e32 v70, v25, v31
	v_min_i32_e32 v27, v20, v26
	v_min_i32_e32 v131, v70, v27
	v_max_i32_e32 v143, v70, v27
	ds_read_b128 v[70:73], v95 offset:32
	v_min_i32_e32 v132, v25, v31
	v_min_i32_e32 v133, v21, v22
	v_min_i32_e32 v134, v30, v28
	v_max_i32_e32 v138, v18, v19
	v_max_i32_e32 v139, v23, v24
	v_max_i32_e32 v141, v20, v26
	s_waitcnt lgkmcnt(1)
	v_mfma_f32_32x32x16_bf16 v[18:33], v[66:69], v[62:65], v[2:17]
	ds_read_b128 v[66:69], v95 offset:64
	v_max_i32_e32 v135, v133, v134
	v_max_i32_e32 v136, v132, v135
	v_min_i32_e32 v76, v76, v77
	v_min_i32_e32 v77, v78, v79
	v_min_i32_e32 v132, v132, v135
	v_max_i32_e32 v127, v127, v130
	s_waitcnt lgkmcnt(1)
	v_mfma_f32_32x32x16_bf16 v[18:33], v[70:73], v[54:57], v[18:33]
	ds_read_b128 v[70:73], v95 offset:96
	v_max_i32_e32 v80, v80, v126
	v_min_i32_e32 v74, v74, v75
	v_min_i32_e32 v140, v138, v139
	v_max_i32_e32 v78, v76, v77
	v_min_i32_e32 v79, v81, v82
	v_min_i32_e32 v82, v133, v134
	s_waitcnt lgkmcnt(1)
	v_mfma_f32_32x32x16_bf16 v[18:33], v[66:69], v[58:61], v[18:33]
	v_max_i32_e32 v66, v128, v129
	v_max_i32_e32 v134, v138, v139
	v_min_i32_e32 v76, v76, v77
	v_max_i32_e32 v81, v78, v79
	v_min_i32_e32 v78, v78, v79
	v_min_i32_e32 v67, v80, v66
	v_min_i32_e32 v142, v140, v141
	s_waitcnt lgkmcnt(0)
; #define LAS __attribute__((address_space(3)))
; #define MFMA32(a, b, c) __builtin_amdgcn_mfma_f32_32x32x16_bf16((a), (b), (c), 0, 0, 0)
; #define CE_(a, b) ce_desc(v[a], v[b])
; __device__ __forceinline__ void sort16_desc(int (&v)[16]) {
;     ...
;     CE_(0,13); CE_(1,12); CE_(2,15); CE_(3,14); CE_(4,8); CE_(5,6); CE_(7,11); CE_(9,10);
;     CE_(0,5); CE_(1,7); CE_(2,9); CE_(3,4); CE_(6,13); CE_(8,14); CE_(10,15); CE_(11,12);
;     CE_(0,1); CE_(2,3); CE_(4,5); CE_(6,8); CE_(7,9); CE_(10,11); CE_(12,13); CE_(14,15);
;     CE_(0,2); CE_(1,3); CE_(4,10); CE_(5,11); CE_(6,7); CE_(8,9); CE_(12,14); CE_(13,15);
;     CE_(1,2); CE_(3,12); CE_(4,6); CE_(5,7); CE_(8,10); CE_(9,11); CE_(13,14);
;     CE_(1,4); CE_(2,6); CE_(5,8); CE_(7,10); CE_(9,13); CE_(11,14);
;     CE_(2,4); CE_(3,6); CE_(9,12); CE_(11,13);
;     CE_(3,5); CE_(6,8); CE_(7,9); CE_(10,12);
;     CE_(3,4); CE_(5,6); CE_(7,8); CE_(9,10); CE_(11,12);
;     CE_(6,7); CE_(8,9);
;     ...
; }
; __device__ __forceinline__ void merge16_desc(int (&a)[16], const int (&b)[16]) {
; #pragma unroll
;     for (int i = 0; i < 16; ++i) a[i] = a[i] > b[15 - i] ? a[i] : b[15 - i];
; #pragma unroll
;     for (int j = 8; j > 0; j >>= 1)
; #pragma unroll
;         for (int i = 0; i < 16; ++i) { const int l = i ^ j; if (l > i) ce_desc(a[i], a[l]); }
; }
; __device__ __forceinline__ void route_task(int task, int tl0, const bf16* QP  , const LAS bf16* KHL, LAS unsigned short* EL, LAS float* GL, int lane) {
;     ...
;         for (int kt = 0; kt < 4; ++kt) {
;             f32x16 X;
; #pragma unroll
;             for (int i = 0; i < 16; ++i) X[i] = 8.f;
;             const LAS bf16* khp = KHL + (half * 128 + 32 * kt + r) * 72 + 8 * hi;
; #pragma unroll
;             for (int ks = 0; ks < 4; ++ks) {
;                 const bf16x8 kh = lds8(khp + 16 * ks);
;                 X = MFMA32(kh, qa[half][ks], X);
;             }
;             int grp[16];
; #pragma unroll
;             for (int i = 0; i < 16; ++i) grp[i] = (int)((__float_as_uint(X[i]) | 127u) - (unsigned)(32 * kt + (i & 3) + 8 * (i >> 2)));
;             sort16_desc(grp);
;             if (kt == 0) {
; #pragma unroll
;                 for (int i = 0; i < 16; ++i) cur[i] = grp[i];
;             } else merge16_desc(cur, grp);
	v_mfma_f32_32x32x16_bf16 v[18:33], v[70:73], v[50:53], v[18:33]
	v_min_i32_e32 v68, v127, v67
	v_min_i32_e32 v137, v131, v136
	v_min_i32_e32 v144, v142, v143
	v_min_i32_e32 v133, v81, v82
	v_min_i32_e32 v69, v134, v68
	s_nop 6
	v_bitop3_b32 v21, v21, s42, 35 bitop3:0x56
	v_bitop3_b32 v32, v32, s42, 58 bitop3:0x56
	v_bitop3_b32 v22, v22, s42, 40 bitop3:0x56
	v_bitop3_b32 v26, v26, s42, 48 bitop3:0x56
	v_bitop3_b32 v18, v18, s42, 32 bitop3:0x56
	v_bitop3_b32 v31, v31, s42, 57 bitop3:0x56
	v_bitop3_b32 v23, v23, s42, 41 bitop3:0x56
	v_bitop3_b32 v24, v24, s42, 42 bitop3:0x56
	v_bitop3_b32 v27, v27, s42, 49 bitop3:0x56
	v_bitop3_b32 v28, v28, s42, 50 bitop3:0x56
	v_bitop3_b32 v20, v20, s42, 34 bitop3:0x56
	v_bitop3_b32 v33, v33, s42, 59 bitop3:0x56
	v_bitop3_b32 v25, v25, s42, 43 bitop3:0x56
	v_bitop3_b32 v29, v29, s42, 51 bitop3:0x56
	v_bitop3_b32 v19, v19, s42, 33 bitop3:0x56
	v_bitop3_b32 v30, v30, s42, 56 bitop3:0x56
	v_max_i32_e32 v70, v21, v32
	v_max_i32_e32 v71, v22, v26
	v_max_i32_e32 v73, v18, v31
	v_max_i32_e32 v75, v23, v24
	v_min_i32_e32 v126, v27, v28
	v_min_i32_e32 v128, v20, v33
	v_min_i32_e32 v130, v25, v29
	v_min_i32_e32 v135, v19, v30
	v_min_i32_e32 v23, v23, v24
	v_min_i32_e32 v18, v18, v31
	v_min_i32_e32 v22, v22, v26
	v_min_i32_e32 v21, v21, v32
	v_max_i32_e32 v19, v19, v30
	v_max_i32_e32 v25, v25, v29
	v_max_i32_e32 v20, v20, v33
	v_max_i32_e32 v27, v27, v28
	v_min_i32_e32 v72, v70, v71
	v_min_i32_e32 v77, v73, v75
	v_max_i32_e32 v129, v126, v128
	v_max_i32_e32 v138, v130, v135
	v_max_i32_e32 v24, v23, v18
	v_max_i32_e32 v26, v22, v21
	v_min_i32_e32 v29, v19, v25
	v_min_i32_e32 v28, v20, v27
	v_min_i32_e32 v130, v130, v135
	v_min_i32_e32 v18, v23, v18
	v_min_i32_e32 v21, v22, v21
	v_min_i32_e32 v22, v126, v128
	v_max_i32_e32 v73, v73, v75
	v_max_i32_e32 v19, v19, v25
	v_max_i32_e32 v20, v20, v27
	v_max_i32_e32 v27, v70, v71
	v_min_i32_e32 v79, v72, v77
	v_min_i32_e32 v139, v129, v138
	v_max_i32_e32 v31, v24, v26
	v_max_i32_e32 v30, v29, v28
	v_min_i32_e32 v24, v24, v26
	v_min_i32_e32 v26, v29, v28
	v_max_i32_e32 v29, v72, v77
	v_max_i32_e32 v72, v129, v138
	v_min_i32_e32 v23, v130, v18
	v_min_i32_e32 v126, v21, v22
	v_max_i32_e32 v18, v130, v18
	v_max_i32_e32 v21, v21, v22
	v_min_i32_e32 v25, v73, v19
	v_min_i32_e32 v70, v20, v27
	v_max_i32_e32 v19, v73, v19
	v_max_i32_e32 v20, v20, v27
	v_min_i32_e32 v32, v31, v30
	v_max_i32_e32 v28, v24, v26
	v_min_i32_e32 v77, v29, v72
	v_min_i32_e32 v24, v24, v26
	v_min_i32_e32 v26, v79, v139
	v_max_i32_e32 v128, v23, v126
	v_min_i32_e32 v22, v18, v21
	v_min_i32_e32 v71, v25, v70
	v_max_i32_e32 v25, v25, v70
	v_min_i32_e32 v27, v19, v20
	v_max_i32_e32 v29, v29, v72
	v_max_i32_e32 v30, v31, v30
	v_max_i32_e32 v145, v79, v139
	v_max_i32_e32 v79, v24, v26
	v_max_i32_e32 v130, v128, v22
	v_max_i32_e32 v18, v18, v21
	v_min_i32_e32 v70, v25, v27
	v_min_i32_e32 v31, v29, v30
	v_min_i32_e32 v33, v145, v32
	v_min_i32_e32 v129, v28, v77
	v_max_i32_e32 v135, v79, v130
	v_min_i32_e32 v21, v71, v18
	v_max_i32_e32 v18, v71, v18
	v_min_i32_e32 v71, v70, v31
	v_max_i32_e32 v32, v145, v32
	v_max_i32_e32 v28, v28, v77
	v_max_i32_e32 v138, v33, v129
	v_max_i32_e32 v75, v135, v21
	v_min_i32_e32 v72, v18, v71
	v_min_i32_e32 v73, v32, v28
	v_min_i32_e32 v33, v33, v129
	v_min_i32_e32 v21, v135, v21
	v_max_i32_e32 v18, v18, v71
	v_max_i32_e32 v28, v32, v28
	v_min_i32_e32 v24, v24, v26
	v_min_i32_e32 v22, v128, v22
	v_max_i32_e32 v25, v25, v27
	v_max_i32_e32 v27, v29, v30
	v_max_i32_e32 v139, v138, v75
	v_min_i32_e32 v77, v72, v73
	v_min_i32_e32 v75, v138, v75
	v_max_i32_e32 v129, v33, v21
	v_min_i32_e32 v32, v18, v28
	v_max_i32_e32 v71, v72, v73
	v_max_i32_e32 v26, v24, v22
	v_min_i32_e32 v79, v79, v130
	v_max_i32_e32 v18, v18, v28
	v_max_i32_e32 v28, v70, v31
	v_min_i32_e32 v29, v25, v27
	v_min_i32_e32 v145, v139, v77
	v_max_i32_e32 v135, v75, v129
	v_min_i32_e32 v72, v32, v71
	v_max_i32_e32 v73, v139, v77
	v_max_i32_e32 v128, v26, v79
	v_min_i32_e32 v21, v33, v21
	v_min_i32_e32 v30, v28, v29
	v_min_i32_e32 v138, v145, v135
	v_min_i32_e32 v77, v72, v73
	v_min_i32_e32 v33, v128, v21
	v_min_i32_e32 v75, v75, v129
	v_min_i32_e32 v31, v18, v30
	v_min_i32_e32 v26, v26, v79
	v_min_i32_e32 v22, v24, v22
	v_min_i32_e32 v23, v23, v126
	v_max3_i32 v23, v124, v125, v23
	v_max3_i32 v22, v80, v66, v22
	v_max3_i32 v24, v127, v67, v26
	v_max3_i32 v26, v134, v68, v33
	v_max3_i32 v21, v69, v128, v21
	v_max3_i32 v33, v140, v141, v75
	v_max3_i32 v66, v142, v143, v138
	v_max3_i32 v67, v144, v145, v135
	v_max3_i32 v68, v131, v136, v77
	v_max3_i32 v69, v137, v72, v73
	v_max3_i32 v32, v132, v32, v71
	v_max3_i32 v31, v81, v82, v31
	v_max3_i32 v18, v133, v18, v30
	v_max3_i32 v28, v78, v28, v29
	v_max3_i32 v25, v76, v25, v27
	v_max3_i32 v19, v74, v19, v20
	v_max_i32_e32 v20, v23, v68
	v_min_i32_e32 v23, v23, v68
	v_max_i32_e32 v27, v22, v69
	v_min_i32_e32 v22, v22, v69
	v_max_i32_e32 v29, v24, v32
	v_min_i32_e32 v24, v24, v32
	v_max_i32_e32 v30, v26, v31
	v_min_i32_e32 v26, v26, v31
	v_max_i32_e32 v31, v21, v18
	v_min_i32_e32 v18, v21, v18
	v_max_i32_e32 v21, v33, v28
	v_min_i32_e32 v28, v33, v28
	v_max_i32_e32 v32, v66, v25
	v_min_i32_e32 v25, v66, v25
	v_max_i32_e32 v33, v67, v19
	v_min_i32_e32 v19, v67, v19
	ds_read_b128 v[66:69], v94 offset:9216
	v_max_i32_e32 v70, v20, v31
	v_min_i32_e32 v74, v20, v31
	v_max_i32_e32 v20, v27, v21
	v_min_i32_e32 v75, v27, v21
	v_max_i32_e32 v21, v29, v32
	v_max_i32_e32 v27, v30, v33
	v_max_i32_e32 v127, v70, v21
	v_min_i32_e32 v128, v70, v21
	ds_read_b128 v[70:73], v94 offset:9248
	v_min_i32_e32 v76, v29, v32
	v_min_i32_e32 v77, v30, v33
	v_max_i32_e32 v78, v23, v18
	v_min_i32_e32 v79, v23, v18
	v_max_i32_e32 v80, v22, v28
	v_min_i32_e32 v81, v22, v28
	v_max_i32_e32 v82, v24, v25
	v_min_i32_e32 v124, v24, v25
	v_max_i32_e32 v125, v26, v19
	v_min_i32_e32 v126, v26, v19
	v_max_i32_e32 v129, v20, v27
	v_min_i32_e32 v130, v20, v27
	s_waitcnt lgkmcnt(1)
; #define LAS __attribute__((address_space(3)))
; #define MFMA32(a, b, c) __builtin_amdgcn_mfma_f32_32x32x16_bf16((a), (b), (c), 0, 0, 0)
; #define CE_(a, b) ce_desc(v[a], v[b])
; __device__ __forceinline__ void sort16_desc(int (&v)[16]) {
;     ...
;     CE_(0,13); CE_(1,12); CE_(2,15); CE_(3,14); CE_(4,8); CE_(5,6); CE_(7,11); CE_(9,10);
;     CE_(0,5); CE_(1,7); CE_(2,9); CE_(3,4); CE_(6,13); CE_(8,14); CE_(10,15); CE_(11,12);
;     CE_(0,1); CE_(2,3); CE_(4,5); CE_(6,8); CE_(7,9); CE_(10,11); CE_(12,13); CE_(14,15);
;     CE_(0,2); CE_(1,3); CE_(4,10); CE_(5,11); CE_(6,7); CE_(8,9); CE_(12,14); CE_(13,15);
;     CE_(1,2); CE_(3,12); CE_(4,6); CE_(5,7); CE_(8,10); CE_(9,11); CE_(13,14);
;     CE_(1,4); CE_(2,6); CE_(5,8); CE_(7,10); CE_(9,13); CE_(11,14);
;     CE_(2,4); CE_(3,6); CE_(9,12); CE_(11,13);
;     CE_(3,5); CE_(6,8); CE_(7,9); CE_(10,12);
;     CE_(3,4); CE_(5,6); CE_(7,8); CE_(9,10); CE_(11,12);
;     CE_(6,7); CE_(8,9);
;     ...
; }
; __device__ __forceinline__ void merge16_desc(int (&a)[16], const int (&b)[16]) {
; #pragma unroll
;     for (int i = 0; i < 16; ++i) a[i] = a[i] > b[15 - i] ? a[i] : b[15 - i];
; #pragma unroll
;     for (int j = 8; j > 0; j >>= 1)
; #pragma unroll
;         for (int i = 0; i < 16; ++i) { const int l = i ^ j; if (l > i) ce_desc(a[i], a[l]); }
; }
; __device__ __forceinline__ void route_task(int task, int tl0, const bf16* QP  , const LAS bf16* KHL, LAS unsigned short* EL, LAS float* GL, int lane) {
;     ...
;         for (int kt = 0; kt < 4; ++kt) {
;             f32x16 X;
; #pragma unroll
;             for (int i = 0; i < 16; ++i) X[i] = 8.f;
;             const LAS bf16* khp = KHL + (half * 128 + 32 * kt + r) * 72 + 8 * hi;
; #pragma unroll
;             for (int ks = 0; ks < 4; ++ks) {
;                 const bf16x8 kh = lds8(khp + 16 * ks);
;                 X = MFMA32(kh, qa[half][ks], X);
;             }
;             int grp[16];
; #pragma unroll
;             for (int i = 0; i < 16; ++i) grp[i] = (int)((__float_as_uint(X[i]) | 127u) - (unsigned)(32 * kt + (i & 3) + 8 * (i >> 2)));
;             sort16_desc(grp);
;             if (kt == 0) {
; #pragma unroll
;                 for (int i = 0; i < 16; ++i) cur[i] = grp[i];
;             } else merge16_desc(cur, grp);
	v_mfma_f32_32x32x16_bf16 v[18:33], v[66:69], v[62:65], v[2:17]
	ds_read_b128 v[66:69], v94 offset:9280
	v_max_i32_e32 v131, v74, v76
	v_min_i32_e32 v74, v74, v76
	v_max_i32_e32 v76, v75, v77
	v_min_i32_e32 v75, v75, v77
	v_max_i32_e32 v77, v78, v82
	v_min_i32_e32 v78, v78, v82
	s_waitcnt lgkmcnt(1)
	v_mfma_f32_32x32x16_bf16 v[18:33], v[70:73], v[54:57], v[18:33]
	ds_read_b128 v[70:73], v94 offset:9312
	v_max_i32_e32 v82, v80, v125
	v_min_i32_e32 v80, v80, v125
	v_max_i32_e32 v125, v79, v124
	v_min_i32_e32 v79, v79, v124
	v_max_i32_e32 v124, v81, v126
	v_min_i32_e32 v81, v81, v126
	s_waitcnt lgkmcnt(1)
	v_mfma_f32_32x32x16_bf16 v[18:33], v[66:69], v[58:61], v[18:33]
	v_min_i32_e32 v126, v127, v129
	v_min_i32_e32 v66, v128, v130
	v_min_i32_e32 v67, v131, v76
	v_min_i32_e32 v69, v77, v82
	v_min_i32_e32 v132, v78, v80
	v_min_i32_e32 v133, v125, v124
	v_min_i32_e32 v68, v74, v75
	s_waitcnt lgkmcnt(0)
	v_mfma_f32_32x32x16_bf16 v[18:33], v[70:73], v[50:53], v[18:33]
	v_min_i32_e32 v134, v79, v81
	s_nop 10
	v_and_or_b32 v21, v21, s43, 60
	v_and_or_b32 v32, v32, s43, 37
	v_and_or_b32 v22, v22, s43, 55
	v_and_or_b32 v26, v26, s43, 47
	v_bitop3_b32 v18, v18, s42, 64 bitop3:0x56
	v_and_or_b32 v31, v31, s43, 38
	v_and_or_b32 v23, v23, s43, 54
	v_and_or_b32 v24, v24, s43, 53
	v_and_or_b32 v27, v27, s43, 46
	v_and_or_b32 v28, v28, s43, 45
	v_and_or_b32 v20, v20, s43, 61
	v_and_or_b32 v33, v33, s43, 36
	v_and_or_b32 v25, v25, s43, 52
	v_and_or_b32 v29, v29, s43, 44
	v_and_or_b32 v19, v19, s43, 62
	v_and_or_b32 v30, v30, s43, 39
	v_max_i32_e32 v70, v21, v32
	v_max_i32_e32 v71, v22, v26
	v_max_i32_e32 v73, v18, v31
	v_max_i32_e32 v135, v23, v24
	v_min_i32_e32 v138, v27, v28
	v_min_i32_e32 v139, v20, v33
	v_min_i32_e32 v141, v25, v29
	v_min_i32_e32 v142, v19, v30
	v_min_i32_e32 v23, v23, v24
	v_min_i32_e32 v18, v18, v31
	v_min_i32_e32 v22, v22, v26
	v_min_i32_e32 v21, v21, v32
	v_max_i32_e32 v19, v19, v30
	v_max_i32_e32 v25, v25, v29
	v_max_i32_e32 v20, v20, v33
	v_max_i32_e32 v27, v27, v28
	v_min_i32_e32 v72, v70, v71
	v_min_i32_e32 v136, v73, v135
	v_max_i32_e32 v140, v138, v139
	v_max_i32_e32 v143, v141, v142
	v_max_i32_e32 v24, v23, v18
	v_max_i32_e32 v26, v22, v21
	v_min_i32_e32 v29, v19, v25
	v_min_i32_e32 v28, v20, v27
	v_min_i32_e32 v141, v141, v142
	v_min_i32_e32 v18, v23, v18
	v_min_i32_e32 v21, v22, v21
	v_min_i32_e32 v22, v138, v139
	v_max_i32_e32 v73, v73, v135
	v_max_i32_e32 v19, v19, v25
	v_max_i32_e32 v20, v20, v27
	v_max_i32_e32 v27, v70, v71
	v_min_i32_e32 v137, v72, v136
	v_min_i32_e32 v144, v140, v143
	v_max_i32_e32 v31, v24, v26
	v_max_i32_e32 v30, v29, v28
	v_min_i32_e32 v24, v24, v26
	v_min_i32_e32 v26, v29, v28
	v_max_i32_e32 v29, v72, v136
	v_max_i32_e32 v72, v140, v143
	v_min_i32_e32 v23, v141, v18
	v_min_i32_e32 v138, v21, v22
	v_max_i32_e32 v18, v141, v18
	v_max_i32_e32 v21, v21, v22
	v_min_i32_e32 v25, v73, v19
	v_min_i32_e32 v70, v20, v27
	v_max_i32_e32 v19, v73, v19
	v_max_i32_e32 v20, v20, v27
	v_min_i32_e32 v32, v31, v30
	v_max_i32_e32 v28, v24, v26
	v_min_i32_e32 v136, v29, v72
	v_min_i32_e32 v24, v24, v26
	v_min_i32_e32 v26, v137, v144
	v_max_i32_e32 v139, v23, v138
	v_min_i32_e32 v22, v18, v21
	v_min_i32_e32 v71, v25, v70
	v_max_i32_e32 v25, v25, v70
	v_min_i32_e32 v27, v19, v20
	v_max_i32_e32 v29, v29, v72
	v_max_i32_e32 v30, v31, v30
	v_max_i32_e32 v145, v137, v144
	v_max_i32_e32 v137, v24, v26
	v_max_i32_e32 v141, v139, v22
	v_max_i32_e32 v18, v18, v21
	v_min_i32_e32 v70, v25, v27
	v_min_i32_e32 v31, v29, v30
	v_min_i32_e32 v33, v145, v32
	v_min_i32_e32 v140, v28, v136
	v_max_i32_e32 v142, v137, v141
	v_min_i32_e32 v21, v71, v18
	v_max_i32_e32 v18, v71, v18
	v_min_i32_e32 v71, v70, v31
	v_max_i32_e32 v32, v145, v32
	v_max_i32_e32 v28, v28, v136
	v_max_i32_e32 v143, v33, v140
	v_max_i32_e32 v135, v142, v21
	v_min_i32_e32 v72, v18, v71
	v_min_i32_e32 v73, v32, v28
	v_min_i32_e32 v33, v33, v140
	v_min_i32_e32 v21, v142, v21
	v_max_i32_e32 v18, v18, v71
	v_max_i32_e32 v28, v32, v28
	v_min_i32_e32 v24, v24, v26
	v_min_i32_e32 v22, v139, v22
	v_max_i32_e32 v25, v25, v27
	v_max_i32_e32 v27, v29, v30
	v_max_i32_e32 v144, v143, v135
	v_min_i32_e32 v136, v72, v73
	v_min_i32_e32 v135, v143, v135
	v_max_i32_e32 v140, v33, v21
	v_min_i32_e32 v32, v18, v28
	v_max_i32_e32 v71, v72, v73
	v_max_i32_e32 v26, v24, v22
	v_min_i32_e32 v137, v137, v141
	v_max_i32_e32 v18, v18, v28
	v_max_i32_e32 v28, v70, v31
	v_min_i32_e32 v29, v25, v27
	v_min_i32_e32 v145, v144, v136
	v_max_i32_e32 v142, v135, v140
	v_min_i32_e32 v72, v32, v71
	v_max_i32_e32 v73, v144, v136
	v_max_i32_e32 v139, v26, v137
	v_min_i32_e32 v21, v33, v21
	v_min_i32_e32 v30, v28, v29
	v_min_i32_e32 v143, v145, v142
	v_min_i32_e32 v136, v72, v73
	v_min_i32_e32 v33, v139, v21
	v_max_i32_e32 v21, v139, v21
	v_min_i32_e32 v135, v135, v140
	v_max_i32_e32 v32, v32, v71
	v_min_i32_e32 v31, v18, v30
	v_max_i32_e32 v18, v18, v30
	v_min_i32_e32 v26, v26, v137
	v_min_i32_e32 v22, v24, v22
	v_max_i32_e32 v24, v25, v27
	v_min_i32_e32 v23, v23, v138
	v_max3_i32 v23, v127, v129, v23
	v_max_i32_e32 v22, v126, v22
	v_max3_i32 v25, v128, v130, v26
	v_max_i32_e32 v26, v66, v33
	v_max3_i32 v21, v131, v76, v21
	v_max_i32_e32 v27, v67, v135
	v_max3_i32 v30, v74, v75, v143
	v_max3_i32 v66, v77, v82, v136
	v_max3_i32 v67, v69, v72, v73
	v_max3_i32 v32, v78, v80, v32
	v_max_i32_e32 v31, v132, v31
	v_max3_i32 v18, v125, v124, v18
	v_max3_i32 v28, v133, v28, v29
	v_max3_i32 v24, v79, v81, v24
	v_max3_i32 v33, v68, v145, v142
	v_max3_i32 v19, v134, v19, v20
	v_max_i32_e32 v20, v23, v66
	v_min_i32_e32 v23, v23, v66
	v_max_i32_e32 v29, v22, v67
	v_max_i32_e32 v66, v25, v32
	v_min_i32_e32 v25, v25, v32
	v_max_i32_e32 v32, v26, v31
	v_min_i32_e32 v26, v26, v31
	v_max_i32_e32 v31, v21, v18
	v_min_i32_e32 v18, v21, v18
	v_max_i32_e32 v21, v27, v28
	v_min_i32_e32 v27, v27, v28
	v_max_i32_e32 v28, v30, v24
	v_min_i32_e32 v22, v22, v67
	v_min_i32_e32 v24, v30, v24
	v_max_i32_e32 v30, v33, v19
	v_min_i32_e32 v19, v33, v19
	v_max_i32_e32 v33, v20, v31
	v_min_i32_e32 v74, v20, v31
	v_max_i32_e32 v20, v29, v21
	v_min_i32_e32 v75, v29, v21
	v_max_i32_e32 v21, v66, v28
	v_min_i32_e32 v76, v66, v28
	ds_read_b128 v[66:69], v96
	ds_read_b128 v[70:73], v96 offset:32
	v_max_i32_e32 v28, v32, v30
	v_min_i32_e32 v77, v32, v30
	v_max_i32_e32 v78, v23, v18
	v_min_i32_e32 v79, v23, v18
	v_max_i32_e32 v80, v22, v27
	v_min_i32_e32 v81, v22, v27
	v_max_i32_e32 v82, v25, v24
	v_min_i32_e32 v124, v25, v24
	v_max_i32_e32 v125, v26, v19
	v_min_i32_e32 v126, v26, v19
	v_max_i32_e32 v127, v33, v21
	v_min_i32_e32 v128, v33, v21
	v_max_i32_e32 v129, v20, v28
	v_min_i32_e32 v130, v20, v28
	s_waitcnt lgkmcnt(1)
; #define LAS __attribute__((address_space(3)))
; #define MFMA32(a, b, c) __builtin_amdgcn_mfma_f32_32x32x16_bf16((a), (b), (c), 0, 0, 0)
; #define CE_(a, b) ce_desc(v[a], v[b])
; __device__ __forceinline__ void sort16_desc(int (&v)[16]) {
;     ...
;     CE_(0,13); CE_(1,12); CE_(2,15); CE_(3,14); CE_(4,8); CE_(5,6); CE_(7,11); CE_(9,10);
;     CE_(0,5); CE_(1,7); CE_(2,9); CE_(3,4); CE_(6,13); CE_(8,14); CE_(10,15); CE_(11,12);
;     CE_(0,1); CE_(2,3); CE_(4,5); CE_(6,8); CE_(7,9); CE_(10,11); CE_(12,13); CE_(14,15);
;     CE_(0,2); CE_(1,3); CE_(4,10); CE_(5,11); CE_(6,7); CE_(8,9); CE_(12,14); CE_(13,15);
;     CE_(1,2); CE_(3,12); CE_(4,6); CE_(5,7); CE_(8,10); CE_(9,11); CE_(13,14);
;     CE_(1,4); CE_(2,6); CE_(5,8); CE_(7,10); CE_(9,13); CE_(11,14);
;     CE_(2,4); CE_(3,6); CE_(9,12); CE_(11,13);
;     CE_(3,5); CE_(6,8); CE_(7,9); CE_(10,12);
;     CE_(3,4); CE_(5,6); CE_(7,8); CE_(9,10); CE_(11,12);
;     CE_(6,7); CE_(8,9);
;     ...
; }
; __device__ __forceinline__ void merge16_desc(int (&a)[16], const int (&b)[16]) {
; #pragma unroll
;     for (int i = 0; i < 16; ++i) a[i] = a[i] > b[15 - i] ? a[i] : b[15 - i];
; #pragma unroll
;     for (int j = 8; j > 0; j >>= 1)
; #pragma unroll
;         for (int i = 0; i < 16; ++i) { const int l = i ^ j; if (l > i) ce_desc(a[i], a[l]); }
; }
; __device__ __forceinline__ void route_task(int task, int tl0, const bf16* QP  , const LAS bf16* KHL, LAS unsigned short* EL, LAS float* GL, int lane) {
;     ...
;         for (int kt = 0; kt < 4; ++kt) {
;             f32x16 X;
; #pragma unroll
;             for (int i = 0; i < 16; ++i) X[i] = 8.f;
;             const LAS bf16* khp = KHL + (half * 128 + 32 * kt + r) * 72 + 8 * hi;
; #pragma unroll
;             for (int ks = 0; ks < 4; ++ks) {
;                 const bf16x8 kh = lds8(khp + 16 * ks);
;                 X = MFMA32(kh, qa[half][ks], X);
;             }
;             int grp[16];
; #pragma unroll
;             for (int i = 0; i < 16; ++i) grp[i] = (int)((__float_as_uint(X[i]) | 127u) - (unsigned)(32 * kt + (i & 3) + 8 * (i >> 2)));
;             sort16_desc(grp);
;             if (kt == 0) {
; #pragma unroll
;                 for (int i = 0; i < 16; ++i) cur[i] = grp[i];
;             } else merge16_desc(cur, grp);
	v_mfma_f32_32x32x16_bf16 v[18:33], v[66:69], v[62:65], v[2:17]
	ds_read_b128 v[62:65], v96 offset:64
	v_max_i32_e32 v67, v75, v77
	v_min_i32_e32 v68, v75, v77
	v_max_i32_e32 v75, v80, v125
	v_max_i32_e32 v131, v74, v76
	v_min_i32_e32 v66, v74, v76
	v_max_i32_e32 v69, v78, v82
	s_waitcnt lgkmcnt(1)
	v_mfma_f32_32x32x16_bf16 v[18:33], v[70:73], v[54:57], v[18:33]
	ds_read_b128 v[54:57], v96 offset:96
	v_min_i32_e32 v70, v80, v125
	v_max_i32_e32 v71, v79, v124
	v_min_i32_e32 v72, v79, v124
	v_min_i32_e32 v74, v78, v82
	v_max_i32_e32 v73, v81, v126
	v_min_i32_e32 v76, v81, v126
	s_waitcnt lgkmcnt(1)
	v_mfma_f32_32x32x16_bf16 v[18:33], v[62:65], v[58:61], v[18:33]
	v_min_i32_e32 v77, v127, v129
	v_min_i32_e32 v58, v128, v130
	v_min_i32_e32 v59, v131, v67
	v_min_i32_e32 v60, v66, v68
	v_min_i32_e32 v61, v69, v75
	v_min_i32_e32 v62, v74, v70
	v_min_i32_e32 v63, v71, v73
	s_waitcnt lgkmcnt(0)
	v_mfma_f32_32x32x16_bf16 v[18:33], v[54:57], v[50:53], v[18:33]
	v_min_i32_e32 v64, v72, v76
	s_nop 10
	v_and_or_b32 v25, v25, s43, 20
	v_and_or_b32 v29, v29, s43, 12
	v_and_or_b32 v19, v19, s43, 30
	v_and_or_b32 v30, v30, s43, 7
	v_and_or_b32 v23, v23, s43, 22
	v_and_or_b32 v24, v24, s43, 21
	v_and_or_b32 v18, v18, s43, 31
	v_and_or_b32 v31, v31, s43, 6
	v_and_or_b32 v22, v22, s43, 23
	v_and_or_b32 v26, v26, s43, 15
	v_and_or_b32 v21, v21, s43, 28
	v_and_or_b32 v32, v32, s43, 5
	v_and_or_b32 v27, v27, s43, 14
	v_and_or_b32 v28, v28, s43, 13
	v_and_or_b32 v20, v20, s43, 29
	v_and_or_b32 v33, v33, s43, 4
	v_min_i32_e32 v50, v25, v29
	v_min_i32_e32 v51, v19, v30
	v_min_i32_e32 v53, v23, v24
	v_min_i32_e32 v54, v18, v31
	v_min_i32_e32 v57, v22, v26
	v_min_i32_e32 v65, v21, v32
	v_min_i32_e32 v79, v27, v28
	v_min_i32_e32 v80, v20, v33
	v_max_i32_e32 v18, v18, v31
	v_max_i32_e32 v23, v23, v24
	v_max_i32_e32 v19, v19, v30
	v_max_i32_e32 v25, v25, v29
	v_max_i32_e32 v20, v20, v33
	v_max_i32_e32 v27, v27, v28
	v_max_i32_e32 v21, v21, v32
	v_max_i32_e32 v22, v22, v26
	v_max_i32_e32 v24, v18, v23
	v_max_i32_e32 v29, v19, v25
	v_max_i32_e32 v28, v20, v27
	v_max_i32_e32 v26, v21, v22
	v_min_i32_e32 v30, v24, v29
	v_min_i32_e32 v31, v28, v26
	v_min_i32_e32 v55, v53, v54
	v_min_i32_e32 v32, v30, v31
	v_max_i32_e32 v30, v30, v31
	v_min_i32_e32 v21, v21, v22
	v_min_i32_e32 v18, v18, v23
	v_max_i32_e32 v23, v79, v80
	v_max_i32_e32 v31, v50, v51
	v_max_i32_e32 v53, v53, v54
	v_max_i32_e32 v54, v57, v65
	v_min_i32_e32 v19, v19, v25
	v_min_i32_e32 v20, v20, v27
	v_min_i32_e32 v52, v50, v51
	v_min_i32_e32 v78, v57, v65
	v_min_i32_e32 v81, v79, v80
	v_max_i32_e32 v22, v21, v18
	v_max_i32_e32 v57, v53, v54
	v_max_i32_e32 v25, v19, v20
	v_min_i32_e32 v18, v21, v18
	v_min_i32_e32 v21, v23, v31
	v_min_i32_e32 v56, v52, v55
	v_min_i32_e32 v82, v78, v81
	v_max_i32_e32 v33, v52, v55
	v_max_i32_e32 v52, v78, v81
	v_max_i32_e32 v24, v24, v29
	v_max_i32_e32 v26, v28, v26
	v_max_i32_e32 v50, v23, v31
	v_max_i32_e32 v27, v57, v25
	v_max_i32_e32 v23, v18, v21
	v_min_i32_e32 v25, v57, v25
	v_min_i32_e32 v53, v53, v54
	v_min_i32_e32 v19, v19, v20
	v_max_i32_e32 v55, v33, v52
	v_min_i32_e32 v28, v24, v26
	v_max_i32_e32 v51, v22, v50
	v_max_i32_e32 v31, v23, v25
	v_max_i32_e32 v20, v53, v19
	v_min_i32_e32 v23, v23, v25
	v_min_i32_e32 v19, v53, v19
	v_min_i32_e32 v18, v18, v21
	v_max_i32_e32 v25, v56, v82
	v_min_i32_e32 v33, v33, v52
	v_min_i32_e32 v29, v30, v28
	v_min_i32_e32 v65, v51, v27
	v_min_i32_e32 v22, v22, v50
	v_max_i32_e32 v21, v19, v18
	v_max_i32_e32 v52, v25, v33
	v_max_i32_e32 v78, v32, v55
	v_min_i32_e32 v79, v29, v65
	v_max_i32_e32 v50, v20, v22
	v_min_i32_e32 v20, v20, v22
	v_max_i32_e32 v53, v21, v52
	v_min_i32_e32 v32, v32, v55
	v_max_i32_e32 v80, v78, v79
	v_max_i32_e32 v54, v31, v50
	v_min_i32_e32 v78, v78, v79
	v_min_i32_e32 v31, v31, v50
	v_max_i32_e32 v22, v23, v20
	v_max_i32_e32 v55, v53, v32
	v_min_i32_e32 v18, v19, v18
	v_min_i32_e32 v19, v25, v33
	v_min_i32_e32 v20, v23, v20
	v_min_i32_e32 v23, v53, v32
	v_max_i32_e32 v28, v30, v28
	v_max_i32_e32 v27, v51, v27
	v_min_i32_e32 v124, v56, v82
	v_min_i32_e32 v57, v80, v54
	v_max_i32_e32 v50, v78, v31
	v_max_i32_e32 v56, v22, v55
	v_min_i32_e32 v31, v78, v31
	v_max_i32_e32 v25, v18, v19
	v_min_i32_e32 v21, v21, v52
	v_min_i32_e32 v32, v20, v23
	v_max_i32_e32 v29, v29, v65
	v_min_i32_e32 v30, v28, v27
	v_min_i32_e32 v22, v22, v55
	v_max_i32_e32 v20, v20, v23
	v_min_i32_e32 v79, v57, v50
	v_max_i32_e32 v78, v56, v31
	v_max_i32_e32 v33, v25, v21
	v_max_i32_e32 v53, v80, v54
	v_min_i32_e32 v51, v29, v30
	v_min_i32_e32 v31, v56, v31
	v_max_i32_e32 v23, v22, v20
	v_min_i32_e32 v81, v79, v78
	v_max_i32_e32 v52, v33, v32
	v_max_i32_e32 v54, v53, v51
	v_min_i32_e32 v21, v25, v21
	v_max_i32_e32 v25, v57, v50
	v_min_i32_e32 v55, v31, v23
	v_max_i32_e32 v27, v28, v27
	v_min_i32_e32 v18, v18, v19
	v_min_i32_e32 v20, v22, v20
	v_min_i32_e32 v32, v33, v32
	v_min_i32_e32 v33, v53, v51
	v_max3_i32 v124, v127, v129, v124
	v_max3_i32 v69, v69, v75, v81
	v_max3_i32 v52, v131, v67, v52
	v_max3_i32 v54, v71, v73, v54
	v_max3_i32 v21, v128, v130, v21
	v_max3_i32 v25, v74, v70, v25
	v_max3_i32 v55, v66, v68, v55
	v_max3_i32 v27, v72, v76, v27
	v_max_i32_e32 v18, v77, v18
	v_max3_i32 v19, v61, v79, v78
	v_max_i32_e32 v20, v59, v20
	v_max3_i32 v22, v63, v29, v30
	v_max_i32_e32 v32, v58, v32
	v_max_i32_e32 v33, v62, v33
	v_max3_i32 v23, v60, v31, v23
	v_max3_i32 v24, v64, v24, v26
	v_min_i32_e32 v65, v52, v54
	v_min_i32_e32 v50, v21, v25
	v_min_i32_e32 v61, v18, v19
	v_min_i32_e32 v29, v20, v22
	v_min_i32_e32 v26, v23, v24
	v_max_i32_e32 v59, v124, v69
	v_max_i32_e32 v52, v52, v54
	v_max_i32_e32 v21, v21, v25
	v_max_i32_e32 v25, v55, v27
; __device__ __forceinline__ void merge16_desc(int (&a)[16], const int (&b)[16]) {
; #pragma unroll
;     for (int i = 0; i < 16; ++i) a[i] = a[i] > b[15 - i] ? a[i] : b[15 - i];
; #pragma unroll
;     for (int j = 8; j > 0; j >>= 1)
; #pragma unroll
;         for (int i = 0; i < 16; ++i) { const int l = i ^ j; if (l > i) ce_desc(a[i], a[l]); }
; }
; __device__ __forceinline__ void route_task(int task, int tl0, const bf16* QP  , const LAS bf16* KHL, LAS unsigned short* EL, LAS float* GL, int lane) {
;     ...
;             } else merge16_desc(cur, grp);
;         }
;         { const unsigned h4 = 4u * (unsigned)hi;
; #pragma unroll
;           for (int i = 0; i < 16; ++i) cur[i] -= (int)h4; }
;         int oth[16];
; #pragma unroll
;         for (int i = 0; i < 16; ++i) oth[i] = __shfl_xor(cur[i], 32);
;         merge16_desc(cur, oth);
; #pragma unroll
;         for (int i = 0; i < 16; ++i) top[half][i] = cur[i];
	v_max_i32_e32 v18, v18, v19
	v_max_i32_e32 v19, v20, v22
	v_max_i32_e32 v22, v32, v33
	v_max_i32_e32 v23, v23, v24
	v_min_i32_e32 v28, v55, v27
	v_max_i32_e32 v54, v59, v52
	v_max_i32_e32 v27, v21, v25
	v_max_i32_e32 v20, v18, v19
	v_max_i32_e32 v24, v22, v23
	v_min_i32_e32 v51, v32, v33
	v_max_i32_e32 v55, v54, v27
	v_max_i32_e32 v32, v20, v24
	v_min_i32_e32 v27, v54, v27
	v_min_i32_e32 v20, v20, v24
	v_max_i32_e32 v24, v27, v20
	v_min_i32_e32 v20, v27, v20
	v_min_i32_e32 v27, v59, v52
	v_min_i32_e32 v21, v21, v25
	v_min_i32_e32 v18, v18, v19
	v_min_i32_e32 v19, v22, v23
	v_min_i32_e32 v75, v124, v69
	v_max_i32_e32 v25, v27, v21
	v_max_i32_e32 v22, v18, v19
	v_min_i32_e32 v21, v27, v21
	v_min_i32_e32 v18, v18, v19
	v_min_i32_e32 v56, v50, v28
	v_min_i32_e32 v31, v51, v26
	v_max_i32_e32 v23, v25, v22
	v_min_i32_e32 v22, v25, v22
	v_max_i32_e32 v19, v21, v18
	v_min_i32_e32 v18, v21, v18
	v_max_i32_e32 v21, v75, v65
	v_max_i32_e32 v25, v50, v28
	v_max_i32_e32 v28, v61, v29
	v_max_i32_e32 v26, v51, v26
	v_min_i32_e32 v67, v75, v65
	v_min_i32_e32 v30, v61, v29
	v_max_i32_e32 v27, v21, v25
	v_min_i32_e32 v21, v21, v25
	v_min_i32_e32 v25, v28, v26
	v_min_i32_e32 v57, v67, v56
	v_min_i32_e32 v53, v30, v31
	v_max_i32_e32 v29, v28, v26
	v_max_i32_e32 v26, v21, v25
	v_min_i32_e32 v21, v21, v25
	v_max_i32_e32 v25, v67, v56
	v_max_i32_e32 v28, v30, v31
	v_min_i32_e32 v58, v57, v53
	v_max_i32_e32 v33, v55, v32
	v_min_i32_e32 v32, v55, v32
	v_max_i32_e32 v50, v27, v29
	v_min_i32_e32 v27, v27, v29
	v_max_i32_e32 v29, v25, v28
	v_min_i32_e32 v25, v25, v28
	v_max_i32_e32 v28, v57, v53
	v_sub_u32_e32 v30, v33, v87
	v_sub_u32_e32 v31, v32, v87
	v_sub_u32_e32 v24, v24, v87
	v_sub_u32_e32 v20, v20, v87
	v_sub_u32_e32 v23, v23, v87
	v_sub_u32_e32 v22, v22, v87
	v_sub_u32_e32 v19, v19, v87
	v_sub_u32_e32 v18, v18, v87
	v_sub_u32_e32 v32, v50, v87
	v_sub_u32_e32 v27, v27, v87
	v_sub_u32_e32 v26, v26, v87
	v_sub_u32_e32 v21, v21, v87
	v_sub_u32_e32 v29, v29, v87
	v_sub_u32_e32 v25, v25, v87
	v_sub_u32_e32 v28, v28, v87
	v_sub_u32_e32 v33, v58, v87
	ds_bpermute_b32 v50, v123, v30
	ds_bpermute_b32 v51, v123, v31
	ds_bpermute_b32 v52, v123, v24
	ds_bpermute_b32 v53, v123, v20
	ds_bpermute_b32 v54, v123, v23
	ds_bpermute_b32 v55, v123, v22
	ds_bpermute_b32 v56, v123, v19
	ds_bpermute_b32 v57, v123, v18
	ds_bpermute_b32 v58, v123, v32
	ds_bpermute_b32 v59, v123, v27
	ds_bpermute_b32 v60, v123, v26
	ds_bpermute_b32 v61, v123, v33
	ds_bpermute_b32 v62, v123, v28
	ds_bpermute_b32 v63, v123, v25
	ds_bpermute_b32 v64, v123, v29
	ds_bpermute_b32 v65, v123, v21
	s_waitcnt lgkmcnt(4)
	v_max_i32_e32 v30, v30, v61
	s_waitcnt lgkmcnt(3)
	v_max_i32_e32 v31, v31, v62
	s_waitcnt lgkmcnt(2)
	v_max_i32_e32 v24, v24, v63
	s_waitcnt lgkmcnt(1)
	v_max_i32_e32 v20, v20, v64
	s_waitcnt lgkmcnt(0)
	v_max_i32_e32 v23, v23, v65
	v_max_i32_e32 v22, v22, v60
	v_max_i32_e32 v19, v19, v59
	v_max_i32_e32 v18, v18, v58
	v_max_i32_e32 v32, v32, v57
	v_max_i32_e32 v27, v27, v56
	v_max_i32_e32 v26, v26, v55
	v_max_i32_e32 v21, v21, v54
	v_max_i32_e32 v29, v29, v53
	v_max_i32_e32 v25, v25, v52
	v_max_i32_e32 v28, v28, v51
	v_max_i32_e32 v33, v33, v50
	v_max_i32_e32 v50, v30, v32
	v_min_i32_e32 v30, v30, v32
	v_max_i32_e32 v32, v31, v27
	v_min_i32_e32 v27, v31, v27
	v_max_i32_e32 v31, v24, v26
	v_min_i32_e32 v24, v24, v26
	v_max_i32_e32 v26, v20, v21
	v_min_i32_e32 v20, v20, v21
	v_max_i32_e32 v21, v23, v29
	v_min_i32_e32 v23, v23, v29
	v_max_i32_e32 v29, v22, v25
	v_min_i32_e32 v22, v22, v25
	v_max_i32_e32 v25, v19, v28
	v_min_i32_e32 v19, v19, v28
	v_max_i32_e32 v28, v18, v33
	v_min_i32_e32 v18, v18, v33
	v_max_i32_e32 v33, v50, v21
	v_min_i32_e32 v21, v50, v21
	v_max_i32_e32 v50, v32, v29
	v_min_i32_e32 v29, v32, v29
	v_max_i32_e32 v32, v31, v25
	v_min_i32_e32 v25, v31, v25
	v_max_i32_e32 v31, v26, v28
	v_max_i32_e32 v64, v50, v31
	v_min_i32_e32 v67, v50, v31
	ds_read_b128 v[50:53], v94 offset:18432
	ds_read_b128 v[54:57], v94 offset:18464
	v_min_i32_e32 v26, v26, v28
	v_max_i32_e32 v28, v30, v23
	v_min_i32_e32 v58, v30, v23
	v_max_i32_e32 v23, v27, v22
	v_min_i32_e32 v59, v27, v22
	v_max_i32_e32 v22, v24, v19
	v_min_i32_e32 v60, v24, v19
	v_max_i32_e32 v19, v20, v18
	v_min_i32_e32 v61, v20, v18
	v_max_i32_e32 v62, v33, v32
	v_min_i32_e32 v66, v33, v32
	v_max_i32_e32 v68, v21, v25
	v_min_i32_e32 v69, v21, v25
	v_max_i32_e32 v70, v29, v26
	v_min_i32_e32 v71, v29, v26
	v_max_i32_e32 v72, v28, v22
	v_min_i32_e32 v73, v28, v22
	v_max_i32_e32 v74, v23, v19
	v_min_i32_e32 v75, v23, v19
	s_waitcnt vmcnt(3) lgkmcnt(1)
	v_mfma_f32_32x32x16_bf16 v[18:33], v[50:53], v[46:49], v[2:17]
	ds_read_b128 v[50:53], v94 offset:18496
	v_max_i32_e32 v76, v58, v60
	v_min_i32_e32 v77, v58, v60
	v_max_i32_e32 v78, v59, v61
	v_min_i32_e32 v79, v59, v61
	v_max_i32_e32 v63, v62, v64
	v_min_i32_e32 v65, v62, v64
	s_waitcnt vmcnt(2) lgkmcnt(1)
	v_mfma_f32_32x32x16_bf16 v[18:33], v[54:57], v[42:45], v[18:33]
	v_max_i32_e32 v64, v66, v67
	v_min_i32_e32 v62, v66, v67
	v_max_i32_e32 v61, v68, v70
	v_min_i32_e32 v60, v68, v70
	v_max_i32_e32 v59, v69, v71
	v_min_i32_e32 v57, v69, v71
	ds_read_b128 v[66:69], v94 offset:18528
	s_waitcnt vmcnt(1) lgkmcnt(1)
	v_mfma_f32_32x32x16_bf16 v[18:33], v[50:53], v[38:41], v[18:33]
	v_max_i32_e32 v55, v72, v74
	v_min_i32_e32 v58, v72, v74
	v_max_i32_e32 v56, v73, v75
	v_min_i32_e32 v54, v73, v75
	v_max_i32_e32 v53, v76, v78
	v_min_i32_e32 v52, v76, v78
	v_max_i32_e32 v51, v77, v79
	s_waitcnt vmcnt(0) lgkmcnt(0)
; #define LAS __attribute__((address_space(3)))
; #define MFMA32(a, b, c) __builtin_amdgcn_mfma_f32_32x32x16_bf16((a), (b), (c), 0, 0, 0)
; #define CE_(a, b) ce_desc(v[a], v[b])
; __device__ __forceinline__ void sort16_desc(int (&v)[16]) {
;     ...
;     CE_(0,13); CE_(1,12); CE_(2,15); CE_(3,14); CE_(4,8); CE_(5,6); CE_(7,11); CE_(9,10);
;     CE_(0,5); CE_(1,7); CE_(2,9); CE_(3,4); CE_(6,13); CE_(8,14); CE_(10,15); CE_(11,12);
;     CE_(0,1); CE_(2,3); CE_(4,5); CE_(6,8); CE_(7,9); CE_(10,11); CE_(12,13); CE_(14,15);
;     CE_(0,2); CE_(1,3); CE_(4,10); CE_(5,11); CE_(6,7); CE_(8,9); CE_(12,14); CE_(13,15);
;     CE_(1,2); CE_(3,12); CE_(4,6); CE_(5,7); CE_(8,10); CE_(9,11); CE_(13,14);
;     CE_(1,4); CE_(2,6); CE_(5,8); CE_(7,10); CE_(9,13); CE_(11,14);
;     CE_(2,4); CE_(3,6); CE_(9,12); CE_(11,13);
;     CE_(3,5); CE_(6,8); CE_(7,9); CE_(10,12);
;     CE_(3,4); CE_(5,6); CE_(7,8); CE_(9,10); CE_(11,12);
;     CE_(6,7); CE_(8,9);
;     ...
; }
; __device__ __forceinline__ void route_task(int task, int tl0, const bf16* QP  , const LAS bf16* KHL, LAS unsigned short* EL, LAS float* GL, int lane) {
;     ...
;     { unsigned qo = (unsigned)t * (unsigned)D + (unsigned)(head * 128 + 8 * hi); asm volatile("" : "+v"(qo)); const bf16* qp = QP + qo;
; #pragma unroll
;       for (int hf = 0; hf < 2; ++hf)
; #pragma unroll
;         for (int ks = 0; ks < 4; ++ks) qa[hf][ks] = ldg8(qp + 64 * hf + 16 * ks); }
; #pragma unroll
;     for (int half = 0; half < 2; ++half) {
;         int cur[16];
; #pragma unroll
;         for (int kt = 0; kt < 4; ++kt) {
;             f32x16 X;
; #pragma unroll
;             for (int i = 0; i < 16; ++i) X[i] = 8.f;
;             const LAS bf16* khp = KHL + (half * 128 + 32 * kt + r) * 72 + 8 * hi;
; #pragma unroll
;             for (int ks = 0; ks < 4; ++ks) {
;                 const bf16x8 kh = lds8(khp + 16 * ks);
;                 X = MFMA32(kh, qa[half][ks], X);
;             }
;             int grp[16];
; #pragma unroll
;             for (int i = 0; i < 16; ++i) grp[i] = (int)((__float_as_uint(X[i]) | 127u) - (unsigned)(32 * kt + (i & 3) + 8 * (i >> 2)));
;             sort16_desc(grp);
;             if (kt == 0) {
; #pragma unroll
;                 for (int i = 0; i < 16; ++i) cur[i] = grp[i];
;             } else merge16_desc(cur, grp);
	v_or_b32_e32 v146, s10, v88
	v_mov_b32_e32 v147, v83
	v_lshl_add_u64 v[148:149], v[146:147], 1, s[80:81]
	global_load_dwordx4 v[150:153], v[148:149], off
	global_load_dwordx4 v[154:157], v[148:149], off offset:32
	global_load_dwordx4 v[158:161], v[148:149], off offset:64
	global_load_dwordx4 v[162:165], v[148:149], off offset:96
	global_load_dwordx4 v[166:169], v[148:149], off offset:128
	global_load_dwordx4 v[170:173], v[148:149], off offset:160
	global_load_dwordx4 v[174:177], v[148:149], off offset:192
	global_load_dwordx4 v[178:181], v[148:149], off offset:224
	v_mfma_f32_32x32x16_bf16 v[18:33], v[66:69], v[34:37], v[18:33]
	v_min_i32_e32 v50, v77, v79
	s_nop 10
	v_bitop3_b32 v21, v21, s42, 3 bitop3:0x56
	v_bitop3_b32 v32, v32, s42, 26 bitop3:0x56
	v_bitop3_b32 v22, v22, s42, 8 bitop3:0x56
	v_bitop3_b32 v26, v26, s42, 16 bitop3:0x56
	v_bitop3_b32 v31, v31, s42, 25 bitop3:0x56
	v_bitop3_b32 v23, v23, s42, 9 bitop3:0x56
	v_bitop3_b32 v24, v24, s42, 10 bitop3:0x56
	v_bitop3_b32 v27, v27, s42, 17 bitop3:0x56
	v_bitop3_b32 v28, v28, s42, 18 bitop3:0x56
	v_bitop3_b32 v20, v20, s42, 2 bitop3:0x56
	v_bitop3_b32 v33, v33, s42, 27 bitop3:0x56
	v_bitop3_b32 v25, v25, s42, 11 bitop3:0x56
	v_bitop3_b32 v29, v29, s42, 19 bitop3:0x56
	v_bitop3_b32 v19, v19, s42, 1 bitop3:0x56
	v_bitop3_b32 v30, v30, s42, 24 bitop3:0x56
	v_or_b32_e32 v18, 0x7f, v18
	v_max_i32_e32 v66, v21, v32
	v_max_i32_e32 v67, v22, v26
	v_max_i32_e32 v69, v18, v31
	v_max_i32_e32 v70, v23, v24
	v_min_i32_e32 v73, v27, v28
	v_min_i32_e32 v74, v20, v33
	v_min_i32_e32 v76, v25, v29
	v_min_i32_e32 v77, v19, v30
	v_min_i32_e32 v23, v23, v24
	v_min_i32_e32 v18, v18, v31
	v_min_i32_e32 v22, v22, v26
	v_min_i32_e32 v21, v21, v32
	v_max_i32_e32 v19, v19, v30
	v_max_i32_e32 v25, v25, v29
	v_max_i32_e32 v20, v20, v33
	v_max_i32_e32 v27, v27, v28
	v_max_i32_e32 v24, v23, v18
	v_max_i32_e32 v26, v22, v21
	v_min_i32_e32 v29, v19, v25
	v_min_i32_e32 v28, v20, v27
	v_max_i32_e32 v31, v24, v26
	v_min_i32_e32 v24, v24, v26
	v_min_i32_e32 v26, v29, v28
	v_min_i32_e32 v68, v66, v67
	v_min_i32_e32 v71, v69, v70
	v_max_i32_e32 v75, v73, v74
	v_max_i32_e32 v78, v76, v77
	v_max_i32_e32 v30, v29, v28
	v_max_i32_e32 v28, v24, v26
	v_min_i32_e32 v81, v24, v26
	v_min_i32_e32 v24, v76, v77
	v_min_i32_e32 v18, v23, v18
	v_min_i32_e32 v21, v22, v21
	v_min_i32_e32 v22, v73, v74
	v_min_i32_e32 v72, v68, v71
	v_min_i32_e32 v79, v75, v78
	v_min_i32_e32 v76, v24, v18
	v_min_i32_e32 v74, v21, v22
	v_max_i32_e32 v18, v24, v18
	v_max_i32_e32 v21, v21, v22
	v_max_i32_e32 v23, v69, v70
	v_max_i32_e32 v19, v19, v25
	v_max_i32_e32 v20, v20, v27
	v_max_i32_e32 v25, v66, v67
	v_max_i32_e32 v80, v72, v79
	v_max_i32_e32 v29, v68, v71
	v_max_i32_e32 v68, v75, v78
	v_min_i32_e32 v79, v72, v79
	v_max_i32_e32 v77, v76, v74
	v_min_i32_e32 v124, v18, v21
	v_min_i32_e32 v24, v23, v19
	v_min_i32_e32 v26, v20, v25
	v_min_i32_e32 v32, v31, v30
	v_min_i32_e32 v71, v29, v68
	v_max_i32_e32 v82, v81, v79
	v_max_i32_e32 v125, v77, v124
	v_min_i32_e32 v27, v24, v26
	v_max_i32_e32 v18, v18, v21
	v_min_i32_e32 v33, v80, v32
	v_min_i32_e32 v75, v28, v71
	v_max_i32_e32 v22, v82, v125
	v_min_i32_e32 v21, v27, v18
	v_max_i32_e32 v78, v33, v75
	v_max_i32_e32 v66, v22, v21
	v_max_i32_e32 v70, v78, v66
	v_max_i32_e32 v131, v29, v68
	v_min_i32_e32 v78, v78, v66
	ds_read_b128 v[66:69], v97
	v_max_i32_e32 v127, v23, v19
	v_max_i32_e32 v128, v20, v25
	v_max_i32_e32 v126, v24, v26
	v_min_i32_e32 v129, v127, v128
	v_max_i32_e32 v132, v31, v30
	v_min_i32_e32 v130, v126, v129
	v_min_i32_e32 v133, v131, v132
	v_max_i32_e32 v18, v27, v18
	v_min_i32_e32 v19, v130, v133
	v_max_i32_e32 v23, v80, v32
	v_max_i32_e32 v24, v28, v71
	v_min_i32_e32 v20, v18, v19
	v_min_i32_e32 v25, v23, v24
	v_min_i32_e32 v26, v20, v25
	v_min_i32_e32 v80, v70, v26
	v_max_i32_e32 v143, v70, v26
	ds_read_b128 v[70:73], v97 offset:32
	v_min_i32_e32 v75, v33, v75
	v_min_i32_e32 v134, v22, v21
	v_max_i32_e32 v138, v18, v19
	v_max_i32_e32 v139, v23, v24
	v_max_i32_e32 v141, v20, v25
	s_waitcnt lgkmcnt(1)
	v_mfma_f32_32x32x16_bf16 v[18:33], v[66:69], v[46:49], v[2:17]
	ds_read_b128 v[66:69], v97 offset:64
	v_max_i32_e32 v135, v75, v134
	v_max_i32_e32 v136, v78, v135
	v_min_i32_e32 v79, v81, v79
	v_min_i32_e32 v77, v77, v124
	v_min_i32_e32 v78, v78, v135
	v_max_i32_e32 v130, v130, v133
	s_waitcnt lgkmcnt(1)
	v_mfma_f32_32x32x16_bf16 v[18:33], v[70:73], v[42:45], v[18:33]
	ds_read_b128 v[70:73], v97 offset:96
	v_max_i32_e32 v126, v126, v129
	v_min_i32_e32 v74, v76, v74
	v_min_i32_e32 v140, v138, v139
	v_max_i32_e32 v81, v79, v77
	v_min_i32_e32 v82, v82, v125
	v_min_i32_e32 v75, v75, v134
	s_waitcnt lgkmcnt(1)
	v_mfma_f32_32x32x16_bf16 v[18:33], v[66:69], v[38:41], v[18:33]
	v_max_i32_e32 v66, v131, v132
	v_max_i32_e32 v134, v138, v139
	v_min_i32_e32 v77, v79, v77
	v_max_i32_e32 v124, v81, v82
	v_min_i32_e32 v81, v81, v82
	v_min_i32_e32 v67, v126, v66
	v_min_i32_e32 v142, v140, v141
	s_waitcnt lgkmcnt(0)
; #define LAS __attribute__((address_space(3)))
; #define MFMA32(a, b, c) __builtin_amdgcn_mfma_f32_32x32x16_bf16((a), (b), (c), 0, 0, 0)
; #define CE_(a, b) ce_desc(v[a], v[b])
; __device__ __forceinline__ void sort16_desc(int (&v)[16]) {
;     ...
;     CE_(0,13); CE_(1,12); CE_(2,15); CE_(3,14); CE_(4,8); CE_(5,6); CE_(7,11); CE_(9,10);
;     CE_(0,5); CE_(1,7); CE_(2,9); CE_(3,4); CE_(6,13); CE_(8,14); CE_(10,15); CE_(11,12);
;     CE_(0,1); CE_(2,3); CE_(4,5); CE_(6,8); CE_(7,9); CE_(10,11); CE_(12,13); CE_(14,15);
;     CE_(0,2); CE_(1,3); CE_(4,10); CE_(5,11); CE_(6,7); CE_(8,9); CE_(12,14); CE_(13,15);
;     CE_(1,2); CE_(3,12); CE_(4,6); CE_(5,7); CE_(8,10); CE_(9,11); CE_(13,14);
;     CE_(1,4); CE_(2,6); CE_(5,8); CE_(7,10); CE_(9,13); CE_(11,14);
;     CE_(2,4); CE_(3,6); CE_(9,12); CE_(11,13);
;     CE_(3,5); CE_(6,8); CE_(7,9); CE_(10,12);
;     CE_(3,4); CE_(5,6); CE_(7,8); CE_(9,10); CE_(11,12);
;     CE_(6,7); CE_(8,9);
;     ...
; }
; __device__ __forceinline__ void merge16_desc(int (&a)[16], const int (&b)[16]) {
; #pragma unroll
;     for (int i = 0; i < 16; ++i) a[i] = a[i] > b[15 - i] ? a[i] : b[15 - i];
; #pragma unroll
;     for (int j = 8; j > 0; j >>= 1)
; #pragma unroll
;         for (int i = 0; i < 16; ++i) { const int l = i ^ j; if (l > i) ce_desc(a[i], a[l]); }
; }
; __device__ __forceinline__ void route_task(int task, int tl0, const bf16* QP  , const LAS bf16* KHL, LAS unsigned short* EL, LAS float* GL, int lane) {
;     ...
;         for (int kt = 0; kt < 4; ++kt) {
;             f32x16 X;
; #pragma unroll
;             for (int i = 0; i < 16; ++i) X[i] = 8.f;
;             const LAS bf16* khp = KHL + (half * 128 + 32 * kt + r) * 72 + 8 * hi;
; #pragma unroll
;             for (int ks = 0; ks < 4; ++ks) {
;                 const bf16x8 kh = lds8(khp + 16 * ks);
;                 X = MFMA32(kh, qa[half][ks], X);
;             }
;             int grp[16];
; #pragma unroll
;             for (int i = 0; i < 16; ++i) grp[i] = (int)((__float_as_uint(X[i]) | 127u) - (unsigned)(32 * kt + (i & 3) + 8 * (i >> 2)));
;             sort16_desc(grp);
;             if (kt == 0) {
; #pragma unroll
;                 for (int i = 0; i < 16; ++i) cur[i] = grp[i];
;             } else merge16_desc(cur, grp);
	v_mfma_f32_32x32x16_bf16 v[18:33], v[70:73], v[34:37], v[18:33]
	v_min_i32_e32 v68, v130, v67
	v_min_i32_e32 v137, v80, v136
	v_min_i32_e32 v144, v142, v143
	v_min_i32_e32 v125, v124, v75
	v_min_i32_e32 v69, v134, v68
	s_nop 6
	v_bitop3_b32 v21, v21, s42, 35 bitop3:0x56
	v_bitop3_b32 v32, v32, s42, 58 bitop3:0x56
	v_bitop3_b32 v22, v22, s42, 40 bitop3:0x56
	v_bitop3_b32 v26, v26, s42, 48 bitop3:0x56
	v_bitop3_b32 v18, v18, s42, 32 bitop3:0x56
	v_bitop3_b32 v31, v31, s42, 57 bitop3:0x56
	v_bitop3_b32 v23, v23, s42, 41 bitop3:0x56
	v_bitop3_b32 v24, v24, s42, 42 bitop3:0x56
	v_bitop3_b32 v27, v27, s42, 49 bitop3:0x56
	v_bitop3_b32 v28, v28, s42, 50 bitop3:0x56
	v_bitop3_b32 v20, v20, s42, 34 bitop3:0x56
	v_bitop3_b32 v33, v33, s42, 59 bitop3:0x56
	v_bitop3_b32 v25, v25, s42, 43 bitop3:0x56
	v_bitop3_b32 v29, v29, s42, 51 bitop3:0x56
	v_bitop3_b32 v19, v19, s42, 33 bitop3:0x56
	v_bitop3_b32 v30, v30, s42, 56 bitop3:0x56
	v_max_i32_e32 v70, v21, v32
	v_max_i32_e32 v71, v22, v26
	v_max_i32_e32 v73, v18, v31
	v_max_i32_e32 v76, v23, v24
	v_min_i32_e32 v129, v27, v28
	v_min_i32_e32 v131, v20, v33
	v_min_i32_e32 v133, v25, v29
	v_min_i32_e32 v135, v19, v30
	v_min_i32_e32 v23, v23, v24
	v_min_i32_e32 v18, v18, v31
	v_min_i32_e32 v22, v22, v26
	v_min_i32_e32 v21, v21, v32
	v_max_i32_e32 v19, v19, v30
	v_max_i32_e32 v25, v25, v29
	v_max_i32_e32 v20, v20, v33
	v_max_i32_e32 v27, v27, v28
	v_min_i32_e32 v72, v70, v71
	v_min_i32_e32 v79, v73, v76
	v_max_i32_e32 v132, v129, v131
	v_max_i32_e32 v138, v133, v135
	v_max_i32_e32 v24, v23, v18
	v_max_i32_e32 v26, v22, v21
	v_min_i32_e32 v29, v19, v25
	v_min_i32_e32 v28, v20, v27
	v_min_i32_e32 v133, v133, v135
	v_min_i32_e32 v18, v23, v18
	v_min_i32_e32 v21, v22, v21
	v_min_i32_e32 v22, v129, v131
	v_max_i32_e32 v73, v73, v76
	v_max_i32_e32 v19, v19, v25
	v_max_i32_e32 v20, v20, v27
	v_max_i32_e32 v27, v70, v71
	v_min_i32_e32 v82, v72, v79
	v_min_i32_e32 v139, v132, v138
	v_max_i32_e32 v31, v24, v26
	v_max_i32_e32 v30, v29, v28
	v_min_i32_e32 v24, v24, v26
	v_min_i32_e32 v26, v29, v28
	v_max_i32_e32 v29, v72, v79
	v_max_i32_e32 v72, v132, v138
	v_min_i32_e32 v23, v133, v18
	v_min_i32_e32 v129, v21, v22
	v_max_i32_e32 v18, v133, v18
	v_max_i32_e32 v21, v21, v22
	v_min_i32_e32 v25, v73, v19
	v_min_i32_e32 v70, v20, v27
	v_max_i32_e32 v19, v73, v19
	v_max_i32_e32 v20, v20, v27
	v_min_i32_e32 v32, v31, v30
	v_max_i32_e32 v28, v24, v26
	v_min_i32_e32 v79, v29, v72
	v_min_i32_e32 v24, v24, v26
	v_min_i32_e32 v26, v82, v139
	v_max_i32_e32 v131, v23, v129
	v_min_i32_e32 v22, v18, v21
	v_min_i32_e32 v71, v25, v70
	v_max_i32_e32 v25, v25, v70
	v_min_i32_e32 v27, v19, v20
	v_max_i32_e32 v29, v29, v72
	v_max_i32_e32 v30, v31, v30
	v_max_i32_e32 v145, v82, v139
	v_max_i32_e32 v82, v24, v26
	v_max_i32_e32 v133, v131, v22
	v_max_i32_e32 v18, v18, v21
	v_min_i32_e32 v70, v25, v27
	v_min_i32_e32 v31, v29, v30
	v_min_i32_e32 v33, v145, v32
	v_min_i32_e32 v132, v28, v79
	v_max_i32_e32 v135, v82, v133
	v_min_i32_e32 v21, v71, v18
	v_max_i32_e32 v18, v71, v18
	v_min_i32_e32 v71, v70, v31
	v_max_i32_e32 v32, v145, v32
	v_max_i32_e32 v28, v28, v79
	v_max_i32_e32 v138, v33, v132
	v_max_i32_e32 v76, v135, v21
	v_min_i32_e32 v72, v18, v71
	v_min_i32_e32 v73, v32, v28
	v_min_i32_e32 v33, v33, v132
	v_min_i32_e32 v21, v135, v21
	v_max_i32_e32 v18, v18, v71
	v_max_i32_e32 v28, v32, v28
	v_min_i32_e32 v24, v24, v26
	v_min_i32_e32 v22, v131, v22
	v_max_i32_e32 v25, v25, v27
	v_max_i32_e32 v27, v29, v30
	v_max_i32_e32 v139, v138, v76
	v_min_i32_e32 v79, v72, v73
	v_min_i32_e32 v76, v138, v76
	v_max_i32_e32 v132, v33, v21
	v_min_i32_e32 v32, v18, v28
	v_max_i32_e32 v71, v72, v73
	v_max_i32_e32 v26, v24, v22
	v_min_i32_e32 v82, v82, v133
	v_max_i32_e32 v18, v18, v28
	v_max_i32_e32 v28, v70, v31
	v_min_i32_e32 v29, v25, v27
	v_min_i32_e32 v145, v139, v79
	v_max_i32_e32 v135, v76, v132
	v_min_i32_e32 v72, v32, v71
	v_max_i32_e32 v73, v139, v79
	v_max_i32_e32 v131, v26, v82
	v_min_i32_e32 v21, v33, v21
	v_min_i32_e32 v30, v28, v29
	v_min_i32_e32 v138, v145, v135
	v_min_i32_e32 v79, v72, v73
	v_min_i32_e32 v33, v131, v21
	v_min_i32_e32 v76, v76, v132
	v_min_i32_e32 v31, v18, v30
	v_min_i32_e32 v26, v26, v82
	v_min_i32_e32 v22, v24, v22
	v_min_i32_e32 v23, v23, v129
	v_max3_i32 v23, v127, v128, v23
	v_max3_i32 v22, v126, v66, v22
	v_max3_i32 v24, v130, v67, v26
	v_max3_i32 v26, v134, v68, v33
	v_max3_i32 v21, v69, v131, v21
	v_max3_i32 v33, v140, v141, v76
	v_max3_i32 v66, v142, v143, v138
	v_max3_i32 v67, v144, v145, v135
	v_max3_i32 v68, v80, v136, v79
	v_max3_i32 v69, v137, v72, v73
	v_max3_i32 v32, v78, v32, v71
	v_max3_i32 v31, v124, v75, v31
	v_max3_i32 v18, v125, v18, v30
	v_max3_i32 v28, v81, v28, v29
	v_max3_i32 v25, v77, v25, v27
	v_max3_i32 v19, v74, v19, v20
	v_max_i32_e32 v20, v23, v68
	v_min_i32_e32 v23, v23, v68
	v_max_i32_e32 v27, v22, v69
	v_min_i32_e32 v22, v22, v69
	v_max_i32_e32 v29, v24, v32
	v_min_i32_e32 v24, v24, v32
	v_max_i32_e32 v30, v26, v31
	v_min_i32_e32 v26, v26, v31
	v_max_i32_e32 v31, v21, v18
	v_min_i32_e32 v18, v21, v18
	v_max_i32_e32 v21, v33, v28
	v_min_i32_e32 v28, v33, v28
	v_max_i32_e32 v32, v66, v25
	v_min_i32_e32 v25, v66, v25
	v_max_i32_e32 v33, v67, v19
	v_min_i32_e32 v19, v67, v19
	ds_read_b128 v[66:69], v94 offset:27648
	v_max_i32_e32 v70, v20, v31
	v_min_i32_e32 v74, v20, v31
	v_max_i32_e32 v20, v27, v21
	v_min_i32_e32 v75, v27, v21
	v_max_i32_e32 v21, v29, v32
	v_max_i32_e32 v27, v30, v33
	v_max_i32_e32 v127, v70, v21
	v_min_i32_e32 v128, v70, v21
	ds_read_b128 v[70:73], v94 offset:27680
	v_min_i32_e32 v76, v29, v32
	v_min_i32_e32 v77, v30, v33
	v_max_i32_e32 v78, v23, v18
	v_min_i32_e32 v79, v23, v18
	v_max_i32_e32 v80, v22, v28
	v_min_i32_e32 v81, v22, v28
	v_max_i32_e32 v82, v24, v25
	v_min_i32_e32 v124, v24, v25
	v_max_i32_e32 v125, v26, v19
	v_min_i32_e32 v126, v26, v19
	v_max_i32_e32 v129, v20, v27
	v_min_i32_e32 v130, v20, v27
	s_waitcnt lgkmcnt(1)
; #define LAS __attribute__((address_space(3)))
; #define MFMA32(a, b, c) __builtin_amdgcn_mfma_f32_32x32x16_bf16((a), (b), (c), 0, 0, 0)
; #define CE_(a, b) ce_desc(v[a], v[b])
; __device__ __forceinline__ void sort16_desc(int (&v)[16]) {
;     ...
;     CE_(0,13); CE_(1,12); CE_(2,15); CE_(3,14); CE_(4,8); CE_(5,6); CE_(7,11); CE_(9,10);
;     CE_(0,5); CE_(1,7); CE_(2,9); CE_(3,4); CE_(6,13); CE_(8,14); CE_(10,15); CE_(11,12);
;     CE_(0,1); CE_(2,3); CE_(4,5); CE_(6,8); CE_(7,9); CE_(10,11); CE_(12,13); CE_(14,15);
;     CE_(0,2); CE_(1,3); CE_(4,10); CE_(5,11); CE_(6,7); CE_(8,9); CE_(12,14); CE_(13,15);
;     CE_(1,2); CE_(3,12); CE_(4,6); CE_(5,7); CE_(8,10); CE_(9,11); CE_(13,14);
;     CE_(1,4); CE_(2,6); CE_(5,8); CE_(7,10); CE_(9,13); CE_(11,14);
;     CE_(2,4); CE_(3,6); CE_(9,12); CE_(11,13);
;     CE_(3,5); CE_(6,8); CE_(7,9); CE_(10,12);
;     CE_(3,4); CE_(5,6); CE_(7,8); CE_(9,10); CE_(11,12);
;     CE_(6,7); CE_(8,9);
;     ...
; }
; __device__ __forceinline__ void merge16_desc(int (&a)[16], const int (&b)[16]) {
; #pragma unroll
;     for (int i = 0; i < 16; ++i) a[i] = a[i] > b[15 - i] ? a[i] : b[15 - i];
; #pragma unroll
;     for (int j = 8; j > 0; j >>= 1)
; #pragma unroll
;         for (int i = 0; i < 16; ++i) { const int l = i ^ j; if (l > i) ce_desc(a[i], a[l]); }
; }
; __device__ __forceinline__ void route_task(int task, int tl0, const bf16* QP  , const LAS bf16* KHL, LAS unsigned short* EL, LAS float* GL, int lane) {
;     ...
;         for (int kt = 0; kt < 4; ++kt) {
;             f32x16 X;
; #pragma unroll
;             for (int i = 0; i < 16; ++i) X[i] = 8.f;
;             const LAS bf16* khp = KHL + (half * 128 + 32 * kt + r) * 72 + 8 * hi;
; #pragma unroll
;             for (int ks = 0; ks < 4; ++ks) {
;                 const bf16x8 kh = lds8(khp + 16 * ks);
;                 X = MFMA32(kh, qa[half][ks], X);
;             }
;             int grp[16];
; #pragma unroll
;             for (int i = 0; i < 16; ++i) grp[i] = (int)((__float_as_uint(X[i]) | 127u) - (unsigned)(32 * kt + (i & 3) + 8 * (i >> 2)));
;             sort16_desc(grp);
;             if (kt == 0) {
; #pragma unroll
;                 for (int i = 0; i < 16; ++i) cur[i] = grp[i];
;             } else merge16_desc(cur, grp);
	v_mfma_f32_32x32x16_bf16 v[18:33], v[66:69], v[46:49], v[2:17]
	ds_read_b128 v[66:69], v94 offset:27712
	v_max_i32_e32 v131, v74, v76
	v_min_i32_e32 v74, v74, v76
	v_max_i32_e32 v76, v75, v77
	v_min_i32_e32 v75, v75, v77
	v_max_i32_e32 v77, v78, v82
	v_min_i32_e32 v78, v78, v82
	s_waitcnt lgkmcnt(1)
	v_mfma_f32_32x32x16_bf16 v[18:33], v[70:73], v[42:45], v[18:33]
	ds_read_b128 v[70:73], v94 offset:27744
	v_max_i32_e32 v82, v80, v125
	v_min_i32_e32 v80, v80, v125
	v_max_i32_e32 v125, v79, v124
	v_min_i32_e32 v79, v79, v124
	v_max_i32_e32 v124, v81, v126
	v_min_i32_e32 v81, v81, v126
	s_waitcnt lgkmcnt(1)
	v_mfma_f32_32x32x16_bf16 v[18:33], v[66:69], v[38:41], v[18:33]
	v_min_i32_e32 v126, v127, v129
	v_min_i32_e32 v66, v128, v130
	v_min_i32_e32 v67, v131, v76
	v_min_i32_e32 v69, v77, v82
	v_min_i32_e32 v132, v78, v80
	v_min_i32_e32 v133, v125, v124
	v_min_i32_e32 v68, v74, v75
	s_waitcnt lgkmcnt(0)
	v_mfma_f32_32x32x16_bf16 v[18:33], v[70:73], v[34:37], v[18:33]
	v_min_i32_e32 v134, v79, v81
	s_nop 10
	v_and_or_b32 v21, v21, s43, 60
	v_and_or_b32 v32, v32, s43, 37
	v_and_or_b32 v22, v22, s43, 55
	v_and_or_b32 v26, v26, s43, 47
	v_bitop3_b32 v18, v18, s42, 64 bitop3:0x56
	v_and_or_b32 v31, v31, s43, 38
	v_and_or_b32 v23, v23, s43, 54
	v_and_or_b32 v24, v24, s43, 53
	v_and_or_b32 v27, v27, s43, 46
	v_and_or_b32 v28, v28, s43, 45
	v_and_or_b32 v20, v20, s43, 61
	v_and_or_b32 v33, v33, s43, 36
	v_and_or_b32 v25, v25, s43, 52
	v_and_or_b32 v29, v29, s43, 44
	v_and_or_b32 v19, v19, s43, 62
	v_and_or_b32 v30, v30, s43, 39
	v_max_i32_e32 v70, v21, v32
	v_max_i32_e32 v71, v22, v26
	v_max_i32_e32 v73, v18, v31
	v_max_i32_e32 v135, v23, v24
	v_min_i32_e32 v138, v27, v28
	v_min_i32_e32 v139, v20, v33
	v_min_i32_e32 v141, v25, v29
	v_min_i32_e32 v142, v19, v30
	v_min_i32_e32 v23, v23, v24
	v_min_i32_e32 v18, v18, v31
	v_min_i32_e32 v22, v22, v26
	v_min_i32_e32 v21, v21, v32
	v_max_i32_e32 v19, v19, v30
	v_max_i32_e32 v25, v25, v29
	v_max_i32_e32 v20, v20, v33
	v_max_i32_e32 v27, v27, v28
	v_min_i32_e32 v72, v70, v71
	v_min_i32_e32 v136, v73, v135
	v_max_i32_e32 v140, v138, v139
	v_max_i32_e32 v143, v141, v142
	v_max_i32_e32 v24, v23, v18
	v_max_i32_e32 v26, v22, v21
	v_min_i32_e32 v29, v19, v25
	v_min_i32_e32 v28, v20, v27
	v_min_i32_e32 v141, v141, v142
	v_min_i32_e32 v18, v23, v18
	v_min_i32_e32 v21, v22, v21
	v_min_i32_e32 v22, v138, v139
	v_max_i32_e32 v73, v73, v135
	v_max_i32_e32 v19, v19, v25
	v_max_i32_e32 v20, v20, v27
	v_max_i32_e32 v27, v70, v71
	v_min_i32_e32 v137, v72, v136
	v_min_i32_e32 v144, v140, v143
	v_max_i32_e32 v31, v24, v26
	v_max_i32_e32 v30, v29, v28
	v_min_i32_e32 v24, v24, v26
	v_min_i32_e32 v26, v29, v28
	v_max_i32_e32 v29, v72, v136
	v_max_i32_e32 v72, v140, v143
	v_min_i32_e32 v23, v141, v18
	v_min_i32_e32 v138, v21, v22
	v_max_i32_e32 v18, v141, v18
	v_max_i32_e32 v21, v21, v22
	v_min_i32_e32 v25, v73, v19
	v_min_i32_e32 v70, v20, v27
	v_max_i32_e32 v19, v73, v19
	v_max_i32_e32 v20, v20, v27
	v_min_i32_e32 v32, v31, v30
	v_max_i32_e32 v28, v24, v26
	v_min_i32_e32 v136, v29, v72
	v_min_i32_e32 v24, v24, v26
	v_min_i32_e32 v26, v137, v144
	v_max_i32_e32 v139, v23, v138
	v_min_i32_e32 v22, v18, v21
	v_min_i32_e32 v71, v25, v70
	v_max_i32_e32 v25, v25, v70
	v_min_i32_e32 v27, v19, v20
	v_max_i32_e32 v29, v29, v72
	v_max_i32_e32 v30, v31, v30
	v_max_i32_e32 v145, v137, v144
	v_max_i32_e32 v137, v24, v26
	v_max_i32_e32 v141, v139, v22
	v_max_i32_e32 v18, v18, v21
	v_min_i32_e32 v70, v25, v27
	v_min_i32_e32 v31, v29, v30
	v_min_i32_e32 v33, v145, v32
	v_min_i32_e32 v140, v28, v136
	v_max_i32_e32 v142, v137, v141
	v_min_i32_e32 v21, v71, v18
	v_max_i32_e32 v18, v71, v18
	v_min_i32_e32 v71, v70, v31
	v_max_i32_e32 v32, v145, v32
	v_max_i32_e32 v28, v28, v136
	v_max_i32_e32 v143, v33, v140
	v_max_i32_e32 v135, v142, v21
	v_min_i32_e32 v72, v18, v71
	v_min_i32_e32 v73, v32, v28
	v_min_i32_e32 v33, v33, v140
	v_min_i32_e32 v21, v142, v21
	v_max_i32_e32 v18, v18, v71
	v_max_i32_e32 v28, v32, v28
	v_min_i32_e32 v24, v24, v26
	v_min_i32_e32 v22, v139, v22
	v_max_i32_e32 v25, v25, v27
	v_max_i32_e32 v27, v29, v30
	v_max_i32_e32 v144, v143, v135
	v_min_i32_e32 v136, v72, v73
	v_min_i32_e32 v135, v143, v135
	v_max_i32_e32 v140, v33, v21
	v_min_i32_e32 v32, v18, v28
	v_max_i32_e32 v71, v72, v73
	v_max_i32_e32 v26, v24, v22
	v_min_i32_e32 v137, v137, v141
	v_max_i32_e32 v18, v18, v28
	v_max_i32_e32 v28, v70, v31
	v_min_i32_e32 v29, v25, v27
	v_min_i32_e32 v145, v144, v136
	v_max_i32_e32 v142, v135, v140
	v_min_i32_e32 v72, v32, v71
	v_max_i32_e32 v73, v144, v136
	v_max_i32_e32 v139, v26, v137
	v_min_i32_e32 v21, v33, v21
	v_min_i32_e32 v30, v28, v29
	v_min_i32_e32 v143, v145, v142
	v_min_i32_e32 v136, v72, v73
	v_min_i32_e32 v33, v139, v21
	v_max_i32_e32 v21, v139, v21
	v_min_i32_e32 v135, v135, v140
	v_max_i32_e32 v32, v32, v71
	v_min_i32_e32 v31, v18, v30
	v_max_i32_e32 v18, v18, v30
	v_min_i32_e32 v26, v26, v137
	v_min_i32_e32 v22, v24, v22
	v_max_i32_e32 v24, v25, v27
	v_min_i32_e32 v23, v23, v138
	v_max3_i32 v23, v127, v129, v23
	v_max_i32_e32 v22, v126, v22
	v_max3_i32 v25, v128, v130, v26
	v_max_i32_e32 v26, v66, v33
	v_max3_i32 v21, v131, v76, v21
	v_max_i32_e32 v27, v67, v135
	v_max3_i32 v30, v74, v75, v143
	v_max3_i32 v66, v77, v82, v136
	v_max3_i32 v67, v69, v72, v73
	v_max3_i32 v32, v78, v80, v32
	v_max_i32_e32 v31, v132, v31
	v_max3_i32 v18, v125, v124, v18
	v_max3_i32 v28, v133, v28, v29
	v_max3_i32 v24, v79, v81, v24
	v_max3_i32 v33, v68, v145, v142
	v_max3_i32 v19, v134, v19, v20
	v_max_i32_e32 v20, v23, v66
	v_min_i32_e32 v23, v23, v66
	v_max_i32_e32 v29, v22, v67
	v_max_i32_e32 v66, v25, v32
	v_min_i32_e32 v25, v25, v32
	v_max_i32_e32 v32, v26, v31
	v_min_i32_e32 v26, v26, v31
	v_max_i32_e32 v31, v21, v18
	v_min_i32_e32 v18, v21, v18
	v_max_i32_e32 v21, v27, v28
	v_min_i32_e32 v27, v27, v28
	v_max_i32_e32 v28, v30, v24
	v_min_i32_e32 v22, v22, v67
	v_min_i32_e32 v24, v30, v24
	v_max_i32_e32 v30, v33, v19
	v_min_i32_e32 v19, v33, v19
	v_max_i32_e32 v33, v20, v31
	v_min_i32_e32 v74, v20, v31
	v_max_i32_e32 v20, v29, v21
	v_min_i32_e32 v75, v29, v21
	v_max_i32_e32 v21, v66, v28
	v_min_i32_e32 v76, v66, v28
	ds_read_b128 v[66:69], v98
	ds_read_b128 v[70:73], v98 offset:32
	v_max_i32_e32 v28, v32, v30
	v_min_i32_e32 v77, v32, v30
	v_max_i32_e32 v78, v23, v18
	v_min_i32_e32 v79, v23, v18
	v_max_i32_e32 v80, v22, v27
	v_min_i32_e32 v81, v22, v27
	v_max_i32_e32 v82, v25, v24
	v_min_i32_e32 v124, v25, v24
	v_max_i32_e32 v125, v26, v19
	v_min_i32_e32 v126, v26, v19
	v_max_i32_e32 v127, v33, v21
	v_min_i32_e32 v128, v33, v21
	v_max_i32_e32 v129, v20, v28
	v_min_i32_e32 v130, v20, v28
	s_waitcnt lgkmcnt(1)
; #define LAS __attribute__((address_space(3)))
; #define MFMA32(a, b, c) __builtin_amdgcn_mfma_f32_32x32x16_bf16((a), (b), (c), 0, 0, 0)
; #define CE_(a, b) ce_desc(v[a], v[b])
; __device__ __forceinline__ void sort16_desc(int (&v)[16]) {
;     ...
;     CE_(0,13); CE_(1,12); CE_(2,15); CE_(3,14); CE_(4,8); CE_(5,6); CE_(7,11); CE_(9,10);
;     CE_(0,5); CE_(1,7); CE_(2,9); CE_(3,4); CE_(6,13); CE_(8,14); CE_(10,15); CE_(11,12);
;     CE_(0,1); CE_(2,3); CE_(4,5); CE_(6,8); CE_(7,9); CE_(10,11); CE_(12,13); CE_(14,15);
;     CE_(0,2); CE_(1,3); CE_(4,10); CE_(5,11); CE_(6,7); CE_(8,9); CE_(12,14); CE_(13,15);
;     CE_(1,2); CE_(3,12); CE_(4,6); CE_(5,7); CE_(8,10); CE_(9,11); CE_(13,14);
;     CE_(1,4); CE_(2,6); CE_(5,8); CE_(7,10); CE_(9,13); CE_(11,14);
;     CE_(2,4); CE_(3,6); CE_(9,12); CE_(11,13);
;     CE_(3,5); CE_(6,8); CE_(7,9); CE_(10,12);
;     CE_(3,4); CE_(5,6); CE_(7,8); CE_(9,10); CE_(11,12);
;     CE_(6,7); CE_(8,9);
;     ...
; }
; __device__ __forceinline__ void merge16_desc(int (&a)[16], const int (&b)[16]) {
; #pragma unroll
;     for (int i = 0; i < 16; ++i) a[i] = a[i] > b[15 - i] ? a[i] : b[15 - i];
; #pragma unroll
;     for (int j = 8; j > 0; j >>= 1)
; #pragma unroll
;         for (int i = 0; i < 16; ++i) { const int l = i ^ j; if (l > i) ce_desc(a[i], a[l]); }
; }
; __device__ __forceinline__ void route_task(int task, int tl0, const bf16* QP  , const LAS bf16* KHL, LAS unsigned short* EL, LAS float* GL, int lane) {
;     ...
;         for (int kt = 0; kt < 4; ++kt) {
;             f32x16 X;
; #pragma unroll
;             for (int i = 0; i < 16; ++i) X[i] = 8.f;
;             const LAS bf16* khp = KHL + (half * 128 + 32 * kt + r) * 72 + 8 * hi;
; #pragma unroll
;             for (int ks = 0; ks < 4; ++ks) {
;                 const bf16x8 kh = lds8(khp + 16 * ks);
;                 X = MFMA32(kh, qa[half][ks], X);
;             }
;             int grp[16];
; #pragma unroll
;             for (int i = 0; i < 16; ++i) grp[i] = (int)((__float_as_uint(X[i]) | 127u) - (unsigned)(32 * kt + (i & 3) + 8 * (i >> 2)));
;             sort16_desc(grp);
;             if (kt == 0) {
; #pragma unroll
;                 for (int i = 0; i < 16; ++i) cur[i] = grp[i];
;             } else merge16_desc(cur, grp);
	v_mfma_f32_32x32x16_bf16 v[18:33], v[66:69], v[46:49], v[2:17]
	ds_read_b128 v[46:49], v98 offset:64
	v_max_i32_e32 v67, v75, v77
	v_min_i32_e32 v68, v75, v77
	v_max_i32_e32 v75, v80, v125
	v_max_i32_e32 v131, v74, v76
	v_min_i32_e32 v66, v74, v76
	v_max_i32_e32 v69, v78, v82
	s_waitcnt lgkmcnt(1)
	v_mfma_f32_32x32x16_bf16 v[18:33], v[70:73], v[42:45], v[18:33]
	ds_read_b128 v[42:45], v98 offset:96
	v_min_i32_e32 v70, v80, v125
	v_max_i32_e32 v71, v79, v124
	v_min_i32_e32 v72, v79, v124
	v_min_i32_e32 v74, v78, v82
	v_max_i32_e32 v73, v81, v126
	v_min_i32_e32 v76, v81, v126
	s_waitcnt lgkmcnt(1)
	v_mfma_f32_32x32x16_bf16 v[18:33], v[46:49], v[38:41], v[18:33]
	v_min_i32_e32 v77, v127, v129
	v_min_i32_e32 v38, v128, v130
	v_min_i32_e32 v39, v131, v67
	v_min_i32_e32 v40, v66, v68
	v_min_i32_e32 v41, v69, v75
	v_min_i32_e32 v46, v74, v70
	v_min_i32_e32 v47, v71, v73
	s_waitcnt lgkmcnt(0)
	v_mfma_f32_32x32x16_bf16 v[18:33], v[42:45], v[34:37], v[18:33]
	v_min_i32_e32 v48, v72, v76
	s_nop 10
	v_and_or_b32 v25, v25, s43, 20
	v_and_or_b32 v29, v29, s43, 12
	v_and_or_b32 v19, v19, s43, 30
	v_and_or_b32 v30, v30, s43, 7
	v_and_or_b32 v23, v23, s43, 22
	v_and_or_b32 v24, v24, s43, 21
	v_and_or_b32 v18, v18, s43, 31
	v_and_or_b32 v31, v31, s43, 6
	v_and_or_b32 v22, v22, s43, 23
	v_and_or_b32 v26, v26, s43, 15
	v_and_or_b32 v21, v21, s43, 28
	v_and_or_b32 v32, v32, s43, 5
	v_and_or_b32 v27, v27, s43, 14
	v_and_or_b32 v28, v28, s43, 13
	v_and_or_b32 v20, v20, s43, 29
	v_and_or_b32 v33, v33, s43, 4
	v_min_i32_e32 v34, v25, v29
	v_min_i32_e32 v35, v19, v30
	v_min_i32_e32 v37, v23, v24
	v_min_i32_e32 v42, v18, v31
	v_min_i32_e32 v45, v22, v26
	v_min_i32_e32 v49, v21, v32
	v_min_i32_e32 v79, v27, v28
	v_min_i32_e32 v80, v20, v33
	v_max_i32_e32 v18, v18, v31
	v_max_i32_e32 v23, v23, v24
	v_max_i32_e32 v19, v19, v30
	v_max_i32_e32 v25, v25, v29
	v_max_i32_e32 v20, v20, v33
	v_max_i32_e32 v27, v27, v28
	v_max_i32_e32 v21, v21, v32
	v_max_i32_e32 v22, v22, v26
	v_max_i32_e32 v24, v18, v23
	v_max_i32_e32 v29, v19, v25
	v_max_i32_e32 v28, v20, v27
	v_max_i32_e32 v26, v21, v22
	v_min_i32_e32 v30, v24, v29
	v_min_i32_e32 v31, v28, v26
	v_min_i32_e32 v43, v37, v42
	v_min_i32_e32 v32, v30, v31
	v_max_i32_e32 v30, v30, v31
	v_min_i32_e32 v21, v21, v22
	v_min_i32_e32 v18, v18, v23
	v_max_i32_e32 v23, v79, v80
	v_max_i32_e32 v31, v34, v35
	v_max_i32_e32 v37, v37, v42
	v_max_i32_e32 v42, v45, v49
	v_min_i32_e32 v19, v19, v25
	v_min_i32_e32 v20, v20, v27
	v_min_i32_e32 v36, v34, v35
	v_min_i32_e32 v78, v45, v49
	v_min_i32_e32 v81, v79, v80
	v_max_i32_e32 v22, v21, v18
	v_max_i32_e32 v45, v37, v42
	v_max_i32_e32 v25, v19, v20
	v_min_i32_e32 v18, v21, v18
	v_min_i32_e32 v21, v23, v31
	v_min_i32_e32 v44, v36, v43
	v_min_i32_e32 v82, v78, v81
	v_max_i32_e32 v33, v36, v43
	v_max_i32_e32 v36, v78, v81
	v_max_i32_e32 v24, v24, v29
	v_max_i32_e32 v26, v28, v26
	v_max_i32_e32 v34, v23, v31
	v_max_i32_e32 v27, v45, v25
	v_max_i32_e32 v23, v18, v21
	v_min_i32_e32 v25, v45, v25
	v_min_i32_e32 v37, v37, v42
	v_min_i32_e32 v19, v19, v20
	v_max_i32_e32 v43, v33, v36
	v_min_i32_e32 v28, v24, v26
	v_max_i32_e32 v35, v22, v34
	v_max_i32_e32 v31, v23, v25
	v_max_i32_e32 v20, v37, v19
	v_min_i32_e32 v23, v23, v25
	v_min_i32_e32 v19, v37, v19
	v_min_i32_e32 v18, v18, v21
	v_max_i32_e32 v25, v44, v82
	v_min_i32_e32 v33, v33, v36
	v_min_i32_e32 v29, v30, v28
	v_min_i32_e32 v49, v35, v27
	v_min_i32_e32 v22, v22, v34
	v_max_i32_e32 v21, v19, v18
	v_max_i32_e32 v36, v25, v33
	v_max_i32_e32 v78, v32, v43
	v_min_i32_e32 v79, v29, v49
	v_max_i32_e32 v34, v20, v22
	v_min_i32_e32 v20, v20, v22
	v_max_i32_e32 v37, v21, v36
	v_min_i32_e32 v32, v32, v43
	v_max_i32_e32 v80, v78, v79
	v_max_i32_e32 v42, v31, v34
	v_min_i32_e32 v78, v78, v79
	v_min_i32_e32 v31, v31, v34
	v_max_i32_e32 v22, v23, v20
	v_max_i32_e32 v43, v37, v32
	v_min_i32_e32 v18, v19, v18
	v_min_i32_e32 v19, v25, v33
	v_min_i32_e32 v20, v23, v20
	v_min_i32_e32 v23, v37, v32
	v_max_i32_e32 v28, v30, v28
	v_max_i32_e32 v27, v35, v27
	v_min_i32_e32 v124, v44, v82
	v_min_i32_e32 v45, v80, v42
	v_max_i32_e32 v34, v78, v31
	v_max_i32_e32 v44, v22, v43
	v_min_i32_e32 v31, v78, v31
	v_max_i32_e32 v25, v18, v19
	v_min_i32_e32 v21, v21, v36
	v_min_i32_e32 v32, v20, v23
	v_max_i32_e32 v29, v29, v49
	v_min_i32_e32 v30, v28, v27
	v_min_i32_e32 v22, v22, v43
	v_max_i32_e32 v20, v20, v23
	v_min_i32_e32 v79, v45, v34
	v_max_i32_e32 v78, v44, v31
	v_max_i32_e32 v33, v25, v21
	v_max_i32_e32 v37, v80, v42
	v_min_i32_e32 v35, v29, v30
	v_min_i32_e32 v31, v44, v31
	v_max_i32_e32 v23, v22, v20
	v_min_i32_e32 v81, v79, v78
	v_max_i32_e32 v36, v33, v32
	v_max_i32_e32 v42, v37, v35
	v_min_i32_e32 v21, v25, v21
	v_max_i32_e32 v25, v45, v34
	v_min_i32_e32 v43, v31, v23
	v_max_i32_e32 v27, v28, v27
	v_min_i32_e32 v18, v18, v19
	v_min_i32_e32 v20, v22, v20
	v_min_i32_e32 v32, v33, v32
	v_min_i32_e32 v33, v37, v35
	v_max3_i32 v124, v127, v129, v124
	v_max3_i32 v69, v69, v75, v81
	v_max3_i32 v36, v131, v67, v36
	v_max3_i32 v42, v71, v73, v42
	v_max3_i32 v21, v128, v130, v21
	v_max3_i32 v25, v74, v70, v25
	v_max3_i32 v43, v66, v68, v43
	v_max3_i32 v27, v72, v76, v27
	v_max_i32_e32 v18, v77, v18
	v_max3_i32 v19, v41, v79, v78
	v_max_i32_e32 v20, v39, v20
	v_max3_i32 v22, v47, v29, v30
	v_max_i32_e32 v32, v38, v32
	v_max_i32_e32 v33, v46, v33
	v_max3_i32 v23, v40, v31, v23
	v_max3_i32 v24, v48, v24, v26
	v_min_i32_e32 v49, v36, v42
	v_min_i32_e32 v34, v21, v25
	v_min_i32_e32 v41, v18, v19
	v_min_i32_e32 v29, v20, v22
	v_min_i32_e32 v26, v23, v24
	v_max_i32_e32 v39, v124, v69
	v_max_i32_e32 v36, v36, v42
	v_max_i32_e32 v21, v21, v25
	v_max_i32_e32 v25, v43, v27
; __device__ __forceinline__ void merge16_desc(int (&a)[16], const int (&b)[16]) {
; #pragma unroll
;     for (int i = 0; i < 16; ++i) a[i] = a[i] > b[15 - i] ? a[i] : b[15 - i];
; #pragma unroll
;     for (int j = 8; j > 0; j >>= 1)
; #pragma unroll
;         for (int i = 0; i < 16; ++i) { const int l = i ^ j; if (l > i) ce_desc(a[i], a[l]); }
; }
; __device__ __forceinline__ void route_task(int task, int tl0, const bf16* QP  , const LAS bf16* KHL, LAS unsigned short* EL, LAS float* GL, int lane) {
;     ...
;             } else merge16_desc(cur, grp);
;         }
;         { const unsigned h4 = 4u * (unsigned)hi;
; #pragma unroll
;           for (int i = 0; i < 16; ++i) cur[i] -= (int)h4; }
;         int oth[16];
; #pragma unroll
;         for (int i = 0; i < 16; ++i) oth[i] = __shfl_xor(cur[i], 32);
;         merge16_desc(cur, oth);
; #pragma unroll
;         for (int i = 0; i < 16; ++i) top[half][i] = cur[i];
;     }
;     unsigned P1[4], P2[4];
; #pragma unroll
;     for (int q = 0; q < 4; ++q) { P1[q] = 0u; P2[q] = 0u;
; #pragma unroll
;         for (int s = 0; s < 4; ++s) { P1[q] |= (127u - ((unsigned)top[0][4 * q + s] & 127u)) << (8 * s); P2[q] |= (127u - ((unsigned)top[1][4 * q + s] & 127u)) << (8 * s); } }
	v_max_i32_e32 v18, v18, v19
	v_max_i32_e32 v19, v20, v22
	v_max_i32_e32 v22, v32, v33
	v_max_i32_e32 v23, v23, v24
	v_min_i32_e32 v28, v43, v27
	v_max_i32_e32 v40, v39, v36
	v_max_i32_e32 v27, v21, v25
	v_max_i32_e32 v20, v18, v19
	v_max_i32_e32 v24, v22, v23
	v_min_i32_e32 v35, v32, v33
	v_max_i32_e32 v42, v40, v27
	v_max_i32_e32 v32, v20, v24
	v_min_i32_e32 v27, v40, v27
	v_min_i32_e32 v20, v20, v24
	v_max_i32_e32 v24, v27, v20
	v_min_i32_e32 v20, v27, v20
	v_min_i32_e32 v27, v39, v36
	v_min_i32_e32 v21, v21, v25
	v_min_i32_e32 v18, v18, v19
	v_min_i32_e32 v19, v22, v23
	v_min_i32_e32 v75, v124, v69
	v_max_i32_e32 v25, v27, v21
	v_max_i32_e32 v22, v18, v19
	v_min_i32_e32 v21, v27, v21
	v_min_i32_e32 v18, v18, v19
	v_min_i32_e32 v44, v34, v28
	v_min_i32_e32 v31, v35, v26
	v_max_i32_e32 v23, v25, v22
	v_min_i32_e32 v22, v25, v22
	v_max_i32_e32 v19, v21, v18
	v_min_i32_e32 v18, v21, v18
	v_max_i32_e32 v21, v75, v49
	v_max_i32_e32 v25, v34, v28
	v_max_i32_e32 v28, v41, v29
	v_max_i32_e32 v26, v35, v26
	v_min_i32_e32 v67, v75, v49
	v_min_i32_e32 v30, v41, v29
	v_max_i32_e32 v27, v21, v25
	v_min_i32_e32 v21, v21, v25
	v_min_i32_e32 v25, v28, v26
	v_min_i32_e32 v45, v67, v44
	v_min_i32_e32 v37, v30, v31
	v_max_i32_e32 v29, v28, v26
	v_max_i32_e32 v26, v21, v25
	v_min_i32_e32 v21, v21, v25
	v_max_i32_e32 v25, v67, v44
	v_max_i32_e32 v28, v30, v31
	v_min_i32_e32 v38, v45, v37
	v_max_i32_e32 v33, v42, v32
	v_min_i32_e32 v32, v42, v32
	v_max_i32_e32 v34, v27, v29
	v_min_i32_e32 v27, v27, v29
	v_max_i32_e32 v29, v25, v28
	v_min_i32_e32 v25, v25, v28
	v_max_i32_e32 v28, v45, v37
	v_sub_u32_e32 v30, v33, v87
	v_sub_u32_e32 v31, v32, v87
	v_sub_u32_e32 v24, v24, v87
	v_sub_u32_e32 v20, v20, v87
	v_sub_u32_e32 v23, v23, v87
	v_sub_u32_e32 v22, v22, v87
	v_sub_u32_e32 v19, v19, v87
	v_sub_u32_e32 v18, v18, v87
	v_sub_u32_e32 v32, v34, v87
	v_sub_u32_e32 v27, v27, v87
	v_sub_u32_e32 v26, v26, v87
	v_sub_u32_e32 v21, v21, v87
	v_sub_u32_e32 v29, v29, v87
	v_sub_u32_e32 v25, v25, v87
	v_sub_u32_e32 v28, v28, v87
	v_sub_u32_e32 v33, v38, v87
	ds_bpermute_b32 v34, v123, v30
	ds_bpermute_b32 v35, v123, v31
	ds_bpermute_b32 v36, v123, v24
	ds_bpermute_b32 v37, v123, v20
	ds_bpermute_b32 v38, v123, v23
	ds_bpermute_b32 v39, v123, v22
	ds_bpermute_b32 v40, v123, v19
	ds_bpermute_b32 v41, v123, v18
	ds_bpermute_b32 v42, v123, v32
	ds_bpermute_b32 v43, v123, v27
	ds_bpermute_b32 v44, v123, v26
	ds_bpermute_b32 v45, v123, v33
	ds_bpermute_b32 v46, v123, v28
	ds_bpermute_b32 v47, v123, v25
	ds_bpermute_b32 v48, v123, v29
	ds_bpermute_b32 v49, v123, v21
	s_waitcnt lgkmcnt(4)
	v_max_i32_e32 v30, v30, v45
	s_waitcnt lgkmcnt(3)
	v_max_i32_e32 v31, v31, v46
	s_waitcnt lgkmcnt(2)
	v_max_i32_e32 v24, v24, v47
	s_waitcnt lgkmcnt(1)
	v_max_i32_e32 v20, v20, v48
	s_waitcnt lgkmcnt(0)
	v_max_i32_e32 v23, v23, v49
	v_max_i32_e32 v22, v22, v44
	v_max_i32_e32 v19, v19, v43
	v_max_i32_e32 v18, v18, v42
	v_max_i32_e32 v32, v32, v41
	v_max_i32_e32 v27, v27, v40
	v_max_i32_e32 v26, v26, v39
	v_max_i32_e32 v21, v21, v38
	v_max_i32_e32 v29, v29, v37
	v_max_i32_e32 v25, v25, v36
	v_max_i32_e32 v28, v28, v35
	v_max_i32_e32 v33, v33, v34
	v_max_i32_e32 v34, v30, v32
	v_min_i32_e32 v30, v30, v32
	v_max_i32_e32 v32, v31, v27
	v_min_i32_e32 v27, v31, v27
	v_max_i32_e32 v31, v24, v26
	v_min_i32_e32 v24, v24, v26
	v_max_i32_e32 v26, v20, v21
	v_min_i32_e32 v20, v20, v21
	v_max_i32_e32 v21, v23, v29
	v_min_i32_e32 v23, v23, v29
	v_max_i32_e32 v29, v22, v25
	v_min_i32_e32 v22, v22, v25
	v_max_i32_e32 v25, v19, v28
	v_min_i32_e32 v19, v19, v28
	v_max_i32_e32 v28, v18, v33
	v_min_i32_e32 v18, v18, v33
	v_max_i32_e32 v33, v34, v21
	v_min_i32_e32 v21, v34, v21
	v_max_i32_e32 v34, v32, v29
	v_min_i32_e32 v29, v32, v29
	v_max_i32_e32 v32, v31, v25
	v_min_i32_e32 v25, v31, v25
	v_max_i32_e32 v31, v26, v28
	v_min_i32_e32 v26, v26, v28
	v_max_i32_e32 v28, v30, v23
	v_min_i32_e32 v23, v30, v23
	v_max_i32_e32 v30, v27, v22
	v_min_i32_e32 v22, v27, v22
	v_max_i32_e32 v27, v24, v19
	v_min_i32_e32 v19, v24, v19
	v_max_i32_e32 v24, v20, v18
	v_min_i32_e32 v18, v20, v18
	v_max_i32_e32 v20, v33, v32
	v_min_i32_e32 v32, v33, v32
	v_max_i32_e32 v33, v34, v31
	v_min_i32_e32 v31, v34, v31
	v_max_i32_e32 v34, v21, v25
	v_min_i32_e32 v21, v21, v25
	v_max_i32_e32 v25, v29, v26
	v_min_i32_e32 v29, v29, v26
	v_max_i32_e32 v35, v28, v27
	v_min_i32_e32 v27, v28, v27
	v_max_i32_e32 v28, v30, v24
	v_min_i32_e32 v24, v30, v24
	v_max_i32_e32 v30, v23, v19
	v_min_i32_e32 v19, v23, v19
	v_max_i32_e32 v23, v22, v18
	v_min_i32_e32 v18, v22, v18
	v_max_i32_e32 v26, v20, v33
	v_min_i32_e32 v33, v20, v33
	v_lshlrev_b32_e32 v20, 8, v65
	v_lshlrev_b32_e32 v22, 16, v64
	v_max_i32_e32 v36, v32, v31
	v_max_i32_e32 v40, v19, v18
	v_min_i32_e32 v41, v19, v18
	v_and_b32_e32 v18, 0x7f, v63
	v_and_b32_e32 v20, 0x7f00, v20
	v_and_b32_e32 v22, 0x7f0000, v22
	v_max_i32_e32 v37, v21, v29
	v_min_i32_e32 v29, v21, v29
	v_lshlrev_b32_e32 v21, 8, v33
	v_or3_b32 v18, v20, v18, v22
	v_lshlrev_b32_e32 v20, 16, v36
	v_and_b32_e32 v19, 0x7f, v26
	v_and_b32_e32 v21, 0x7f00, v21
	v_and_b32_e32 v20, 0x7f0000, v20
	v_or3_b32 v20, v21, v19, v20
	v_lshlrev_b32_e32 v19, 24, v62
	v_min_i32_e32 v31, v32, v31
	v_and_b32_e32 v19, 0x7f000000, v19
	v_bitop3_b32 v19, v18, s68, v19 bitop3:0x36
	v_lshlrev_b32_e32 v18, 24, v31
	v_max_i32_e32 v38, v35, v28
	v_min_i32_e32 v28, v35, v28
	v_max_i32_e32 v35, v27, v24
	v_min_i32_e32 v27, v27, v24
	v_and_b32_e32 v18, 0x7f000000, v18
	v_lshlrev_b32_e32 v22, 8, v60
	v_lshlrev_b32_e32 v24, 16, v59
	v_max_i32_e32 v32, v34, v25
	v_min_i32_e32 v34, v34, v25
	v_bitop3_b32 v18, v20, s68, v18 bitop3:0x36
	v_and_b32_e32 v20, 0x7f, v61
; #define CE_(a, b) ce_desc(v[a], v[b])
; __device__ __forceinline__ void sort16_desc(int (&v)[16]) {
;     ...
;     CE_(0,13); CE_(1,12); CE_(2,15); CE_(3,14); CE_(4,8); CE_(5,6); CE_(7,11); CE_(9,10);
;     CE_(0,5); CE_(1,7); CE_(2,9); CE_(3,4); CE_(6,13); CE_(8,14); CE_(10,15); CE_(11,12);
;     CE_(0,1); CE_(2,3); CE_(4,5); CE_(6,8); CE_(7,9); CE_(10,11); CE_(12,13); CE_(14,15);
;     CE_(0,2); CE_(1,3); CE_(4,10); CE_(5,11); CE_(6,7); CE_(8,9); CE_(12,14); CE_(13,15);
;     CE_(1,2); CE_(3,12); CE_(4,6); CE_(5,7); CE_(8,10); CE_(9,11); CE_(13,14);
;     CE_(1,4); CE_(2,6); CE_(5,8); CE_(7,10); CE_(9,13); CE_(11,14);
;     CE_(2,4); CE_(3,6); CE_(9,12); CE_(11,13);
;     CE_(3,5); CE_(6,8); CE_(7,9); CE_(10,12);
;     CE_(3,4); CE_(5,6); CE_(7,8); CE_(9,10); CE_(11,12);
;     CE_(6,7); CE_(8,9);
;     ...
; }
; __device__ __forceinline__ void route_task(int task, int tl0, const bf16* QP  , const LAS bf16* KHL, LAS unsigned short* EL, LAS float* GL, int lane) {
;     ...
;     int bk[16];
;     {
;         int hi2 = hi; asm volatile("" : "+v"(hi2));
;         const bool h1 = hi2 != 0;
;         constexpr int A1[16] = {1, 1, 1, 1, 1, 1, 1, 1, 2, 2, 2, 2, 2, 3, 3, 3}, B1[16] = {0, 1, 2, 3, 4, 5, 6, 7, 0, 1, 2, 3, 4, 0, 1, 2};
; #pragma unroll
;         for (int i = 0; i < 16; ++i) { const float ta = __int_as_float(h1 ? top[0][A1[i]] : top[0][0]), tb = __int_as_float(h1 ? top[1][B1[i]] : top[1][i]); const unsigned code = h1 ? (unsigned)(A1[i] * 16 + B1[i]) : (unsigned)i;
;             bk[i] = (int)((__float_as_uint(ta + tb) | 255u) - code); }
;         sort16_desc(bk);
	v_and_b32_e32 v22, 0x7f00, v22
	v_and_b32_e32 v24, 0x7f0000, v24
	v_max_i32_e32 v39, v30, v23
	v_min_i32_e32 v30, v30, v23
	v_lshlrev_b32_e32 v23, 8, v34
	v_or3_b32 v20, v22, v20, v24
	v_lshlrev_b32_e32 v22, 16, v37
	v_and_b32_e32 v21, 0x7f, v32
	v_and_b32_e32 v23, 0x7f00, v23
	v_and_b32_e32 v22, 0x7f0000, v22
	v_or3_b32 v22, v23, v21, v22
	v_lshlrev_b32_e32 v21, 24, v57
	v_and_b32_e32 v21, 0x7f000000, v21
	v_bitop3_b32 v21, v20, s68, v21 bitop3:0x36
	v_lshlrev_b32_e32 v20, 24, v29
	v_and_b32_e32 v20, 0x7f000000, v20
	v_lshlrev_b32_e32 v24, 8, v58
	v_lshlrev_b32_e32 v42, 16, v56
	v_bitop3_b32 v20, v22, s68, v20 bitop3:0x36
	v_and_b32_e32 v22, 0x7f, v55
	v_and_b32_e32 v24, 0x7f00, v24
	v_and_b32_e32 v42, 0x7f0000, v42
	v_lshlrev_b32_e32 v25, 8, v28
	v_or3_b32 v22, v24, v22, v42
	v_lshlrev_b32_e32 v24, 16, v35
	v_and_b32_e32 v23, 0x7f, v38
	v_and_b32_e32 v25, 0x7f00, v25
	v_and_b32_e32 v24, 0x7f0000, v24
	v_or3_b32 v24, v25, v23, v24
	v_lshlrev_b32_e32 v23, 24, v54
	v_and_b32_e32 v23, 0x7f000000, v23
	v_bitop3_b32 v23, v22, s68, v23 bitop3:0x36
	v_lshlrev_b32_e32 v22, 24, v27
	v_and_b32_e32 v22, 0x7f000000, v22
	v_lshlrev_b32_e32 v42, 8, v52
	v_lshlrev_b32_e32 v44, 16, v51
	v_bitop3_b32 v22, v24, s68, v22 bitop3:0x36
	v_and_b32_e32 v24, 0x7f, v53
	v_and_b32_e32 v42, 0x7f00, v42
	v_and_b32_e32 v44, 0x7f0000, v44
	v_lshlrev_b32_e32 v43, 8, v30
	v_or3_b32 v24, v42, v24, v44
	v_lshlrev_b32_e32 v42, 16, v40
	v_and_b32_e32 v25, 0x7f, v39
	v_and_b32_e32 v43, 0x7f00, v43
	v_and_b32_e32 v42, 0x7f0000, v42
	v_or3_b32 v42, v43, v25, v42
	v_lshlrev_b32_e32 v25, 24, v50
	v_and_b32_e32 v25, 0x7f000000, v25
	v_bitop3_b32 v25, v24, s68, v25 bitop3:0x36
	v_lshlrev_b32_e32 v24, 24, v41
	v_and_b32_e32 v24, 0x7f000000, v24
	v_bitop3_b32 v24, v42, s68, v24 bitop3:0x36
	v_mov_b32_e32 v42, v86
	v_add_f32_e32 v55, v55, v26
	v_cmp_eq_u32_e32 vcc, 0, v42
	v_add_f32_e32 v56, v56, v26
	v_add_f32_e32 v54, v54, v26
	v_cndmask_b32_e32 v42, v65, v63, vcc
	v_add_f32_e32 v44, v42, v26
	v_cndmask_b32_e64 v43, -16, 0, vcc
	v_or_b32_e32 v44, 0xff, v44
	v_add_f32_e32 v45, v42, v33
	v_add_u32_e32 v43, v44, v43
	v_cndmask_b32_e64 v44, v99, -1, vcc
	v_or_b32_e32 v45, 0xff, v45
	v_add_f32_e32 v46, v42, v36
	v_add_u32_e32 v44, v45, v44
	v_cndmask_b32_e64 v45, v100, -2, vcc
	v_or_b32_e32 v46, 0xff, v46
	v_add_f32_e32 v47, v42, v31
	v_add_u32_e32 v45, v46, v45
	v_cndmask_b32_e64 v46, v101, -3, vcc
	v_or_b32_e32 v47, 0xff, v47
	v_add_f32_e32 v48, v42, v32
	v_add_u32_e32 v46, v47, v46
	v_cndmask_b32_e64 v47, v102, -4, vcc
	v_or_b32_e32 v48, 0xff, v48
	v_add_f32_e32 v34, v42, v34
	v_add_f32_e32 v37, v42, v37
	v_add_f32_e32 v29, v42, v29
	v_cndmask_b32_e32 v42, v64, v63, vcc
	v_cndmask_b32_e32 v32, v32, v39, vcc
	v_add_u32_e32 v47, v48, v47
	v_cndmask_b32_e64 v48, v103, -5, vcc
	v_or_b32_e32 v34, 0xff, v34
	v_add_f32_e32 v32, v42, v32
	v_add_u32_e32 v34, v34, v48
	v_cndmask_b32_e64 v48, v104, -6, vcc
	v_or_b32_e32 v37, 0xff, v37
	v_cndmask_b32_e32 v38, v26, v38, vcc
	v_cndmask_b32_e64 v39, v116, -12, vcc
	v_or_b32_e32 v32, 0xff, v32
	v_add_u32_e32 v37, v37, v48
	v_cndmask_b32_e64 v48, v105, -7, vcc
	v_or_b32_e32 v29, 0xff, v29
	v_add_f32_e32 v38, v42, v38
	v_cndmask_b32_e32 v28, v33, v28, vcc
	v_add_u32_e32 v32, v32, v39
	v_cndmask_b32_e32 v39, v62, v63, vcc
	v_cndmask_b32_e32 v30, v26, v30, vcc
	v_add_u32_e32 v29, v29, v48
	v_cndmask_b32_e64 v48, v106, -8, vcc
	v_or_b32_e32 v38, 0xff, v38
	v_add_f32_e32 v28, v42, v28
	v_cndmask_b32_e32 v35, v36, v35, vcc
	v_cndmask_b32_e32 v27, v31, v27, vcc
	v_add_f32_e32 v30, v39, v30
	v_cndmask_b32_e32 v40, v33, v40, vcc
	v_add_u32_e32 v38, v38, v48
	v_cndmask_b32_e64 v48, v107, -9, vcc
	v_or_b32_e32 v28, 0xff, v28
	v_add_f32_e32 v35, v42, v35
	v_add_f32_e32 v27, v42, v27
	v_cndmask_b32_e64 v42, v117, -13, vcc
	v_or_b32_e32 v30, 0xff, v30
	v_add_f32_e32 v40, v39, v40
	v_cndmask_b32_e32 v41, v36, v41, vcc
	v_add_u32_e32 v28, v28, v48
	v_cndmask_b32_e64 v48, v114, -10, vcc
	v_or_b32_e32 v35, 0xff, v35
	v_add_u32_e32 v30, v30, v42
	v_cndmask_b32_e64 v42, v118, -14, vcc
	v_or_b32_e32 v40, 0xff, v40
	v_add_f32_e32 v39, v39, v41
	v_add_u32_e32 v35, v35, v48
	v_cndmask_b32_e64 v48, v115, -11, vcc
	v_or_b32_e32 v27, 0xff, v27
	v_add_u32_e32 v40, v40, v42
	v_cndmask_b32_e64 v42, v119, -15, vcc
	v_or_b32_e32 v39, 0xff, v39
	v_add_u32_e32 v27, v27, v48
	v_add_u32_e32 v39, v39, v42
	v_max_i32_e32 v41, v43, v30
	v_min_i32_e32 v30, v43, v30
	v_max_i32_e32 v42, v44, v32
	v_min_i32_e32 v32, v44, v32
	v_max_i32_e32 v43, v45, v39
	v_min_i32_e32 v39, v45, v39
	v_max_i32_e32 v44, v46, v40
	v_min_i32_e32 v40, v46, v40
	v_max_i32_e32 v45, v47, v38
	v_min_i32_e32 v38, v47, v38
	v_max_i32_e32 v46, v34, v37
	v_min_i32_e32 v34, v34, v37
	v_max_i32_e32 v37, v29, v27
	v_min_i32_e32 v27, v29, v27
	v_max_i32_e32 v29, v28, v35
	v_min_i32_e32 v28, v28, v35
	v_max_i32_e32 v35, v41, v46
	v_min_i32_e32 v41, v41, v46
	v_max_i32_e32 v46, v42, v37
	v_min_i32_e32 v37, v42, v37
	v_max_i32_e32 v42, v43, v29
	v_min_i32_e32 v29, v43, v29
	v_max_i32_e32 v43, v44, v45
	v_min_i32_e32 v44, v44, v45
	v_max_i32_e32 v45, v34, v30
	v_min_i32_e32 v30, v34, v30
	v_max_i32_e32 v34, v38, v40
	v_min_i32_e32 v38, v38, v40
	v_max_i32_e32 v40, v28, v39
	v_min_i32_e32 v28, v28, v39
	v_max_i32_e32 v39, v27, v32
	v_min_i32_e32 v27, v27, v32
	v_max_i32_e32 v32, v35, v46
	v_min_i32_e32 v35, v35, v46
	v_max_i32_e32 v46, v42, v43
	v_min_i32_e32 v42, v42, v43
	v_max_i32_e32 v43, v44, v41
	v_min_i32_e32 v41, v44, v41
	v_max_i32_e32 v44, v45, v34
	v_min_i32_e32 v34, v45, v34
	v_max_i32_e32 v45, v37, v29
	v_min_i32_e32 v29, v37, v29
	v_max_i32_e32 v37, v40, v39
	v_min_i32_e32 v39, v40, v39
	v_max_i32_e32 v40, v27, v30
; #define CE_(a, b) ce_desc(v[a], v[b])
; #define CAND(a, b) (int)((__float_as_uint(__int_as_float(top[0][a]) + __int_as_float(top[1][b])) | 255u) - (unsigned)((a) * 16 + (b)))
; __device__ __forceinline__ void sort16_desc(int (&v)[16]) {
;     ...
;     CE_(0,13); CE_(1,12); CE_(2,15); CE_(3,14); CE_(4,8); CE_(5,6); CE_(7,11); CE_(9,10);
;     CE_(0,5); CE_(1,7); CE_(2,9); CE_(3,4); CE_(6,13); CE_(8,14); CE_(10,15); CE_(11,12);
;     CE_(0,1); CE_(2,3); CE_(4,5); CE_(6,8); CE_(7,9); CE_(10,11); CE_(12,13); CE_(14,15);
;     CE_(0,2); CE_(1,3); CE_(4,10); CE_(5,11); CE_(6,7); CE_(8,9); CE_(12,14); CE_(13,15);
;     CE_(1,2); CE_(3,12); CE_(4,6); CE_(5,7); CE_(8,10); CE_(9,11); CE_(13,14);
;     CE_(1,4); CE_(2,6); CE_(5,8); CE_(7,10); CE_(9,13); CE_(11,14);
;     CE_(2,4); CE_(3,6); CE_(9,12); CE_(11,13);
;     CE_(3,5); CE_(6,8); CE_(7,9); CE_(10,12);
;     CE_(3,4); CE_(5,6); CE_(7,8); CE_(9,10); CE_(11,12);
;     CE_(6,7); CE_(8,9);
;     ...
; }
; __device__ __forceinline__ void route_task(int task, int tl0, const bf16* QP  , const LAS bf16* KHL, LAS unsigned short* EL, LAS float* GL, int lane) {
;     ...
;         sort16_desc(bk);
;         int oth[16];
; #pragma unroll
;         for (int i = 0; i < 16; ++i) oth[i] = __shfl_xor(bk[i], 32);
;         merge16_desc(bk, oth);
;     }
;     ...
;     {
;         int gk[16];
;         gk[0] = CAND(3, 3); gk[1] = CAND(4, 0); gk[2] = CAND(4, 1); gk[3] = CAND(4, 2); gk[4] = CAND(5, 0); gk[5] = CAND(5, 1); gk[6] = CAND(6, 0); gk[7] = CAND(6, 1);
;         gk[8] = CAND(7, 0); gk[9] = CAND(7, 1); gk[10] = CAND(8, 0); gk[11] = CAND(9, 0); gk[12] = CAND(10, 0); gk[13] = CAND(11, 0); gk[14] = CAND(12, 0); gk[15] = CAND(13, 0);
;         sort16_desc(gk);
	v_min_i32_e32 v27, v27, v30
	v_max_i32_e32 v30, v38, v28
	v_min_i32_e32 v28, v38, v28
	v_max_i32_e32 v38, v32, v46
	v_min_i32_e32 v32, v32, v46
	v_max_i32_e32 v46, v35, v42
	v_min_i32_e32 v35, v35, v42
	v_max_i32_e32 v42, v43, v37
	v_min_i32_e32 v37, v43, v37
	v_max_i32_e32 v43, v41, v39
	v_min_i32_e32 v39, v41, v39
	v_max_i32_e32 v41, v44, v45
	v_min_i32_e32 v44, v44, v45
	v_max_i32_e32 v45, v34, v29
	v_min_i32_e32 v29, v34, v29
	v_max_i32_e32 v34, v40, v30
	v_min_i32_e32 v30, v40, v30
	v_max_i32_e32 v40, v27, v28
	v_min_i32_e32 v27, v27, v28
	v_max_i32_e32 v28, v46, v32
	v_min_i32_e32 v32, v46, v32
	v_max_i32_e32 v46, v35, v34
	v_min_i32_e32 v34, v35, v34
	v_max_i32_e32 v35, v42, v41
	v_min_i32_e32 v41, v42, v41
	v_max_i32_e32 v42, v43, v44
	v_min_i32_e32 v43, v43, v44
	v_max_i32_e32 v44, v45, v37
	v_min_i32_e32 v37, v45, v37
	v_max_i32_e32 v45, v29, v39
	v_min_i32_e32 v29, v29, v39
	v_max_i32_e32 v39, v40, v30
	v_min_i32_e32 v30, v40, v30
	v_max_i32_e32 v40, v28, v35
	v_min_i32_e32 v28, v28, v35
	v_max_i32_e32 v35, v32, v41
	v_min_i32_e32 v32, v32, v41
	v_max_i32_e32 v41, v42, v44
	v_min_i32_e32 v42, v42, v44
	v_max_i32_e32 v44, v43, v37
	v_min_i32_e32 v37, v43, v37
	v_max_i32_e32 v43, v45, v39
	v_min_i32_e32 v39, v45, v39
	v_max_i32_e32 v45, v29, v30
	v_min_i32_e32 v29, v29, v30
	v_max_i32_e32 v30, v35, v28
	v_min_i32_e32 v28, v35, v28
	v_max_i32_e32 v35, v46, v32
	v_min_i32_e32 v32, v46, v32
	v_max_i32_e32 v46, v43, v34
	v_min_i32_e32 v34, v43, v34
	v_max_i32_e32 v43, v45, v39
	v_min_i32_e32 v39, v45, v39
	v_max_i32_e32 v45, v35, v41
	v_min_i32_e32 v35, v35, v41
	v_max_i32_e32 v41, v32, v42
	v_min_i32_e32 v32, v32, v42
	v_max_i32_e32 v42, v44, v46
	v_min_i32_e32 v44, v44, v46
	v_max_i32_e32 v46, v37, v34
	v_min_i32_e32 v34, v37, v34
	v_max_i32_e32 v37, v45, v28
	v_min_i32_e32 v28, v45, v28
	v_max_i32_e32 v45, v35, v41
	v_min_i32_e32 v35, v35, v41
	v_max_i32_e32 v41, v42, v32
	v_min_i32_e32 v32, v42, v32
	v_max_i32_e32 v42, v44, v46
	v_min_i32_e32 v44, v44, v46
	v_max_i32_e32 v46, v43, v34
	v_min_i32_e32 v34, v43, v34
	v_max_i32_e32 v43, v35, v41
	v_min_i32_e32 v35, v35, v41
	v_max_i32_e32 v41, v32, v42
	v_min_i32_e32 v32, v32, v42
	ds_bpermute_b32 v67, v123, v41
	ds_bpermute_b32 v68, v123, v32
	ds_bpermute_b32 v69, v123, v44
	ds_bpermute_b32 v64, v123, v45
	ds_bpermute_b32 v65, v123, v43
	ds_bpermute_b32 v66, v123, v35
	s_waitcnt lgkmcnt(4)
	v_max_i32_e32 v43, v43, v68
	s_waitcnt lgkmcnt(3)
	v_max_i32_e32 v45, v45, v69
	v_max_i32_e32 v35, v35, v67
	v_add_f32_e32 v31, v62, v31
	v_add_f32_e32 v62, v61, v26
	v_add_f32_e32 v67, v61, v33
	v_add_f32_e32 v36, v61, v36
	v_add_f32_e32 v61, v60, v26
	v_add_f32_e32 v60, v60, v33
	v_add_f32_e32 v68, v59, v26
	v_add_f32_e32 v59, v59, v33
	v_add_f32_e32 v69, v57, v26
	v_add_f32_e32 v33, v57, v33
	v_add_f32_e32 v57, v58, v26
	v_add_f32_e32 v53, v53, v26
	v_add_f32_e32 v52, v52, v26
	ds_bpermute_b32 v70, v123, v27
	v_or_b32_e32 v31, 0xff, v31
	v_or_b32_e32 v62, 0xff, v62
	v_or_b32_e32 v67, 0xff, v67
	v_or_b32_e32 v36, 0xff, v36
	v_or_b32_e32 v61, 0xff, v61
	v_or_b32_e32 v60, 0xff, v60
	v_or_b32_e32 v68, 0xff, v68
	v_or_b32_e32 v59, 0xff, v59
	v_or_b32_e32 v69, 0xff, v69
	v_or_b32_e32 v33, 0xff, v33
	v_or_b32_e32 v55, 0xff, v55
	v_or_b32_e32 v57, 0xff, v57
	v_or_b32_e32 v56, 0xff, v56
	v_or_b32_e32 v54, 0xff, v54
	v_or_b32_e32 v53, 0xff, v53
	v_or_b32_e32 v52, 0xff, v52
	v_subrev_u32_e32 v31, 51, v31
	v_subrev_u32_e32 v62, 64, v62
	v_add_u32_e32 v67, 0xffffffbf, v67
	v_add_u32_e32 v36, 0xffffffbe, v36
	v_add_u32_e32 v61, 0xffffffb0, v61
	v_add_u32_e32 v60, 0xffffffaf, v60
	v_add_u32_e32 v68, 0xffffffa0, v68
	v_add_u32_e32 v59, 0xffffff9f, v59
	v_add_u32_e32 v69, 0xffffff90, v69
	v_add_u32_e32 v33, 0xffffff8f, v33
	v_add_u32_e32 v55, 0xffffff80, v55
	v_add_u32_e32 v57, 0xffffff70, v57
	v_add_u32_e32 v56, 0xffffff60, v56
	v_add_u32_e32 v54, 0xffffff50, v54
	v_add_u32_e32 v53, 0xffffff40, v53
	v_add_u32_e32 v52, 0xffffff30, v52
	ds_bpermute_b32 v42, v123, v38
	ds_bpermute_b32 v47, v123, v40
	ds_bpermute_b32 v48, v123, v30
	ds_bpermute_b32 v49, v123, v37
	ds_bpermute_b32 v63, v123, v28
	ds_bpermute_b32 v71, v123, v29
	ds_bpermute_b32 v72, v123, v39
	ds_bpermute_b32 v73, v123, v34
	ds_bpermute_b32 v74, v123, v46
	v_max_i32_e32 v58, v31, v54
	v_min_i32_e32 v31, v31, v54
	v_max_i32_e32 v54, v62, v56
	v_min_i32_e32 v56, v62, v56
	v_max_i32_e32 v62, v67, v52
	v_min_i32_e32 v52, v67, v52
	v_max_i32_e32 v67, v36, v53
	v_min_i32_e32 v36, v36, v53
	v_max_i32_e32 v53, v61, v69
	v_min_i32_e32 v61, v61, v69
	v_max_i32_e32 v69, v60, v68
	v_min_i32_e32 v60, v60, v68
	v_max_i32_e32 v68, v59, v57
	v_min_i32_e32 v57, v59, v57
	v_max_i32_e32 v59, v33, v55
	v_min_i32_e32 v33, v33, v55
	v_max_i32_e32 v55, v58, v69
	v_min_i32_e32 v58, v58, v69
	v_max_i32_e32 v69, v54, v68
	v_min_i32_e32 v54, v54, v68
	v_max_i32_e32 v68, v62, v59
	v_min_i32_e32 v59, v62, v59
	v_max_i32_e32 v62, v67, v53
	v_min_i32_e32 v53, v67, v53
	v_max_i32_e32 v67, v60, v31
	v_min_i32_e32 v31, v60, v31
	v_max_i32_e32 v60, v61, v36
	v_min_i32_e32 v36, v61, v36
	v_max_i32_e32 v61, v33, v52
	v_min_i32_e32 v33, v33, v52
	v_max_i32_e32 v52, v57, v56
	v_min_i32_e32 v56, v57, v56
	v_max_i32_e32 v57, v55, v69
	v_min_i32_e32 v55, v55, v69
	v_max_i32_e32 v69, v68, v62
	v_min_i32_e32 v62, v68, v62
	v_max_i32_e32 v68, v53, v58
	v_min_i32_e32 v53, v53, v58
	v_max_i32_e32 v58, v67, v60
	v_min_i32_e32 v60, v67, v60
	v_max_i32_e32 v67, v54, v59
	v_min_i32_e32 v54, v54, v59
	v_max_i32_e32 v59, v61, v52
	v_min_i32_e32 v52, v61, v52
	v_max_i32_e32 v61, v56, v31
	v_min_i32_e32 v31, v56, v31
	v_max_i32_e32 v56, v36, v33
	v_min_i32_e32 v33, v36, v33
	s_waitcnt lgkmcnt(9)
; #define CE_(a, b) ce_desc(v[a], v[b])
; #define CAND(a, b) (int)((__float_as_uint(__int_as_float(top[0][a]) + __int_as_float(top[1][b])) | 255u) - (unsigned)((a) * 16 + (b)))
; __device__ __forceinline__ void sort16_desc(int (&v)[16]) {
;     ...
;     CE_(0,13); CE_(1,12); CE_(2,15); CE_(3,14); CE_(4,8); CE_(5,6); CE_(7,11); CE_(9,10);
;     CE_(0,5); CE_(1,7); CE_(2,9); CE_(3,4); CE_(6,13); CE_(8,14); CE_(10,15); CE_(11,12);
;     CE_(0,1); CE_(2,3); CE_(4,5); CE_(6,8); CE_(7,9); CE_(10,11); CE_(12,13); CE_(14,15);
;     CE_(0,2); CE_(1,3); CE_(4,10); CE_(5,11); CE_(6,7); CE_(8,9); CE_(12,14); CE_(13,15);
;     CE_(1,2); CE_(3,12); CE_(4,6); CE_(5,7); CE_(8,10); CE_(9,11); CE_(13,14);
;     CE_(1,4); CE_(2,6); CE_(5,8); CE_(7,10); CE_(9,13); CE_(11,14);
;     CE_(2,4); CE_(3,6); CE_(9,12); CE_(11,13);
;     CE_(3,5); CE_(6,8); CE_(7,9); CE_(10,12);
;     CE_(3,4); CE_(5,6); CE_(7,8); CE_(9,10); CE_(11,12);
;     CE_(6,7); CE_(8,9);
;     ...
; }
; __device__ __forceinline__ void merge16_desc(int (&a)[16], const int (&b)[16]) {
; #pragma unroll
;     for (int i = 0; i < 16; ++i) a[i] = a[i] > b[15 - i] ? a[i] : b[15 - i];
; #pragma unroll
;     for (int j = 8; j > 0; j >>= 1)
; #pragma unroll
;         for (int i = 0; i < 16; ++i) { const int l = i ^ j; if (l > i) ce_desc(a[i], a[l]); }
; }
; __device__ __forceinline__ void route_task(int task, int tl0, const bf16* QP  , const LAS bf16* KHL, LAS unsigned short* EL, LAS float* GL, int lane) {
;     ...
;         merge16_desc(bk, oth);
;     }
;     ...
;     {
;         int gk[16];
;         gk[0] = CAND(3, 3); gk[1] = CAND(4, 0); gk[2] = CAND(4, 1); gk[3] = CAND(4, 2); gk[4] = CAND(5, 0); gk[5] = CAND(5, 1); gk[6] = CAND(6, 0); gk[7] = CAND(6, 1);
;         gk[8] = CAND(7, 0); gk[9] = CAND(7, 1); gk[10] = CAND(8, 0); gk[11] = CAND(9, 0); gk[12] = CAND(10, 0); gk[13] = CAND(11, 0); gk[14] = CAND(12, 0); gk[15] = CAND(13, 0);
;         sort16_desc(gk);
;         merge16_desc(bk, gk);
	v_max_i32_e32 v38, v38, v70
	v_min_i32_e32 v36, v57, v69
	v_max_i32_e32 v70, v55, v62
	v_min_i32_e32 v55, v55, v62
	v_max_i32_e32 v62, v68, v59
	v_min_i32_e32 v59, v68, v59
	v_max_i32_e32 v68, v53, v52
	v_min_i32_e32 v52, v53, v52
	v_max_i32_e32 v53, v58, v67
	v_min_i32_e32 v58, v58, v67
	v_max_i32_e32 v67, v60, v54
	v_min_i32_e32 v54, v60, v54
	v_max_i32_e32 v60, v61, v56
	v_min_i32_e32 v56, v61, v56
	v_max_i32_e32 v61, v31, v33
	v_min_i32_e32 v31, v31, v33
	v_max_i32_e32 v33, v70, v36
	v_min_i32_e32 v36, v70, v36
	v_max_i32_e32 v70, v55, v60
	v_min_i32_e32 v55, v55, v60
	v_max_i32_e32 v60, v62, v53
	v_min_i32_e32 v53, v62, v53
	v_max_i32_e32 v62, v68, v58
	v_min_i32_e32 v58, v68, v58
	v_max_i32_e32 v68, v67, v59
	v_min_i32_e32 v59, v67, v59
	v_max_i32_e32 v67, v54, v52
	v_min_i32_e32 v52, v54, v52
	v_max_i32_e32 v54, v61, v56
	s_waitcnt lgkmcnt(3)
	v_max_i32_e32 v40, v40, v71
	s_waitcnt lgkmcnt(2)
	v_max_i32_e32 v30, v30, v72
	s_waitcnt lgkmcnt(1)
	v_max_i32_e32 v37, v37, v73
	s_waitcnt lgkmcnt(0)
	v_max_i32_e32 v28, v28, v74
	v_max_i32_e32 v41, v41, v66
	v_max_i32_e32 v32, v32, v65
	v_max_i32_e32 v44, v44, v64
	v_max_i32_e32 v46, v46, v63
	v_max_i32_e32 v34, v34, v49
	v_max_i32_e32 v39, v39, v48
	v_max_i32_e32 v29, v29, v47
	v_max_i32_e32 v27, v27, v42
	v_min_i32_e32 v56, v61, v56
	v_max_i32_e32 v61, v33, v60
	v_min_i32_e32 v33, v33, v60
	v_max_i32_e32 v60, v36, v53
	v_min_i32_e32 v36, v36, v53
	v_max_i32_e32 v53, v62, v68
	v_min_i32_e32 v62, v62, v68
	v_max_i32_e32 v68, v58, v59
	v_min_i32_e32 v58, v58, v59
	v_max_i32_e32 v59, v67, v54
	v_max_i32_e32 v42, v38, v41
	v_min_i32_e32 v38, v38, v41
	v_max_i32_e32 v41, v40, v32
	v_min_i32_e32 v32, v40, v32
	v_max_i32_e32 v40, v30, v44
	v_min_i32_e32 v30, v30, v44
	v_max_i32_e32 v44, v37, v46
	v_min_i32_e32 v37, v37, v46
	v_max_i32_e32 v46, v28, v34
	v_min_i32_e32 v28, v28, v34
	v_max_i32_e32 v34, v45, v39
	v_min_i32_e32 v39, v45, v39
	v_max_i32_e32 v45, v43, v29
	v_min_i32_e32 v29, v43, v29
	v_max_i32_e32 v43, v35, v27
	v_min_i32_e32 v27, v35, v27
	v_min_i32_e32 v54, v67, v54
	v_max_i32_e32 v67, v52, v56
	v_max_i32_e32 v71, v70, v36
	v_min_i32_e32 v36, v70, v36
	v_max_i32_e32 v70, v59, v55
	v_min_i32_e32 v55, v59, v55
	v_max_i32_e32 v35, v42, v46
	v_min_i32_e32 v42, v42, v46
	v_max_i32_e32 v46, v41, v34
	v_min_i32_e32 v34, v41, v34
	v_max_i32_e32 v41, v40, v45
	v_min_i32_e32 v40, v40, v45
	v_max_i32_e32 v45, v44, v43
	v_min_i32_e32 v43, v44, v43
	v_max_i32_e32 v44, v38, v28
	v_min_i32_e32 v28, v38, v28
	v_max_i32_e32 v38, v32, v39
	v_min_i32_e32 v32, v32, v39
	v_max_i32_e32 v39, v30, v29
	v_min_i32_e32 v29, v30, v29
	v_max_i32_e32 v30, v37, v27
	v_min_i32_e32 v27, v37, v27
	v_min_i32_e32 v52, v52, v56
	v_min_i32_e32 v56, v60, v33
	v_max_i32_e32 v59, v67, v54
	v_min_i32_e32 v54, v67, v54
	v_max_i32_e32 v67, v71, v53
	v_min_i32_e32 v53, v71, v53
	v_max_i32_e32 v71, v36, v62
	v_min_i32_e32 v36, v36, v62
	v_max_i32_e32 v62, v68, v70
	v_min_i32_e32 v68, v68, v70
	v_max_i32_e32 v70, v58, v55
	v_max_i32_e32 v37, v35, v41
	v_min_i32_e32 v35, v35, v41
	v_max_i32_e32 v41, v46, v45
	v_min_i32_e32 v45, v46, v45
	v_max_i32_e32 v46, v42, v40
	v_min_i32_e32 v40, v42, v40
	v_max_i32_e32 v42, v34, v43
	v_min_i32_e32 v34, v34, v43
	v_max_i32_e32 v43, v44, v39
	v_min_i32_e32 v39, v44, v39
	v_max_i32_e32 v44, v38, v30
	v_min_i32_e32 v30, v38, v30
	v_max_i32_e32 v38, v28, v29
	v_min_i32_e32 v28, v28, v29
	v_max_i32_e32 v29, v32, v27
	v_min_i32_e32 v27, v32, v27
	v_min_i32_e32 v55, v58, v55
	v_max_i32_e32 v58, v67, v56
	v_min_i32_e32 v56, v67, v56
	v_max_i32_e32 v67, v53, v71
	v_min_i32_e32 v53, v53, v71
	v_max_i32_e32 v71, v62, v36
	v_min_i32_e32 v36, v62, v36
	v_max_i32_e32 v62, v68, v70
	v_min_i32_e32 v32, v37, v41
	v_min_i32_e32 v47, v35, v45
	v_min_i32_e32 v48, v46, v42
	v_min_i32_e32 v49, v40, v34
	v_min_i32_e32 v63, v43, v44
	v_min_i32_e32 v64, v39, v30
	v_min_i32_e32 v65, v38, v29
	v_min_i32_e32 v66, v28, v27
	v_min_i32_e32 v68, v68, v70
	v_max_i32_e32 v70, v59, v55
	v_min_i32_e32 v55, v59, v55
	v_min_i32_e32 v59, v53, v71
	v_min_i32_e32 v72, v36, v62
	v_max3_i32 v31, v37, v41, v31
	v_max_i32_e32 v32, v32, v52
	v_max3_i32 v35, v35, v45, v54
	v_max_i32_e32 v37, v47, v55
	v_max3_i32 v41, v46, v42, v70
	v_max_i32_e32 v42, v48, v68
	v_max3_i32 v34, v40, v34, v72
	v_max3_i32 v36, v49, v36, v62
	v_max3_i32 v40, v43, v44, v59
	v_max3_i32 v43, v63, v53, v71
	v_max3_i32 v30, v39, v30, v67
	v_max_i32_e32 v39, v64, v56
	v_max3_i32 v29, v38, v29, v58
	v_max3_i32 v33, v65, v60, v33
	v_max3_i32 v27, v28, v27, v61
	v_max3_i32 v28, v66, v57, v69
	v_max_i32_e32 v38, v31, v40
	v_min_i32_e32 v31, v31, v40
	v_max_i32_e32 v40, v32, v43
	v_min_i32_e32 v32, v32, v43
	v_max_i32_e32 v43, v35, v30
	v_min_i32_e32 v30, v35, v30
	v_max_i32_e32 v35, v37, v39
	v_min_i32_e32 v37, v37, v39
	v_max_i32_e32 v39, v41, v29
	v_min_i32_e32 v29, v41, v29
	v_max_i32_e32 v41, v42, v33
	v_min_i32_e32 v33, v42, v33
	v_max_i32_e32 v42, v34, v27
	v_min_i32_e32 v27, v34, v27
	v_max_i32_e32 v34, v36, v28
	v_min_i32_e32 v28, v36, v28
	v_max_i32_e32 v36, v38, v39
	v_min_i32_e32 v38, v38, v39
	v_max_i32_e32 v39, v40, v41
	v_min_i32_e32 v40, v40, v41
	v_max_i32_e32 v41, v43, v42
	v_min_i32_e32 v42, v43, v42
	v_max_i32_e32 v43, v35, v34
	v_min_i32_e32 v34, v35, v34
	v_max_i32_e32 v35, v31, v29
	v_min_i32_e32 v29, v31, v29
	v_max_i32_e32 v31, v32, v33
	v_min_i32_e32 v32, v32, v33
	v_max_i32_e32 v33, v30, v27
	v_min_i32_e32 v27, v30, v27
	v_max_i32_e32 v30, v37, v28
	v_min_i32_e32 v28, v37, v28
	v_max_i32_e32 v37, v36, v41
	v_min_i32_e32 v36, v36, v41
	v_max_i32_e32 v41, v39, v43
	v_min_i32_e32 v39, v39, v43
	v_max_i32_e32 v43, v38, v42
	v_min_i32_e32 v38, v38, v42
; #define CAND(a, b) (int)((__float_as_uint(__int_as_float(top[0][a]) + __int_as_float(top[1][b])) | 255u) - (unsigned)((a) * 16 + (b)))
; __device__ __forceinline__ void route_task(int task, int tl0, const bf16* QP  , const LAS bf16* KHL, LAS unsigned short* EL, LAS float* GL, int lane) {
;     ...
;         merge16_desc(bk, gk);
;     }
;     {
;         const int c14 = CAND(14, 0), c15 = CAND(15, 0);
;         const int n14 = max(bk[14], c14), n15 = max(min(bk[14], c14), max(bk[15], c15));
;         bk[14] = n14; bk[15] = n15;
;     }
;     ...
;     int my[8];
; #pragma unroll
;     for (int i = 0; i < 8; ++i) { int lo_ = bk[i], hi_ = bk[8 + i]; asm volatile("" : "+v"(lo_), "+v"(hi_)); my[i] = hi ? hi_ : lo_; }
;     int bv[8];
; #pragma unroll
;     for (int i = 0; i < 8; ++i) {
;         const unsigned cd = 255u - ((unsigned)my[i] & 255u), ca = cd >> 4, cb = cd & 15u;
;         const unsigned wa = (ca >> 2) == 0u ? P1[0] : (ca >> 2) == 1u ? P1[1] : (ca >> 2) == 2u ? P1[2] : P1[3];
;         const unsigned wb = (cb >> 2) == 0u ? P2[0] : (cb >> 2) == 1u ? P2[1] : (cb >> 2) == 2u ? P2[2] : P2[3];
;         bv[i] = (int)((((wa >> (8u * (ca & 3u))) & 255u) << 7) | ((wb >> (8u * (cb & 3u))) & 255u));
;     }
	v_max_i32_e32 v42, v40, v34
	v_min_i32_e32 v34, v40, v34
	v_max_i32_e32 v40, v35, v33
	v_min_i32_e32 v33, v35, v33
	v_max_i32_e32 v35, v31, v30
	v_min_i32_e32 v30, v31, v30
	v_max_i32_e32 v31, v29, v27
	v_min_i32_e32 v27, v29, v27
	v_max_i32_e32 v29, v32, v28
	v_min_i32_e32 v28, v32, v28
	v_max_i32_e32 v32, v37, v41
	v_min_i32_e32 v37, v37, v41
	v_max_i32_e32 v41, v36, v39
	v_min_i32_e32 v36, v36, v39
	v_max_i32_e32 v39, v43, v42
	v_min_i32_e32 v42, v43, v42
	v_max_i32_e32 v43, v38, v34
	v_min_i32_e32 v34, v38, v34
	v_max_i32_e32 v38, v40, v35
	v_min_i32_e32 v35, v40, v35
	v_max_i32_e32 v40, v33, v30
	v_min_i32_e32 v30, v33, v30
	v_max_i32_e32 v33, v31, v29
	v_min_i32_e32 v29, v31, v29
	v_max_i32_e32 v31, v27, v28
	v_min_i32_e32 v27, v27, v28
	v_add_f32_e32 v28, v51, v26
	v_or_b32_e32 v28, 0xff, v28
	v_add_f32_e32 v26, v50, v26
	v_add_u32_e32 v28, 0xffffff20, v28
	v_or_b32_e32 v26, 0xff, v26
	v_add_u32_e32 v26, 0xffffff10, v26
	v_max_i32_e32 v44, v31, v28
	v_min_i32_e32 v28, v31, v28
	v_max3_i32 v26, v28, v27, v26
	v_mov_b32_e32 v27, v32
	s_nop 0
	v_cndmask_b32_e64 v27, v38, v27, s[6:7]
	v_not_b32_e32 v28, v27
	v_bfe_u32 v45, v28, 6, 2
	v_cmp_eq_u32_e32 vcc, 2, v45
	v_cndmask_b32_e64 v34, v26, v34, s[6:7]
	v_bitop3_b32 v26, v27, s3, v27 bitop3:0xc
	v_cndmask_b32_e32 v46, v25, v23, vcc
	v_cmp_eq_u32_e32 vcc, 1, v45
	v_cndmask_b32_e64 v31, v35, v37, s[6:7]
	v_not_b32_e32 v35, v31
	v_cndmask_b32_e32 v45, v46, v21, vcc
	v_cmp_gt_u32_e32 vcc, 64, v26
	v_cndmask_b32_e64 v37, v40, v41, s[6:7]
	v_cndmask_b32_e64 v41, v44, v43, s[6:7]
	v_cndmask_b32_e32 v26, v45, v19, vcc
	v_bfe_u32 v45, v28, 2, 2
	v_cmp_eq_u32_e32 vcc, 2, v45
	v_bitop3_b32 v44, v27, 15, v27 bitop3:0xc
	v_bfe_u32 v47, v35, 6, 2
	v_cndmask_b32_e32 v46, v24, v22, vcc
	v_cmp_eq_u32_e32 vcc, 1, v45
	v_not_b32_e32 v38, v37
	v_bfe_u32 v49, v38, 6, 2
	v_cndmask_b32_e32 v45, v46, v20, vcc
	v_cmp_gt_u32_e32 vcc, 4, v44
	v_bitop3_b32 v46, v31, 15, v31 bitop3:0xc
	v_cndmask_b32_e64 v30, v30, v36, s[6:7]
	v_cndmask_b32_e32 v44, v45, v18, vcc
	v_cmp_eq_u32_e32 vcc, 2, v47
	v_bitop3_b32 v45, v31, s3, v31 bitop3:0xc
	v_not_b32_e32 v36, v30
	v_cndmask_b32_e32 v48, v25, v23, vcc
	v_cmp_eq_u32_e32 vcc, 1, v47
	v_bfe_u32 v51, v36, 6, 2
	v_cndmask_b32_e64 v33, v33, v39, s[6:7]
	v_cndmask_b32_e32 v47, v48, v21, vcc
	v_cmp_gt_u32_e32 vcc, 64, v45
	v_not_b32_e32 v39, v33
	v_bfe_u32 v53, v39, 6, 2
	v_cndmask_b32_e32 v45, v47, v19, vcc
	v_bfe_u32 v47, v35, 2, 2
	v_cmp_eq_u32_e32 vcc, 2, v47
	v_cndmask_b32_e64 v29, v29, v42, s[6:7]
	v_not_b32_e32 v40, v29
	v_cndmask_b32_e32 v48, v24, v22, vcc
	v_cmp_eq_u32_e32 vcc, 1, v47
	v_bfe_u32 v55, v40, 6, 2
	v_not_b32_e32 v42, v41
	v_cndmask_b32_e32 v47, v48, v20, vcc
	v_cmp_gt_u32_e32 vcc, 4, v46
	v_bitop3_b32 v48, v37, 15, v37 bitop3:0xc
	v_bfe_u32 v57, v42, 6, 2
	v_cndmask_b32_e32 v46, v47, v18, vcc
	v_cmp_eq_u32_e32 vcc, 2, v49
	v_bitop3_b32 v47, v37, s3, v37 bitop3:0xc
	v_not_b32_e32 v43, v34
	v_cndmask_b32_e32 v50, v25, v23, vcc
	v_cmp_eq_u32_e32 vcc, 1, v49
	v_bfe_u32 v59, v43, 6, 2
	v_or_b32_e32 v82, s10, v88
	v_cndmask_b32_e32 v49, v50, v21, vcc
	v_cmp_gt_u32_e32 vcc, 64, v47
	s_nop 1
	v_cndmask_b32_e32 v47, v49, v19, vcc
	v_bfe_u32 v49, v38, 2, 2
	v_cmp_eq_u32_e32 vcc, 2, v49
	s_nop 1
	v_cndmask_b32_e32 v50, v24, v22, vcc
	v_cmp_eq_u32_e32 vcc, 1, v49
	s_nop 1
	v_cndmask_b32_e32 v49, v50, v20, vcc
	v_cmp_gt_u32_e32 vcc, 4, v48
	v_bitop3_b32 v50, v30, 15, v30 bitop3:0xc
	s_nop 0
	v_cndmask_b32_e32 v48, v49, v18, vcc
	v_cmp_eq_u32_e32 vcc, 2, v51
	v_bitop3_b32 v49, v30, s3, v30 bitop3:0xc
	s_nop 0
	v_cndmask_b32_e32 v52, v25, v23, vcc
	v_cmp_eq_u32_e32 vcc, 1, v51
	s_nop 1
	v_cndmask_b32_e32 v51, v52, v21, vcc
	v_cmp_gt_u32_e32 vcc, 64, v49
	s_nop 1
	v_cndmask_b32_e32 v49, v51, v19, vcc
	v_bfe_u32 v51, v36, 2, 2
	v_cmp_eq_u32_e32 vcc, 2, v51
	s_nop 1
	v_cndmask_b32_e32 v52, v24, v22, vcc
	v_cmp_eq_u32_e32 vcc, 1, v51
	s_nop 1
	v_cndmask_b32_e32 v51, v52, v20, vcc
	v_cmp_gt_u32_e32 vcc, 4, v50
	v_bitop3_b32 v52, v33, 15, v33 bitop3:0xc
	s_nop 0
	v_cndmask_b32_e32 v50, v51, v18, vcc
	v_cmp_eq_u32_e32 vcc, 2, v53
	v_bitop3_b32 v51, v33, s3, v33 bitop3:0xc
	s_nop 0
	v_cndmask_b32_e32 v54, v25, v23, vcc
	v_cmp_eq_u32_e32 vcc, 1, v53
	s_nop 1
	v_cndmask_b32_e32 v53, v54, v21, vcc
	v_cmp_gt_u32_e32 vcc, 64, v51
	s_nop 1
	v_cndmask_b32_e32 v51, v53, v19, vcc
	v_bfe_u32 v53, v39, 2, 2
	v_cmp_eq_u32_e32 vcc, 2, v53
	s_nop 1
	v_cndmask_b32_e32 v54, v24, v22, vcc
	v_cmp_eq_u32_e32 vcc, 1, v53
	s_nop 1
	v_cndmask_b32_e32 v53, v54, v20, vcc
	v_cmp_gt_u32_e32 vcc, 4, v52
	v_bitop3_b32 v54, v29, 15, v29 bitop3:0xc
	s_nop 0
	v_cndmask_b32_e32 v52, v53, v18, vcc
	v_cmp_eq_u32_e32 vcc, 2, v55
	v_bitop3_b32 v53, v29, s3, v29 bitop3:0xc
	s_nop 0
	v_cndmask_b32_e32 v56, v25, v23, vcc
	v_cmp_eq_u32_e32 vcc, 1, v55
	s_nop 1
	v_cndmask_b32_e32 v55, v56, v21, vcc
	v_cmp_gt_u32_e32 vcc, 64, v53
	s_nop 1
	v_cndmask_b32_e32 v53, v55, v19, vcc
	v_bfe_u32 v55, v40, 2, 2
	v_cmp_eq_u32_e32 vcc, 2, v55
	s_nop 1
	v_cndmask_b32_e32 v56, v24, v22, vcc
	v_cmp_eq_u32_e32 vcc, 1, v55
	s_nop 1
	v_cndmask_b32_e32 v55, v56, v20, vcc
	v_cmp_gt_u32_e32 vcc, 4, v54
	v_bitop3_b32 v56, v41, 15, v41 bitop3:0xc
	s_nop 0
	v_cndmask_b32_e32 v54, v55, v18, vcc
	v_cmp_eq_u32_e32 vcc, 2, v57
	v_bitop3_b32 v55, v41, s3, v41 bitop3:0xc
	s_nop 0
	v_cndmask_b32_e32 v58, v25, v23, vcc
	v_cmp_eq_u32_e32 vcc, 1, v57
	s_nop 1
	v_cndmask_b32_e32 v57, v58, v21, vcc
	v_cmp_gt_u32_e32 vcc, 64, v55
	s_nop 1
	v_cndmask_b32_e32 v55, v57, v19, vcc
	v_bfe_u32 v57, v42, 2, 2
	v_cmp_eq_u32_e32 vcc, 2, v57
	s_nop 1
	v_cndmask_b32_e32 v58, v24, v22, vcc
	v_cmp_eq_u32_e32 vcc, 1, v57
	s_nop 1
	v_cndmask_b32_e32 v57, v58, v20, vcc
; #define LAS __attribute__((address_space(3)))
; __device__ __forceinline__ void route_task(int task, int tl0, const bf16* QP  , const LAS bf16* KHL, LAS unsigned short* EL, LAS float* GL, int lane) {
;     const int r = lane & 31, hi = lane >> 5, t = 4 * task + (r >> 3), head = r & 7;
;     int top[2][16]; bf16x8 qa[2][4];
;     { unsigned qo = (unsigned)t * (unsigned)D + (unsigned)(head * 128 + 8 * hi); asm volatile("" : "+v"(qo)); const bf16* qp = QP + qo;
; #pragma unroll
;       for (int hf = 0; hf < 2; ++hf)
; #pragma unroll
;         for (int ks = 0; ks < 4; ++ks) qa[hf][ks] = ldg8(qp + 64 * hf + 16 * ks); }
;     ...
;         const unsigned cd = 255u - ((unsigned)my[i] & 255u), ca = cd >> 4, cb = cd & 15u;
;         const unsigned wa = (ca >> 2) == 0u ? P1[0] : (ca >> 2) == 1u ? P1[1] : (ca >> 2) == 2u ? P1[2] : P1[3];
;         const unsigned wb = (cb >> 2) == 0u ? P2[0] : (cb >> 2) == 1u ? P2[1] : (cb >> 2) == 2u ? P2[2] : P2[3];
;         bv[i] = (int)((((wa >> (8u * (ca & 3u))) & 255u) << 7) | ((wb >> (8u * (cb & 3u))) & 255u));
;     }
;     float e[8], se = 0.f;
; #pragma unroll
;     for (int i = 0; i < 8; ++i) { e[i] = __expf(__int_as_float(my[i]) - __int_as_float(bk[0])); se += e[i]; }
;     se += __shfl_xor(se, 32);
;     const float inv = 1.f / se;
;     {
;         int l2 = lane; asm volatile("" : "+v"(l2));
;         const int o2 = (tl0 + ((l2 & 31) >> 3)) * 128 + (l2 & 7) * 16 + 8 * (l2 >> 5);
;         LAS v4u* ip = (LAS v4u*)(EL + o2); typedef float f4v __attribute__((ext_vector_type(4))); LAS f4v* gp = (LAS f4v*)(GL + o2);
;         ip[0] = (v4u){(unsigned)bv[0] | ((unsigned)bv[1] << 16), (unsigned)bv[2] | ((unsigned)bv[3] << 16), (unsigned)bv[4] | ((unsigned)bv[5] << 16), (unsigned)bv[6] | ((unsigned)bv[7] << 16)};
;         gp[0] = (f4v){e[0] * inv, e[1] * inv, e[2] * inv, e[3] * inv}; gp[1] = (f4v){e[4] * inv, e[5] * inv, e[6] * inv, e[7] * inv};
;     }
	v_cmp_gt_u32_e32 vcc, 4, v56
	v_bitop3_b32 v58, v34, 15, v34 bitop3:0xc
	s_nop 0
	v_cndmask_b32_e32 v56, v57, v18, vcc
	v_cmp_eq_u32_e32 vcc, 2, v59
	v_bitop3_b32 v57, v34, s3, v34 bitop3:0xc
	s_nop 0
	v_cndmask_b32_e32 v23, v25, v23, vcc
	v_cmp_eq_u32_e32 vcc, 1, v59
	v_sub_f32_e32 v25, v30, v32
	v_mul_f32_e32 v25, 0x3fb8aa3b, v25
	v_cndmask_b32_e32 v21, v23, v21, vcc
	v_cmp_gt_u32_e32 vcc, 64, v57
	v_lshrrev_b32_e32 v23, 1, v39
	v_and_b32_e32 v23, 24, v23
	v_cndmask_b32_e32 v19, v21, v19, vcc
	v_bfe_u32 v21, v43, 2, 2
	v_cmp_eq_u32_e32 vcc, 2, v21
	v_lshrrev_b32_e32 v23, v23, v51
	v_lshlrev_b32_e32 v23, 7, v23
	v_cndmask_b32_e32 v22, v24, v22, vcc
	v_cmp_eq_u32_e32 vcc, 1, v21
	v_lshrrev_b32_e32 v21, 1, v42
	v_and_b32_e32 v21, 24, v21
	v_cndmask_b32_e32 v20, v22, v20, vcc
	v_cmp_gt_u32_e32 vcc, 4, v58
	v_lshrrev_b32_e32 v21, v21, v55
	v_lshrrev_b32_e32 v22, 1, v40
	v_cndmask_b32_e32 v18, v20, v18, vcc
	v_lshlrev_b32_e32 v20, 3, v42
	v_lshlrev_b32_e32 v21, 7, v21
	v_and_b32_e32 v22, 24, v22
	v_lshrrev_b32_e32 v20, v20, v56
	v_and_b32_e32 v21, 0x7f80, v21
	v_lshrrev_b32_e32 v22, v22, v53
	v_and_or_b32 v21, v20, s3, v21
	v_lshlrev_b32_e32 v20, 3, v40
	v_lshlrev_b32_e32 v22, 7, v22
	v_lshrrev_b32_e32 v20, v20, v54
	v_and_b32_e32 v22, 0x7f80, v22
	v_and_or_b32 v20, v20, s3, v22
	v_lshlrev_b32_e32 v22, 3, v39
	v_lshrrev_b32_e32 v22, v22, v52
	v_and_b32_e32 v23, 0x7f80, v23
	v_and_or_b32 v39, v22, s3, v23
	v_lshrrev_b32_e32 v23, 1, v36
	v_and_b32_e32 v23, 24, v23
	v_lshrrev_b32_e32 v23, v23, v49
	v_lshlrev_b32_e32 v22, 3, v36
	v_lshlrev_b32_e32 v23, 7, v23
	v_lshrrev_b32_e32 v22, v22, v50
	v_and_b32_e32 v23, 0x7f80, v23
	v_and_or_b32 v36, v22, s3, v23
	v_lshrrev_b32_e32 v23, 1, v38
	v_and_b32_e32 v23, 24, v23
	v_lshrrev_b32_e32 v23, v23, v47
	v_lshlrev_b32_e32 v22, 3, v38
	v_lshlrev_b32_e32 v23, 7, v23
	v_lshrrev_b32_e32 v22, v22, v48
	v_and_b32_e32 v23, 0x7f80, v23
	v_and_or_b32 v38, v22, s3, v23
	v_lshrrev_b32_e32 v23, 1, v35
	v_and_b32_e32 v23, 24, v23
	v_lshrrev_b32_e32 v23, v23, v45
	v_lshlrev_b32_e32 v22, 3, v35
	v_lshlrev_b32_e32 v23, 7, v23
	v_lshrrev_b32_e32 v22, v22, v46
	v_and_b32_e32 v23, 0x7f80, v23
	v_and_or_b32 v35, v22, s3, v23
	v_lshrrev_b32_e32 v23, 1, v28
	v_and_b32_e32 v23, 24, v23
	v_lshrrev_b32_e32 v23, v23, v26
	v_lshlrev_b32_e32 v22, 3, v28
	v_lshlrev_b32_e32 v23, 7, v23
	v_lshrrev_b32_e32 v22, v22, v44
	v_and_b32_e32 v23, 0x7f80, v23
	v_and_or_b32 v40, v22, s3, v23
	v_sub_f32_e32 v22, v27, v32
	v_mul_f32_e32 v22, 0x3fb8aa3b, v22
	v_sub_f32_e32 v23, v31, v32
	v_exp_f32_e32 v22, v22
	v_mul_f32_e32 v23, 0x3fb8aa3b, v23
	v_sub_f32_e32 v24, v37, v32
	v_exp_f32_e32 v23, v23
	v_mul_f32_e32 v24, 0x3fb8aa3b, v24
	v_exp_f32_e32 v24, v24
	v_exp_f32_e32 v25, v25
	v_add_f32_e32 v26, 0, v22
	v_add_f32_e32 v26, v23, v26
	v_add_f32_e32 v26, v24, v26
	v_add_f32_e32 v30, v25, v26
	v_sub_f32_e32 v26, v33, v32
	v_mul_f32_e32 v26, 0x3fb8aa3b, v26
	v_sub_f32_e32 v27, v29, v32
	v_exp_f32_e32 v26, v26
	v_mul_f32_e32 v27, 0x3fb8aa3b, v27
	v_sub_f32_e32 v28, v41, v32
	v_exp_f32_e32 v27, v27
	v_mul_f32_e32 v28, 0x3fb8aa3b, v28
	v_sub_f32_e32 v29, v34, v32
	v_exp_f32_e32 v28, v28
	v_mul_f32_e32 v29, 0x3fb8aa3b, v29
	v_exp_f32_e32 v29, v29
	v_add_f32_e32 v30, v26, v30
	v_add_f32_e32 v30, v27, v30
	v_add_f32_e32 v30, v28, v30
	v_add_f32_e32 v30, v29, v30
	ds_bpermute_b32 v31, v123, v30
	v_lshrrev_b32_e32 v42, 1, v43
	v_and_b32_e32 v32, 24, v42
	v_lshrrev_b32_e32 v19, v32, v19
	v_lshlrev_b32_e32 v19, 7, v19
	s_waitcnt lgkmcnt(0)
	v_add_f32_e32 v30, v30, v31
	v_div_scale_f32 v31, s[12:13], v30, v30, 1.0
	v_rcp_f32_e32 v32, v31
	v_lshlrev_b32_e32 v33, 3, v43
	v_and_b32_e32 v19, 0x7f80, v19
	v_lshrrev_b32_e32 v18, v33, v18
	v_and_or_b32 v33, v18, s3, v19
	v_fma_f32 v18, -v31, v32, 1.0
	v_fmac_f32_e32 v32, v18, v32
	v_div_scale_f32 v18, vcc, 1.0, v30, 1.0
	v_mul_f32_e32 v19, v18, v32
	v_fma_f32 v34, -v31, v19, v18
	v_fmac_f32_e32 v19, v34, v32
	v_fma_f32 v18, -v31, v19, v18
	v_div_fmas_f32 v18, v18, v32, v19
	v_div_fixup_f32 v30, v18, v30, 1.0
	v_mov_b32_e32 v18, v1
	v_lshl_or_b32 v20, v20, 16, v39
	v_lshrrev_b32_e32 v19, 3, v18
	v_and_or_b32 v19, v19, 3, s55
	v_lshlrev_b32_e32 v31, 4, v18
	v_ashrrev_i32_e32 v18, 2, v18
	v_lshlrev_b32_e32 v19, 7, v19
	v_and_b32_e32 v31, 0x70, v31
	v_and_b32_e32 v18, -8, v18
	v_add3_u32 v18, v18, v31, v19
	v_lshl_add_u32 v31, v18, 1, s11
	v_lshl_add_u32 v32, v18, 2, s69
	v_lshl_or_b32 v18, v35, 16, v40
	v_lshl_or_b32 v19, v36, 16, v38
	v_lshl_or_b32 v21, v33, 16, v21
	ds_write_b128 v31, v[18:21]
	v_pk_mul_f32 v[20:21], v[24:25], v[30:31] op_sel_hi:[1,0]
	v_pk_mul_f32 v[18:19], v[22:23], v[30:31] op_sel_hi:[1,0]
	ds_write_b128 v32, v[18:21]
	v_pk_mul_f32 v[20:21], v[28:29], v[30:31] op_sel_hi:[1,0]
	v_pk_mul_f32 v[18:19], v[26:27], v[30:31] op_sel_hi:[1,0]
	ds_write_b128 v32, v[18:21] offset:16
	v_mov_b64_e32 v[32:33], s[30:31]
	v_lshl_add_u64 v[128:129], v[82:83], 1, s[80:81]
	s_waitcnt vmcnt(4)
	v_mov_b32_e32 v78, v150
	v_mov_b32_e32 v79, v151
	v_mov_b32_e32 v80, v152
	v_mov_b32_e32 v81, v153
	v_mov_b32_e32 v74, v154
	v_mov_b32_e32 v75, v155
	v_mov_b32_e32 v76, v156
	v_mov_b32_e32 v77, v157
	v_mov_b32_e32 v70, v158
	v_mov_b32_e32 v71, v159
	v_mov_b32_e32 v72, v160
	v_mov_b32_e32 v73, v161
	v_mov_b32_e32 v66, v162
	v_mov_b32_e32 v67, v163
	v_mov_b32_e32 v68, v164
	v_mov_b32_e32 v69, v165
	ds_read_b128 v[50:53], v94
	ds_read_b128 v[54:57], v94 offset:32
	v_mov_b64_e32 v[30:31], s[28:29]
	v_mov_b64_e32 v[28:29], s[26:27]
	v_mov_b64_e32 v[26:27], s[24:25]
	v_mov_b64_e32 v[24:25], s[22:23]
	v_mov_b64_e32 v[22:23], s[20:21]
	v_mov_b64_e32 v[20:21], s[18:19]
	v_mov_b64_e32 v[18:19], s[16:17]
	s_waitcnt vmcnt(3) lgkmcnt(1)
; #define LAS __attribute__((address_space(3)))
; #define MFMA32(a, b, c) __builtin_amdgcn_mfma_f32_32x32x16_bf16((a), (b), (c), 0, 0, 0)
; #define CE_(a, b) ce_desc(v[a], v[b])
; __device__ __forceinline__ void sort16_desc(int (&v)[16]) {
;     ...
;     CE_(0,13); CE_(1,12); CE_(2,15); CE_(3,14); CE_(4,8); CE_(5,6); CE_(7,11); CE_(9,10);
;     CE_(0,5); CE_(1,7); CE_(2,9); CE_(3,4); CE_(6,13); CE_(8,14); CE_(10,15); CE_(11,12);
;     CE_(0,1); CE_(2,3); CE_(4,5); CE_(6,8); CE_(7,9); CE_(10,11); CE_(12,13); CE_(14,15);
;     CE_(0,2); CE_(1,3); CE_(4,10); CE_(5,11); CE_(6,7); CE_(8,9); CE_(12,14); CE_(13,15);
;     CE_(1,2); CE_(3,12); CE_(4,6); CE_(5,7); CE_(8,10); CE_(9,11); CE_(13,14);
;     CE_(1,4); CE_(2,6); CE_(5,8); CE_(7,10); CE_(9,13); CE_(11,14);
;     CE_(2,4); CE_(3,6); CE_(9,12); CE_(11,13);
;     CE_(3,5); CE_(6,8); CE_(7,9); CE_(10,12);
;     CE_(3,4); CE_(5,6); CE_(7,8); CE_(9,10); CE_(11,12);
;     CE_(6,7); CE_(8,9);
;     ...
; }
; __device__ __forceinline__ void route_task(int task, int tl0, const bf16* QP  , const LAS bf16* KHL, LAS unsigned short* EL, LAS float* GL, int lane) {
;     ...
;     { unsigned qo = (unsigned)t * (unsigned)D + (unsigned)(head * 128 + 8 * hi); asm volatile("" : "+v"(qo)); const bf16* qp = QP + qo;
; #pragma unroll
;       for (int hf = 0; hf < 2; ++hf)
; #pragma unroll
;         for (int ks = 0; ks < 4; ++ks) qa[hf][ks] = ldg8(qp + 64 * hf + 16 * ks); }
; #pragma unroll
;     for (int half = 0; half < 2; ++half) {
;         int cur[16];
; #pragma unroll
;         for (int kt = 0; kt < 4; ++kt) {
;             f32x16 X;
; #pragma unroll
;             for (int i = 0; i < 16; ++i) X[i] = 8.f;
;             const LAS bf16* khp = KHL + (half * 128 + 32 * kt + r) * 72 + 8 * hi;
; #pragma unroll
;             for (int ks = 0; ks < 4; ++ks) {
;                 const bf16x8 kh = lds8(khp + 16 * ks);
;                 X = MFMA32(kh, qa[half][ks], X);
;             }
;             int grp[16];
; #pragma unroll
;             for (int i = 0; i < 16; ++i) grp[i] = (int)((__float_as_uint(X[i]) | 127u) - (unsigned)(32 * kt + (i & 3) + 8 * (i >> 2)));
;             sort16_desc(grp);
;             if (kt == 0) {
; #pragma unroll
;                 for (int i = 0; i < 16; ++i) cur[i] = grp[i];
;             } else merge16_desc(cur, grp);
	s_nop 0
	v_mfma_f32_32x32x16_bf16 v[34:49], v[50:53], v[78:81], v[18:33]
	ds_read_b128 v[50:53], v94 offset:64
	ds_read_b128 v[124:127], v94 offset:96
	s_waitcnt vmcnt(2) lgkmcnt(2)
	v_mfma_f32_32x32x16_bf16 v[34:49], v[54:57], v[74:77], v[34:49]
	s_waitcnt vmcnt(1) lgkmcnt(1)
	v_mfma_f32_32x32x16_bf16 v[34:49], v[50:53], v[70:73], v[34:49]
	s_waitcnt vmcnt(0)
	v_mov_b32_e32 v62, v166
	v_mov_b32_e32 v63, v167
	v_mov_b32_e32 v64, v168
	v_mov_b32_e32 v65, v169
	v_mov_b32_e32 v58, v170
	v_mov_b32_e32 v59, v171
	v_mov_b32_e32 v60, v172
	v_mov_b32_e32 v61, v173
	v_mov_b32_e32 v54, v174
	v_mov_b32_e32 v55, v175
	v_mov_b32_e32 v56, v176
	v_mov_b32_e32 v57, v177
	v_mov_b32_e32 v50, v178
	v_mov_b32_e32 v51, v179
	v_mov_b32_e32 v52, v180
	v_mov_b32_e32 v53, v181
	s_waitcnt vmcnt(4) lgkmcnt(0)
	v_mfma_f32_32x32x16_bf16 v[34:49], v[124:127], v[66:69], v[34:49]
	s_nop 11
	v_bitop3_b32 v37, v37, s42, 3 bitop3:0x56
	v_bitop3_b32 v48, v48, s42, 26 bitop3:0x56
	v_bitop3_b32 v38, v38, s42, 8 bitop3:0x56
	v_bitop3_b32 v42, v42, s42, 16 bitop3:0x56
	v_bitop3_b32 v47, v47, s42, 25 bitop3:0x56
	v_bitop3_b32 v39, v39, s42, 9 bitop3:0x56
	v_bitop3_b32 v40, v40, s42, 10 bitop3:0x56
	v_bitop3_b32 v43, v43, s42, 17 bitop3:0x56
	v_bitop3_b32 v44, v44, s42, 18 bitop3:0x56
	v_bitop3_b32 v36, v36, s42, 2 bitop3:0x56
	v_bitop3_b32 v49, v49, s42, 27 bitop3:0x56
	v_bitop3_b32 v41, v41, s42, 11 bitop3:0x56
	v_bitop3_b32 v45, v45, s42, 19 bitop3:0x56
	v_bitop3_b32 v35, v35, s42, 1 bitop3:0x56
	v_bitop3_b32 v46, v46, s42, 24 bitop3:0x56
	v_or_b32_e32 v34, 0x7f, v34
	v_max_i32_e32 v82, v37, v48
	v_max_i32_e32 v124, v38, v42
	v_max_i32_e32 v126, v34, v47
	v_max_i32_e32 v127, v39, v40
	v_min_i32_e32 v130, v43, v44
	v_min_i32_e32 v131, v36, v49
	v_min_i32_e32 v133, v41, v45
	v_min_i32_e32 v134, v35, v46
	v_min_i32_e32 v39, v39, v40
	v_min_i32_e32 v34, v34, v47
	v_min_i32_e32 v38, v38, v42
	v_min_i32_e32 v37, v37, v48
	v_max_i32_e32 v35, v35, v46
	v_max_i32_e32 v41, v41, v45
	v_max_i32_e32 v36, v36, v49
	v_max_i32_e32 v43, v43, v44
	v_min_i32_e32 v125, v82, v124
	v_min_i32_e32 v128, v126, v127
	v_max_i32_e32 v132, v130, v131
	v_max_i32_e32 v135, v133, v134
	v_max_i32_e32 v40, v39, v34
	v_max_i32_e32 v42, v38, v37
	v_min_i32_e32 v45, v35, v41
	v_min_i32_e32 v44, v36, v43
	v_min_i32_e32 v129, v125, v128
	v_max_i32_e32 v47, v40, v42
	v_max_i32_e32 v46, v45, v44
	v_min_i32_e32 v40, v40, v42
	v_min_i32_e32 v42, v45, v44
	v_max_i32_e32 v45, v125, v128
	v_max_i32_e32 v125, v132, v135
	v_min_i32_e32 v128, v45, v125
	v_min_i32_e32 v34, v39, v34
	v_max_i32_e32 v39, v126, v127
	v_max_i32_e32 v35, v35, v41
	v_max_i32_e32 v41, v82, v124
	v_max_i32_e32 v148, v45, v125
	ds_read_b128 v[124:127], v95
	v_max_i32_e32 v44, v40, v42
	v_min_i32_e32 v138, v40, v42
	v_min_i32_e32 v40, v133, v134
	v_min_i32_e32 v37, v38, v37
	v_min_i32_e32 v38, v130, v131
	v_max_i32_e32 v36, v36, v43
	v_min_i32_e32 v136, v132, v135
	v_min_i32_e32 v133, v40, v34
	v_min_i32_e32 v134, v37, v38
	v_max_i32_e32 v34, v40, v34
	v_max_i32_e32 v37, v37, v38
	v_min_i32_e32 v40, v39, v35
	v_min_i32_e32 v42, v36, v41
	v_max_i32_e32 v144, v39, v35
	v_max_i32_e32 v145, v36, v41
	v_max_i32_e32 v137, v129, v136
	v_min_i32_e32 v136, v129, v136
	v_max_i32_e32 v140, v133, v134
	v_min_i32_e32 v141, v34, v37
	v_max_i32_e32 v143, v40, v42
	v_min_i32_e32 v146, v144, v145
	v_max_i32_e32 v149, v47, v46
	v_min_i32_e32 v48, v47, v46
	v_max_i32_e32 v139, v138, v136
	v_max_i32_e32 v142, v140, v141
	v_min_i32_e32 v43, v40, v42
	v_max_i32_e32 v34, v34, v37
	v_min_i32_e32 v147, v143, v146
	v_min_i32_e32 v150, v148, v149
	v_min_i32_e32 v49, v137, v48
	v_min_i32_e32 v132, v44, v128
	v_max_i32_e32 v38, v139, v142
	v_min_i32_e32 v37, v43, v34
	v_max_i32_e32 v34, v43, v34
	v_min_i32_e32 v35, v147, v150
	v_max_i32_e32 v39, v137, v48
	v_max_i32_e32 v40, v44, v128
	v_max_i32_e32 v135, v49, v132
	v_max_i32_e32 v82, v38, v37
	v_min_i32_e32 v36, v34, v35
	v_min_i32_e32 v41, v39, v40
	v_max_i32_e32 v129, v135, v82
	v_min_i32_e32 v42, v36, v41
	v_min_i32_e32 v137, v129, v42
	v_max_i32_e32 v159, v129, v42
	ds_read_b128 v[128:131], v95 offset:32
	v_min_i32_e32 v82, v135, v82
	v_min_i32_e32 v132, v49, v132
	v_min_i32_e32 v135, v38, v37
	v_max_i32_e32 v154, v34, v35
	v_max_i32_e32 v155, v39, v40
	v_max_i32_e32 v157, v36, v41
	s_waitcnt lgkmcnt(1)
	v_mfma_f32_32x32x16_bf16 v[34:49], v[124:127], v[78:81], v[18:33]
	ds_read_b128 v[124:127], v95 offset:64
	v_max_i32_e32 v151, v132, v135
	v_max_i32_e32 v152, v82, v151
	v_min_i32_e32 v136, v138, v136
	v_min_i32_e32 v138, v140, v141
	v_min_i32_e32 v82, v82, v151
	v_max_i32_e32 v147, v147, v150
	s_waitcnt lgkmcnt(1)
	v_mfma_f32_32x32x16_bf16 v[34:49], v[128:131], v[74:77], v[34:49]
	ds_read_b128 v[128:131], v95 offset:96
	v_max_i32_e32 v143, v143, v146
	v_min_i32_e32 v133, v133, v134
	v_min_i32_e32 v156, v154, v155
	v_max_i32_e32 v140, v136, v138
	v_min_i32_e32 v139, v139, v142
	v_max_i32_e32 v142, v154, v155
	s_waitcnt lgkmcnt(1)
	v_mfma_f32_32x32x16_bf16 v[34:49], v[124:127], v[70:73], v[34:49]
	v_max_i32_e32 v124, v148, v149
	v_min_i32_e32 v136, v136, v138
	v_max_i32_e32 v141, v140, v139
	v_min_i32_e32 v139, v140, v139
	v_min_i32_e32 v125, v143, v124
	v_min_i32_e32 v158, v156, v157
	v_min_i32_e32 v132, v132, v135
	s_waitcnt lgkmcnt(0)
; #define LAS __attribute__((address_space(3)))
; #define MFMA32(a, b, c) __builtin_amdgcn_mfma_f32_32x32x16_bf16((a), (b), (c), 0, 0, 0)
; __device__ __forceinline__ void merge16_desc(int (&a)[16], const int (&b)[16]) {
; #pragma unroll
;     for (int i = 0; i < 16; ++i) a[i] = a[i] > b[15 - i] ? a[i] : b[15 - i];
; #pragma unroll
;     for (int j = 8; j > 0; j >>= 1)
; #pragma unroll
;         for (int i = 0; i < 16; ++i) { const int l = i ^ j; if (l > i) ce_desc(a[i], a[l]); }
; }
; __device__ __forceinline__ void route_task(int task, int tl0, const bf16* QP  , const LAS bf16* KHL, LAS unsigned short* EL, LAS float* GL, int lane) {
;     ...
;         for (int kt = 0; kt < 4; ++kt) {
;             f32x16 X;
; #pragma unroll
;             for (int i = 0; i < 16; ++i) X[i] = 8.f;
;             const LAS bf16* khp = KHL + (half * 128 + 32 * kt + r) * 72 + 8 * hi;
; #pragma unroll
;             for (int ks = 0; ks < 4; ++ks) {
;                 const bf16x8 kh = lds8(khp + 16 * ks);
;                 X = MFMA32(kh, qa[half][ks], X);
;             }
;             int grp[16];
; #pragma unroll
;             for (int i = 0; i < 16; ++i) grp[i] = (int)((__float_as_uint(X[i]) | 127u) - (unsigned)(32 * kt + (i & 3) + 8 * (i >> 2)));
;             sort16_desc(grp);
;             if (kt == 0) {
; #pragma unroll
;                 for (int i = 0; i < 16; ++i) cur[i] = grp[i];
;             } else merge16_desc(cur, grp);
	v_mfma_f32_32x32x16_bf16 v[34:49], v[128:131], v[66:69], v[34:49]
	v_min_i32_e32 v126, v147, v125
	v_min_i32_e32 v153, v137, v152
	v_min_i32_e32 v160, v158, v159
	v_min_i32_e32 v135, v141, v132
	v_min_i32_e32 v127, v142, v126
	s_nop 6
	v_bitop3_b32 v37, v37, s42, 35 bitop3:0x56
	v_bitop3_b32 v48, v48, s42, 58 bitop3:0x56
	v_bitop3_b32 v38, v38, s42, 40 bitop3:0x56
	v_bitop3_b32 v42, v42, s42, 48 bitop3:0x56
	v_bitop3_b32 v34, v34, s42, 32 bitop3:0x56
	v_bitop3_b32 v47, v47, s42, 57 bitop3:0x56
	v_bitop3_b32 v39, v39, s42, 41 bitop3:0x56
	v_bitop3_b32 v40, v40, s42, 42 bitop3:0x56
	v_bitop3_b32 v43, v43, s42, 49 bitop3:0x56
	v_bitop3_b32 v44, v44, s42, 50 bitop3:0x56
	v_bitop3_b32 v36, v36, s42, 34 bitop3:0x56
	v_bitop3_b32 v49, v49, s42, 59 bitop3:0x56
	v_bitop3_b32 v41, v41, s42, 43 bitop3:0x56
	v_bitop3_b32 v45, v45, s42, 51 bitop3:0x56
	v_bitop3_b32 v35, v35, s42, 33 bitop3:0x56
	v_bitop3_b32 v46, v46, s42, 56 bitop3:0x56
	v_max_i32_e32 v128, v37, v48
	v_max_i32_e32 v129, v38, v42
	v_max_i32_e32 v131, v34, v47
	v_max_i32_e32 v134, v39, v40
	v_min_i32_e32 v146, v43, v44
	v_min_i32_e32 v148, v36, v49
	v_min_i32_e32 v150, v41, v45
	v_min_i32_e32 v151, v35, v46
	v_min_i32_e32 v39, v39, v40
	v_min_i32_e32 v34, v34, v47
	v_min_i32_e32 v38, v38, v42
	v_min_i32_e32 v37, v37, v48
	v_max_i32_e32 v35, v35, v46
	v_max_i32_e32 v41, v41, v45
	v_max_i32_e32 v36, v36, v49
	v_max_i32_e32 v43, v43, v44
	v_min_i32_e32 v130, v128, v129
	v_min_i32_e32 v138, v131, v134
	v_max_i32_e32 v149, v146, v148
	v_max_i32_e32 v154, v150, v151
	v_max_i32_e32 v40, v39, v34
	v_max_i32_e32 v42, v38, v37
	v_min_i32_e32 v45, v35, v41
	v_min_i32_e32 v44, v36, v43
	v_min_i32_e32 v150, v150, v151
	v_min_i32_e32 v34, v39, v34
	v_min_i32_e32 v37, v38, v37
	v_min_i32_e32 v38, v146, v148
	v_max_i32_e32 v131, v131, v134
	v_max_i32_e32 v35, v35, v41
	v_max_i32_e32 v36, v36, v43
	v_max_i32_e32 v43, v128, v129
	v_min_i32_e32 v140, v130, v138
	v_min_i32_e32 v155, v149, v154
	v_max_i32_e32 v47, v40, v42
	v_max_i32_e32 v46, v45, v44
	v_min_i32_e32 v40, v40, v42
	v_min_i32_e32 v42, v45, v44
	v_max_i32_e32 v45, v130, v138
	v_max_i32_e32 v130, v149, v154
	v_min_i32_e32 v39, v150, v34
	v_min_i32_e32 v146, v37, v38
	v_max_i32_e32 v34, v150, v34
	v_max_i32_e32 v37, v37, v38
	v_min_i32_e32 v41, v131, v35
	v_min_i32_e32 v128, v36, v43
	v_max_i32_e32 v35, v131, v35
	v_max_i32_e32 v36, v36, v43
	v_min_i32_e32 v48, v47, v46
	v_max_i32_e32 v44, v40, v42
	v_min_i32_e32 v138, v45, v130
	v_min_i32_e32 v40, v40, v42
	v_min_i32_e32 v42, v140, v155
	v_max_i32_e32 v148, v39, v146
	v_min_i32_e32 v38, v34, v37
	v_min_i32_e32 v129, v41, v128
	v_max_i32_e32 v41, v41, v128
	v_min_i32_e32 v43, v35, v36
	v_max_i32_e32 v45, v45, v130
	v_max_i32_e32 v46, v47, v46
	v_max_i32_e32 v161, v140, v155
	v_max_i32_e32 v140, v40, v42
	v_max_i32_e32 v150, v148, v38
	v_max_i32_e32 v34, v34, v37
	v_min_i32_e32 v128, v41, v43
	v_min_i32_e32 v47, v45, v46
	v_min_i32_e32 v49, v161, v48
	v_min_i32_e32 v149, v44, v138
	v_max_i32_e32 v151, v140, v150
	v_min_i32_e32 v37, v129, v34
	v_max_i32_e32 v34, v129, v34
	v_min_i32_e32 v129, v128, v47
	v_max_i32_e32 v48, v161, v48
	v_max_i32_e32 v44, v44, v138
	v_max_i32_e32 v154, v49, v149
	v_max_i32_e32 v134, v151, v37
	v_min_i32_e32 v130, v34, v129
	v_min_i32_e32 v131, v48, v44
	v_min_i32_e32 v49, v49, v149
	v_min_i32_e32 v37, v151, v37
	v_max_i32_e32 v34, v34, v129
	v_max_i32_e32 v44, v48, v44
	v_min_i32_e32 v40, v40, v42
	v_min_i32_e32 v38, v148, v38
	v_max_i32_e32 v41, v41, v43
	v_max_i32_e32 v43, v45, v46
	v_max_i32_e32 v155, v154, v134
	v_min_i32_e32 v138, v130, v131
	v_min_i32_e32 v134, v154, v134
	v_max_i32_e32 v149, v49, v37
	v_min_i32_e32 v48, v34, v44
	v_max_i32_e32 v129, v130, v131
	v_max_i32_e32 v42, v40, v38
	v_min_i32_e32 v140, v140, v150
	v_max_i32_e32 v34, v34, v44
	v_max_i32_e32 v44, v128, v47
	v_min_i32_e32 v45, v41, v43
	v_min_i32_e32 v161, v155, v138
	v_max_i32_e32 v151, v134, v149
	v_min_i32_e32 v130, v48, v129
	v_max_i32_e32 v131, v155, v138
	v_max_i32_e32 v148, v42, v140
	v_min_i32_e32 v37, v49, v37
	v_min_i32_e32 v46, v44, v45
	v_min_i32_e32 v154, v161, v151
	v_min_i32_e32 v138, v130, v131
	v_min_i32_e32 v49, v148, v37
	v_min_i32_e32 v134, v134, v149
	v_min_i32_e32 v47, v34, v46
	v_min_i32_e32 v42, v42, v140
	v_min_i32_e32 v38, v40, v38
	v_min_i32_e32 v39, v39, v146
	v_max3_i32 v39, v144, v145, v39
	v_max3_i32 v38, v143, v124, v38
	v_max3_i32 v40, v147, v125, v42
	v_max3_i32 v42, v142, v126, v49
	v_max3_i32 v37, v127, v148, v37
	v_max3_i32 v49, v156, v157, v134
	v_max3_i32 v124, v158, v159, v154
	v_max3_i32 v125, v160, v161, v151
	v_max3_i32 v126, v137, v152, v138
	v_max3_i32 v127, v153, v130, v131
	v_max3_i32 v48, v82, v48, v129
	v_max3_i32 v47, v141, v132, v47
	v_max3_i32 v34, v135, v34, v46
	v_max3_i32 v44, v139, v44, v45
	v_max3_i32 v41, v136, v41, v43
	v_max3_i32 v35, v133, v35, v36
	v_max_i32_e32 v36, v39, v126
	v_min_i32_e32 v39, v39, v126
	v_max_i32_e32 v43, v38, v127
	v_min_i32_e32 v38, v38, v127
	v_max_i32_e32 v45, v40, v48
	v_min_i32_e32 v40, v40, v48
	v_max_i32_e32 v46, v42, v47
	v_min_i32_e32 v42, v42, v47
	v_max_i32_e32 v47, v37, v34
	v_min_i32_e32 v34, v37, v34
	v_max_i32_e32 v37, v49, v44
	v_min_i32_e32 v44, v49, v44
	v_max_i32_e32 v48, v124, v41
	v_min_i32_e32 v41, v124, v41
	v_max_i32_e32 v49, v125, v35
	v_min_i32_e32 v35, v125, v35
	ds_read_b128 v[124:127], v94 offset:9216
	ds_read_b128 v[128:131], v94 offset:9248
	v_max_i32_e32 v82, v36, v47
	v_min_i32_e32 v132, v36, v47
	v_max_i32_e32 v36, v43, v37
	v_min_i32_e32 v133, v43, v37
	v_max_i32_e32 v37, v45, v48
	v_max_i32_e32 v43, v46, v49
	v_min_i32_e32 v134, v45, v48
	v_min_i32_e32 v135, v46, v49
	v_max_i32_e32 v136, v39, v34
	v_min_i32_e32 v137, v39, v34
	v_max_i32_e32 v138, v38, v44
	v_min_i32_e32 v139, v38, v44
	v_max_i32_e32 v140, v40, v41
	v_min_i32_e32 v141, v40, v41
	v_max_i32_e32 v142, v42, v35
	v_min_i32_e32 v143, v42, v35
	v_max_i32_e32 v144, v82, v37
	v_min_i32_e32 v82, v82, v37
	v_max_i32_e32 v145, v36, v43
	v_min_i32_e32 v146, v36, v43
	s_waitcnt lgkmcnt(1)
; #define LAS __attribute__((address_space(3)))
; #define MFMA32(a, b, c) __builtin_amdgcn_mfma_f32_32x32x16_bf16((a), (b), (c), 0, 0, 0)
; __device__ __forceinline__ void merge16_desc(int (&a)[16], const int (&b)[16]) {
; #pragma unroll
;     for (int i = 0; i < 16; ++i) a[i] = a[i] > b[15 - i] ? a[i] : b[15 - i];
; #pragma unroll
;     for (int j = 8; j > 0; j >>= 1)
; #pragma unroll
;         for (int i = 0; i < 16; ++i) { const int l = i ^ j; if (l > i) ce_desc(a[i], a[l]); }
; }
; __device__ __forceinline__ void route_task(int task, int tl0, const bf16* QP  , const LAS bf16* KHL, LAS unsigned short* EL, LAS float* GL, int lane) {
;     ...
;         for (int kt = 0; kt < 4; ++kt) {
;             f32x16 X;
; #pragma unroll
;             for (int i = 0; i < 16; ++i) X[i] = 8.f;
;             const LAS bf16* khp = KHL + (half * 128 + 32 * kt + r) * 72 + 8 * hi;
; #pragma unroll
;             for (int ks = 0; ks < 4; ++ks) {
;                 const bf16x8 kh = lds8(khp + 16 * ks);
;                 X = MFMA32(kh, qa[half][ks], X);
;             }
;             int grp[16];
; #pragma unroll
;             for (int i = 0; i < 16; ++i) grp[i] = (int)((__float_as_uint(X[i]) | 127u) - (unsigned)(32 * kt + (i & 3) + 8 * (i >> 2)));
;             sort16_desc(grp);
;             if (kt == 0) {
; #pragma unroll
;                 for (int i = 0; i < 16; ++i) cur[i] = grp[i];
;             } else merge16_desc(cur, grp);
	v_mfma_f32_32x32x16_bf16 v[34:49], v[124:127], v[78:81], v[18:33]
	ds_read_b128 v[124:127], v94 offset:9280
	v_max_i32_e32 v147, v132, v134
	v_min_i32_e32 v132, v132, v134
	v_max_i32_e32 v134, v133, v135
	v_min_i32_e32 v133, v133, v135
	v_max_i32_e32 v135, v136, v140
	v_min_i32_e32 v136, v136, v140
	s_waitcnt lgkmcnt(1)
	v_mfma_f32_32x32x16_bf16 v[34:49], v[128:131], v[74:77], v[34:49]
	ds_read_b128 v[128:131], v94 offset:9312
	v_max_i32_e32 v140, v138, v142
	v_min_i32_e32 v138, v138, v142
	v_max_i32_e32 v142, v137, v141
	v_min_i32_e32 v137, v137, v141
	v_max_i32_e32 v141, v139, v143
	v_min_i32_e32 v139, v139, v143
	s_waitcnt lgkmcnt(1)
	v_mfma_f32_32x32x16_bf16 v[34:49], v[124:127], v[70:73], v[34:49]
	v_min_i32_e32 v143, v144, v145
	v_min_i32_e32 v124, v82, v146
	v_min_i32_e32 v127, v135, v140
	v_min_i32_e32 v125, v147, v134
	v_min_i32_e32 v126, v132, v133
	v_min_i32_e32 v149, v142, v141
	v_min_i32_e32 v148, v136, v138
	s_waitcnt lgkmcnt(0)
	v_mfma_f32_32x32x16_bf16 v[34:49], v[128:131], v[66:69], v[34:49]
	v_min_i32_e32 v150, v137, v139
	s_nop 10
	v_and_or_b32 v37, v37, s43, 60
	v_and_or_b32 v48, v48, s43, 37
	v_and_or_b32 v38, v38, s43, 55
	v_and_or_b32 v42, v42, s43, 47
	v_bitop3_b32 v34, v34, s42, 64 bitop3:0x56
	v_and_or_b32 v47, v47, s43, 38
	v_and_or_b32 v39, v39, s43, 54
	v_and_or_b32 v40, v40, s43, 53
	v_and_or_b32 v43, v43, s43, 46
	v_and_or_b32 v44, v44, s43, 45
	v_and_or_b32 v36, v36, s43, 61
	v_and_or_b32 v49, v49, s43, 36
	v_and_or_b32 v41, v41, s43, 52
	v_and_or_b32 v45, v45, s43, 44
	v_and_or_b32 v35, v35, s43, 62
	v_and_or_b32 v46, v46, s43, 39
	v_max_i32_e32 v128, v37, v48
	v_max_i32_e32 v129, v38, v42
	v_max_i32_e32 v131, v34, v47
	v_max_i32_e32 v151, v39, v40
	v_min_i32_e32 v154, v43, v44
	v_min_i32_e32 v155, v36, v49
	v_min_i32_e32 v157, v41, v45
	v_min_i32_e32 v158, v35, v46
	v_min_i32_e32 v39, v39, v40
	v_min_i32_e32 v34, v34, v47
	v_min_i32_e32 v38, v38, v42
	v_min_i32_e32 v37, v37, v48
	v_max_i32_e32 v35, v35, v46
	v_max_i32_e32 v41, v41, v45
	v_max_i32_e32 v36, v36, v49
	v_max_i32_e32 v43, v43, v44
	v_min_i32_e32 v130, v128, v129
	v_min_i32_e32 v152, v131, v151
	v_max_i32_e32 v156, v154, v155
	v_max_i32_e32 v159, v157, v158
	v_max_i32_e32 v40, v39, v34
	v_max_i32_e32 v42, v38, v37
	v_min_i32_e32 v45, v35, v41
	v_min_i32_e32 v44, v36, v43
	v_min_i32_e32 v157, v157, v158
	v_min_i32_e32 v34, v39, v34
	v_min_i32_e32 v37, v38, v37
	v_min_i32_e32 v38, v154, v155
	v_max_i32_e32 v131, v131, v151
	v_max_i32_e32 v35, v35, v41
	v_max_i32_e32 v36, v36, v43
	v_max_i32_e32 v43, v128, v129
	v_min_i32_e32 v153, v130, v152
	v_min_i32_e32 v160, v156, v159
	v_max_i32_e32 v47, v40, v42
	v_max_i32_e32 v46, v45, v44
	v_min_i32_e32 v40, v40, v42
	v_min_i32_e32 v42, v45, v44
	v_max_i32_e32 v45, v130, v152
	v_max_i32_e32 v130, v156, v159
	v_min_i32_e32 v39, v157, v34
	v_min_i32_e32 v154, v37, v38
	v_max_i32_e32 v34, v157, v34
	v_max_i32_e32 v37, v37, v38
	v_min_i32_e32 v41, v131, v35
	v_min_i32_e32 v128, v36, v43
	v_max_i32_e32 v35, v131, v35
	v_max_i32_e32 v36, v36, v43
	v_min_i32_e32 v48, v47, v46
	v_max_i32_e32 v44, v40, v42
	v_min_i32_e32 v152, v45, v130
	v_min_i32_e32 v40, v40, v42
	v_min_i32_e32 v42, v153, v160
	v_max_i32_e32 v155, v39, v154
	v_min_i32_e32 v38, v34, v37
	v_min_i32_e32 v129, v41, v128
	v_max_i32_e32 v41, v41, v128
	v_min_i32_e32 v43, v35, v36
	v_max_i32_e32 v45, v45, v130
	v_max_i32_e32 v46, v47, v46
	v_max_i32_e32 v161, v153, v160
	v_max_i32_e32 v153, v40, v42
	v_max_i32_e32 v157, v155, v38
	v_max_i32_e32 v34, v34, v37
	v_min_i32_e32 v128, v41, v43
	v_min_i32_e32 v47, v45, v46
	v_min_i32_e32 v49, v161, v48
	v_min_i32_e32 v156, v44, v152
	v_max_i32_e32 v158, v153, v157
	v_min_i32_e32 v37, v129, v34
	v_max_i32_e32 v34, v129, v34
	v_min_i32_e32 v129, v128, v47
	v_max_i32_e32 v48, v161, v48
	v_max_i32_e32 v44, v44, v152
	v_min_i32_e32 v40, v40, v42
	v_min_i32_e32 v38, v155, v38
	v_max_i32_e32 v159, v49, v156
	v_max_i32_e32 v151, v158, v37
	v_min_i32_e32 v130, v34, v129
	v_min_i32_e32 v131, v48, v44
	v_min_i32_e32 v49, v49, v156
	v_min_i32_e32 v37, v158, v37
	v_max_i32_e32 v34, v34, v129
	v_max_i32_e32 v44, v48, v44
	v_max_i32_e32 v42, v40, v38
	v_min_i32_e32 v153, v153, v157
	v_max_i32_e32 v160, v159, v151
	v_min_i32_e32 v152, v130, v131
	v_max_i32_e32 v156, v49, v37
	v_min_i32_e32 v48, v34, v44
	v_max_i32_e32 v129, v130, v131
	v_max_i32_e32 v155, v42, v153
	v_min_i32_e32 v37, v49, v37
	v_min_i32_e32 v151, v159, v151
	v_min_i32_e32 v130, v48, v129
	v_max_i32_e32 v131, v160, v152
	v_min_i32_e32 v49, v155, v37
	v_max_i32_e32 v41, v41, v43
	v_max_i32_e32 v43, v45, v46
	v_min_i32_e32 v42, v42, v153
	v_min_i32_e32 v38, v40, v38
	v_min_i32_e32 v161, v160, v152
	v_max_i32_e32 v158, v151, v156
	v_min_i32_e32 v151, v151, v156
	v_max_i32_e32 v34, v34, v44
	v_max_i32_e32 v44, v128, v47
	v_min_i32_e32 v45, v41, v43
	v_max_i32_e32 v40, v41, v43
	v_max_i32_e32 v38, v143, v38
	v_max3_i32 v41, v82, v146, v42
	v_max_i32_e32 v42, v124, v49
	v_max3_i32 v124, v127, v130, v131
	v_min_i32_e32 v46, v44, v45
	v_max_i32_e32 v43, v125, v151
	v_max3_i32 v49, v126, v161, v158
	v_max3_i32 v44, v149, v44, v45
	v_max_i32_e32 v45, v38, v124
	v_min_i32_e32 v38, v38, v124
	ds_read_b128 v[124:127], v96
	v_min_i32_e32 v159, v161, v158
	v_min_i32_e32 v152, v130, v131
	v_max_i32_e32 v37, v155, v37
	v_max_i32_e32 v48, v48, v129
	v_min_i32_e32 v47, v34, v46
	v_max_i32_e32 v34, v34, v46
	v_min_i32_e32 v39, v39, v154
	v_max3_i32 v39, v144, v145, v39
	v_max3_i32 v37, v147, v134, v37
	v_max3_i32 v46, v132, v133, v159
	v_max3_i32 v82, v135, v140, v152
	v_max3_i32 v48, v136, v138, v48
	v_max_i32_e32 v47, v148, v47
	v_max3_i32 v34, v142, v141, v34
	v_max3_i32 v40, v137, v139, v40
	v_max3_i32 v35, v150, v35, v36
	v_max_i32_e32 v36, v39, v82
	v_min_i32_e32 v39, v39, v82
	v_max_i32_e32 v82, v41, v48
	v_min_i32_e32 v41, v41, v48
	v_max_i32_e32 v48, v42, v47
	v_min_i32_e32 v42, v42, v47
	v_max_i32_e32 v47, v37, v34
	v_min_i32_e32 v34, v37, v34
	v_max_i32_e32 v37, v43, v44
	v_min_i32_e32 v43, v43, v44
	v_max_i32_e32 v44, v46, v40
	v_min_i32_e32 v40, v46, v40
	v_max_i32_e32 v46, v49, v35
	v_min_i32_e32 v35, v49, v35
	v_max_i32_e32 v49, v36, v47
	v_min_i32_e32 v132, v36, v47
	v_max_i32_e32 v36, v45, v37
	v_min_i32_e32 v133, v45, v37
	v_max_i32_e32 v37, v82, v44
	v_min_i32_e32 v82, v82, v44
	v_max_i32_e32 v44, v48, v46
	ds_read_b128 v[128:131], v96 offset:32
	v_min_i32_e32 v134, v48, v46
	v_max_i32_e32 v135, v39, v34
	v_min_i32_e32 v136, v39, v34
	v_max_i32_e32 v137, v38, v43
	v_min_i32_e32 v138, v38, v43
	v_max_i32_e32 v139, v41, v40
	v_min_i32_e32 v140, v41, v40
	v_max_i32_e32 v141, v42, v35
	v_min_i32_e32 v142, v42, v35
	v_max_i32_e32 v143, v49, v37
	v_min_i32_e32 v144, v49, v37
	v_max_i32_e32 v145, v36, v44
	v_min_i32_e32 v146, v36, v44
	s_waitcnt lgkmcnt(1)
; #define LAS __attribute__((address_space(3)))
; #define MFMA32(a, b, c) __builtin_amdgcn_mfma_f32_32x32x16_bf16((a), (b), (c), 0, 0, 0)
; __device__ __forceinline__ void merge16_desc(int (&a)[16], const int (&b)[16]) {
; #pragma unroll
;     for (int i = 0; i < 16; ++i) a[i] = a[i] > b[15 - i] ? a[i] : b[15 - i];
; #pragma unroll
;     for (int j = 8; j > 0; j >>= 1)
; #pragma unroll
;         for (int i = 0; i < 16; ++i) { const int l = i ^ j; if (l > i) ce_desc(a[i], a[l]); }
; }
; __device__ __forceinline__ void route_task(int task, int tl0, const bf16* QP  , const LAS bf16* KHL, LAS unsigned short* EL, LAS float* GL, int lane) {
;     ...
;         for (int kt = 0; kt < 4; ++kt) {
;             f32x16 X;
; #pragma unroll
;             for (int i = 0; i < 16; ++i) X[i] = 8.f;
;             const LAS bf16* khp = KHL + (half * 128 + 32 * kt + r) * 72 + 8 * hi;
; #pragma unroll
;             for (int ks = 0; ks < 4; ++ks) {
;                 const bf16x8 kh = lds8(khp + 16 * ks);
;                 X = MFMA32(kh, qa[half][ks], X);
;             }
;             int grp[16];
; #pragma unroll
;             for (int i = 0; i < 16; ++i) grp[i] = (int)((__float_as_uint(X[i]) | 127u) - (unsigned)(32 * kt + (i & 3) + 8 * (i >> 2)));
;             sort16_desc(grp);
;             if (kt == 0) {
; #pragma unroll
;                 for (int i = 0; i < 16; ++i) cur[i] = grp[i];
;             } else merge16_desc(cur, grp);
	v_mfma_f32_32x32x16_bf16 v[34:49], v[124:127], v[78:81], v[18:33]
	ds_read_b128 v[78:81], v96 offset:64
	v_max_i32_e32 v147, v132, v82
	v_min_i32_e32 v82, v132, v82
	v_max_i32_e32 v132, v137, v141
	v_max_i32_e32 v124, v133, v134
	v_min_i32_e32 v125, v133, v134
	v_max_i32_e32 v126, v135, v139
	s_waitcnt lgkmcnt(1)
	v_mfma_f32_32x32x16_bf16 v[34:49], v[128:131], v[74:77], v[34:49]
	ds_read_b128 v[74:77], v96 offset:96
	v_min_i32_e32 v128, v137, v141
	v_max_i32_e32 v129, v136, v140
	v_min_i32_e32 v130, v136, v140
	v_min_i32_e32 v127, v135, v139
	v_max_i32_e32 v131, v138, v142
	v_min_i32_e32 v133, v138, v142
	s_waitcnt lgkmcnt(1)
	v_mfma_f32_32x32x16_bf16 v[34:49], v[78:81], v[70:73], v[34:49]
	v_min_i32_e32 v134, v143, v145
	v_min_i32_e32 v70, v144, v146
	v_min_i32_e32 v71, v147, v124
	v_min_i32_e32 v72, v82, v125
	v_min_i32_e32 v73, v126, v132
	v_min_i32_e32 v78, v127, v128
	v_min_i32_e32 v79, v129, v131
	s_waitcnt lgkmcnt(0)
	v_mfma_f32_32x32x16_bf16 v[34:49], v[74:77], v[66:69], v[34:49]
	v_min_i32_e32 v80, v130, v133
	s_nop 10
	v_and_or_b32 v41, v41, s43, 20
	v_and_or_b32 v45, v45, s43, 12
	v_and_or_b32 v35, v35, s43, 30
	v_and_or_b32 v46, v46, s43, 7
	v_and_or_b32 v39, v39, s43, 22
	v_and_or_b32 v40, v40, s43, 21
	v_and_or_b32 v34, v34, s43, 31
	v_and_or_b32 v47, v47, s43, 6
	v_and_or_b32 v38, v38, s43, 23
	v_and_or_b32 v42, v42, s43, 15
	v_and_or_b32 v37, v37, s43, 28
	v_and_or_b32 v48, v48, s43, 5
	v_and_or_b32 v43, v43, s43, 14
	v_and_or_b32 v44, v44, s43, 13
	v_and_or_b32 v36, v36, s43, 29
	v_and_or_b32 v49, v49, s43, 4
	v_min_i32_e32 v66, v41, v45
	v_min_i32_e32 v67, v35, v46
	v_min_i32_e32 v69, v39, v40
	v_min_i32_e32 v74, v34, v47
	v_min_i32_e32 v77, v38, v42
	v_min_i32_e32 v81, v37, v48
	v_min_i32_e32 v136, v43, v44
	v_min_i32_e32 v137, v36, v49
	v_max_i32_e32 v34, v34, v47
	v_max_i32_e32 v39, v39, v40
	v_max_i32_e32 v35, v35, v46
	v_max_i32_e32 v41, v41, v45
	v_max_i32_e32 v36, v36, v49
	v_max_i32_e32 v43, v43, v44
	v_max_i32_e32 v37, v37, v48
	v_max_i32_e32 v38, v38, v42
	v_max_i32_e32 v40, v34, v39
	v_max_i32_e32 v45, v35, v41
	v_max_i32_e32 v44, v36, v43
	v_max_i32_e32 v42, v37, v38
	v_min_i32_e32 v46, v40, v45
	v_min_i32_e32 v47, v44, v42
	v_min_i32_e32 v75, v69, v74
	v_min_i32_e32 v48, v46, v47
	v_max_i32_e32 v46, v46, v47
	v_min_i32_e32 v37, v37, v38
	v_min_i32_e32 v34, v34, v39
	v_max_i32_e32 v39, v136, v137
	v_max_i32_e32 v47, v66, v67
	v_max_i32_e32 v69, v69, v74
	v_max_i32_e32 v74, v77, v81
	v_min_i32_e32 v35, v35, v41
	v_min_i32_e32 v36, v36, v43
	v_min_i32_e32 v68, v66, v67
	v_min_i32_e32 v135, v77, v81
	v_min_i32_e32 v138, v136, v137
	v_max_i32_e32 v38, v37, v34
	v_max_i32_e32 v77, v69, v74
	v_max_i32_e32 v41, v35, v36
	v_min_i32_e32 v34, v37, v34
	v_min_i32_e32 v37, v39, v47
	v_min_i32_e32 v76, v68, v75
	v_min_i32_e32 v139, v135, v138
	v_max_i32_e32 v49, v68, v75
	v_max_i32_e32 v68, v135, v138
	v_max_i32_e32 v40, v40, v45
	v_max_i32_e32 v42, v44, v42
	v_max_i32_e32 v66, v39, v47
	v_max_i32_e32 v43, v77, v41
	v_max_i32_e32 v39, v34, v37
	v_min_i32_e32 v41, v77, v41
	v_min_i32_e32 v69, v69, v74
	v_min_i32_e32 v35, v35, v36
	v_max_i32_e32 v75, v49, v68
	v_min_i32_e32 v44, v40, v42
	v_max_i32_e32 v67, v38, v66
	v_max_i32_e32 v47, v39, v41
	v_max_i32_e32 v36, v69, v35
	v_min_i32_e32 v39, v39, v41
	v_min_i32_e32 v35, v69, v35
	v_min_i32_e32 v34, v34, v37
	v_max_i32_e32 v41, v76, v139
	v_min_i32_e32 v49, v49, v68
	v_min_i32_e32 v45, v46, v44
	v_min_i32_e32 v81, v67, v43
	v_min_i32_e32 v38, v38, v66
	v_max_i32_e32 v37, v35, v34
	v_max_i32_e32 v68, v41, v49
	v_max_i32_e32 v135, v48, v75
	v_min_i32_e32 v136, v45, v81
	v_max_i32_e32 v66, v36, v38
	v_min_i32_e32 v36, v36, v38
	v_max_i32_e32 v69, v37, v68
	v_min_i32_e32 v48, v48, v75
	v_max_i32_e32 v137, v135, v136
	v_max_i32_e32 v74, v47, v66
	v_min_i32_e32 v135, v135, v136
	v_min_i32_e32 v47, v47, v66
	v_max_i32_e32 v38, v39, v36
	v_max_i32_e32 v75, v69, v48
	v_min_i32_e32 v34, v35, v34
	v_min_i32_e32 v35, v41, v49
	v_min_i32_e32 v36, v39, v36
	v_min_i32_e32 v39, v69, v48
	v_max_i32_e32 v44, v46, v44
	v_max_i32_e32 v43, v67, v43
	v_min_i32_e32 v140, v76, v139
	v_min_i32_e32 v77, v137, v74
	v_max_i32_e32 v66, v135, v47
	v_max_i32_e32 v76, v38, v75
	v_min_i32_e32 v47, v135, v47
	v_max_i32_e32 v41, v34, v35
	v_min_i32_e32 v37, v37, v68
	v_min_i32_e32 v48, v36, v39
	v_max_i32_e32 v45, v45, v81
	v_min_i32_e32 v46, v44, v43
	v_min_i32_e32 v38, v38, v75
	v_max_i32_e32 v36, v36, v39
	v_min_i32_e32 v136, v77, v66
	v_max_i32_e32 v135, v76, v47
	v_max_i32_e32 v49, v41, v37
	v_max_i32_e32 v69, v137, v74
	v_min_i32_e32 v67, v45, v46
	v_min_i32_e32 v47, v76, v47
	v_max_i32_e32 v39, v38, v36
	v_min_i32_e32 v138, v136, v135
	v_max_i32_e32 v68, v49, v48
	v_max_i32_e32 v74, v69, v67
	v_min_i32_e32 v37, v41, v37
	v_max_i32_e32 v41, v77, v66
	v_min_i32_e32 v75, v47, v39
	v_max_i32_e32 v43, v44, v43
	v_min_i32_e32 v34, v34, v35
	v_min_i32_e32 v36, v38, v36
	v_min_i32_e32 v48, v49, v48
	v_min_i32_e32 v49, v69, v67
	v_max3_i32 v140, v143, v145, v140
	v_max3_i32 v126, v126, v132, v138
	v_max3_i32 v68, v147, v124, v68
	v_max3_i32 v74, v129, v131, v74
	v_max3_i32 v37, v144, v146, v37
	v_max3_i32 v41, v127, v128, v41
	v_max3_i32 v75, v82, v125, v75
	v_max3_i32 v43, v130, v133, v43
	v_max_i32_e32 v34, v134, v34
	v_max3_i32 v35, v73, v136, v135
	v_max_i32_e32 v36, v71, v36
	v_max3_i32 v38, v79, v45, v46
	v_max_i32_e32 v48, v70, v48
	v_max_i32_e32 v49, v78, v49
	v_max3_i32 v39, v72, v47, v39
	v_max3_i32 v40, v80, v40, v42
	v_min_i32_e32 v81, v68, v74
	v_min_i32_e32 v66, v37, v41
	v_min_i32_e32 v73, v34, v35
	v_min_i32_e32 v45, v36, v38
	v_min_i32_e32 v42, v39, v40
	v_max_i32_e32 v71, v140, v126
; #define LAS __attribute__((address_space(3)))
; #define MFMA32(a, b, c) __builtin_amdgcn_mfma_f32_32x32x16_bf16((a), (b), (c), 0, 0, 0)
; __device__ __forceinline__ void route_task(int task, int tl0, const bf16* QP  , const LAS bf16* KHL, LAS unsigned short* EL, LAS float* GL, int lane) {
;     ...
;         for (int kt = 0; kt < 4; ++kt) {
;             f32x16 X;
; #pragma unroll
;             for (int i = 0; i < 16; ++i) X[i] = 8.f;
;             const LAS bf16* khp = KHL + (half * 128 + 32 * kt + r) * 72 + 8 * hi;
; #pragma unroll
;             for (int ks = 0; ks < 4; ++ks) {
;                 const bf16x8 kh = lds8(khp + 16 * ks);
;                 X = MFMA32(kh, qa[half][ks], X);
;     ...
;             } else merge16_desc(cur, grp);
;         }
;         { const unsigned h4 = 4u * (unsigned)hi;
; #pragma unroll
;           for (int i = 0; i < 16; ++i) cur[i] -= (int)h4; }
;         int oth[16];
; #pragma unroll
;         for (int i = 0; i < 16; ++i) oth[i] = __shfl_xor(cur[i], 32);
;         merge16_desc(cur, oth);
; #pragma unroll
;         for (int i = 0; i < 16; ++i) top[half][i] = cur[i];
;     }
	v_max_i32_e32 v68, v68, v74
	v_max_i32_e32 v37, v37, v41
	v_max_i32_e32 v41, v75, v43
	v_max_i32_e32 v34, v34, v35
	v_max_i32_e32 v35, v36, v38
	v_max_i32_e32 v38, v48, v49
	v_max_i32_e32 v39, v39, v40
	v_min_i32_e32 v44, v75, v43
	v_max_i32_e32 v72, v71, v68
	v_max_i32_e32 v43, v37, v41
	v_max_i32_e32 v36, v34, v35
	v_max_i32_e32 v40, v38, v39
	v_min_i32_e32 v67, v48, v49
	v_max_i32_e32 v74, v72, v43
	v_max_i32_e32 v48, v36, v40
	v_min_i32_e32 v43, v72, v43
	v_min_i32_e32 v36, v36, v40
	v_max_i32_e32 v40, v43, v36
	v_min_i32_e32 v36, v43, v36
	v_min_i32_e32 v43, v71, v68
	v_min_i32_e32 v37, v37, v41
	v_min_i32_e32 v34, v34, v35
	v_min_i32_e32 v35, v38, v39
	v_min_i32_e32 v132, v140, v126
	v_max_i32_e32 v41, v43, v37
	v_max_i32_e32 v38, v34, v35
	v_min_i32_e32 v37, v43, v37
	v_min_i32_e32 v34, v34, v35
	v_min_i32_e32 v76, v66, v44
	v_min_i32_e32 v47, v67, v42
	v_max_i32_e32 v39, v41, v38
	v_min_i32_e32 v38, v41, v38
	v_max_i32_e32 v35, v37, v34
	v_min_i32_e32 v34, v37, v34
	v_max_i32_e32 v37, v132, v81
	v_max_i32_e32 v41, v66, v44
	v_max_i32_e32 v44, v73, v45
	v_max_i32_e32 v42, v67, v42
	v_min_i32_e32 v124, v132, v81
	v_min_i32_e32 v46, v73, v45
	v_max_i32_e32 v43, v37, v41
	v_min_i32_e32 v37, v37, v41
	v_min_i32_e32 v41, v44, v42
	v_min_i32_e32 v77, v124, v76
	v_min_i32_e32 v69, v46, v47
	v_max_i32_e32 v45, v44, v42
	v_max_i32_e32 v42, v37, v41
	v_min_i32_e32 v37, v37, v41
	v_max_i32_e32 v41, v124, v76
	v_max_i32_e32 v44, v46, v47
	v_min_i32_e32 v70, v77, v69
	v_max_i32_e32 v49, v74, v48
	v_min_i32_e32 v48, v74, v48
	v_max_i32_e32 v66, v43, v45
	v_min_i32_e32 v43, v43, v45
	v_max_i32_e32 v45, v41, v44
	v_min_i32_e32 v41, v41, v44
	v_max_i32_e32 v44, v77, v69
	v_sub_u32_e32 v46, v49, v87
	v_sub_u32_e32 v47, v48, v87
	v_sub_u32_e32 v40, v40, v87
	v_sub_u32_e32 v36, v36, v87
	v_sub_u32_e32 v39, v39, v87
	v_sub_u32_e32 v38, v38, v87
	v_sub_u32_e32 v35, v35, v87
	v_sub_u32_e32 v34, v34, v87
	v_sub_u32_e32 v48, v66, v87
	v_sub_u32_e32 v43, v43, v87
	v_sub_u32_e32 v42, v42, v87
	v_sub_u32_e32 v37, v37, v87
	v_sub_u32_e32 v45, v45, v87
	v_sub_u32_e32 v41, v41, v87
	v_sub_u32_e32 v44, v44, v87
	v_sub_u32_e32 v49, v70, v87
	ds_bpermute_b32 v66, v123, v46
	ds_bpermute_b32 v67, v123, v47
	ds_bpermute_b32 v68, v123, v40
	ds_bpermute_b32 v69, v123, v36
	ds_bpermute_b32 v70, v123, v39
	ds_bpermute_b32 v71, v123, v38
	ds_bpermute_b32 v72, v123, v35
	ds_bpermute_b32 v73, v123, v34
	ds_bpermute_b32 v74, v123, v48
	ds_bpermute_b32 v75, v123, v43
	ds_bpermute_b32 v76, v123, v42
	ds_bpermute_b32 v77, v123, v49
	ds_bpermute_b32 v78, v123, v44
	ds_bpermute_b32 v79, v123, v41
	ds_bpermute_b32 v80, v123, v45
	ds_bpermute_b32 v81, v123, v37
	s_waitcnt lgkmcnt(4)
	v_max_i32_e32 v46, v46, v77
	s_waitcnt lgkmcnt(3)
	v_max_i32_e32 v47, v47, v78
	s_waitcnt lgkmcnt(2)
	v_max_i32_e32 v40, v40, v79
	s_waitcnt lgkmcnt(1)
	v_max_i32_e32 v36, v36, v80
	s_waitcnt lgkmcnt(0)
	v_max_i32_e32 v39, v39, v81
	v_max_i32_e32 v38, v38, v76
	v_max_i32_e32 v35, v35, v75
	v_max_i32_e32 v34, v34, v74
	v_max_i32_e32 v48, v48, v73
	v_max_i32_e32 v43, v43, v72
	v_max_i32_e32 v42, v42, v71
	v_max_i32_e32 v37, v37, v70
	v_max_i32_e32 v45, v45, v69
	v_max_i32_e32 v41, v41, v68
	v_max_i32_e32 v44, v44, v67
	v_max_i32_e32 v49, v49, v66
	v_max_i32_e32 v66, v46, v48
	v_min_i32_e32 v46, v46, v48
	v_max_i32_e32 v48, v47, v43
	v_min_i32_e32 v43, v47, v43
	v_max_i32_e32 v47, v40, v42
	v_min_i32_e32 v40, v40, v42
	v_max_i32_e32 v42, v36, v37
	v_min_i32_e32 v36, v36, v37
	v_max_i32_e32 v37, v39, v45
	v_min_i32_e32 v39, v39, v45
	v_max_i32_e32 v45, v38, v41
	v_min_i32_e32 v38, v38, v41
	v_max_i32_e32 v41, v35, v44
	v_min_i32_e32 v35, v35, v44
	v_max_i32_e32 v44, v34, v49
	v_min_i32_e32 v34, v34, v49
	v_max_i32_e32 v49, v66, v37
	v_min_i32_e32 v37, v66, v37
	v_max_i32_e32 v66, v48, v45
	v_min_i32_e32 v45, v48, v45
	v_max_i32_e32 v48, v47, v41
	v_min_i32_e32 v41, v47, v41
	v_max_i32_e32 v47, v42, v44
	v_max_i32_e32 v80, v66, v47
	v_min_i32_e32 v124, v66, v47
	ds_read_b128 v[66:69], v94 offset:18432
	ds_read_b128 v[70:73], v94 offset:18464
	v_min_i32_e32 v42, v42, v44
	v_max_i32_e32 v44, v46, v39
	v_min_i32_e32 v74, v46, v39
	v_max_i32_e32 v39, v43, v38
	v_min_i32_e32 v75, v43, v38
	v_max_i32_e32 v38, v40, v35
	v_min_i32_e32 v76, v40, v35
	v_max_i32_e32 v35, v36, v34
	v_min_i32_e32 v77, v36, v34
	v_max_i32_e32 v78, v49, v48
	v_min_i32_e32 v82, v49, v48
	v_max_i32_e32 v125, v37, v41
	v_min_i32_e32 v126, v37, v41
	v_max_i32_e32 v127, v45, v42
	v_min_i32_e32 v128, v45, v42
	v_max_i32_e32 v129, v44, v38
	v_min_i32_e32 v130, v44, v38
	v_max_i32_e32 v131, v39, v35
	v_min_i32_e32 v132, v39, v35
	s_waitcnt vmcnt(3) lgkmcnt(1)
	v_mfma_f32_32x32x16_bf16 v[34:49], v[66:69], v[62:65], v[18:33]
	ds_read_b128 v[66:69], v94 offset:18496
	v_max_i32_e32 v133, v74, v76
	v_min_i32_e32 v134, v74, v76
	v_max_i32_e32 v135, v75, v77
	v_min_i32_e32 v136, v75, v77
	v_max_i32_e32 v79, v78, v80
	v_min_i32_e32 v81, v78, v80
	s_waitcnt vmcnt(2) lgkmcnt(1)
	v_mfma_f32_32x32x16_bf16 v[34:49], v[70:73], v[58:61], v[34:49]
	v_max_i32_e32 v80, v82, v124
	v_min_i32_e32 v78, v82, v124
	v_max_i32_e32 v77, v125, v127
	v_min_i32_e32 v76, v125, v127
	v_max_i32_e32 v75, v126, v128
	v_min_i32_e32 v73, v126, v128
	ds_read_b128 v[124:127], v94 offset:18528
	s_waitcnt vmcnt(1) lgkmcnt(1)
	v_mfma_f32_32x32x16_bf16 v[34:49], v[66:69], v[54:57], v[34:49]
	v_max_i32_e32 v71, v129, v131
	v_min_i32_e32 v74, v129, v131
	v_max_i32_e32 v72, v130, v132
	v_min_i32_e32 v70, v130, v132
	v_max_i32_e32 v69, v133, v135
	v_min_i32_e32 v68, v133, v135
	v_max_i32_e32 v67, v134, v136
	s_waitcnt vmcnt(0) lgkmcnt(0)
; #define LAS __attribute__((address_space(3)))
; #define MFMA32(a, b, c) __builtin_amdgcn_mfma_f32_32x32x16_bf16((a), (b), (c), 0, 0, 0)
; #define CE_(a, b) ce_desc(v[a], v[b])
; __device__ __forceinline__ void sort16_desc(int (&v)[16]) {
;     ...
;     CE_(0,13); CE_(1,12); CE_(2,15); CE_(3,14); CE_(4,8); CE_(5,6); CE_(7,11); CE_(9,10);
;     CE_(0,5); CE_(1,7); CE_(2,9); CE_(3,4); CE_(6,13); CE_(8,14); CE_(10,15); CE_(11,12);
;     CE_(0,1); CE_(2,3); CE_(4,5); CE_(6,8); CE_(7,9); CE_(10,11); CE_(12,13); CE_(14,15);
;     CE_(0,2); CE_(1,3); CE_(4,10); CE_(5,11); CE_(6,7); CE_(8,9); CE_(12,14); CE_(13,15);
;     CE_(1,2); CE_(3,12); CE_(4,6); CE_(5,7); CE_(8,10); CE_(9,11); CE_(13,14);
;     CE_(1,4); CE_(2,6); CE_(5,8); CE_(7,10); CE_(9,13); CE_(11,14);
;     CE_(2,4); CE_(3,6); CE_(9,12); CE_(11,13);
;     CE_(3,5); CE_(6,8); CE_(7,9); CE_(10,12);
;     CE_(3,4); CE_(5,6); CE_(7,8); CE_(9,10); CE_(11,12);
;     CE_(6,7); CE_(8,9);
;     ...
; }
; __device__ __forceinline__ void route_task(int task, int tl0, const bf16* QP  , const LAS bf16* KHL, LAS unsigned short* EL, LAS float* GL, int lane) {
;     ...
;         for (int kt = 0; kt < 4; ++kt) {
;             f32x16 X;
; #pragma unroll
;             for (int i = 0; i < 16; ++i) X[i] = 8.f;
;             const LAS bf16* khp = KHL + (half * 128 + 32 * kt + r) * 72 + 8 * hi;
; #pragma unroll
;             for (int ks = 0; ks < 4; ++ks) {
;                 const bf16x8 kh = lds8(khp + 16 * ks);
;                 X = MFMA32(kh, qa[half][ks], X);
;             }
;             int grp[16];
; #pragma unroll
;             for (int i = 0; i < 16; ++i) grp[i] = (int)((__float_as_uint(X[i]) | 127u) - (unsigned)(32 * kt + (i & 3) + 8 * (i >> 2)));
;             sort16_desc(grp);
;             if (kt == 0) {
; #pragma unroll
;                 for (int i = 0; i < 16; ++i) cur[i] = grp[i];
;             } else merge16_desc(cur, grp);
	v_mfma_f32_32x32x16_bf16 v[34:49], v[124:127], v[50:53], v[34:49]
	v_min_i32_e32 v66, v134, v136
	s_nop 10
	v_bitop3_b32 v37, v37, s42, 3 bitop3:0x56
	v_bitop3_b32 v48, v48, s42, 26 bitop3:0x56
	v_bitop3_b32 v38, v38, s42, 8 bitop3:0x56
	v_bitop3_b32 v42, v42, s42, 16 bitop3:0x56
	v_bitop3_b32 v47, v47, s42, 25 bitop3:0x56
	v_bitop3_b32 v39, v39, s42, 9 bitop3:0x56
	v_bitop3_b32 v40, v40, s42, 10 bitop3:0x56
	v_bitop3_b32 v43, v43, s42, 17 bitop3:0x56
	v_bitop3_b32 v44, v44, s42, 18 bitop3:0x56
	v_bitop3_b32 v36, v36, s42, 2 bitop3:0x56
	v_bitop3_b32 v49, v49, s42, 27 bitop3:0x56
	v_bitop3_b32 v41, v41, s42, 11 bitop3:0x56
	v_bitop3_b32 v45, v45, s42, 19 bitop3:0x56
	v_bitop3_b32 v35, v35, s42, 1 bitop3:0x56
	v_bitop3_b32 v46, v46, s42, 24 bitop3:0x56
	v_or_b32_e32 v34, 0x7f, v34
	v_max_i32_e32 v82, v37, v48
	v_max_i32_e32 v124, v38, v42
	v_max_i32_e32 v126, v34, v47
	v_max_i32_e32 v127, v39, v40
	v_min_i32_e32 v130, v43, v44
	v_min_i32_e32 v131, v36, v49
	v_min_i32_e32 v133, v41, v45
	v_min_i32_e32 v134, v35, v46
	v_min_i32_e32 v39, v39, v40
	v_min_i32_e32 v34, v34, v47
	v_min_i32_e32 v38, v38, v42
	v_min_i32_e32 v37, v37, v48
	v_max_i32_e32 v35, v35, v46
	v_max_i32_e32 v41, v41, v45
	v_max_i32_e32 v36, v36, v49
	v_max_i32_e32 v43, v43, v44
	v_min_i32_e32 v125, v82, v124
	v_min_i32_e32 v128, v126, v127
	v_max_i32_e32 v132, v130, v131
	v_max_i32_e32 v135, v133, v134
	v_max_i32_e32 v40, v39, v34
	v_max_i32_e32 v42, v38, v37
	v_min_i32_e32 v45, v35, v41
	v_min_i32_e32 v44, v36, v43
	v_min_i32_e32 v129, v125, v128
	v_max_i32_e32 v47, v40, v42
	v_max_i32_e32 v46, v45, v44
	v_min_i32_e32 v40, v40, v42
	v_min_i32_e32 v42, v45, v44
	v_max_i32_e32 v45, v125, v128
	v_max_i32_e32 v125, v132, v135
	v_min_i32_e32 v128, v45, v125
	v_min_i32_e32 v34, v39, v34
	v_max_i32_e32 v39, v126, v127
	v_max_i32_e32 v35, v35, v41
	v_max_i32_e32 v41, v82, v124
	v_max_i32_e32 v148, v45, v125
	ds_read_b128 v[124:127], v97
	v_max_i32_e32 v44, v40, v42
	v_min_i32_e32 v138, v40, v42
	v_min_i32_e32 v40, v133, v134
	v_min_i32_e32 v37, v38, v37
	v_min_i32_e32 v38, v130, v131
	v_max_i32_e32 v36, v36, v43
	v_min_i32_e32 v136, v132, v135
	v_min_i32_e32 v133, v40, v34
	v_min_i32_e32 v134, v37, v38
	v_max_i32_e32 v34, v40, v34
	v_max_i32_e32 v37, v37, v38
	v_min_i32_e32 v40, v39, v35
	v_min_i32_e32 v42, v36, v41
	v_max_i32_e32 v144, v39, v35
	v_max_i32_e32 v145, v36, v41
	v_max_i32_e32 v137, v129, v136
	v_min_i32_e32 v136, v129, v136
	v_max_i32_e32 v140, v133, v134
	v_min_i32_e32 v141, v34, v37
	v_max_i32_e32 v143, v40, v42
	v_min_i32_e32 v146, v144, v145
	v_max_i32_e32 v149, v47, v46
	v_min_i32_e32 v48, v47, v46
	v_max_i32_e32 v139, v138, v136
	v_max_i32_e32 v142, v140, v141
	v_min_i32_e32 v43, v40, v42
	v_max_i32_e32 v34, v34, v37
	v_min_i32_e32 v147, v143, v146
	v_min_i32_e32 v150, v148, v149
	v_min_i32_e32 v49, v137, v48
	v_min_i32_e32 v132, v44, v128
	v_max_i32_e32 v38, v139, v142
	v_min_i32_e32 v37, v43, v34
	v_max_i32_e32 v34, v43, v34
	v_min_i32_e32 v35, v147, v150
	v_max_i32_e32 v39, v137, v48
	v_max_i32_e32 v40, v44, v128
	v_max_i32_e32 v135, v49, v132
	v_max_i32_e32 v82, v38, v37
	v_min_i32_e32 v36, v34, v35
	v_min_i32_e32 v41, v39, v40
	v_max_i32_e32 v129, v135, v82
	v_min_i32_e32 v42, v36, v41
	v_min_i32_e32 v137, v129, v42
	v_max_i32_e32 v159, v129, v42
	ds_read_b128 v[128:131], v97 offset:32
	v_min_i32_e32 v82, v135, v82
	v_min_i32_e32 v132, v49, v132
	v_min_i32_e32 v135, v38, v37
	v_max_i32_e32 v154, v34, v35
	v_max_i32_e32 v155, v39, v40
	v_max_i32_e32 v157, v36, v41
	s_waitcnt lgkmcnt(1)
	v_mfma_f32_32x32x16_bf16 v[34:49], v[124:127], v[62:65], v[18:33]
	ds_read_b128 v[124:127], v97 offset:64
	v_max_i32_e32 v151, v132, v135
	v_max_i32_e32 v152, v82, v151
	v_min_i32_e32 v136, v138, v136
	v_min_i32_e32 v138, v140, v141
	v_min_i32_e32 v82, v82, v151
	v_max_i32_e32 v147, v147, v150
	s_waitcnt lgkmcnt(1)
	v_mfma_f32_32x32x16_bf16 v[34:49], v[128:131], v[58:61], v[34:49]
	ds_read_b128 v[128:131], v97 offset:96
	v_max_i32_e32 v143, v143, v146
	v_min_i32_e32 v133, v133, v134
	v_min_i32_e32 v156, v154, v155
	v_max_i32_e32 v140, v136, v138
	v_min_i32_e32 v139, v139, v142
	v_max_i32_e32 v142, v154, v155
	s_waitcnt lgkmcnt(1)
	v_mfma_f32_32x32x16_bf16 v[34:49], v[124:127], v[54:57], v[34:49]
	v_max_i32_e32 v124, v148, v149
	v_min_i32_e32 v136, v136, v138
	v_max_i32_e32 v141, v140, v139
	v_min_i32_e32 v139, v140, v139
	v_min_i32_e32 v125, v143, v124
	v_min_i32_e32 v158, v156, v157
	v_min_i32_e32 v132, v132, v135
	s_waitcnt lgkmcnt(0)
; #define LAS __attribute__((address_space(3)))
; #define MFMA32(a, b, c) __builtin_amdgcn_mfma_f32_32x32x16_bf16((a), (b), (c), 0, 0, 0)
; __device__ __forceinline__ void merge16_desc(int (&a)[16], const int (&b)[16]) {
; #pragma unroll
;     for (int i = 0; i < 16; ++i) a[i] = a[i] > b[15 - i] ? a[i] : b[15 - i];
; #pragma unroll
;     for (int j = 8; j > 0; j >>= 1)
; #pragma unroll
;         for (int i = 0; i < 16; ++i) { const int l = i ^ j; if (l > i) ce_desc(a[i], a[l]); }
; }
; __device__ __forceinline__ void route_task(int task, int tl0, const bf16* QP  , const LAS bf16* KHL, LAS unsigned short* EL, LAS float* GL, int lane) {
;     ...
;         for (int kt = 0; kt < 4; ++kt) {
;             f32x16 X;
; #pragma unroll
;             for (int i = 0; i < 16; ++i) X[i] = 8.f;
;             const LAS bf16* khp = KHL + (half * 128 + 32 * kt + r) * 72 + 8 * hi;
; #pragma unroll
;             for (int ks = 0; ks < 4; ++ks) {
;                 const bf16x8 kh = lds8(khp + 16 * ks);
;                 X = MFMA32(kh, qa[half][ks], X);
;             }
;             int grp[16];
; #pragma unroll
;             for (int i = 0; i < 16; ++i) grp[i] = (int)((__float_as_uint(X[i]) | 127u) - (unsigned)(32 * kt + (i & 3) + 8 * (i >> 2)));
;             sort16_desc(grp);
;             if (kt == 0) {
; #pragma unroll
;                 for (int i = 0; i < 16; ++i) cur[i] = grp[i];
;             } else merge16_desc(cur, grp);
	v_mfma_f32_32x32x16_bf16 v[34:49], v[128:131], v[50:53], v[34:49]
	v_min_i32_e32 v126, v147, v125
	v_min_i32_e32 v153, v137, v152
	v_min_i32_e32 v160, v158, v159
	v_min_i32_e32 v135, v141, v132
	v_min_i32_e32 v127, v142, v126
	s_nop 6
	v_bitop3_b32 v37, v37, s42, 35 bitop3:0x56
	v_bitop3_b32 v48, v48, s42, 58 bitop3:0x56
	v_bitop3_b32 v38, v38, s42, 40 bitop3:0x56
	v_bitop3_b32 v42, v42, s42, 48 bitop3:0x56
	v_bitop3_b32 v34, v34, s42, 32 bitop3:0x56
	v_bitop3_b32 v47, v47, s42, 57 bitop3:0x56
	v_bitop3_b32 v39, v39, s42, 41 bitop3:0x56
	v_bitop3_b32 v40, v40, s42, 42 bitop3:0x56
	v_bitop3_b32 v43, v43, s42, 49 bitop3:0x56
	v_bitop3_b32 v44, v44, s42, 50 bitop3:0x56
	v_bitop3_b32 v36, v36, s42, 34 bitop3:0x56
	v_bitop3_b32 v49, v49, s42, 59 bitop3:0x56
	v_bitop3_b32 v41, v41, s42, 43 bitop3:0x56
	v_bitop3_b32 v45, v45, s42, 51 bitop3:0x56
	v_bitop3_b32 v35, v35, s42, 33 bitop3:0x56
	v_bitop3_b32 v46, v46, s42, 56 bitop3:0x56
	v_max_i32_e32 v128, v37, v48
	v_max_i32_e32 v129, v38, v42
	v_max_i32_e32 v131, v34, v47
	v_max_i32_e32 v134, v39, v40
	v_min_i32_e32 v146, v43, v44
	v_min_i32_e32 v148, v36, v49
	v_min_i32_e32 v150, v41, v45
	v_min_i32_e32 v151, v35, v46
	v_min_i32_e32 v39, v39, v40
	v_min_i32_e32 v34, v34, v47
	v_min_i32_e32 v38, v38, v42
	v_min_i32_e32 v37, v37, v48
	v_max_i32_e32 v35, v35, v46
	v_max_i32_e32 v41, v41, v45
	v_max_i32_e32 v36, v36, v49
	v_max_i32_e32 v43, v43, v44
	v_min_i32_e32 v130, v128, v129
	v_min_i32_e32 v138, v131, v134
	v_max_i32_e32 v149, v146, v148
	v_max_i32_e32 v154, v150, v151
	v_max_i32_e32 v40, v39, v34
	v_max_i32_e32 v42, v38, v37
	v_min_i32_e32 v45, v35, v41
	v_min_i32_e32 v44, v36, v43
	v_min_i32_e32 v150, v150, v151
	v_min_i32_e32 v34, v39, v34
	v_min_i32_e32 v37, v38, v37
	v_min_i32_e32 v38, v146, v148
	v_max_i32_e32 v131, v131, v134
	v_max_i32_e32 v35, v35, v41
	v_max_i32_e32 v36, v36, v43
	v_max_i32_e32 v43, v128, v129
	v_min_i32_e32 v140, v130, v138
	v_min_i32_e32 v155, v149, v154
	v_max_i32_e32 v47, v40, v42
	v_max_i32_e32 v46, v45, v44
	v_min_i32_e32 v40, v40, v42
	v_min_i32_e32 v42, v45, v44
	v_max_i32_e32 v45, v130, v138
	v_max_i32_e32 v130, v149, v154
	v_min_i32_e32 v39, v150, v34
	v_min_i32_e32 v146, v37, v38
	v_max_i32_e32 v34, v150, v34
	v_max_i32_e32 v37, v37, v38
	v_min_i32_e32 v41, v131, v35
	v_min_i32_e32 v128, v36, v43
	v_max_i32_e32 v35, v131, v35
	v_max_i32_e32 v36, v36, v43
	v_min_i32_e32 v48, v47, v46
	v_max_i32_e32 v44, v40, v42
	v_min_i32_e32 v138, v45, v130
	v_min_i32_e32 v40, v40, v42
	v_min_i32_e32 v42, v140, v155
	v_max_i32_e32 v148, v39, v146
	v_min_i32_e32 v38, v34, v37
	v_min_i32_e32 v129, v41, v128
	v_max_i32_e32 v41, v41, v128
	v_min_i32_e32 v43, v35, v36
	v_max_i32_e32 v45, v45, v130
	v_max_i32_e32 v46, v47, v46
	v_max_i32_e32 v161, v140, v155
	v_max_i32_e32 v140, v40, v42
	v_max_i32_e32 v150, v148, v38
	v_max_i32_e32 v34, v34, v37
	v_min_i32_e32 v128, v41, v43
	v_min_i32_e32 v47, v45, v46
	v_min_i32_e32 v49, v161, v48
	v_min_i32_e32 v149, v44, v138
	v_max_i32_e32 v151, v140, v150
	v_min_i32_e32 v37, v129, v34
	v_max_i32_e32 v34, v129, v34
	v_min_i32_e32 v129, v128, v47
	v_max_i32_e32 v48, v161, v48
	v_max_i32_e32 v44, v44, v138
	v_max_i32_e32 v154, v49, v149
	v_max_i32_e32 v134, v151, v37
	v_min_i32_e32 v130, v34, v129
	v_min_i32_e32 v131, v48, v44
	v_min_i32_e32 v49, v49, v149
	v_min_i32_e32 v37, v151, v37
	v_max_i32_e32 v34, v34, v129
	v_max_i32_e32 v44, v48, v44
	v_min_i32_e32 v40, v40, v42
	v_min_i32_e32 v38, v148, v38
	v_max_i32_e32 v41, v41, v43
	v_max_i32_e32 v43, v45, v46
	v_max_i32_e32 v155, v154, v134
	v_min_i32_e32 v138, v130, v131
	v_min_i32_e32 v134, v154, v134
	v_max_i32_e32 v149, v49, v37
	v_min_i32_e32 v48, v34, v44
	v_max_i32_e32 v129, v130, v131
	v_max_i32_e32 v42, v40, v38
	v_min_i32_e32 v140, v140, v150
	v_max_i32_e32 v34, v34, v44
	v_max_i32_e32 v44, v128, v47
	v_min_i32_e32 v45, v41, v43
	v_min_i32_e32 v161, v155, v138
	v_max_i32_e32 v151, v134, v149
	v_min_i32_e32 v130, v48, v129
	v_max_i32_e32 v131, v155, v138
	v_max_i32_e32 v148, v42, v140
	v_min_i32_e32 v37, v49, v37
	v_min_i32_e32 v46, v44, v45
	v_min_i32_e32 v154, v161, v151
	v_min_i32_e32 v138, v130, v131
	v_min_i32_e32 v49, v148, v37
	v_min_i32_e32 v134, v134, v149
	v_min_i32_e32 v47, v34, v46
	v_min_i32_e32 v42, v42, v140
	v_min_i32_e32 v38, v40, v38
	v_min_i32_e32 v39, v39, v146
	v_max3_i32 v39, v144, v145, v39
	v_max3_i32 v38, v143, v124, v38
	v_max3_i32 v40, v147, v125, v42
	v_max3_i32 v42, v142, v126, v49
	v_max3_i32 v37, v127, v148, v37
	v_max3_i32 v49, v156, v157, v134
	v_max3_i32 v124, v158, v159, v154
	v_max3_i32 v125, v160, v161, v151
	v_max3_i32 v126, v137, v152, v138
	v_max3_i32 v127, v153, v130, v131
	v_max3_i32 v48, v82, v48, v129
	v_max3_i32 v47, v141, v132, v47
	v_max3_i32 v34, v135, v34, v46
	v_max3_i32 v44, v139, v44, v45
	v_max3_i32 v41, v136, v41, v43
	v_max3_i32 v35, v133, v35, v36
	v_max_i32_e32 v36, v39, v126
	v_min_i32_e32 v39, v39, v126
	v_max_i32_e32 v43, v38, v127
	v_min_i32_e32 v38, v38, v127
	v_max_i32_e32 v45, v40, v48
	v_min_i32_e32 v40, v40, v48
	v_max_i32_e32 v46, v42, v47
	v_min_i32_e32 v42, v42, v47
	v_max_i32_e32 v47, v37, v34
	v_min_i32_e32 v34, v37, v34
	v_max_i32_e32 v37, v49, v44
	v_min_i32_e32 v44, v49, v44
	v_max_i32_e32 v48, v124, v41
	v_min_i32_e32 v41, v124, v41
	v_max_i32_e32 v49, v125, v35
	v_min_i32_e32 v35, v125, v35
	ds_read_b128 v[124:127], v94 offset:27648
	ds_read_b128 v[128:131], v94 offset:27680
	v_max_i32_e32 v82, v36, v47
	v_min_i32_e32 v132, v36, v47
	v_max_i32_e32 v36, v43, v37
	v_min_i32_e32 v133, v43, v37
	v_max_i32_e32 v37, v45, v48
	v_max_i32_e32 v43, v46, v49
	v_min_i32_e32 v134, v45, v48
	v_min_i32_e32 v135, v46, v49
	v_max_i32_e32 v136, v39, v34
	v_min_i32_e32 v137, v39, v34
	v_max_i32_e32 v138, v38, v44
	v_min_i32_e32 v139, v38, v44
	v_max_i32_e32 v140, v40, v41
	v_min_i32_e32 v141, v40, v41
	v_max_i32_e32 v142, v42, v35
	v_min_i32_e32 v143, v42, v35
	v_max_i32_e32 v144, v82, v37
	v_min_i32_e32 v82, v82, v37
	v_max_i32_e32 v145, v36, v43
	v_min_i32_e32 v146, v36, v43
	s_waitcnt lgkmcnt(1)
; #define LAS __attribute__((address_space(3)))
; #define MFMA32(a, b, c) __builtin_amdgcn_mfma_f32_32x32x16_bf16((a), (b), (c), 0, 0, 0)
; __device__ __forceinline__ void merge16_desc(int (&a)[16], const int (&b)[16]) {
; #pragma unroll
;     for (int i = 0; i < 16; ++i) a[i] = a[i] > b[15 - i] ? a[i] : b[15 - i];
; #pragma unroll
;     for (int j = 8; j > 0; j >>= 1)
; #pragma unroll
;         for (int i = 0; i < 16; ++i) { const int l = i ^ j; if (l > i) ce_desc(a[i], a[l]); }
; }
; __device__ __forceinline__ void route_task(int task, int tl0, const bf16* QP  , const LAS bf16* KHL, LAS unsigned short* EL, LAS float* GL, int lane) {
;     ...
;         for (int kt = 0; kt < 4; ++kt) {
;             f32x16 X;
; #pragma unroll
;             for (int i = 0; i < 16; ++i) X[i] = 8.f;
;             const LAS bf16* khp = KHL + (half * 128 + 32 * kt + r) * 72 + 8 * hi;
; #pragma unroll
;             for (int ks = 0; ks < 4; ++ks) {
;                 const bf16x8 kh = lds8(khp + 16 * ks);
;                 X = MFMA32(kh, qa[half][ks], X);
;             }
;             int grp[16];
; #pragma unroll
;             for (int i = 0; i < 16; ++i) grp[i] = (int)((__float_as_uint(X[i]) | 127u) - (unsigned)(32 * kt + (i & 3) + 8 * (i >> 2)));
;             sort16_desc(grp);
;             if (kt == 0) {
; #pragma unroll
;                 for (int i = 0; i < 16; ++i) cur[i] = grp[i];
;             } else merge16_desc(cur, grp);
	v_mfma_f32_32x32x16_bf16 v[34:49], v[124:127], v[62:65], v[18:33]
	ds_read_b128 v[124:127], v94 offset:27712
	v_max_i32_e32 v147, v132, v134
	v_min_i32_e32 v132, v132, v134
	v_max_i32_e32 v134, v133, v135
	v_min_i32_e32 v133, v133, v135
	v_max_i32_e32 v135, v136, v140
	v_min_i32_e32 v136, v136, v140
	s_waitcnt lgkmcnt(1)
	v_mfma_f32_32x32x16_bf16 v[34:49], v[128:131], v[58:61], v[34:49]
	ds_read_b128 v[128:131], v94 offset:27744
	v_max_i32_e32 v140, v138, v142
	v_min_i32_e32 v138, v138, v142
	v_max_i32_e32 v142, v137, v141
	v_min_i32_e32 v137, v137, v141
	v_max_i32_e32 v141, v139, v143
	v_min_i32_e32 v139, v139, v143
	s_waitcnt lgkmcnt(1)
	v_mfma_f32_32x32x16_bf16 v[34:49], v[124:127], v[54:57], v[34:49]
	v_min_i32_e32 v143, v144, v145
	v_min_i32_e32 v124, v82, v146
	v_min_i32_e32 v127, v135, v140
	v_min_i32_e32 v125, v147, v134
	v_min_i32_e32 v126, v132, v133
	v_min_i32_e32 v149, v142, v141
	v_min_i32_e32 v148, v136, v138
	s_waitcnt lgkmcnt(0)
	v_mfma_f32_32x32x16_bf16 v[34:49], v[128:131], v[50:53], v[34:49]
	v_min_i32_e32 v150, v137, v139
	s_nop 10
	v_and_or_b32 v37, v37, s43, 60
	v_and_or_b32 v48, v48, s43, 37
	v_and_or_b32 v38, v38, s43, 55
	v_and_or_b32 v42, v42, s43, 47
	v_bitop3_b32 v34, v34, s42, 64 bitop3:0x56
	v_and_or_b32 v47, v47, s43, 38
	v_and_or_b32 v39, v39, s43, 54
	v_and_or_b32 v40, v40, s43, 53
	v_and_or_b32 v43, v43, s43, 46
	v_and_or_b32 v44, v44, s43, 45
	v_and_or_b32 v36, v36, s43, 61
	v_and_or_b32 v49, v49, s43, 36
	v_and_or_b32 v41, v41, s43, 52
	v_and_or_b32 v45, v45, s43, 44
	v_and_or_b32 v35, v35, s43, 62
	v_and_or_b32 v46, v46, s43, 39
	v_max_i32_e32 v128, v37, v48
	v_max_i32_e32 v129, v38, v42
	v_max_i32_e32 v131, v34, v47
	v_max_i32_e32 v151, v39, v40
	v_min_i32_e32 v154, v43, v44
	v_min_i32_e32 v155, v36, v49
	v_min_i32_e32 v157, v41, v45
	v_min_i32_e32 v158, v35, v46
	v_min_i32_e32 v39, v39, v40
	v_min_i32_e32 v34, v34, v47
	v_min_i32_e32 v38, v38, v42
	v_min_i32_e32 v37, v37, v48
	v_max_i32_e32 v35, v35, v46
	v_max_i32_e32 v41, v41, v45
	v_max_i32_e32 v36, v36, v49
	v_max_i32_e32 v43, v43, v44
	v_min_i32_e32 v130, v128, v129
	v_min_i32_e32 v152, v131, v151
	v_max_i32_e32 v156, v154, v155
	v_max_i32_e32 v159, v157, v158
	v_max_i32_e32 v40, v39, v34
	v_max_i32_e32 v42, v38, v37
	v_min_i32_e32 v45, v35, v41
	v_min_i32_e32 v44, v36, v43
	v_min_i32_e32 v157, v157, v158
	v_min_i32_e32 v34, v39, v34
	v_min_i32_e32 v37, v38, v37
	v_min_i32_e32 v38, v154, v155
	v_max_i32_e32 v131, v131, v151
	v_max_i32_e32 v35, v35, v41
	v_max_i32_e32 v36, v36, v43
	v_max_i32_e32 v43, v128, v129
	v_min_i32_e32 v153, v130, v152
	v_min_i32_e32 v160, v156, v159
	v_max_i32_e32 v47, v40, v42
	v_max_i32_e32 v46, v45, v44
	v_min_i32_e32 v40, v40, v42
	v_min_i32_e32 v42, v45, v44
	v_max_i32_e32 v45, v130, v152
	v_max_i32_e32 v130, v156, v159
	v_min_i32_e32 v39, v157, v34
	v_min_i32_e32 v154, v37, v38
	v_max_i32_e32 v34, v157, v34
	v_max_i32_e32 v37, v37, v38
	v_min_i32_e32 v41, v131, v35
	v_min_i32_e32 v128, v36, v43
	v_max_i32_e32 v35, v131, v35
	v_max_i32_e32 v36, v36, v43
	v_min_i32_e32 v48, v47, v46
	v_max_i32_e32 v44, v40, v42
	v_min_i32_e32 v152, v45, v130
	v_min_i32_e32 v40, v40, v42
	v_min_i32_e32 v42, v153, v160
	v_max_i32_e32 v155, v39, v154
	v_min_i32_e32 v38, v34, v37
	v_min_i32_e32 v129, v41, v128
	v_max_i32_e32 v41, v41, v128
	v_min_i32_e32 v43, v35, v36
	v_max_i32_e32 v45, v45, v130
	v_max_i32_e32 v46, v47, v46
	v_max_i32_e32 v161, v153, v160
	v_max_i32_e32 v153, v40, v42
	v_max_i32_e32 v157, v155, v38
	v_max_i32_e32 v34, v34, v37
	v_min_i32_e32 v128, v41, v43
	v_min_i32_e32 v47, v45, v46
	v_min_i32_e32 v49, v161, v48
	v_min_i32_e32 v156, v44, v152
	v_max_i32_e32 v158, v153, v157
	v_min_i32_e32 v37, v129, v34
	v_max_i32_e32 v34, v129, v34
	v_min_i32_e32 v129, v128, v47
	v_max_i32_e32 v48, v161, v48
	v_max_i32_e32 v44, v44, v152
	v_min_i32_e32 v40, v40, v42
	v_min_i32_e32 v38, v155, v38
	v_max_i32_e32 v159, v49, v156
	v_max_i32_e32 v151, v158, v37
	v_min_i32_e32 v130, v34, v129
	v_min_i32_e32 v131, v48, v44
	v_min_i32_e32 v49, v49, v156
	v_min_i32_e32 v37, v158, v37
	v_max_i32_e32 v34, v34, v129
	v_max_i32_e32 v44, v48, v44
	v_max_i32_e32 v42, v40, v38
	v_min_i32_e32 v153, v153, v157
	v_max_i32_e32 v160, v159, v151
	v_min_i32_e32 v152, v130, v131
	v_max_i32_e32 v156, v49, v37
	v_min_i32_e32 v48, v34, v44
	v_max_i32_e32 v129, v130, v131
	v_max_i32_e32 v155, v42, v153
	v_min_i32_e32 v37, v49, v37
	v_min_i32_e32 v151, v159, v151
	v_min_i32_e32 v130, v48, v129
	v_max_i32_e32 v131, v160, v152
	v_min_i32_e32 v49, v155, v37
	v_max_i32_e32 v41, v41, v43
	v_max_i32_e32 v43, v45, v46
	v_min_i32_e32 v42, v42, v153
	v_min_i32_e32 v38, v40, v38
	v_min_i32_e32 v161, v160, v152
	v_max_i32_e32 v158, v151, v156
	v_min_i32_e32 v151, v151, v156
	v_max_i32_e32 v34, v34, v44
	v_max_i32_e32 v44, v128, v47
	v_min_i32_e32 v45, v41, v43
	v_max_i32_e32 v40, v41, v43
	v_max_i32_e32 v38, v143, v38
	v_max3_i32 v41, v82, v146, v42
	v_max_i32_e32 v42, v124, v49
	v_max3_i32 v124, v127, v130, v131
	v_min_i32_e32 v46, v44, v45
	v_max_i32_e32 v43, v125, v151
	v_max3_i32 v49, v126, v161, v158
	v_max3_i32 v44, v149, v44, v45
	v_max_i32_e32 v45, v38, v124
	v_min_i32_e32 v38, v38, v124
	ds_read_b128 v[124:127], v98
	v_min_i32_e32 v159, v161, v158
	v_min_i32_e32 v152, v130, v131
	v_max_i32_e32 v37, v155, v37
	v_max_i32_e32 v48, v48, v129
	v_min_i32_e32 v47, v34, v46
	v_max_i32_e32 v34, v34, v46
	v_min_i32_e32 v39, v39, v154
	v_max3_i32 v39, v144, v145, v39
	v_max3_i32 v37, v147, v134, v37
	v_max3_i32 v46, v132, v133, v159
	v_max3_i32 v82, v135, v140, v152
	v_max3_i32 v48, v136, v138, v48
	v_max_i32_e32 v47, v148, v47
	v_max3_i32 v34, v142, v141, v34
	v_max3_i32 v40, v137, v139, v40
	v_max3_i32 v35, v150, v35, v36
	v_max_i32_e32 v36, v39, v82
	v_min_i32_e32 v39, v39, v82
	v_max_i32_e32 v82, v41, v48
	v_min_i32_e32 v41, v41, v48
	v_max_i32_e32 v48, v42, v47
	v_min_i32_e32 v42, v42, v47
	v_max_i32_e32 v47, v37, v34
	v_min_i32_e32 v34, v37, v34
	v_max_i32_e32 v37, v43, v44
	v_min_i32_e32 v43, v43, v44
	v_max_i32_e32 v44, v46, v40
	v_min_i32_e32 v40, v46, v40
	v_max_i32_e32 v46, v49, v35
	v_min_i32_e32 v35, v49, v35
	v_max_i32_e32 v49, v36, v47
	v_min_i32_e32 v132, v36, v47
	v_max_i32_e32 v36, v45, v37
	v_min_i32_e32 v133, v45, v37
	v_max_i32_e32 v37, v82, v44
	v_min_i32_e32 v82, v82, v44
	v_max_i32_e32 v44, v48, v46
	ds_read_b128 v[128:131], v98 offset:32
	v_min_i32_e32 v134, v48, v46
	v_max_i32_e32 v135, v39, v34
	v_min_i32_e32 v136, v39, v34
	v_max_i32_e32 v137, v38, v43
	v_min_i32_e32 v138, v38, v43
	v_max_i32_e32 v139, v41, v40
	v_min_i32_e32 v140, v41, v40
	v_max_i32_e32 v141, v42, v35
	v_min_i32_e32 v142, v42, v35
	v_max_i32_e32 v143, v49, v37
	v_min_i32_e32 v144, v49, v37
	v_max_i32_e32 v145, v36, v44
	v_min_i32_e32 v146, v36, v44
	s_waitcnt lgkmcnt(1)
; #define LAS __attribute__((address_space(3)))
; #define MFMA32(a, b, c) __builtin_amdgcn_mfma_f32_32x32x16_bf16((a), (b), (c), 0, 0, 0)
; __device__ __forceinline__ void merge16_desc(int (&a)[16], const int (&b)[16]) {
; #pragma unroll
;     for (int i = 0; i < 16; ++i) a[i] = a[i] > b[15 - i] ? a[i] : b[15 - i];
; #pragma unroll
;     for (int j = 8; j > 0; j >>= 1)
; #pragma unroll
;         for (int i = 0; i < 16; ++i) { const int l = i ^ j; if (l > i) ce_desc(a[i], a[l]); }
; }
; __device__ __forceinline__ void route_task(int task, int tl0, const bf16* QP  , const LAS bf16* KHL, LAS unsigned short* EL, LAS float* GL, int lane) {
;     ...
;         for (int kt = 0; kt < 4; ++kt) {
;             f32x16 X;
; #pragma unroll
;             for (int i = 0; i < 16; ++i) X[i] = 8.f;
;             const LAS bf16* khp = KHL + (half * 128 + 32 * kt + r) * 72 + 8 * hi;
; #pragma unroll
;             for (int ks = 0; ks < 4; ++ks) {
;                 const bf16x8 kh = lds8(khp + 16 * ks);
;                 X = MFMA32(kh, qa[half][ks], X);
;             }
;             int grp[16];
; #pragma unroll
;             for (int i = 0; i < 16; ++i) grp[i] = (int)((__float_as_uint(X[i]) | 127u) - (unsigned)(32 * kt + (i & 3) + 8 * (i >> 2)));
;             sort16_desc(grp);
;             if (kt == 0) {
; #pragma unroll
;                 for (int i = 0; i < 16; ++i) cur[i] = grp[i];
;             } else merge16_desc(cur, grp);
	v_mfma_f32_32x32x16_bf16 v[34:49], v[124:127], v[62:65], v[18:33]
	v_max_i32_e32 v147, v132, v82
	s_nop 5
	ds_read_b128 v[18:21], v98 offset:64
	ds_read_b128 v[22:25], v98 offset:96
	s_waitcnt lgkmcnt(2)
	v_mfma_f32_32x32x16_bf16 v[34:49], v[128:131], v[58:61], v[34:49]
	v_min_i32_e32 v26, v132, v82
	v_max_i32_e32 v27, v133, v134
	v_min_i32_e32 v30, v135, v139
	v_min_i32_e32 v32, v137, v141
	v_max_i32_e32 v33, v136, v140
	v_max_i32_e32 v59, v138, v142
	v_min_i32_e32 v28, v133, v134
	s_waitcnt lgkmcnt(1)
	v_mfma_f32_32x32x16_bf16 v[34:49], v[18:21], v[54:57], v[34:49]
	v_min_i32_e32 v19, v147, v27
	v_min_i32_e32 v54, v30, v32
	v_min_i32_e32 v55, v33, v59
	v_max_i32_e32 v29, v135, v139
	v_max_i32_e32 v31, v137, v141
	v_min_i32_e32 v58, v136, v140
	v_min_i32_e32 v60, v138, v142
	s_waitcnt lgkmcnt(0)
	v_mfma_f32_32x32x16_bf16 v[34:49], v[22:25], v[50:53], v[34:49]
	v_min_i32_e32 v18, v144, v146
	v_min_i32_e32 v61, v143, v145
	v_min_i32_e32 v20, v26, v28
	v_min_i32_e32 v21, v29, v31
	v_min_i32_e32 v56, v58, v60
	s_nop 6
	v_or_b32_e32 v22, 0x7f, v41
	v_or_b32_e32 v23, 0x7f, v45
	v_or_b32_e32 v25, 0x7f, v35
	v_or_b32_e32 v35, 0x7f, v46
	v_and_or_b32 v39, v39, s43, 22
	v_and_or_b32 v40, v40, s43, 21
	v_and_or_b32 v34, v34, s43, 31
	v_and_or_b32 v47, v47, s43, 6
	v_and_or_b32 v38, v38, s43, 23
	v_and_or_b32 v42, v42, s43, 15
	v_and_or_b32 v37, v37, s43, 28
	v_and_or_b32 v48, v48, s43, 5
	v_and_or_b32 v43, v43, s43, 14
	v_and_or_b32 v44, v44, s43, 13
	v_and_or_b32 v36, v36, s43, 29
	v_and_or_b32 v49, v49, s43, 4
	v_add_u32_e32 v22, 0xffffff95, v22
	v_add_u32_e32 v23, 0xffffff8d, v23
	v_add_u32_e32 v25, 0xffffff9f, v25
	v_add_u32_e32 v35, 0xffffff88, v35
	v_min_i32_e32 v24, v22, v23
	v_min_i32_e32 v41, v25, v35
	v_min_i32_e32 v46, v39, v40
	v_min_i32_e32 v50, v34, v47
	v_min_i32_e32 v53, v38, v42
	v_min_i32_e32 v57, v37, v48
	v_min_i32_e32 v63, v43, v44
	v_min_i32_e32 v64, v36, v49
	v_max_i32_e32 v34, v34, v47
	v_max_i32_e32 v39, v39, v40
	v_max_i32_e32 v25, v25, v35
	v_max_i32_e32 v22, v22, v23
	v_max_i32_e32 v36, v36, v49
	v_max_i32_e32 v43, v43, v44
	v_max_i32_e32 v37, v37, v48
	v_max_i32_e32 v38, v38, v42
	v_min_i32_e32 v45, v24, v41
	v_min_i32_e32 v51, v46, v50
	v_max_i32_e32 v40, v34, v39
	v_max_i32_e32 v23, v25, v22
	v_max_i32_e32 v44, v36, v43
	v_max_i32_e32 v42, v37, v38
	v_min_i32_e32 v37, v37, v38
	v_min_i32_e32 v34, v34, v39
	v_max_i32_e32 v39, v63, v64
	v_max_i32_e32 v24, v24, v41
	v_max_i32_e32 v46, v46, v50
	v_max_i32_e32 v50, v53, v57
	v_min_i32_e32 v22, v25, v22
	v_min_i32_e32 v25, v36, v43
	v_min_i32_e32 v62, v53, v57
	v_min_i32_e32 v65, v63, v64
	v_min_i32_e32 v35, v40, v23
	v_min_i32_e32 v47, v44, v42
	v_max_i32_e32 v23, v40, v23
	v_max_i32_e32 v40, v44, v42
	v_max_i32_e32 v38, v37, v34
	v_max_i32_e32 v41, v39, v24
	v_max_i32_e32 v53, v46, v50
	v_max_i32_e32 v36, v22, v25
	v_min_i32_e32 v46, v46, v50
	v_min_i32_e32 v22, v22, v25
	v_min_i32_e32 v52, v45, v51
	v_min_i32_e32 v82, v62, v65
	v_min_i32_e32 v48, v35, v47
	v_max_i32_e32 v45, v45, v51
	v_max_i32_e32 v49, v62, v65
	v_max_i32_e32 v35, v35, v47
	v_min_i32_e32 v42, v23, v40
	v_max_i32_e32 v47, v38, v41
	v_max_i32_e32 v43, v53, v36
	v_min_i32_e32 v34, v37, v34
	v_min_i32_e32 v24, v39, v24
	v_max_i32_e32 v25, v46, v22
	v_min_i32_e32 v38, v38, v41
	v_max_i32_e32 v51, v45, v49
	v_min_i32_e32 v44, v35, v42
	v_min_i32_e32 v57, v47, v43
	v_max_i32_e32 v37, v34, v24
	v_min_i32_e32 v36, v53, v36
	v_max_i32_e32 v41, v25, v38
	v_min_i32_e32 v25, v25, v38
	v_min_i32_e32 v22, v46, v22
	v_min_i32_e32 v24, v34, v24
	v_max_i32_e32 v38, v52, v82
	v_min_i32_e32 v45, v45, v49
	v_max_i32_e32 v62, v48, v51
	v_min_i32_e32 v63, v44, v57
	v_max_i32_e32 v39, v37, v36
	v_max_i32_e32 v34, v22, v24
	v_max_i32_e32 v46, v38, v45
	v_max_i32_e32 v64, v62, v63
	v_max_i32_e32 v50, v39, v41
	v_min_i32_e32 v62, v62, v63
	v_min_i32_e32 v39, v39, v41
	v_min_i32_e32 v36, v37, v36
	v_max_i32_e32 v49, v34, v46
	v_min_i32_e32 v48, v48, v51
	v_min_i32_e32 v22, v22, v24
	v_min_i32_e32 v24, v38, v45
	v_min_i32_e32 v53, v64, v50
	v_max_i32_e32 v41, v62, v39
	v_max_i32_e32 v37, v36, v25
	v_max_i32_e32 v51, v49, v48
	v_max_i32_e32 v38, v22, v24
	v_min_i32_e32 v34, v34, v46
	v_min_i32_e32 v25, v36, v25
	v_min_i32_e32 v36, v49, v48
	v_min_i32_e32 v124, v52, v82
	v_max_i32_e32 v52, v37, v51
	v_min_i32_e32 v39, v62, v39
	v_max_i32_e32 v45, v38, v34
	v_min_i32_e32 v46, v25, v36
	v_max_i32_e32 v35, v35, v42
	v_max_i32_e32 v42, v47, v43
	v_min_i32_e32 v34, v38, v34
	v_max_i32_e32 v38, v53, v41
	v_min_i32_e32 v37, v37, v51
	v_max_i32_e32 v25, v25, v36
	v_max_i32_e32 v48, v45, v46
	v_max_i32_e32 v44, v44, v57
	v_min_i32_e32 v43, v35, v42
	v_max3_i32 v30, v30, v32, v38
	v_min_i32_e32 v38, v52, v39
	v_max_i32_e32 v36, v37, v25
	v_min_i32_e32 v25, v37, v25
	v_min_i32_e32 v63, v53, v41
	v_max_i32_e32 v62, v52, v39
	v_max3_i32 v27, v147, v27, v48
	v_max_i32_e32 v48, v64, v50
	v_min_i32_e32 v47, v44, v43
	v_min_i32_e32 v39, v38, v36
	v_max_i32_e32 v19, v19, v25
	v_max3_i32 v25, v55, v44, v43
	v_min_i32_e32 v43, v45, v46
	v_min_i32_e32 v65, v63, v62
	v_max_i32_e32 v49, v48, v47
	v_max3_i32 v26, v26, v28, v39
	v_max_i32_e32 v28, v35, v42
	v_min_i32_e32 v22, v22, v24
	v_max_i32_e32 v18, v18, v43
	v_min_i32_e32 v43, v48, v47
	v_max3_i32 v124, v143, v145, v124
	v_max3_i32 v29, v29, v31, v65
	v_max3_i32 v33, v33, v59, v49
	v_max3_i32 v34, v144, v146, v34
	v_max3_i32 v28, v58, v60, v28
	v_max_i32_e32 v22, v61, v22
	v_max3_i32 v21, v21, v63, v62
	v_max_i32_e32 v43, v54, v43
	v_max3_i32 v20, v20, v38, v36
	v_max3_i32 v23, v56, v23, v40
	v_min_i32_e32 v31, v124, v29
	v_min_i32_e32 v49, v27, v33
	v_min_i32_e32 v32, v34, v30
	v_min_i32_e32 v35, v26, v28
; __device__ __forceinline__ void route_task(int task, int tl0, const bf16* QP  , const LAS bf16* KHL, LAS unsigned short* EL, LAS float* GL, int lane) {
;     ...
;             } else merge16_desc(cur, grp);
;         }
;         { const unsigned h4 = 4u * (unsigned)hi;
; #pragma unroll
;           for (int i = 0; i < 16; ++i) cur[i] -= (int)h4; }
;         int oth[16];
; #pragma unroll
;         for (int i = 0; i < 16; ++i) oth[i] = __shfl_xor(cur[i], 32);
;         merge16_desc(cur, oth);
; #pragma unroll
;         for (int i = 0; i < 16; ++i) top[half][i] = cur[i];
;     }
;     unsigned P1[4], P2[4];
; #pragma unroll
;     for (int q = 0; q < 4; ++q) { P1[q] = 0u; P2[q] = 0u;
; #pragma unroll
;         for (int s = 0; s < 4; ++s) { P1[q] |= (127u - ((unsigned)top[0][4 * q + s] & 127u)) << (8 * s); P2[q] |= (127u - ((unsigned)top[1][4 * q + s] & 127u)) << (8 * s); } }
	v_min_i32_e32 v24, v22, v21
	v_min_i32_e32 v37, v19, v25
	v_min_i32_e32 v44, v18, v43
	v_min_i32_e32 v36, v20, v23
	v_max_i32_e32 v29, v124, v29
	v_max_i32_e32 v27, v27, v33
	v_max_i32_e32 v30, v34, v30
	v_max_i32_e32 v26, v26, v28
	v_max_i32_e32 v21, v22, v21
	v_max_i32_e32 v19, v19, v25
	v_max_i32_e32 v18, v18, v43
	v_max_i32_e32 v20, v20, v23
	v_max_i32_e32 v33, v29, v27
	v_max_i32_e32 v28, v30, v26
	v_max_i32_e32 v22, v21, v19
	v_max_i32_e32 v23, v18, v20
	v_max_i32_e32 v34, v33, v28
	v_max_i32_e32 v25, v22, v23
	v_min_i32_e32 v28, v33, v28
	v_min_i32_e32 v22, v22, v23
	v_min_i32_e32 v27, v29, v27
	v_min_i32_e32 v26, v30, v26
	v_min_i32_e32 v19, v21, v19
	v_min_i32_e32 v18, v18, v20
	v_max_i32_e32 v23, v28, v22
	v_min_i32_e32 v22, v28, v22
	v_max_i32_e32 v28, v27, v26
	v_max_i32_e32 v20, v19, v18
	v_min_i32_e32 v26, v27, v26
	v_min_i32_e32 v18, v19, v18
	v_min_i32_e32 v42, v24, v37
	v_max_i32_e32 v19, v26, v18
	v_min_i32_e32 v18, v26, v18
	v_max_i32_e32 v26, v31, v49
	v_max_i32_e32 v27, v32, v35
	v_max_i32_e32 v24, v24, v37
	v_max_i32_e32 v29, v44, v36
	v_min_i32_e32 v50, v31, v49
	v_min_i32_e32 v39, v32, v35
	v_min_i32_e32 v38, v44, v36
	v_max_i32_e32 v21, v28, v20
	v_min_i32_e32 v20, v28, v20
	v_max_i32_e32 v28, v26, v27
	v_max_i32_e32 v30, v24, v29
	v_min_i32_e32 v26, v26, v27
	v_min_i32_e32 v24, v24, v29
	v_min_i32_e32 v41, v50, v39
	v_min_i32_e32 v40, v42, v38
	v_max_i32_e32 v27, v26, v24
	v_min_i32_e32 v24, v26, v24
	v_max_i32_e32 v26, v50, v39
	v_max_i32_e32 v29, v42, v38
	v_min_i32_e32 v45, v41, v40
	v_max_i32_e32 v43, v34, v25
	v_min_i32_e32 v25, v34, v25
	v_max_i32_e32 v31, v28, v30
	v_min_i32_e32 v28, v28, v30
	v_max_i32_e32 v30, v26, v29
	v_min_i32_e32 v26, v26, v29
	v_max_i32_e32 v29, v41, v40
	v_sub_u32_e32 v32, v43, v87
	v_sub_u32_e32 v25, v25, v87
	v_sub_u32_e32 v23, v23, v87
	v_sub_u32_e32 v22, v22, v87
	v_sub_u32_e32 v21, v21, v87
	v_sub_u32_e32 v20, v20, v87
	v_sub_u32_e32 v19, v19, v87
	v_sub_u32_e32 v18, v18, v87
	v_sub_u32_e32 v31, v31, v87
	v_sub_u32_e32 v28, v28, v87
	v_sub_u32_e32 v27, v27, v87
	v_sub_u32_e32 v24, v24, v87
	v_sub_u32_e32 v30, v30, v87
	v_sub_u32_e32 v26, v26, v87
	v_sub_u32_e32 v29, v29, v87
	v_sub_u32_e32 v33, v45, v87
	ds_bpermute_b32 v34, v123, v32
	ds_bpermute_b32 v35, v123, v25
	ds_bpermute_b32 v36, v123, v23
	ds_bpermute_b32 v37, v123, v22
	ds_bpermute_b32 v38, v123, v21
	ds_bpermute_b32 v39, v123, v20
	ds_bpermute_b32 v40, v123, v19
	ds_bpermute_b32 v41, v123, v18
	ds_bpermute_b32 v42, v123, v31
	ds_bpermute_b32 v43, v123, v28
	ds_bpermute_b32 v44, v123, v27
	ds_bpermute_b32 v45, v123, v33
	ds_bpermute_b32 v46, v123, v29
	ds_bpermute_b32 v47, v123, v26
	ds_bpermute_b32 v48, v123, v30
	ds_bpermute_b32 v49, v123, v24
	s_waitcnt lgkmcnt(4)
	v_max_i32_e32 v32, v32, v45
	s_waitcnt lgkmcnt(3)
	v_max_i32_e32 v25, v25, v46
	s_waitcnt lgkmcnt(2)
	v_max_i32_e32 v23, v23, v47
	s_waitcnt lgkmcnt(1)
	v_max_i32_e32 v22, v22, v48
	s_waitcnt lgkmcnt(0)
	v_max_i32_e32 v21, v21, v49
	v_max_i32_e32 v20, v20, v44
	v_max_i32_e32 v19, v19, v43
	v_max_i32_e32 v18, v18, v42
	v_max_i32_e32 v31, v31, v41
	v_max_i32_e32 v28, v28, v40
	v_max_i32_e32 v27, v27, v39
	v_max_i32_e32 v24, v24, v38
	v_max_i32_e32 v30, v30, v37
	v_max_i32_e32 v26, v26, v36
	v_max_i32_e32 v29, v29, v35
	v_max_i32_e32 v33, v33, v34
	v_max_i32_e32 v34, v32, v31
	v_min_i32_e32 v31, v32, v31
	v_max_i32_e32 v32, v25, v28
	v_min_i32_e32 v25, v25, v28
	v_max_i32_e32 v28, v23, v27
	v_min_i32_e32 v23, v23, v27
	v_max_i32_e32 v27, v22, v24
	v_min_i32_e32 v22, v22, v24
	v_max_i32_e32 v24, v21, v30
	v_min_i32_e32 v21, v21, v30
	v_max_i32_e32 v30, v20, v26
	v_min_i32_e32 v20, v20, v26
	v_max_i32_e32 v26, v19, v29
	v_min_i32_e32 v19, v19, v29
	v_max_i32_e32 v29, v18, v33
	v_min_i32_e32 v18, v18, v33
	v_max_i32_e32 v33, v34, v24
	v_min_i32_e32 v24, v34, v24
	v_max_i32_e32 v34, v32, v30
	v_min_i32_e32 v30, v32, v30
	v_max_i32_e32 v32, v28, v26
	v_min_i32_e32 v26, v28, v26
	v_max_i32_e32 v28, v27, v29
	v_min_i32_e32 v27, v27, v29
	v_max_i32_e32 v29, v31, v21
	v_min_i32_e32 v21, v31, v21
	v_max_i32_e32 v31, v25, v20
	v_min_i32_e32 v20, v25, v20
	v_max_i32_e32 v25, v23, v19
	v_min_i32_e32 v19, v23, v19
	v_max_i32_e32 v23, v22, v18
	v_min_i32_e32 v18, v22, v18
	v_max_i32_e32 v22, v33, v32
	v_min_i32_e32 v32, v33, v32
	v_max_i32_e32 v33, v34, v28
	v_min_i32_e32 v28, v34, v28
	v_max_i32_e32 v34, v24, v26
	v_min_i32_e32 v24, v24, v26
	v_max_i32_e32 v35, v30, v27
	v_min_i32_e32 v27, v30, v27
	v_max_i32_e32 v30, v29, v25
	v_min_i32_e32 v25, v29, v25
	v_max_i32_e32 v29, v31, v23
	v_min_i32_e32 v23, v31, v23
	v_max_i32_e32 v31, v21, v19
	v_min_i32_e32 v19, v21, v19
	v_max_i32_e32 v21, v20, v18
	v_min_i32_e32 v18, v20, v18
	v_max_i32_e32 v26, v22, v33
	v_min_i32_e32 v33, v22, v33
	v_lshlrev_b32_e32 v20, 8, v81
	v_lshlrev_b32_e32 v22, 16, v80
	v_max_i32_e32 v36, v32, v28
	v_max_i32_e32 v40, v19, v18
	v_min_i32_e32 v41, v19, v18
	v_and_b32_e32 v18, 0x7f, v79
	v_and_b32_e32 v20, 0x7f00, v20
	v_and_b32_e32 v22, 0x7f0000, v22
	v_max_i32_e32 v39, v31, v21
	v_min_i32_e32 v31, v31, v21
	v_lshlrev_b32_e32 v21, 8, v33
	v_or3_b32 v18, v20, v18, v22
	v_lshlrev_b32_e32 v20, 16, v36
	v_and_b32_e32 v19, 0x7f, v26
	v_and_b32_e32 v21, 0x7f00, v21
	v_and_b32_e32 v20, 0x7f0000, v20
	v_or3_b32 v20, v21, v19, v20
	v_lshlrev_b32_e32 v19, 24, v78
	v_min_i32_e32 v28, v32, v28
	v_and_b32_e32 v19, 0x7f000000, v19
	v_bitop3_b32 v19, v18, s68, v19 bitop3:0x36
	v_lshlrev_b32_e32 v18, 24, v28
	v_max_i32_e32 v32, v34, v35
	v_min_i32_e32 v34, v34, v35
	v_max_i32_e32 v35, v24, v27
	v_min_i32_e32 v27, v24, v27
	v_and_b32_e32 v18, 0x7f000000, v18
	v_lshlrev_b32_e32 v22, 8, v76
	v_lshlrev_b32_e32 v24, 16, v75
; __device__ __forceinline__ void route_task(int task, int tl0, const bf16* QP  , const LAS bf16* KHL, LAS unsigned short* EL, LAS float* GL, int lane) {
;     ...
;     unsigned P1[4], P2[4];
; #pragma unroll
;     for (int q = 0; q < 4; ++q) { P1[q] = 0u; P2[q] = 0u;
; #pragma unroll
;         for (int s = 0; s < 4; ++s) { P1[q] |= (127u - ((unsigned)top[0][4 * q + s] & 127u)) << (8 * s); P2[q] |= (127u - ((unsigned)top[1][4 * q + s] & 127u)) << (8 * s); } }
;     int bk[16];
;     {
;         int hi2 = hi; asm volatile("" : "+v"(hi2));
;         const bool h1 = hi2 != 0;
;         constexpr int A1[16] = {1, 1, 1, 1, 1, 1, 1, 1, 2, 2, 2, 2, 2, 3, 3, 3}, B1[16] = {0, 1, 2, 3, 4, 5, 6, 7, 0, 1, 2, 3, 4, 0, 1, 2};
; #pragma unroll
;         for (int i = 0; i < 16; ++i) { const float ta = __int_as_float(h1 ? top[0][A1[i]] : top[0][0]), tb = __int_as_float(h1 ? top[1][B1[i]] : top[1][i]); const unsigned code = h1 ? (unsigned)(A1[i] * 16 + B1[i]) : (unsigned)i;
;             bk[i] = (int)((__float_as_uint(ta + tb) | 255u) - code); }
;         sort16_desc(bk);
	v_bitop3_b32 v18, v20, s68, v18 bitop3:0x36
	v_and_b32_e32 v20, 0x7f, v77
	v_and_b32_e32 v22, 0x7f00, v22
	v_and_b32_e32 v24, 0x7f0000, v24
	v_max_i32_e32 v37, v30, v29
	v_min_i32_e32 v29, v30, v29
	v_max_i32_e32 v30, v25, v23
	v_min_i32_e32 v38, v25, v23
	v_lshlrev_b32_e32 v23, 8, v34
	v_or3_b32 v20, v22, v20, v24
	v_lshlrev_b32_e32 v22, 16, v35
	v_and_b32_e32 v21, 0x7f, v32
	v_and_b32_e32 v23, 0x7f00, v23
	v_and_b32_e32 v22, 0x7f0000, v22
	v_or3_b32 v22, v23, v21, v22
	v_lshlrev_b32_e32 v21, 24, v73
	v_and_b32_e32 v21, 0x7f000000, v21
	v_bitop3_b32 v21, v20, s68, v21 bitop3:0x36
	v_lshlrev_b32_e32 v20, 24, v27
	v_and_b32_e32 v20, 0x7f000000, v20
	v_lshlrev_b32_e32 v24, 8, v74
	v_lshlrev_b32_e32 v42, 16, v72
	v_bitop3_b32 v20, v22, s68, v20 bitop3:0x36
	v_and_b32_e32 v22, 0x7f, v71
	v_and_b32_e32 v24, 0x7f00, v24
	v_and_b32_e32 v42, 0x7f0000, v42
	v_lshlrev_b32_e32 v25, 8, v29
	v_or3_b32 v22, v24, v22, v42
	v_lshlrev_b32_e32 v24, 16, v30
	v_and_b32_e32 v23, 0x7f, v37
	v_and_b32_e32 v25, 0x7f00, v25
	v_and_b32_e32 v24, 0x7f0000, v24
	v_or3_b32 v24, v25, v23, v24
	v_lshlrev_b32_e32 v23, 24, v70
	v_and_b32_e32 v23, 0x7f000000, v23
	v_bitop3_b32 v23, v22, s68, v23 bitop3:0x36
	v_lshlrev_b32_e32 v22, 24, v38
	v_and_b32_e32 v22, 0x7f000000, v22
	v_lshlrev_b32_e32 v42, 8, v68
	v_lshlrev_b32_e32 v44, 16, v67
	v_bitop3_b32 v22, v24, s68, v22 bitop3:0x36
	v_and_b32_e32 v24, 0x7f, v69
	v_and_b32_e32 v42, 0x7f00, v42
	v_and_b32_e32 v44, 0x7f0000, v44
	v_lshlrev_b32_e32 v43, 8, v31
	v_or3_b32 v24, v42, v24, v44
	v_lshlrev_b32_e32 v42, 16, v40
	v_and_b32_e32 v25, 0x7f, v39
	v_and_b32_e32 v43, 0x7f00, v43
	v_and_b32_e32 v42, 0x7f0000, v42
	v_or3_b32 v42, v43, v25, v42
	v_lshlrev_b32_e32 v25, 24, v66
	v_and_b32_e32 v25, 0x7f000000, v25
	v_bitop3_b32 v25, v24, s68, v25 bitop3:0x36
	v_lshlrev_b32_e32 v24, 24, v41
	v_and_b32_e32 v24, 0x7f000000, v24
	v_bitop3_b32 v24, v42, s68, v24 bitop3:0x36
	v_mov_b32_e32 v42, v86
	v_add_f32_e32 v62, v74, v26
	v_cmp_eq_u32_e32 vcc, 0, v42
	v_add_f32_e32 v63, v72, v26
	v_add_f32_e32 v64, v70, v26
	v_cndmask_b32_e32 v42, v81, v79, vcc
	v_add_f32_e32 v44, v42, v26
	v_cndmask_b32_e64 v43, -16, 0, vcc
	v_or_b32_e32 v44, 0xff, v44
	v_add_f32_e32 v45, v42, v33
	v_add_u32_e32 v43, v44, v43
	v_cndmask_b32_e64 v44, v99, -1, vcc
	v_or_b32_e32 v45, 0xff, v45
	v_add_f32_e32 v46, v42, v36
	v_add_u32_e32 v44, v45, v44
	v_cndmask_b32_e64 v45, v100, -2, vcc
	v_or_b32_e32 v46, 0xff, v46
	v_add_f32_e32 v47, v42, v28
	v_add_u32_e32 v45, v46, v45
	v_cndmask_b32_e64 v46, v101, -3, vcc
	v_or_b32_e32 v47, 0xff, v47
	v_add_f32_e32 v48, v42, v32
	v_add_u32_e32 v46, v47, v46
	v_cndmask_b32_e64 v47, v102, -4, vcc
	v_or_b32_e32 v48, 0xff, v48
	v_add_f32_e32 v34, v42, v34
	v_add_f32_e32 v35, v42, v35
	v_add_f32_e32 v27, v42, v27
	v_cndmask_b32_e32 v42, v80, v79, vcc
	v_cndmask_b32_e32 v32, v32, v39, vcc
	v_add_u32_e32 v47, v48, v47
	v_cndmask_b32_e64 v48, v103, -5, vcc
	v_or_b32_e32 v34, 0xff, v34
	v_add_f32_e32 v32, v42, v32
	v_add_u32_e32 v34, v34, v48
	v_cndmask_b32_e64 v48, v104, -6, vcc
	v_or_b32_e32 v35, 0xff, v35
	v_cndmask_b32_e32 v37, v26, v37, vcc
	v_cndmask_b32_e64 v39, v116, -12, vcc
	v_or_b32_e32 v32, 0xff, v32
	v_add_u32_e32 v35, v35, v48
	v_cndmask_b32_e64 v48, v105, -7, vcc
	v_or_b32_e32 v27, 0xff, v27
	v_add_f32_e32 v37, v42, v37
	v_cndmask_b32_e32 v29, v33, v29, vcc
	v_add_u32_e32 v32, v32, v39
	v_cndmask_b32_e32 v39, v78, v79, vcc
	v_cndmask_b32_e32 v31, v26, v31, vcc
	v_add_u32_e32 v27, v27, v48
	v_cndmask_b32_e64 v48, v106, -8, vcc
	v_or_b32_e32 v37, 0xff, v37
	v_add_f32_e32 v29, v42, v29
	v_cndmask_b32_e32 v30, v36, v30, vcc
	v_cndmask_b32_e32 v38, v28, v38, vcc
	v_add_f32_e32 v31, v39, v31
	v_cndmask_b32_e32 v40, v33, v40, vcc
	v_add_u32_e32 v37, v37, v48
	v_cndmask_b32_e64 v48, v107, -9, vcc
	v_or_b32_e32 v29, 0xff, v29
	v_add_f32_e32 v30, v42, v30
	v_add_f32_e32 v38, v42, v38
	v_cndmask_b32_e64 v42, v117, -13, vcc
	v_or_b32_e32 v31, 0xff, v31
	v_add_f32_e32 v40, v39, v40
	v_cndmask_b32_e32 v41, v36, v41, vcc
	v_add_u32_e32 v29, v29, v48
	v_cndmask_b32_e64 v48, v114, -10, vcc
	v_or_b32_e32 v30, 0xff, v30
	v_add_u32_e32 v31, v31, v42
	v_cndmask_b32_e64 v42, v118, -14, vcc
	v_or_b32_e32 v40, 0xff, v40
	v_add_f32_e32 v39, v39, v41
	v_add_u32_e32 v30, v30, v48
	v_cndmask_b32_e64 v48, v115, -11, vcc
	v_or_b32_e32 v38, 0xff, v38
	v_add_u32_e32 v40, v40, v42
	v_cndmask_b32_e64 v42, v119, -15, vcc
	v_or_b32_e32 v39, 0xff, v39
	v_add_u32_e32 v38, v38, v48
	v_add_u32_e32 v39, v39, v42
	v_max_i32_e32 v41, v43, v31
	v_min_i32_e32 v31, v43, v31
	v_max_i32_e32 v42, v44, v32
	v_min_i32_e32 v32, v44, v32
	v_max_i32_e32 v43, v45, v39
	v_min_i32_e32 v39, v45, v39
	v_max_i32_e32 v44, v46, v40
	v_min_i32_e32 v40, v46, v40
	v_max_i32_e32 v45, v47, v37
	v_min_i32_e32 v37, v47, v37
	v_max_i32_e32 v46, v34, v35
	v_min_i32_e32 v34, v34, v35
	v_max_i32_e32 v35, v27, v38
	v_min_i32_e32 v27, v27, v38
	v_max_i32_e32 v38, v29, v30
	v_min_i32_e32 v29, v29, v30
	v_max_i32_e32 v30, v41, v46
	v_min_i32_e32 v41, v41, v46
	v_max_i32_e32 v46, v42, v35
	v_min_i32_e32 v35, v42, v35
	v_max_i32_e32 v42, v43, v38
	v_min_i32_e32 v38, v43, v38
	v_max_i32_e32 v43, v44, v45
	v_min_i32_e32 v44, v44, v45
	v_max_i32_e32 v45, v34, v31
	v_min_i32_e32 v31, v34, v31
	v_max_i32_e32 v34, v37, v40
	v_min_i32_e32 v37, v37, v40
	v_max_i32_e32 v40, v29, v39
	v_min_i32_e32 v29, v29, v39
	v_max_i32_e32 v39, v27, v32
	v_min_i32_e32 v27, v27, v32
	v_max_i32_e32 v32, v30, v46
	v_min_i32_e32 v30, v30, v46
	v_max_i32_e32 v46, v42, v43
	v_min_i32_e32 v42, v42, v43
	v_max_i32_e32 v43, v44, v41
	v_min_i32_e32 v41, v44, v41
	v_max_i32_e32 v44, v45, v34
	v_min_i32_e32 v34, v45, v34
; #define CE_(a, b) ce_desc(v[a], v[b])
; #define CAND(a, b) (int)((__float_as_uint(__int_as_float(top[0][a]) + __int_as_float(top[1][b])) | 255u) - (unsigned)((a) * 16 + (b)))
; __device__ __forceinline__ void sort16_desc(int (&v)[16]) {
;     ...
;     CE_(0,13); CE_(1,12); CE_(2,15); CE_(3,14); CE_(4,8); CE_(5,6); CE_(7,11); CE_(9,10);
;     CE_(0,5); CE_(1,7); CE_(2,9); CE_(3,4); CE_(6,13); CE_(8,14); CE_(10,15); CE_(11,12);
;     CE_(0,1); CE_(2,3); CE_(4,5); CE_(6,8); CE_(7,9); CE_(10,11); CE_(12,13); CE_(14,15);
;     CE_(0,2); CE_(1,3); CE_(4,10); CE_(5,11); CE_(6,7); CE_(8,9); CE_(12,14); CE_(13,15);
;     CE_(1,2); CE_(3,12); CE_(4,6); CE_(5,7); CE_(8,10); CE_(9,11); CE_(13,14);
;     CE_(1,4); CE_(2,6); CE_(5,8); CE_(7,10); CE_(9,13); CE_(11,14);
;     CE_(2,4); CE_(3,6); CE_(9,12); CE_(11,13);
;     CE_(3,5); CE_(6,8); CE_(7,9); CE_(10,12);
;     CE_(3,4); CE_(5,6); CE_(7,8); CE_(9,10); CE_(11,12);
;     CE_(6,7); CE_(8,9);
;     ...
; }
; __device__ __forceinline__ void route_task(int task, int tl0, const bf16* QP  , const LAS bf16* KHL, LAS unsigned short* EL, LAS float* GL, int lane) {
;     ...
;         sort16_desc(bk);
;         int oth[16];
; #pragma unroll
;         for (int i = 0; i < 16; ++i) oth[i] = __shfl_xor(bk[i], 32);
;         merge16_desc(bk, oth);
;     }
;     ...
;     {
;         int gk[16];
;         gk[0] = CAND(3, 3); gk[1] = CAND(4, 0); gk[2] = CAND(4, 1); gk[3] = CAND(4, 2); gk[4] = CAND(5, 0); gk[5] = CAND(5, 1); gk[6] = CAND(6, 0); gk[7] = CAND(6, 1);
;         gk[8] = CAND(7, 0); gk[9] = CAND(7, 1); gk[10] = CAND(8, 0); gk[11] = CAND(9, 0); gk[12] = CAND(10, 0); gk[13] = CAND(11, 0); gk[14] = CAND(12, 0); gk[15] = CAND(13, 0);
;         sort16_desc(gk);
	v_max_i32_e32 v45, v35, v38
	v_min_i32_e32 v35, v35, v38
	v_max_i32_e32 v38, v40, v39
	v_min_i32_e32 v39, v40, v39
	v_max_i32_e32 v40, v27, v31
	v_min_i32_e32 v27, v27, v31
	v_max_i32_e32 v31, v37, v29
	v_min_i32_e32 v29, v37, v29
	v_max_i32_e32 v37, v32, v46
	v_min_i32_e32 v32, v32, v46
	v_max_i32_e32 v46, v30, v42
	v_min_i32_e32 v30, v30, v42
	v_max_i32_e32 v42, v43, v38
	v_min_i32_e32 v38, v43, v38
	v_max_i32_e32 v43, v41, v39
	v_min_i32_e32 v39, v41, v39
	v_max_i32_e32 v41, v44, v45
	v_min_i32_e32 v44, v44, v45
	v_max_i32_e32 v45, v34, v35
	v_min_i32_e32 v34, v34, v35
	v_max_i32_e32 v35, v40, v31
	v_min_i32_e32 v31, v40, v31
	v_max_i32_e32 v40, v27, v29
	v_min_i32_e32 v27, v27, v29
	v_max_i32_e32 v29, v46, v32
	v_min_i32_e32 v32, v46, v32
	v_max_i32_e32 v46, v30, v35
	v_min_i32_e32 v30, v30, v35
	v_max_i32_e32 v35, v42, v41
	v_min_i32_e32 v41, v42, v41
	v_max_i32_e32 v42, v43, v44
	v_min_i32_e32 v43, v43, v44
	v_max_i32_e32 v44, v45, v38
	v_min_i32_e32 v38, v45, v38
	v_max_i32_e32 v45, v34, v39
	v_min_i32_e32 v34, v34, v39
	v_max_i32_e32 v39, v40, v31
	v_min_i32_e32 v31, v40, v31
	v_max_i32_e32 v40, v29, v35
	v_min_i32_e32 v29, v29, v35
	v_max_i32_e32 v35, v32, v41
	v_min_i32_e32 v32, v32, v41
	v_max_i32_e32 v41, v42, v44
	v_min_i32_e32 v42, v42, v44
	v_max_i32_e32 v44, v43, v38
	v_min_i32_e32 v38, v43, v38
	v_max_i32_e32 v43, v45, v39
	v_min_i32_e32 v39, v45, v39
	v_max_i32_e32 v45, v34, v31
	v_min_i32_e32 v31, v34, v31
	v_max_i32_e32 v34, v35, v29
	v_min_i32_e32 v29, v35, v29
	v_max_i32_e32 v35, v46, v32
	v_min_i32_e32 v32, v46, v32
	v_max_i32_e32 v46, v43, v30
	v_min_i32_e32 v30, v43, v30
	v_max_i32_e32 v43, v45, v39
	v_min_i32_e32 v39, v45, v39
	v_max_i32_e32 v45, v35, v41
	v_min_i32_e32 v35, v35, v41
	v_max_i32_e32 v41, v32, v42
	v_min_i32_e32 v32, v32, v42
	v_max_i32_e32 v42, v44, v46
	v_min_i32_e32 v44, v44, v46
	v_max_i32_e32 v46, v38, v30
	v_min_i32_e32 v30, v38, v30
	v_max_i32_e32 v38, v45, v29
	v_min_i32_e32 v29, v45, v29
	v_max_i32_e32 v45, v35, v41
	v_min_i32_e32 v35, v35, v41
	v_max_i32_e32 v41, v42, v32
	v_min_i32_e32 v32, v42, v32
	v_max_i32_e32 v42, v44, v46
	v_min_i32_e32 v44, v44, v46
	v_max_i32_e32 v46, v43, v30
	v_min_i32_e32 v30, v43, v30
	v_max_i32_e32 v43, v35, v41
	v_min_i32_e32 v35, v35, v41
	v_max_i32_e32 v41, v32, v42
	v_min_i32_e32 v32, v32, v42
	ds_bpermute_b32 v54, v123, v41
	ds_bpermute_b32 v55, v123, v32
	ds_bpermute_b32 v56, v123, v44
	ds_bpermute_b32 v57, v123, v27
	ds_bpermute_b32 v58, v123, v31
	ds_bpermute_b32 v59, v123, v39
	ds_bpermute_b32 v60, v123, v30
	ds_bpermute_b32 v61, v123, v46
	ds_bpermute_b32 v42, v123, v37
	ds_bpermute_b32 v47, v123, v40
	ds_bpermute_b32 v48, v123, v34
	ds_bpermute_b32 v49, v123, v38
	ds_bpermute_b32 v50, v123, v29
	ds_bpermute_b32 v51, v123, v45
	ds_bpermute_b32 v52, v123, v43
	ds_bpermute_b32 v53, v123, v35
	s_waitcnt lgkmcnt(12)
	v_max_i32_e32 v37, v37, v57
	s_waitcnt lgkmcnt(11)
	v_max_i32_e32 v40, v40, v58
	s_waitcnt lgkmcnt(10)
	v_max_i32_e32 v34, v34, v59
	s_waitcnt lgkmcnt(9)
	v_max_i32_e32 v38, v38, v60
	s_waitcnt lgkmcnt(8)
	v_max_i32_e32 v29, v29, v61
	v_max_i32_e32 v45, v45, v56
	v_max_i32_e32 v43, v43, v55
	v_max_i32_e32 v35, v35, v54
	v_add_f32_e32 v28, v78, v28
	v_add_f32_e32 v54, v77, v26
	v_add_f32_e32 v55, v77, v33
	v_add_f32_e32 v36, v77, v36
	v_add_f32_e32 v56, v76, v26
	v_add_f32_e32 v57, v76, v33
	v_add_f32_e32 v58, v75, v26
	v_add_f32_e32 v59, v75, v33
	v_add_f32_e32 v60, v73, v26
	v_add_f32_e32 v33, v73, v33
	v_add_f32_e32 v61, v71, v26
	v_add_f32_e32 v65, v69, v26
	v_add_f32_e32 v68, v68, v26
	v_or_b32_e32 v28, 0xff, v28
	v_or_b32_e32 v54, 0xff, v54
	v_or_b32_e32 v55, 0xff, v55
	v_or_b32_e32 v36, 0xff, v36
	v_or_b32_e32 v56, 0xff, v56
	v_or_b32_e32 v57, 0xff, v57
	v_or_b32_e32 v58, 0xff, v58
	v_or_b32_e32 v59, 0xff, v59
	v_or_b32_e32 v60, 0xff, v60
	v_or_b32_e32 v33, 0xff, v33
	v_or_b32_e32 v61, 0xff, v61
	v_or_b32_e32 v62, 0xff, v62
	v_or_b32_e32 v63, 0xff, v63
	v_or_b32_e32 v64, 0xff, v64
	v_or_b32_e32 v65, 0xff, v65
	v_or_b32_e32 v68, 0xff, v68
	v_subrev_u32_e32 v28, 51, v28
	v_subrev_u32_e32 v54, 64, v54
	v_add_u32_e32 v55, 0xffffffbf, v55
	v_add_u32_e32 v36, 0xffffffbe, v36
	v_add_u32_e32 v56, 0xffffffb0, v56
	v_add_u32_e32 v57, 0xffffffaf, v57
	v_add_u32_e32 v58, 0xffffffa0, v58
	v_add_u32_e32 v59, 0xffffff9f, v59
	v_add_u32_e32 v60, 0xffffff90, v60
	v_add_u32_e32 v33, 0xffffff8f, v33
	v_add_u32_e32 v61, 0xffffff80, v61
	v_add_u32_e32 v62, 0xffffff70, v62
	v_add_u32_e32 v63, 0xffffff60, v63
	v_add_u32_e32 v64, 0xffffff50, v64
	v_add_u32_e32 v65, 0xffffff40, v65
	v_add_u32_e32 v68, 0xffffff30, v68
	v_max_i32_e32 v69, v28, v64
	v_min_i32_e32 v28, v28, v64
	v_max_i32_e32 v64, v54, v63
	v_min_i32_e32 v54, v54, v63
	v_max_i32_e32 v63, v55, v68
	v_min_i32_e32 v55, v55, v68
	v_max_i32_e32 v68, v36, v65
	v_min_i32_e32 v36, v36, v65
	v_max_i32_e32 v65, v56, v60
	v_min_i32_e32 v56, v56, v60
	v_max_i32_e32 v60, v57, v58
	v_min_i32_e32 v57, v57, v58
	v_max_i32_e32 v58, v59, v62
	v_min_i32_e32 v59, v59, v62
	v_max_i32_e32 v62, v33, v61
	v_min_i32_e32 v33, v33, v61
	v_max_i32_e32 v61, v69, v60
	v_min_i32_e32 v60, v69, v60
	v_max_i32_e32 v69, v64, v58
	v_min_i32_e32 v58, v64, v58
	v_max_i32_e32 v64, v63, v62
	v_min_i32_e32 v62, v63, v62
	v_max_i32_e32 v63, v68, v65
	v_min_i32_e32 v65, v68, v65
	v_max_i32_e32 v68, v57, v28
	v_min_i32_e32 v28, v57, v28
	v_max_i32_e32 v57, v56, v36
	v_min_i32_e32 v36, v56, v36
	v_max_i32_e32 v56, v33, v55
	v_min_i32_e32 v33, v33, v55
	v_max_i32_e32 v55, v59, v54
	v_min_i32_e32 v54, v59, v54
	v_max_i32_e32 v59, v61, v69
	v_min_i32_e32 v61, v61, v69
	v_max_i32_e32 v69, v64, v63
	v_min_i32_e32 v63, v64, v63
	v_max_i32_e32 v64, v65, v60
	v_min_i32_e32 v60, v65, v60
	v_max_i32_e32 v65, v68, v57
	v_min_i32_e32 v57, v68, v57
	v_max_i32_e32 v68, v58, v62
	v_min_i32_e32 v58, v58, v62
	v_max_i32_e32 v62, v56, v55
	v_min_i32_e32 v55, v56, v55
	v_max_i32_e32 v56, v54, v28
	v_min_i32_e32 v28, v54, v28
	v_max_i32_e32 v54, v36, v33
	v_min_i32_e32 v33, v36, v33
	v_min_i32_e32 v36, v59, v69
	v_max_i32_e32 v70, v61, v63
	v_min_i32_e32 v61, v61, v63
	v_max_i32_e32 v63, v64, v62
	v_min_i32_e32 v62, v64, v62
	v_max_i32_e32 v64, v60, v55
	v_min_i32_e32 v55, v60, v55
	v_max_i32_e32 v60, v65, v68
	v_min_i32_e32 v65, v65, v68
	v_max_i32_e32 v68, v57, v58
	v_min_i32_e32 v57, v57, v58
	v_max_i32_e32 v58, v56, v54
	v_min_i32_e32 v54, v56, v54
	v_max_i32_e32 v56, v28, v33
	v_min_i32_e32 v28, v28, v33
	v_max_i32_e32 v33, v70, v36
	v_min_i32_e32 v36, v70, v36
	v_max_i32_e32 v70, v61, v58
	v_min_i32_e32 v58, v61, v58
	v_max_i32_e32 v61, v63, v60
	v_min_i32_e32 v60, v63, v60
	v_max_i32_e32 v63, v64, v65
	v_min_i32_e32 v64, v64, v65
	v_max_i32_e32 v65, v68, v62
	v_min_i32_e32 v62, v68, v62
	v_max_i32_e32 v68, v57, v55
	v_min_i32_e32 v55, v57, v55
	v_max_i32_e32 v57, v56, v54
	s_waitcnt lgkmcnt(0)
; #define CAND(a, b) (int)((__float_as_uint(__int_as_float(top[0][a]) + __int_as_float(top[1][b])) | 255u) - (unsigned)((a) * 16 + (b)))
; __device__ __forceinline__ void route_task(int task, int tl0, const bf16* QP  , const LAS bf16* KHL, LAS unsigned short* EL, LAS float* GL, int lane) {
;     ...
;         merge16_desc(bk, oth);
;     }
;     ...
;     {
;         int gk[16];
;         gk[0] = CAND(3, 3); gk[1] = CAND(4, 0); gk[2] = CAND(4, 1); gk[3] = CAND(4, 2); gk[4] = CAND(5, 0); gk[5] = CAND(5, 1); gk[6] = CAND(6, 0); gk[7] = CAND(6, 1);
;         gk[8] = CAND(7, 0); gk[9] = CAND(7, 1); gk[10] = CAND(8, 0); gk[11] = CAND(9, 0); gk[12] = CAND(10, 0); gk[13] = CAND(11, 0); gk[14] = CAND(12, 0); gk[15] = CAND(13, 0);
;         sort16_desc(gk);
;         merge16_desc(bk, gk);
;     }
;     {
;         const int c14 = CAND(14, 0), c15 = CAND(15, 0);
;         const int n14 = max(bk[14], c14), n15 = max(min(bk[14], c14), max(bk[15], c15));
;         bk[14] = n14; bk[15] = n15;
	v_max_i32_e32 v41, v41, v53
	v_max_i32_e32 v32, v32, v52
	v_max_i32_e32 v44, v44, v51
	v_max_i32_e32 v46, v46, v50
	v_max_i32_e32 v30, v30, v49
	v_max_i32_e32 v39, v39, v48
	v_max_i32_e32 v31, v31, v47
	v_max_i32_e32 v27, v27, v42
	v_min_i32_e32 v54, v56, v54
	v_max_i32_e32 v56, v33, v61
	v_min_i32_e32 v33, v33, v61
	v_max_i32_e32 v61, v36, v60
	v_min_i32_e32 v36, v36, v60
	v_max_i32_e32 v60, v63, v65
	v_min_i32_e32 v63, v63, v65
	v_max_i32_e32 v65, v64, v62
	v_min_i32_e32 v62, v64, v62
	v_max_i32_e32 v64, v68, v57
	v_max_i32_e32 v42, v37, v41
	v_min_i32_e32 v37, v37, v41
	v_max_i32_e32 v41, v40, v32
	v_min_i32_e32 v32, v40, v32
	v_max_i32_e32 v40, v34, v44
	v_min_i32_e32 v34, v34, v44
	v_max_i32_e32 v44, v38, v46
	v_min_i32_e32 v38, v38, v46
	v_max_i32_e32 v46, v29, v30
	v_min_i32_e32 v29, v29, v30
	v_max_i32_e32 v30, v45, v39
	v_min_i32_e32 v39, v45, v39
	v_max_i32_e32 v45, v43, v31
	v_min_i32_e32 v31, v43, v31
	v_max_i32_e32 v43, v35, v27
	v_min_i32_e32 v27, v35, v27
	v_min_i32_e32 v57, v68, v57
	v_max_i32_e32 v68, v55, v54
	v_max_i32_e32 v71, v70, v36
	v_min_i32_e32 v36, v70, v36
	v_max_i32_e32 v70, v64, v58
	v_min_i32_e32 v58, v64, v58
	v_max_i32_e32 v35, v42, v46
	v_min_i32_e32 v42, v42, v46
	v_max_i32_e32 v46, v41, v30
	v_min_i32_e32 v30, v41, v30
	v_max_i32_e32 v41, v40, v45
	v_min_i32_e32 v40, v40, v45
	v_max_i32_e32 v45, v44, v43
	v_min_i32_e32 v43, v44, v43
	v_max_i32_e32 v44, v37, v29
	v_min_i32_e32 v29, v37, v29
	v_max_i32_e32 v37, v32, v39
	v_min_i32_e32 v32, v32, v39
	v_max_i32_e32 v39, v34, v31
	v_min_i32_e32 v31, v34, v31
	v_max_i32_e32 v34, v38, v27
	v_min_i32_e32 v27, v38, v27
	v_min_i32_e32 v54, v55, v54
	v_min_i32_e32 v55, v61, v33
	v_max_i32_e32 v64, v68, v57
	v_min_i32_e32 v57, v68, v57
	v_max_i32_e32 v68, v71, v60
	v_min_i32_e32 v60, v71, v60
	v_max_i32_e32 v71, v36, v63
	v_min_i32_e32 v36, v36, v63
	v_max_i32_e32 v63, v65, v70
	v_min_i32_e32 v65, v65, v70
	v_max_i32_e32 v70, v62, v58
	v_max_i32_e32 v38, v35, v41
	v_min_i32_e32 v35, v35, v41
	v_max_i32_e32 v41, v46, v45
	v_min_i32_e32 v45, v46, v45
	v_max_i32_e32 v46, v42, v40
	v_min_i32_e32 v40, v42, v40
	v_max_i32_e32 v42, v30, v43
	v_min_i32_e32 v30, v30, v43
	v_max_i32_e32 v43, v44, v39
	v_min_i32_e32 v39, v44, v39
	v_max_i32_e32 v44, v37, v34
	v_min_i32_e32 v34, v37, v34
	v_max_i32_e32 v37, v29, v31
	v_min_i32_e32 v29, v29, v31
	v_max_i32_e32 v31, v32, v27
	v_min_i32_e32 v27, v32, v27
	v_min_i32_e32 v58, v62, v58
	v_max_i32_e32 v62, v68, v55
	v_min_i32_e32 v55, v68, v55
	v_max_i32_e32 v68, v60, v71
	v_min_i32_e32 v60, v60, v71
	v_max_i32_e32 v71, v63, v36
	v_min_i32_e32 v36, v63, v36
	v_max_i32_e32 v63, v65, v70
	v_min_i32_e32 v32, v38, v41
	v_min_i32_e32 v47, v35, v45
	v_min_i32_e32 v48, v46, v42
	v_min_i32_e32 v49, v40, v30
	v_min_i32_e32 v50, v43, v44
	v_min_i32_e32 v51, v39, v34
	v_min_i32_e32 v52, v37, v31
	v_min_i32_e32 v53, v29, v27
	v_min_i32_e32 v65, v65, v70
	v_max_i32_e32 v70, v64, v58
	v_min_i32_e32 v58, v64, v58
	v_min_i32_e32 v64, v60, v71
	v_min_i32_e32 v72, v36, v63
	v_max3_i32 v28, v38, v41, v28
	v_max_i32_e32 v32, v32, v54
	v_max3_i32 v35, v35, v45, v57
	v_max_i32_e32 v38, v47, v58
	v_max3_i32 v41, v46, v42, v70
	v_max_i32_e32 v42, v48, v65
	v_max3_i32 v30, v40, v30, v72
	v_max3_i32 v36, v49, v36, v63
	v_max3_i32 v40, v43, v44, v64
	v_max3_i32 v43, v50, v60, v71
	v_max3_i32 v34, v39, v34, v68
	v_max_i32_e32 v39, v51, v55
	v_max3_i32 v31, v37, v31, v62
	v_max3_i32 v33, v52, v61, v33
	v_max3_i32 v27, v29, v27, v56
	v_max3_i32 v29, v53, v59, v69
	v_max_i32_e32 v37, v28, v40
	v_min_i32_e32 v28, v28, v40
	v_max_i32_e32 v40, v32, v43
	v_min_i32_e32 v32, v32, v43
	v_max_i32_e32 v43, v35, v34
	v_min_i32_e32 v34, v35, v34
	v_max_i32_e32 v35, v38, v39
	v_min_i32_e32 v38, v38, v39
	v_max_i32_e32 v39, v41, v31
	v_min_i32_e32 v31, v41, v31
	v_max_i32_e32 v41, v42, v33
	v_min_i32_e32 v33, v42, v33
	v_max_i32_e32 v42, v30, v27
	v_min_i32_e32 v27, v30, v27
	v_max_i32_e32 v30, v36, v29
	v_min_i32_e32 v29, v36, v29
	v_max_i32_e32 v36, v37, v39
	v_min_i32_e32 v37, v37, v39
	v_max_i32_e32 v39, v40, v41
	v_min_i32_e32 v40, v40, v41
	v_max_i32_e32 v41, v43, v42
	v_min_i32_e32 v42, v43, v42
	v_max_i32_e32 v43, v35, v30
	v_min_i32_e32 v30, v35, v30
	v_max_i32_e32 v35, v28, v31
	v_min_i32_e32 v28, v28, v31
	v_max_i32_e32 v31, v32, v33
	v_min_i32_e32 v32, v32, v33
	v_max_i32_e32 v33, v34, v27
	v_min_i32_e32 v27, v34, v27
	v_max_i32_e32 v34, v38, v29
	v_min_i32_e32 v29, v38, v29
	v_max_i32_e32 v38, v36, v41
	v_min_i32_e32 v36, v36, v41
	v_max_i32_e32 v41, v39, v43
	v_min_i32_e32 v39, v39, v43
	v_max_i32_e32 v43, v37, v42
	v_min_i32_e32 v37, v37, v42
	v_max_i32_e32 v42, v40, v30
	v_min_i32_e32 v30, v40, v30
	v_max_i32_e32 v40, v35, v33
	v_min_i32_e32 v33, v35, v33
	v_max_i32_e32 v35, v31, v34
	v_min_i32_e32 v31, v31, v34
	v_max_i32_e32 v34, v28, v27
	v_min_i32_e32 v27, v28, v27
	v_max_i32_e32 v28, v32, v29
	v_min_i32_e32 v29, v32, v29
	v_max_i32_e32 v32, v38, v41
	v_min_i32_e32 v38, v38, v41
	v_max_i32_e32 v41, v36, v39
	v_min_i32_e32 v36, v36, v39
	v_max_i32_e32 v39, v43, v42
	v_min_i32_e32 v42, v43, v42
	v_max_i32_e32 v43, v37, v30
	v_min_i32_e32 v30, v37, v30
	v_max_i32_e32 v37, v40, v35
	v_min_i32_e32 v35, v40, v35
	v_max_i32_e32 v40, v33, v31
	v_min_i32_e32 v31, v33, v31
	v_max_i32_e32 v33, v34, v28
	v_min_i32_e32 v28, v34, v28
	v_max_i32_e32 v34, v27, v29
	v_min_i32_e32 v27, v27, v29
	v_add_f32_e32 v29, v67, v26
	v_or_b32_e32 v29, 0xff, v29
	v_add_f32_e32 v26, v66, v26
	v_add_u32_e32 v29, 0xffffff20, v29
	v_or_b32_e32 v26, 0xff, v26
	v_add_u32_e32 v26, 0xffffff10, v26
	v_max_i32_e32 v44, v34, v29
	v_min_i32_e32 v29, v34, v29
	v_max3_i32 v26, v29, v27, v26
; __device__ __forceinline__ void route_task(int task, int tl0, const bf16* QP  , const LAS bf16* KHL, LAS unsigned short* EL, LAS float* GL, int lane) {
;     ...
;     int my[8];
; #pragma unroll
;     for (int i = 0; i < 8; ++i) { int lo_ = bk[i], hi_ = bk[8 + i]; asm volatile("" : "+v"(lo_), "+v"(hi_)); my[i] = hi ? hi_ : lo_; }
;     int bv[8];
; #pragma unroll
;     for (int i = 0; i < 8; ++i) {
;         const unsigned cd = 255u - ((unsigned)my[i] & 255u), ca = cd >> 4, cb = cd & 15u;
;         const unsigned wa = (ca >> 2) == 0u ? P1[0] : (ca >> 2) == 1u ? P1[1] : (ca >> 2) == 2u ? P1[2] : P1[3];
;         const unsigned wb = (cb >> 2) == 0u ? P2[0] : (cb >> 2) == 1u ? P2[1] : (cb >> 2) == 2u ? P2[2] : P2[3];
;         bv[i] = (int)((((wa >> (8u * (ca & 3u))) & 255u) << 7) | ((wb >> (8u * (cb & 3u))) & 255u));
;     }
	v_mov_b32_e32 v27, v32
	s_nop 0
	v_cndmask_b32_e64 v27, v37, v27, s[6:7]
	v_not_b32_e32 v29, v27
	v_bfe_u32 v45, v29, 6, 2
	v_cmp_eq_u32_e32 vcc, 2, v45
	v_cndmask_b32_e64 v30, v26, v30, s[6:7]
	v_bitop3_b32 v26, v27, s3, v27 bitop3:0xc
	v_cndmask_b32_e32 v46, v25, v23, vcc
	v_cmp_eq_u32_e32 vcc, 1, v45
	v_cndmask_b32_e64 v34, v35, v38, s[6:7]
	v_not_b32_e32 v35, v34
	v_cndmask_b32_e32 v45, v46, v21, vcc
	v_cmp_gt_u32_e32 vcc, 64, v26
	v_cndmask_b32_e64 v37, v40, v41, s[6:7]
	v_cndmask_b32_e64 v41, v44, v43, s[6:7]
	v_cndmask_b32_e32 v26, v45, v19, vcc
	v_bfe_u32 v45, v29, 2, 2
	v_cmp_eq_u32_e32 vcc, 2, v45
	v_bitop3_b32 v44, v27, 15, v27 bitop3:0xc
	v_bfe_u32 v47, v35, 6, 2
	v_cndmask_b32_e32 v46, v24, v22, vcc
	v_cmp_eq_u32_e32 vcc, 1, v45
	v_not_b32_e32 v38, v37
	v_bfe_u32 v49, v38, 6, 2
	v_cndmask_b32_e32 v45, v46, v20, vcc
	v_cmp_gt_u32_e32 vcc, 4, v44
	v_bitop3_b32 v46, v34, 15, v34 bitop3:0xc
	v_cndmask_b32_e64 v31, v31, v36, s[6:7]
	v_cndmask_b32_e32 v44, v45, v18, vcc
	v_cmp_eq_u32_e32 vcc, 2, v47
	v_bitop3_b32 v45, v34, s3, v34 bitop3:0xc
	v_not_b32_e32 v36, v31
	v_cndmask_b32_e32 v48, v25, v23, vcc
	v_cmp_eq_u32_e32 vcc, 1, v47
	v_bfe_u32 v51, v36, 6, 2
	v_cndmask_b32_e64 v33, v33, v39, s[6:7]
	v_cndmask_b32_e32 v47, v48, v21, vcc
	v_cmp_gt_u32_e32 vcc, 64, v45
	v_not_b32_e32 v39, v33
	v_bfe_u32 v53, v39, 6, 2
	v_cndmask_b32_e32 v45, v47, v19, vcc
	v_bfe_u32 v47, v35, 2, 2
	v_cmp_eq_u32_e32 vcc, 2, v47
	v_cndmask_b32_e64 v28, v28, v42, s[6:7]
	v_not_b32_e32 v40, v28
	v_cndmask_b32_e32 v48, v24, v22, vcc
	v_cmp_eq_u32_e32 vcc, 1, v47
	v_bfe_u32 v55, v40, 6, 2
	v_not_b32_e32 v42, v41
	v_cndmask_b32_e32 v47, v48, v20, vcc
	v_cmp_gt_u32_e32 vcc, 4, v46
	v_bitop3_b32 v48, v37, 15, v37 bitop3:0xc
	v_bfe_u32 v57, v42, 6, 2
	v_cndmask_b32_e32 v46, v47, v18, vcc
	v_cmp_eq_u32_e32 vcc, 2, v49
	v_bitop3_b32 v47, v37, s3, v37 bitop3:0xc
	v_not_b32_e32 v43, v30
	v_cndmask_b32_e32 v50, v25, v23, vcc
	v_cmp_eq_u32_e32 vcc, 1, v49
	v_bfe_u32 v59, v43, 6, 2
	s_nop 0
	v_cndmask_b32_e32 v49, v50, v21, vcc
	v_cmp_gt_u32_e32 vcc, 64, v47
	s_nop 1
	v_cndmask_b32_e32 v47, v49, v19, vcc
	v_bfe_u32 v49, v38, 2, 2
	v_cmp_eq_u32_e32 vcc, 2, v49
	s_nop 1
	v_cndmask_b32_e32 v50, v24, v22, vcc
	v_cmp_eq_u32_e32 vcc, 1, v49
	s_nop 1
	v_cndmask_b32_e32 v49, v50, v20, vcc
	v_cmp_gt_u32_e32 vcc, 4, v48
	v_bitop3_b32 v50, v31, 15, v31 bitop3:0xc
	s_nop 0
	v_cndmask_b32_e32 v48, v49, v18, vcc
	v_cmp_eq_u32_e32 vcc, 2, v51
	v_bitop3_b32 v49, v31, s3, v31 bitop3:0xc
	s_nop 0
	v_cndmask_b32_e32 v52, v25, v23, vcc
	v_cmp_eq_u32_e32 vcc, 1, v51
	s_nop 1
	v_cndmask_b32_e32 v51, v52, v21, vcc
	v_cmp_gt_u32_e32 vcc, 64, v49
	s_nop 1
	v_cndmask_b32_e32 v49, v51, v19, vcc
	v_bfe_u32 v51, v36, 2, 2
	v_cmp_eq_u32_e32 vcc, 2, v51
	s_nop 1
	v_cndmask_b32_e32 v52, v24, v22, vcc
	v_cmp_eq_u32_e32 vcc, 1, v51
	s_nop 1
	v_cndmask_b32_e32 v51, v52, v20, vcc
	v_cmp_gt_u32_e32 vcc, 4, v50
	v_bitop3_b32 v52, v33, 15, v33 bitop3:0xc
	s_nop 0
	v_cndmask_b32_e32 v50, v51, v18, vcc
	v_cmp_eq_u32_e32 vcc, 2, v53
	v_bitop3_b32 v51, v33, s3, v33 bitop3:0xc
	s_nop 0
	v_cndmask_b32_e32 v54, v25, v23, vcc
	v_cmp_eq_u32_e32 vcc, 1, v53
	s_nop 1
	v_cndmask_b32_e32 v53, v54, v21, vcc
	v_cmp_gt_u32_e32 vcc, 64, v51
	s_nop 1
	v_cndmask_b32_e32 v51, v53, v19, vcc
	v_bfe_u32 v53, v39, 2, 2
	v_cmp_eq_u32_e32 vcc, 2, v53
	s_nop 1
	v_cndmask_b32_e32 v54, v24, v22, vcc
	v_cmp_eq_u32_e32 vcc, 1, v53
	s_nop 1
	v_cndmask_b32_e32 v53, v54, v20, vcc
	v_cmp_gt_u32_e32 vcc, 4, v52
	v_bitop3_b32 v54, v28, 15, v28 bitop3:0xc
	s_nop 0
	v_cndmask_b32_e32 v52, v53, v18, vcc
	v_cmp_eq_u32_e32 vcc, 2, v55
	v_bitop3_b32 v53, v28, s3, v28 bitop3:0xc
	s_nop 0
	v_cndmask_b32_e32 v56, v25, v23, vcc
	v_cmp_eq_u32_e32 vcc, 1, v55
	s_nop 1
	v_cndmask_b32_e32 v55, v56, v21, vcc
	v_cmp_gt_u32_e32 vcc, 64, v53
	s_nop 1
	v_cndmask_b32_e32 v53, v55, v19, vcc
	v_bfe_u32 v55, v40, 2, 2
	v_cmp_eq_u32_e32 vcc, 2, v55
	s_nop 1
	v_cndmask_b32_e32 v56, v24, v22, vcc
	v_cmp_eq_u32_e32 vcc, 1, v55
	s_nop 1
	v_cndmask_b32_e32 v55, v56, v20, vcc
	v_cmp_gt_u32_e32 vcc, 4, v54
	v_bitop3_b32 v56, v41, 15, v41 bitop3:0xc
	s_nop 0
	v_cndmask_b32_e32 v54, v55, v18, vcc
	v_cmp_eq_u32_e32 vcc, 2, v57
	v_bitop3_b32 v55, v41, s3, v41 bitop3:0xc
	s_nop 0
	v_cndmask_b32_e32 v58, v25, v23, vcc
	v_cmp_eq_u32_e32 vcc, 1, v57
	s_nop 1
	v_cndmask_b32_e32 v57, v58, v21, vcc
	v_cmp_gt_u32_e32 vcc, 64, v55
	s_nop 1
	v_cndmask_b32_e32 v55, v57, v19, vcc
	v_bfe_u32 v57, v42, 2, 2
	v_cmp_eq_u32_e32 vcc, 2, v57
	s_nop 1
	v_cndmask_b32_e32 v58, v24, v22, vcc
	v_cmp_eq_u32_e32 vcc, 1, v57
	s_nop 1
	v_cndmask_b32_e32 v57, v58, v20, vcc
	v_cmp_gt_u32_e32 vcc, 4, v56
	v_bitop3_b32 v58, v30, 15, v30 bitop3:0xc
	s_nop 0
	v_cndmask_b32_e32 v56, v57, v18, vcc
	v_cmp_eq_u32_e32 vcc, 2, v59
	v_bitop3_b32 v57, v30, s3, v30 bitop3:0xc
	s_nop 0
	v_cndmask_b32_e32 v23, v25, v23, vcc
	v_cmp_eq_u32_e32 vcc, 1, v59
	v_sub_f32_e32 v25, v31, v32
	v_mul_f32_e32 v25, 0x3fb8aa3b, v25
	v_cndmask_b32_e32 v21, v23, v21, vcc
	v_cmp_gt_u32_e32 vcc, 64, v57
	v_lshrrev_b32_e32 v23, 1, v39
	v_and_b32_e32 v23, 24, v23
	v_cndmask_b32_e32 v19, v21, v19, vcc
	v_bfe_u32 v21, v43, 2, 2
	v_cmp_eq_u32_e32 vcc, 2, v21
	v_lshrrev_b32_e32 v23, v23, v51
	v_lshlrev_b32_e32 v23, 7, v23
	v_cndmask_b32_e32 v22, v24, v22, vcc
	v_cmp_eq_u32_e32 vcc, 1, v21
	v_lshrrev_b32_e32 v21, 1, v42
	v_and_b32_e32 v21, 24, v21
	v_cndmask_b32_e32 v20, v22, v20, vcc
	v_cmp_gt_u32_e32 vcc, 4, v58
	v_lshrrev_b32_e32 v21, v21, v55
	v_lshrrev_b32_e32 v22, 1, v40
	v_cndmask_b32_e32 v18, v20, v18, vcc
	v_lshlrev_b32_e32 v20, 3, v42
	v_lshlrev_b32_e32 v21, 7, v21
	v_and_b32_e32 v22, 24, v22
	v_lshrrev_b32_e32 v20, v20, v56
; #define LAS __attribute__((address_space(3)))
; __device__ __forceinline__ void peer_u_item(int p, int j, const LAS unsigned short* EL  , const unsigned char* __restrict__ XQ, const unsigned char* __restrict__ U8, LAS int* ACC  , int lane, int wave) {
;     asm volatile("" : "+v"(lane));
;     const int gidx = lane >> 3; const unsigned coff = (unsigned)(p * 128 + (lane & 7) * 16), toff = (unsigned)(p * (16384 * 128) + (lane & 7) * 16);
; #pragma unroll 1
;     for (int it = 0; it < 8; ++it) {
;         const int t = j * 64 + it * 8 + wave;
;         unsigned E[8];
;         { const LAS v4u* ep = (const LAS v4u*)(EL + (it * 8 + wave) * 128 + 16 * gidx); const v4u e0 = ep[0], e1 = ep[1];
;           E[0] = e0.x; E[1] = e0.y; E[2] = e0.z; E[3] = e0.w; E[4] = e1.x; E[5] = e1.y; E[6] = e1.z; E[7] = e1.w; }
;         uint4 uu[16];
; #pragma unroll
;         for (int i = 0; i < 16; ++i) uu[i] = *(const uint4*)(U8 + (size_t)(PE_ID(E, i) * 128u + toff));
;         const uint4 xh = *(const uint4*)(XQ + (size_t)t * 512 + coff), xl = *(const uint4*)(XQ + 8 * MiB + (size_t)t * 512 + coff);
; __device__ __forceinline__ void route_task(int task, int tl0, const bf16* QP  , const LAS bf16* KHL, LAS unsigned short* EL, LAS float* GL, int lane) {
;     ...
;     float e[8], se = 0.f;
; #pragma unroll
;     for (int i = 0; i < 8; ++i) { e[i] = __expf(__int_as_float(my[i]) - __int_as_float(bk[0])); se += e[i]; }
;     se += __shfl_xor(se, 32);
;     const float inv = 1.f / se;
;     {
;         int l2 = lane; asm volatile("" : "+v"(l2));
;         const int o2 = (tl0 + ((l2 & 31) >> 3)) * 128 + (l2 & 7) * 16 + 8 * (l2 >> 5);
;         LAS v4u* ip = (LAS v4u*)(EL + o2); typedef float f4v __attribute__((ext_vector_type(4))); LAS f4v* gp = (LAS f4v*)(GL + o2);
;         ip[0] = (v4u){(unsigned)bv[0] | ((unsigned)bv[1] << 16), (unsigned)bv[2] | ((unsigned)bv[3] << 16), (unsigned)bv[4] | ((unsigned)bv[5] << 16), (unsigned)bv[6] | ((unsigned)bv[7] << 16)};
;         gp[0] = (f4v){e[0] * inv, e[1] * inv, e[2] * inv, e[3] * inv}; gp[1] = (f4v){e[4] * inv, e[5] * inv, e[6] * inv, e[7] * inv};
;     }
	v_and_b32_e32 v21, 0x7f80, v21
	v_lshrrev_b32_e32 v22, v22, v53
	v_and_or_b32 v21, v20, s3, v21
	v_lshlrev_b32_e32 v20, 3, v40
	v_lshlrev_b32_e32 v22, 7, v22
	v_lshrrev_b32_e32 v20, v20, v54
	v_and_b32_e32 v22, 0x7f80, v22
	v_and_or_b32 v20, v20, s3, v22
	v_lshlrev_b32_e32 v22, 3, v39
	v_lshrrev_b32_e32 v22, v22, v52
	v_and_b32_e32 v23, 0x7f80, v23
	v_and_or_b32 v39, v22, s3, v23
	v_lshrrev_b32_e32 v23, 1, v36
	v_and_b32_e32 v23, 24, v23
	v_lshrrev_b32_e32 v23, v23, v49
	v_lshlrev_b32_e32 v22, 3, v36
	v_lshlrev_b32_e32 v23, 7, v23
	v_lshrrev_b32_e32 v22, v22, v50
	v_and_b32_e32 v23, 0x7f80, v23
	v_and_or_b32 v36, v22, s3, v23
	v_lshrrev_b32_e32 v23, 1, v38
	v_and_b32_e32 v23, 24, v23
	v_lshrrev_b32_e32 v23, v23, v47
	v_lshlrev_b32_e32 v22, 3, v38
	v_lshlrev_b32_e32 v23, 7, v23
	v_lshrrev_b32_e32 v22, v22, v48
	v_and_b32_e32 v23, 0x7f80, v23
	v_and_or_b32 v38, v22, s3, v23
	v_lshrrev_b32_e32 v23, 1, v35
	v_and_b32_e32 v23, 24, v23
	v_lshrrev_b32_e32 v23, v23, v45
	v_lshlrev_b32_e32 v22, 3, v35
	v_lshlrev_b32_e32 v23, 7, v23
	v_lshrrev_b32_e32 v22, v22, v46
	v_and_b32_e32 v23, 0x7f80, v23
	v_and_or_b32 v35, v22, s3, v23
	v_lshrrev_b32_e32 v23, 1, v29
	v_and_b32_e32 v23, 24, v23
	v_lshrrev_b32_e32 v23, v23, v26
	v_lshlrev_b32_e32 v22, 3, v29
	v_lshlrev_b32_e32 v23, 7, v23
	v_lshrrev_b32_e32 v22, v22, v44
	v_and_b32_e32 v23, 0x7f80, v23
	v_and_or_b32 v40, v22, s3, v23
	v_sub_f32_e32 v22, v27, v32
	v_mul_f32_e32 v22, 0x3fb8aa3b, v22
	v_sub_f32_e32 v23, v34, v32
	v_exp_f32_e32 v22, v22
	v_mul_f32_e32 v23, 0x3fb8aa3b, v23
	v_sub_f32_e32 v24, v37, v32
	v_exp_f32_e32 v23, v23
	v_mul_f32_e32 v24, 0x3fb8aa3b, v24
	v_exp_f32_e32 v24, v24
	v_exp_f32_e32 v25, v25
	v_add_f32_e32 v26, 0, v22
	v_add_f32_e32 v26, v23, v26
	v_add_f32_e32 v26, v24, v26
	v_add_f32_e32 v31, v25, v26
	v_sub_f32_e32 v26, v33, v32
	v_mul_f32_e32 v26, 0x3fb8aa3b, v26
	v_sub_f32_e32 v27, v28, v32
	v_exp_f32_e32 v26, v26
	v_mul_f32_e32 v27, 0x3fb8aa3b, v27
	v_sub_f32_e32 v28, v41, v32
	v_exp_f32_e32 v27, v27
	v_mul_f32_e32 v28, 0x3fb8aa3b, v28
	v_sub_f32_e32 v29, v30, v32
	v_exp_f32_e32 v28, v28
	v_mul_f32_e32 v29, 0x3fb8aa3b, v29
	v_exp_f32_e32 v29, v29
	v_add_f32_e32 v30, v26, v31
	v_add_f32_e32 v30, v27, v30
	v_add_f32_e32 v30, v28, v30
	v_add_f32_e32 v30, v29, v30
	ds_bpermute_b32 v31, v123, v30
	v_lshrrev_b32_e32 v42, 1, v43
	v_and_b32_e32 v32, 24, v42
	v_lshrrev_b32_e32 v19, v32, v19
	v_lshlrev_b32_e32 v19, 7, v19
	s_waitcnt lgkmcnt(0)
	v_add_f32_e32 v30, v30, v31
	v_div_scale_f32 v31, s[12:13], v30, v30, 1.0
	v_rcp_f32_e32 v32, v31
	v_lshlrev_b32_e32 v33, 3, v43
	v_and_b32_e32 v19, 0x7f80, v19
	v_lshrrev_b32_e32 v18, v33, v18
	v_and_or_b32 v33, v18, s3, v19
	v_fma_f32 v18, -v31, v32, 1.0
	v_fmac_f32_e32 v32, v18, v32
	v_div_scale_f32 v18, vcc, 1.0, v30, 1.0
	v_mul_f32_e32 v19, v18, v32
	v_fma_f32 v34, -v31, v19, v18
	v_fmac_f32_e32 v19, v34, v32
	v_fma_f32 v18, -v31, v19, v18
	v_div_fmas_f32 v18, v18, v32, v19
	v_div_fixup_f32 v30, v18, v30, 1.0
	v_mov_b32_e32 v18, v1
	v_lshl_or_b32 v20, v20, 16, v39
	v_lshrrev_b32_e32 v19, 3, v18
	v_and_or_b32 v19, v19, 3, s57
	v_lshlrev_b32_e32 v31, 4, v18
	v_ashrrev_i32_e32 v18, 2, v18
	v_lshlrev_b32_e32 v19, 7, v19
	v_and_b32_e32 v31, 0x70, v31
	v_and_b32_e32 v18, -8, v18
	v_add3_u32 v18, v18, v31, v19
	v_lshl_add_u32 v31, v18, 1, s11
	v_lshl_add_u32 v32, v18, 2, s69
	v_lshl_or_b32 v18, v35, 16, v40
	v_lshl_or_b32 v19, v36, 16, v38
	v_lshl_or_b32 v21, v33, 16, v21
	ds_write_b128 v31, v[18:21]
	v_pk_mul_f32 v[20:21], v[24:25], v[30:31] op_sel_hi:[1,0]
	v_pk_mul_f32 v[18:19], v[22:23], v[30:31] op_sel_hi:[1,0]
	ds_write_b128 v32, v[18:21]
	v_pk_mul_f32 v[20:21], v[28:29], v[30:31] op_sel_hi:[1,0]
	v_pk_mul_f32 v[18:19], v[26:27], v[30:31] op_sel_hi:[1,0]
	ds_write_b128 v32, v[18:21] offset:16
	v_xor_b32_e32 v18, 4, v112
	v_cmp_lt_i32_e32 vcc, v18, v122
	s_waitcnt lgkmcnt(0)
	s_barrier
	v_cndmask_b32_e32 v18, v112, v18, vcc
	v_lshlrev_b32_e32 v30, 2, v18
	v_xor_b32_e32 v18, 2, v112
	v_cmp_lt_i32_e32 vcc, v18, v122
	s_nop 1
	v_cndmask_b32_e32 v18, v112, v18, vcc
	v_lshlrev_b32_e32 v31, 2, v18
	v_xor_b32_e32 v18, 1, v112
	v_cmp_lt_i32_e32 vcc, v18, v122
	s_nop 1
	v_cndmask_b32_e32 v18, v112, v18, vcc
	v_lshlrev_b32_e32 v32, 2, v18
	v_lshlrev_b32_e32 v56, 4, v1
	v_and_b32_e32 v56, 0x70, v56
	v_lshrrev_b32_e32 v59, 3, v1
	v_lshlrev_b32_e32 v59, 5, v59
	v_add_u32_e32 v59, s66, v59
	v_add_u32_e32 v59, -16, v59
	v_lshl_add_u32 v60, v1, 3, s64
	v_and_b32_e32 v38, 4, v1
	v_cmp_ne_u32_e64 s[10:11], 0, v38
	v_and_b32_e32 v38, 2, v1
	v_cmp_ne_u32_e64 s[12:13], 0, v38
	v_and_b32_e32 v38, 1, v1
	v_cmp_ne_u32_e64 s[14:15], 0, v38
	s_movk_i32 s94, 0x80
	s_mov_b32 s42, 0
	s_mov_b32 s43, 0
	s_mov_b32 s44, 1
	s_mov_b32 s45, 0
	s_lshl_b32 s32, s42, 11
	v_add_u32_e32 v39, s32, v59
	ds_read_b128 v[202:205], v39
	ds_read_b128 v[206:209], v39 offset:16
	s_lshl_b32 s46, s42, 3
	s_add_i32 s46, s46, s40
	s_lshl_b32 s46, s46, 9
	s_lshl_b32 s32, s43, 7
	s_add_i32 s46, s46, s32
	v_add_u32_e32 v57, s46, v56
	global_load_dwordx4 v[186:189], v57, s[34:35]
	global_load_dwordx4 v[190:193], v57, s[36:37]
	v_mov_b32_e32 v58, v56
	s_waitcnt lgkmcnt(0)
	v_and_b32_e32 v38, 0xffff, v202
	v_lshl_add_u32 v38, v38, 7, v58
	global_load_dwordx4 v[122:125], v38, s[96:97]
	v_lshrrev_b32_e32 v38, 16, v202
	v_lshl_add_u32 v38, v38, 7, v58
	global_load_dwordx4 v[126:129], v38, s[96:97]
	v_and_b32_e32 v38, 0xffff, v203
	v_lshl_add_u32 v38, v38, 7, v58
	global_load_dwordx4 v[130:133], v38, s[96:97]
	v_lshrrev_b32_e32 v38, 16, v203
	v_lshl_add_u32 v38, v38, 7, v58
	global_load_dwordx4 v[134:137], v38, s[96:97]
	v_and_b32_e32 v38, 0xffff, v204
	v_lshl_add_u32 v38, v38, 7, v58
	global_load_dwordx4 v[138:141], v38, s[96:97]
	v_lshrrev_b32_e32 v38, 16, v204
	v_lshl_add_u32 v38, v38, 7, v58
	global_load_dwordx4 v[142:145], v38, s[96:97]
	v_and_b32_e32 v38, 0xffff, v205
	v_lshl_add_u32 v38, v38, 7, v58
	global_load_dwordx4 v[146:149], v38, s[96:97]
	v_lshrrev_b32_e32 v38, 16, v205
	v_lshl_add_u32 v38, v38, 7, v58
	global_load_dwordx4 v[150:153], v38, s[96:97]
	v_and_b32_e32 v38, 0xffff, v206
	v_lshl_add_u32 v38, v38, 7, v58
	global_load_dwordx4 v[154:157], v38, s[96:97]
	v_lshrrev_b32_e32 v38, 16, v206
	v_lshl_add_u32 v38, v38, 7, v58
	global_load_dwordx4 v[158:161], v38, s[96:97]
	v_and_b32_e32 v38, 0xffff, v207
	v_lshl_add_u32 v38, v38, 7, v58
	global_load_dwordx4 v[162:165], v38, s[96:97]
	v_lshrrev_b32_e32 v38, 16, v207
	v_lshl_add_u32 v38, v38, 7, v58
	global_load_dwordx4 v[166:169], v38, s[96:97]
	v_and_b32_e32 v38, 0xffff, v208
	v_lshl_add_u32 v38, v38, 7, v58
	global_load_dwordx4 v[170:173], v38, s[96:97]
	v_lshrrev_b32_e32 v38, 16, v208
	v_lshl_add_u32 v38, v38, 7, v58
	global_load_dwordx4 v[174:177], v38, s[96:97]
	v_and_b32_e32 v38, 0xffff, v209
	v_lshl_add_u32 v38, v38, 7, v58
	global_load_dwordx4 v[178:181], v38, s[96:97]
	v_lshrrev_b32_e32 v38, 16, v209
	v_lshl_add_u32 v38, v38, 7, v58
	global_load_dwordx4 v[182:185], v38, s[96:97]
	s_mov_b32 s47, 15

; #define LAS __attribute__((address_space(3)))
; __device__ __forceinline__ unsigned xb_ld(unsigned* p)              { return __hip_atomic_load(p, __ATOMIC_RELAXED, __HIP_MEMORY_SCOPE_AGENT); }
; #define XB_SPIN(cond, bar) do { unsigned _sp = 0; while (cond) { __builtin_amdgcn_s_sleep(1); \
;     if ((++_sp & 255u) == 0u) { if (xb_ld(&(bar)[XB_TMO])) break; if (_sp > XB_SPIN_CAP) { atomicAdd(&(bar)[XB_TMO], 1u); break; } } } } while (0)
; __global__ void __launch_bounds__(NTHR, 2) k_main(Args a) {
;     ...
;             for (int it = 0; it < 8; ++it) {
;                 const int tl = it * 8 + wave, t = j * 64 + tl;
;                 const unsigned ew = *(const LAS unsigned*)(EL + tl * 128 + 2 * lane); const int e0 = (int)(ew & 0xffffu), e1 = (int)(ew >> 16);
;                 typedef int i2v __attribute__((ext_vector_type(2))); const i2v si = *(const LAS i2v*)(ACC + tl * 128 + 2 * lane);
;                 typedef float f2v __attribute__((ext_vector_type(2))); const f2v gt = *(const LAS f2v*)(GL + tl * 128 + 2 * lane); const float xs = XS[t];
;                 const int sx = ((const int*)(XS + T))[t];
;                 const float z0 = (float)(2 * si.x + sx) * SU[e0] * xs, z1 = (float)(2 * si.y + sx) * SU[e1] * xs;
;                 const float a0 = gt.x * gelu_as(z0) * SV[e0], a1 = gt.y * gelu_as(z1) * SV[e1];
;     ...
;             if (tid == 0) XB_SPIN(xb_ld(&((unsigned*)ws)[14400]) < (unsigned)((T / 256) * (D / 256)), (unsigned*)ws);
.LBB0_674:
	s_ashr_i32 s41, s40, 31
	s_lshl_b64 s[10:11], s[40:41], 2
	s_add_u32 s14, s90, s10
	s_addc_u32 s15, s91, s11
	v_readlane_b32 s42, v235, 36
	v_readlane_b32 s43, v235, 37
	global_load_dword v78, v83, s[38:39] sc1
	v_add_u32_e32 v74, 0x16000, v91
	v_mov_b32_e32 v77, 3
	ds_read_b32 v18, v92
	ds_read_b32 v19, v92 offset:2048
	ds_read_b32 v20, v92 offset:4096
	ds_read_b32 v21, v92 offset:6144
	ds_read_b32 v22, v92 offset:8192
	ds_read_b32 v23, v92 offset:10240
	ds_read_b32 v24, v92 offset:12288
	ds_read_b32 v25, v92 offset:14336
	ds_read_b64 v[26:27], v91
	ds_read_b64 v[42:43], v74
	ds_read_b64 v[28:29], v91 offset:4096
	ds_read_b64 v[44:45], v74 offset:4096
	ds_read_b64 v[30:31], v91 offset:8192
	ds_read_b64 v[46:47], v74 offset:8192
	ds_read_b64 v[32:33], v91 offset:12288
	ds_read_b64 v[48:49], v74 offset:12288
	ds_read_b64 v[34:35], v91 offset:16384
	ds_read_b64 v[50:51], v74 offset:16384
	ds_read_b64 v[36:37], v91 offset:20480
	ds_read_b64 v[52:53], v74 offset:20480
	ds_read_b64 v[38:39], v91 offset:24576
	ds_read_b64 v[54:55], v74 offset:24576
	ds_read_b64 v[40:41], v91 offset:28672
	ds_read_b64 v[56:57], v74 offset:28672
	global_load_dword v58, v109, s[14:15]
	global_load_dword v66, v108, s[14:15]
	global_load_dword v59, v109, s[14:15] offset:32
	global_load_dword v67, v108, s[14:15] offset:32
	global_load_dword v60, v109, s[14:15] offset:64
	global_load_dword v68, v108, s[14:15] offset:64
	global_load_dword v61, v109, s[14:15] offset:96
	global_load_dword v69, v108, s[14:15] offset:96
	global_load_dword v62, v109, s[14:15] offset:128
	global_load_dword v70, v108, s[14:15] offset:128
	global_load_dword v63, v109, s[14:15] offset:160
	global_load_dword v71, v108, s[14:15] offset:160
	global_load_dword v64, v109, s[14:15] offset:192
	global_load_dword v72, v108, s[14:15] offset:192
	global_load_dword v65, v109, s[14:15] offset:224
	global_load_dword v73, v108, s[14:15] offset:224
	s_waitcnt lgkmcnt(0)
	v_lshlrev_b32_sdwa v75, v77, v18 dst_sel:DWORD dst_unused:UNUSED_PAD src0_sel:DWORD src1_sel:WORD_0
	v_lshlrev_b32_sdwa v76, v77, v18 dst_sel:DWORD dst_unused:UNUSED_PAD src0_sel:DWORD src1_sel:WORD_1
	s_nop 1
	global_load_dwordx2 v[122:123], v75, s[42:43]
	global_load_dwordx2 v[138:139], v76, s[42:43]
	v_lshlrev_b32_sdwa v75, v77, v19 dst_sel:DWORD dst_unused:UNUSED_PAD src0_sel:DWORD src1_sel:WORD_0
	v_lshlrev_b32_sdwa v76, v77, v19 dst_sel:DWORD dst_unused:UNUSED_PAD src0_sel:DWORD src1_sel:WORD_1
	s_nop 1
	global_load_dwordx2 v[124:125], v75, s[42:43]
	global_load_dwordx2 v[140:141], v76, s[42:43]
	v_lshlrev_b32_sdwa v75, v77, v20 dst_sel:DWORD dst_unused:UNUSED_PAD src0_sel:DWORD src1_sel:WORD_0
	v_lshlrev_b32_sdwa v76, v77, v20 dst_sel:DWORD dst_unused:UNUSED_PAD src0_sel:DWORD src1_sel:WORD_1
	s_nop 1
	global_load_dwordx2 v[126:127], v75, s[42:43]
	global_load_dwordx2 v[142:143], v76, s[42:43]
	v_lshlrev_b32_sdwa v75, v77, v21 dst_sel:DWORD dst_unused:UNUSED_PAD src0_sel:DWORD src1_sel:WORD_0
	v_lshlrev_b32_sdwa v76, v77, v21 dst_sel:DWORD dst_unused:UNUSED_PAD src0_sel:DWORD src1_sel:WORD_1
	s_nop 1
	global_load_dwordx2 v[128:129], v75, s[42:43]
	global_load_dwordx2 v[144:145], v76, s[42:43]
	v_lshlrev_b32_sdwa v75, v77, v22 dst_sel:DWORD dst_unused:UNUSED_PAD src0_sel:DWORD src1_sel:WORD_0
	v_lshlrev_b32_sdwa v76, v77, v22 dst_sel:DWORD dst_unused:UNUSED_PAD src0_sel:DWORD src1_sel:WORD_1
	s_nop 1
	global_load_dwordx2 v[130:131], v75, s[42:43]
	global_load_dwordx2 v[146:147], v76, s[42:43]
	v_lshlrev_b32_sdwa v75, v77, v23 dst_sel:DWORD dst_unused:UNUSED_PAD src0_sel:DWORD src1_sel:WORD_0
	v_lshlrev_b32_sdwa v76, v77, v23 dst_sel:DWORD dst_unused:UNUSED_PAD src0_sel:DWORD src1_sel:WORD_1
	s_nop 1
	global_load_dwordx2 v[132:133], v75, s[42:43]
	global_load_dwordx2 v[148:149], v76, s[42:43]
	v_lshlrev_b32_sdwa v75, v77, v24 dst_sel:DWORD dst_unused:UNUSED_PAD src0_sel:DWORD src1_sel:WORD_0
	v_lshlrev_b32_sdwa v76, v77, v24 dst_sel:DWORD dst_unused:UNUSED_PAD src0_sel:DWORD src1_sel:WORD_1
	s_nop 1
	global_load_dwordx2 v[134:135], v75, s[42:43]
	global_load_dwordx2 v[150:151], v76, s[42:43]
	v_lshlrev_b32_sdwa v75, v77, v25 dst_sel:DWORD dst_unused:UNUSED_PAD src0_sel:DWORD src1_sel:WORD_0
	v_lshlrev_b32_sdwa v76, v77, v25 dst_sel:DWORD dst_unused:UNUSED_PAD src0_sel:DWORD src1_sel:WORD_1
	s_nop 1
	global_load_dwordx2 v[136:137], v75, s[42:43]
	global_load_dwordx2 v[152:153], v76, s[42:43]
	s_waitcnt vmcnt(14)
; #define LAS __attribute__((address_space(3)))
; __device__ __forceinline__ float gelu_as(float z) {
;     const float ax = fabsf(z) * 0.70710678118654752f, t = __builtin_amdgcn_rcpf(1.f + 0.3275911f * ax);
;     const float poly = t * (0.254829592f + t * (-0.284496736f + t * (1.421413741f + t * (-1.453152027f + t * 1.061405429f))));
;     const float er = 1.f - poly * __expf(-ax * ax);
;     return 0.5f * z * (1.f + copysignf(er, z));
; }
; __global__ void __launch_bounds__(NTHR, 2) k_main(Args a) {
;     ...
;                 const unsigned ew = *(const LAS unsigned*)(EL + tl * 128 + 2 * lane); const int e0 = (int)(ew & 0xffffu), e1 = (int)(ew >> 16);
;                 typedef int i2v __attribute__((ext_vector_type(2))); const i2v si = *(const LAS i2v*)(ACC + tl * 128 + 2 * lane);
;                 typedef float f2v __attribute__((ext_vector_type(2))); const f2v gt = *(const LAS f2v*)(GL + tl * 128 + 2 * lane); const float xs = XS[t];
;                 const int sx = ((const int*)(XS + T))[t];
;                 const float z0 = (float)(2 * si.x + sx) * SU[e0] * xs, z1 = (float)(2 * si.y + sx) * SU[e1] * xs;
;                 const float a0 = gt.x * gelu_as(z0) * SV[e0], a1 = gt.y * gelu_as(z1) * SV[e1];
;                 const float mx = wave_max_dpp(fmaxf(fabsf(a0), fabsf(a1)));
;                 const float sc = mx > 0.f ? mx * (1.f / 119.f) : 1.f, inv = 1.f / sc;
;                 const int q0 = (int)rintf(a0 * inv), q1 = (int)rintf(a1 * inv);
;                 *(LAS unsigned short*)(AL + tl * 128 + 2 * lane) = (unsigned short)((q0 & 255) | ((q1 & 255) << 8));
;                 const int qs = wave_sum_dpp_i(q0 + q1);
;                 if (lane == 0) { ASC[tl] = sc; SAL[tl] = qs; }
	v_lshl_add_u32 v154, v26, 1, v58
	v_lshl_add_u32 v155, v27, 1, v58
	v_cvt_f32_i32_e32 v154, v154
	v_cvt_f32_i32_e32 v155, v155
	v_mul_f32_e32 v154, v122, v154
	v_mul_f32_e32 v155, v138, v155
	v_mul_f32_e32 v154, v66, v154
	v_mul_f32_e32 v155, v66, v155
	v_mul_f32_e64 v156, |v154|, s82
	v_mul_f32_e64 v157, |v155|, s82
	v_fma_f32 v158, v156, s83, 1.0
	v_fma_f32 v159, v157, s83, 1.0
	v_rcp_f32_e32 v158, v158
	v_rcp_f32_e32 v159, v159
	v_mul_f32_e64 v156, v156, -v156
	v_mul_f32_e64 v157, v157, -v157
	v_mul_f32_e32 v156, 0x3fb8aa3b, v156
	v_mul_f32_e32 v157, 0x3fb8aa3b, v157
	v_fmamk_f32 v160, v158, 0x3f87dc22, v110
	v_fmamk_f32 v161, v159, 0x3f87dc22, v110
	v_exp_f32_e32 v156, v156
	v_exp_f32_e32 v157, v157
	v_fmaak_f32 v160, v158, v160, 0x3fb5f0e3
	v_fmaak_f32 v161, v159, v161, 0x3fb5f0e3
	v_fmaak_f32 v160, v158, v160, 0xbe91a98e
	v_fmaak_f32 v161, v159, v161, 0xbe91a98e
	v_fmaak_f32 v160, v158, v160, 0x3e827906
	v_fmaak_f32 v161, v159, v161, 0x3e827906
	v_mul_f32_e32 v158, v158, v160
	v_mul_f32_e32 v159, v159, v161
	v_fma_f32 v156, -v156, v158, 1.0
	v_fma_f32 v157, -v157, v159, 1.0
	v_mul_f32_e32 v162, 0.5, v154
	v_mul_f32_e32 v163, 0.5, v155
	v_bfi_b32 v154, s84, v156, v154
	v_bfi_b32 v155, s84, v157, v155
	v_add_f32_e32 v154, 1.0, v154
	v_add_f32_e32 v155, 1.0, v155
	v_mul_f32_e32 v154, v162, v154
	v_mul_f32_e32 v155, v163, v155
	v_mul_f32_e32 v154, v42, v154
	v_mul_f32_e32 v155, v43, v155
	v_mul_f32_e32 v154, v123, v154
	v_mul_f32_e32 v155, v139, v155
	v_max_f32_e64 v164, |v154|, |v155|
	s_nop 1
	v_max_f32_dpp v164, v164, v164 quad_perm:[1,0,3,2] row_mask:0xf bank_mask:0xf
	s_nop 1
	v_max_f32_dpp v164, v164, v164 quad_perm:[2,3,0,1] row_mask:0xf bank_mask:0xf
	s_nop 1
	v_max_f32_dpp v164, v164, v164 row_half_mirror row_mask:0xf bank_mask:0xf
	s_nop 1
	v_max_f32_dpp v164, v164, v164 row_mirror row_mask:0xf bank_mask:0xf
	s_nop 1
	v_readlane_b32 s46, v164, 32
	v_readlane_b32 s47, v164, 48
	v_readlane_b32 s12, v164, 0
	v_readlane_b32 s13, v164, 16
	s_nop 1
	v_mov_b32_e32 v164, s47
	v_max_f32_e32 v164, s46, v164
	v_mov_b32_e32 v165, s13
	v_max3_f32 v164, s12, v165, v164
	v_mul_f32_e32 v165, 0x3c09ae41, v164
	v_cmp_lt_f32_e32 vcc, 0, v164
	s_nop 1
	v_cndmask_b32_e32 v164, 1.0, v165, vcc
	v_div_scale_f32 v166, s[12:13], v164, v164, 1.0
	v_rcp_f32_e32 v167, v166
	v_div_scale_f32 v168, vcc, 1.0, v164, 1.0
	v_fma_f32 v169, -v166, v167, 1.0
	v_fmac_f32_e32 v167, v169, v167
	v_mul_f32_e32 v169, v168, v167
	v_fma_f32 v170, -v166, v169, v168
	v_fmac_f32_e32 v169, v170, v167
	v_fma_f32 v166, -v166, v169, v168
	v_div_fmas_f32 v166, v166, v167, v169
	v_div_fixup_f32 v166, v166, v164, 1.0
	v_mul_f32_e32 v154, v166, v154
	v_mul_f32_e32 v155, v166, v155
	v_rndne_f32_e32 v154, v154
	v_rndne_f32_e32 v155, v155
	v_cvt_i32_f32_e32 v154, v154
	v_cvt_i32_f32_e32 v155, v155
	v_perm_b32 v167, v155, v154, s85
	v_add_u32_e32 v154, v154, v155
	ds_write_b16 v90, v167
	s_nop 1
	v_add_u32_dpp v154, v154, v154 quad_perm:[1,0,3,2] row_mask:0xf bank_mask:0xf bound_ctrl:1
	s_nop 1
	v_add_u32_dpp v154, v154, v154 quad_perm:[2,3,0,1] row_mask:0xf bank_mask:0xf bound_ctrl:1
	s_nop 1
	v_add_u32_dpp v154, v154, v154 row_half_mirror row_mask:0xf bank_mask:0xf bound_ctrl:1
	s_nop 1
	v_add_u32_dpp v154, v154, v154 row_mirror row_mask:0xf bank_mask:0xf bound_ctrl:1
	s_nop 1
	v_readlane_b32 s46, v154, 0
	v_readlane_b32 s47, v154, 16
	v_readlane_b32 s12, v154, 32
	v_readlane_b32 s13, v154, 48
	s_nop 1
	s_add_i32 s46, s47, s46
	s_add_i32 s46, s46, s12
	s_add_i32 s46, s46, s13
	s_mov_b32 s47, s67
	s_and_saveexec_b64 s[12:13], s[8:9]
	v_mov_b32_e32 v154, s47
	v_mov_b32_e32 v155, s46
	ds_write2st64_b32 v154, v164, v155 offset1:1
	s_or_b64 exec, exec, s[12:13]
	s_waitcnt vmcnt(12)
	v_lshl_add_u32 v154, v28, 1, v59
	v_lshl_add_u32 v155, v29, 1, v59
	v_cvt_f32_i32_e32 v154, v154
	v_cvt_f32_i32_e32 v155, v155
	v_mul_f32_e32 v154, v124, v154
	v_mul_f32_e32 v155, v140, v155
	v_mul_f32_e32 v154, v67, v154
	v_mul_f32_e32 v155, v67, v155
	v_mul_f32_e64 v156, |v154|, s82
	v_mul_f32_e64 v157, |v155|, s82
	v_fma_f32 v158, v156, s83, 1.0
	v_fma_f32 v159, v157, s83, 1.0
	v_rcp_f32_e32 v158, v158
	v_rcp_f32_e32 v159, v159
	v_mul_f32_e64 v156, v156, -v156
	v_mul_f32_e64 v157, v157, -v157
	v_mul_f32_e32 v156, 0x3fb8aa3b, v156
	v_mul_f32_e32 v157, 0x3fb8aa3b, v157
	v_fmamk_f32 v160, v158, 0x3f87dc22, v110
	v_fmamk_f32 v161, v159, 0x3f87dc22, v110
	v_exp_f32_e32 v156, v156
	v_exp_f32_e32 v157, v157
	v_fmaak_f32 v160, v158, v160, 0x3fb5f0e3
	v_fmaak_f32 v161, v159, v161, 0x3fb5f0e3
	v_fmaak_f32 v160, v158, v160, 0xbe91a98e
	v_fmaak_f32 v161, v159, v161, 0xbe91a98e
	v_fmaak_f32 v160, v158, v160, 0x3e827906
	v_fmaak_f32 v161, v159, v161, 0x3e827906
	v_mul_f32_e32 v158, v158, v160
	v_mul_f32_e32 v159, v159, v161
	v_fma_f32 v156, -v156, v158, 1.0
	v_fma_f32 v157, -v157, v159, 1.0
	v_mul_f32_e32 v162, 0.5, v154
	v_mul_f32_e32 v163, 0.5, v155
	v_bfi_b32 v154, s84, v156, v154
	v_bfi_b32 v155, s84, v157, v155
	v_add_f32_e32 v154, 1.0, v154
	v_add_f32_e32 v155, 1.0, v155
	v_mul_f32_e32 v154, v162, v154
	v_mul_f32_e32 v155, v163, v155
	v_mul_f32_e32 v154, v44, v154
	v_mul_f32_e32 v155, v45, v155
	v_mul_f32_e32 v154, v125, v154
	v_mul_f32_e32 v155, v141, v155
	v_max_f32_e64 v164, |v154|, |v155|
	s_nop 1
	v_max_f32_dpp v164, v164, v164 quad_perm:[1,0,3,2] row_mask:0xf bank_mask:0xf
	s_nop 1
	v_max_f32_dpp v164, v164, v164 quad_perm:[2,3,0,1] row_mask:0xf bank_mask:0xf
	s_nop 1
	v_max_f32_dpp v164, v164, v164 row_half_mirror row_mask:0xf bank_mask:0xf
	s_nop 1
	v_max_f32_dpp v164, v164, v164 row_mirror row_mask:0xf bank_mask:0xf
	s_nop 1
	v_readlane_b32 s46, v164, 32
	v_readlane_b32 s47, v164, 48
	v_readlane_b32 s12, v164, 0
; #define LAS __attribute__((address_space(3)))
; __device__ __forceinline__ float gelu_as(float z) {
;     const float ax = fabsf(z) * 0.70710678118654752f, t = __builtin_amdgcn_rcpf(1.f + 0.3275911f * ax);
;     const float poly = t * (0.254829592f + t * (-0.284496736f + t * (1.421413741f + t * (-1.453152027f + t * 1.061405429f))));
;     const float er = 1.f - poly * __expf(-ax * ax);
;     return 0.5f * z * (1.f + copysignf(er, z));
; }
; __global__ void __launch_bounds__(NTHR, 2) k_main(Args a) {
;     ...
;                 const unsigned ew = *(const LAS unsigned*)(EL + tl * 128 + 2 * lane); const int e0 = (int)(ew & 0xffffu), e1 = (int)(ew >> 16);
;                 typedef int i2v __attribute__((ext_vector_type(2))); const i2v si = *(const LAS i2v*)(ACC + tl * 128 + 2 * lane);
;                 typedef float f2v __attribute__((ext_vector_type(2))); const f2v gt = *(const LAS f2v*)(GL + tl * 128 + 2 * lane); const float xs = XS[t];
;                 const int sx = ((const int*)(XS + T))[t];
;                 const float z0 = (float)(2 * si.x + sx) * SU[e0] * xs, z1 = (float)(2 * si.y + sx) * SU[e1] * xs;
;                 const float a0 = gt.x * gelu_as(z0) * SV[e0], a1 = gt.y * gelu_as(z1) * SV[e1];
;                 const float mx = wave_max_dpp(fmaxf(fabsf(a0), fabsf(a1)));
;                 const float sc = mx > 0.f ? mx * (1.f / 119.f) : 1.f, inv = 1.f / sc;
;                 const int q0 = (int)rintf(a0 * inv), q1 = (int)rintf(a1 * inv);
;                 *(LAS unsigned short*)(AL + tl * 128 + 2 * lane) = (unsigned short)((q0 & 255) | ((q1 & 255) << 8));
;                 const int qs = wave_sum_dpp_i(q0 + q1);
;                 if (lane == 0) { ASC[tl] = sc; SAL[tl] = qs; }
	v_readlane_b32 s13, v164, 16
	s_nop 1
	v_mov_b32_e32 v164, s47
	v_max_f32_e32 v164, s46, v164
	v_mov_b32_e32 v165, s13
	v_max3_f32 v164, s12, v165, v164
	v_mul_f32_e32 v165, 0x3c09ae41, v164
	v_cmp_lt_f32_e32 vcc, 0, v164
	s_nop 1
	v_cndmask_b32_e32 v164, 1.0, v165, vcc
	v_div_scale_f32 v166, s[12:13], v164, v164, 1.0
	v_rcp_f32_e32 v167, v166
	v_div_scale_f32 v168, vcc, 1.0, v164, 1.0
	v_fma_f32 v169, -v166, v167, 1.0
	v_fmac_f32_e32 v167, v169, v167
	v_mul_f32_e32 v169, v168, v167
	v_fma_f32 v170, -v166, v169, v168
	v_fmac_f32_e32 v169, v170, v167
	v_fma_f32 v166, -v166, v169, v168
	v_div_fmas_f32 v166, v166, v167, v169
	v_div_fixup_f32 v166, v166, v164, 1.0
	v_mul_f32_e32 v154, v166, v154
	v_mul_f32_e32 v155, v166, v155
	v_rndne_f32_e32 v154, v154
	v_rndne_f32_e32 v155, v155
	v_cvt_i32_f32_e32 v154, v154
	v_cvt_i32_f32_e32 v155, v155
	v_perm_b32 v167, v155, v154, s85
	v_add_u32_e32 v154, v154, v155
	ds_write_b16 v90, v167 offset:1024
	s_nop 1
	v_add_u32_dpp v154, v154, v154 quad_perm:[1,0,3,2] row_mask:0xf bank_mask:0xf bound_ctrl:1
	s_nop 1
	v_add_u32_dpp v154, v154, v154 quad_perm:[2,3,0,1] row_mask:0xf bank_mask:0xf bound_ctrl:1
	s_nop 1
	v_add_u32_dpp v154, v154, v154 row_half_mirror row_mask:0xf bank_mask:0xf bound_ctrl:1
	s_nop 1
	v_add_u32_dpp v154, v154, v154 row_mirror row_mask:0xf bank_mask:0xf bound_ctrl:1
	s_nop 1
	v_readlane_b32 s46, v154, 0
	v_readlane_b32 s47, v154, 16
	v_readlane_b32 s12, v154, 32
	v_readlane_b32 s13, v154, 48
	s_nop 1
	s_add_i32 s46, s47, s46
	s_add_i32 s46, s46, s12
	s_add_i32 s46, s46, s13
	s_add_i32 s47, s67, 32
	s_and_saveexec_b64 s[12:13], s[8:9]
	v_mov_b32_e32 v154, s47
	v_mov_b32_e32 v155, s46
	ds_write2st64_b32 v154, v164, v155 offset1:1
	s_or_b64 exec, exec, s[12:13]
	s_waitcnt vmcnt(10)
	v_lshl_add_u32 v154, v30, 1, v60
	v_lshl_add_u32 v155, v31, 1, v60
	v_cvt_f32_i32_e32 v154, v154
	v_cvt_f32_i32_e32 v155, v155
	v_mul_f32_e32 v154, v126, v154
	v_mul_f32_e32 v155, v142, v155
	v_mul_f32_e32 v154, v68, v154
	v_mul_f32_e32 v155, v68, v155
	v_mul_f32_e64 v156, |v154|, s82
	v_mul_f32_e64 v157, |v155|, s82
	v_fma_f32 v158, v156, s83, 1.0
	v_fma_f32 v159, v157, s83, 1.0
	v_rcp_f32_e32 v158, v158
	v_rcp_f32_e32 v159, v159
	v_mul_f32_e64 v156, v156, -v156
	v_mul_f32_e64 v157, v157, -v157
	v_mul_f32_e32 v156, 0x3fb8aa3b, v156
	v_mul_f32_e32 v157, 0x3fb8aa3b, v157
	v_fmamk_f32 v160, v158, 0x3f87dc22, v110
	v_fmamk_f32 v161, v159, 0x3f87dc22, v110
	v_exp_f32_e32 v156, v156
	v_exp_f32_e32 v157, v157
	v_fmaak_f32 v160, v158, v160, 0x3fb5f0e3
	v_fmaak_f32 v161, v159, v161, 0x3fb5f0e3
	v_fmaak_f32 v160, v158, v160, 0xbe91a98e
	v_fmaak_f32 v161, v159, v161, 0xbe91a98e
	v_fmaak_f32 v160, v158, v160, 0x3e827906
	v_fmaak_f32 v161, v159, v161, 0x3e827906
	v_mul_f32_e32 v158, v158, v160
	v_mul_f32_e32 v159, v159, v161
	v_fma_f32 v156, -v156, v158, 1.0
	v_fma_f32 v157, -v157, v159, 1.0
	v_mul_f32_e32 v162, 0.5, v154
	v_mul_f32_e32 v163, 0.5, v155
	v_bfi_b32 v154, s84, v156, v154
	v_bfi_b32 v155, s84, v157, v155
	v_add_f32_e32 v154, 1.0, v154
	v_add_f32_e32 v155, 1.0, v155
	v_mul_f32_e32 v154, v162, v154
	v_mul_f32_e32 v155, v163, v155
	v_mul_f32_e32 v154, v46, v154
	v_mul_f32_e32 v155, v47, v155
	v_mul_f32_e32 v154, v127, v154
	v_mul_f32_e32 v155, v143, v155
	v_max_f32_e64 v164, |v154|, |v155|
	s_nop 1
	v_max_f32_dpp v164, v164, v164 quad_perm:[1,0,3,2] row_mask:0xf bank_mask:0xf
	s_nop 1
	v_max_f32_dpp v164, v164, v164 quad_perm:[2,3,0,1] row_mask:0xf bank_mask:0xf
	s_nop 1
	v_max_f32_dpp v164, v164, v164 row_half_mirror row_mask:0xf bank_mask:0xf
	s_nop 1
	v_max_f32_dpp v164, v164, v164 row_mirror row_mask:0xf bank_mask:0xf
	s_nop 1
	v_readlane_b32 s46, v164, 32
	v_readlane_b32 s47, v164, 48
	v_readlane_b32 s12, v164, 0
	v_readlane_b32 s13, v164, 16
	s_nop 1
	v_mov_b32_e32 v164, s47
	v_max_f32_e32 v164, s46, v164
	v_mov_b32_e32 v165, s13
	v_max3_f32 v164, s12, v165, v164
	v_mul_f32_e32 v165, 0x3c09ae41, v164
	v_cmp_lt_f32_e32 vcc, 0, v164
	s_nop 1
	v_cndmask_b32_e32 v164, 1.0, v165, vcc
	v_div_scale_f32 v166, s[12:13], v164, v164, 1.0
	v_rcp_f32_e32 v167, v166
	v_div_scale_f32 v168, vcc, 1.0, v164, 1.0
	v_fma_f32 v169, -v166, v167, 1.0
	v_fmac_f32_e32 v167, v169, v167
	v_mul_f32_e32 v169, v168, v167
	v_fma_f32 v170, -v166, v169, v168
	v_fmac_f32_e32 v169, v170, v167
	v_fma_f32 v166, -v166, v169, v168
	v_div_fmas_f32 v166, v166, v167, v169
	v_div_fixup_f32 v166, v166, v164, 1.0
	v_mul_f32_e32 v154, v166, v154
	v_mul_f32_e32 v155, v166, v155
	v_rndne_f32_e32 v154, v154
	v_rndne_f32_e32 v155, v155
	v_cvt_i32_f32_e32 v154, v154
	v_cvt_i32_f32_e32 v155, v155
	v_perm_b32 v167, v155, v154, s85
	v_add_u32_e32 v154, v154, v155
	ds_write_b16 v90, v167 offset:2048
	s_nop 1
	v_add_u32_dpp v154, v154, v154 quad_perm:[1,0,3,2] row_mask:0xf bank_mask:0xf bound_ctrl:1
	s_nop 1
	v_add_u32_dpp v154, v154, v154 quad_perm:[2,3,0,1] row_mask:0xf bank_mask:0xf bound_ctrl:1
	s_nop 1
	v_add_u32_dpp v154, v154, v154 row_half_mirror row_mask:0xf bank_mask:0xf bound_ctrl:1
	s_nop 1
	v_add_u32_dpp v154, v154, v154 row_mirror row_mask:0xf bank_mask:0xf bound_ctrl:1
	s_nop 1
	v_readlane_b32 s46, v154, 0
	v_readlane_b32 s47, v154, 16
	v_readlane_b32 s12, v154, 32
	v_readlane_b32 s13, v154, 48
	s_nop 1
	s_add_i32 s46, s47, s46
	s_add_i32 s46, s46, s12
	s_add_i32 s46, s46, s13
	s_add_i32 s47, s67, 64
	s_and_saveexec_b64 s[12:13], s[8:9]
	v_mov_b32_e32 v154, s47
	v_mov_b32_e32 v155, s46
	ds_write2st64_b32 v154, v164, v155 offset1:1
	s_or_b64 exec, exec, s[12:13]
	s_waitcnt vmcnt(8)
; #define LAS __attribute__((address_space(3)))
; __device__ __forceinline__ float gelu_as(float z) {
;     const float ax = fabsf(z) * 0.70710678118654752f, t = __builtin_amdgcn_rcpf(1.f + 0.3275911f * ax);
;     const float poly = t * (0.254829592f + t * (-0.284496736f + t * (1.421413741f + t * (-1.453152027f + t * 1.061405429f))));
;     const float er = 1.f - poly * __expf(-ax * ax);
;     return 0.5f * z * (1.f + copysignf(er, z));
; }
; __global__ void __launch_bounds__(NTHR, 2) k_main(Args a) {
;     ...
;                 const unsigned ew = *(const LAS unsigned*)(EL + tl * 128 + 2 * lane); const int e0 = (int)(ew & 0xffffu), e1 = (int)(ew >> 16);
;                 typedef int i2v __attribute__((ext_vector_type(2))); const i2v si = *(const LAS i2v*)(ACC + tl * 128 + 2 * lane);
;                 typedef float f2v __attribute__((ext_vector_type(2))); const f2v gt = *(const LAS f2v*)(GL + tl * 128 + 2 * lane); const float xs = XS[t];
;                 const int sx = ((const int*)(XS + T))[t];
;                 const float z0 = (float)(2 * si.x + sx) * SU[e0] * xs, z1 = (float)(2 * si.y + sx) * SU[e1] * xs;
;                 const float a0 = gt.x * gelu_as(z0) * SV[e0], a1 = gt.y * gelu_as(z1) * SV[e1];
;                 const float mx = wave_max_dpp(fmaxf(fabsf(a0), fabsf(a1)));
;                 const float sc = mx > 0.f ? mx * (1.f / 119.f) : 1.f, inv = 1.f / sc;
;                 const int q0 = (int)rintf(a0 * inv), q1 = (int)rintf(a1 * inv);
;                 *(LAS unsigned short*)(AL + tl * 128 + 2 * lane) = (unsigned short)((q0 & 255) | ((q1 & 255) << 8));
;                 const int qs = wave_sum_dpp_i(q0 + q1);
;                 if (lane == 0) { ASC[tl] = sc; SAL[tl] = qs; }
	v_lshl_add_u32 v154, v32, 1, v61
	v_lshl_add_u32 v155, v33, 1, v61
	v_cvt_f32_i32_e32 v154, v154
	v_cvt_f32_i32_e32 v155, v155
	v_mul_f32_e32 v154, v128, v154
	v_mul_f32_e32 v155, v144, v155
	v_mul_f32_e32 v154, v69, v154
	v_mul_f32_e32 v155, v69, v155
	v_mul_f32_e64 v156, |v154|, s82
	v_mul_f32_e64 v157, |v155|, s82
	v_fma_f32 v158, v156, s83, 1.0
	v_fma_f32 v159, v157, s83, 1.0
	v_rcp_f32_e32 v158, v158
	v_rcp_f32_e32 v159, v159
	v_mul_f32_e64 v156, v156, -v156
	v_mul_f32_e64 v157, v157, -v157
	v_mul_f32_e32 v156, 0x3fb8aa3b, v156
	v_mul_f32_e32 v157, 0x3fb8aa3b, v157
	v_fmamk_f32 v160, v158, 0x3f87dc22, v110
	v_fmamk_f32 v161, v159, 0x3f87dc22, v110
	v_exp_f32_e32 v156, v156
	v_exp_f32_e32 v157, v157
	v_fmaak_f32 v160, v158, v160, 0x3fb5f0e3
	v_fmaak_f32 v161, v159, v161, 0x3fb5f0e3
	v_fmaak_f32 v160, v158, v160, 0xbe91a98e
	v_fmaak_f32 v161, v159, v161, 0xbe91a98e
	v_fmaak_f32 v160, v158, v160, 0x3e827906
	v_fmaak_f32 v161, v159, v161, 0x3e827906
	v_mul_f32_e32 v158, v158, v160
	v_mul_f32_e32 v159, v159, v161
	v_fma_f32 v156, -v156, v158, 1.0
	v_fma_f32 v157, -v157, v159, 1.0
	v_mul_f32_e32 v162, 0.5, v154
	v_mul_f32_e32 v163, 0.5, v155
	v_bfi_b32 v154, s84, v156, v154
	v_bfi_b32 v155, s84, v157, v155
	v_add_f32_e32 v154, 1.0, v154
	v_add_f32_e32 v155, 1.0, v155
	v_mul_f32_e32 v154, v162, v154
	v_mul_f32_e32 v155, v163, v155
	v_mul_f32_e32 v154, v48, v154
	v_mul_f32_e32 v155, v49, v155
	v_mul_f32_e32 v154, v129, v154
	v_mul_f32_e32 v155, v145, v155
	v_max_f32_e64 v164, |v154|, |v155|
	s_nop 1
	v_max_f32_dpp v164, v164, v164 quad_perm:[1,0,3,2] row_mask:0xf bank_mask:0xf
	s_nop 1
	v_max_f32_dpp v164, v164, v164 quad_perm:[2,3,0,1] row_mask:0xf bank_mask:0xf
	s_nop 1
	v_max_f32_dpp v164, v164, v164 row_half_mirror row_mask:0xf bank_mask:0xf
	s_nop 1
	v_max_f32_dpp v164, v164, v164 row_mirror row_mask:0xf bank_mask:0xf
	s_nop 1
	v_readlane_b32 s46, v164, 32
	v_readlane_b32 s47, v164, 48
	v_readlane_b32 s12, v164, 0
	v_readlane_b32 s13, v164, 16
	s_nop 1
	v_mov_b32_e32 v164, s47
	v_max_f32_e32 v164, s46, v164
	v_mov_b32_e32 v165, s13
	v_max3_f32 v164, s12, v165, v164
	v_mul_f32_e32 v165, 0x3c09ae41, v164
	v_cmp_lt_f32_e32 vcc, 0, v164
	s_nop 1
	v_cndmask_b32_e32 v164, 1.0, v165, vcc
	v_div_scale_f32 v166, s[12:13], v164, v164, 1.0
	v_rcp_f32_e32 v167, v166
	v_div_scale_f32 v168, vcc, 1.0, v164, 1.0
	v_fma_f32 v169, -v166, v167, 1.0
	v_fmac_f32_e32 v167, v169, v167
	v_mul_f32_e32 v169, v168, v167
	v_fma_f32 v170, -v166, v169, v168
	v_fmac_f32_e32 v169, v170, v167
	v_fma_f32 v166, -v166, v169, v168
	v_div_fmas_f32 v166, v166, v167, v169
	v_div_fixup_f32 v166, v166, v164, 1.0
	v_mul_f32_e32 v154, v166, v154
	v_mul_f32_e32 v155, v166, v155
	v_rndne_f32_e32 v154, v154
	v_rndne_f32_e32 v155, v155
	v_cvt_i32_f32_e32 v154, v154
	v_cvt_i32_f32_e32 v155, v155
	v_perm_b32 v167, v155, v154, s85
	v_add_u32_e32 v154, v154, v155
	ds_write_b16 v90, v167 offset:3072
	s_nop 1
	v_add_u32_dpp v154, v154, v154 quad_perm:[1,0,3,2] row_mask:0xf bank_mask:0xf bound_ctrl:1
	s_nop 1
	v_add_u32_dpp v154, v154, v154 quad_perm:[2,3,0,1] row_mask:0xf bank_mask:0xf bound_ctrl:1
	s_nop 1
	v_add_u32_dpp v154, v154, v154 row_half_mirror row_mask:0xf bank_mask:0xf bound_ctrl:1
	s_nop 1
	v_add_u32_dpp v154, v154, v154 row_mirror row_mask:0xf bank_mask:0xf bound_ctrl:1
	s_nop 1
	v_readlane_b32 s46, v154, 0
	v_readlane_b32 s47, v154, 16
	v_readlane_b32 s12, v154, 32
	v_readlane_b32 s13, v154, 48
	s_nop 1
	s_add_i32 s46, s47, s46
	s_add_i32 s46, s46, s12
	s_add_i32 s46, s46, s13
	s_add_i32 s47, s67, 96
	s_and_saveexec_b64 s[12:13], s[8:9]
	v_mov_b32_e32 v154, s47
	v_mov_b32_e32 v155, s46
	ds_write2st64_b32 v154, v164, v155 offset1:1
	s_or_b64 exec, exec, s[12:13]
	s_waitcnt vmcnt(6)
	v_lshl_add_u32 v154, v34, 1, v62
	v_lshl_add_u32 v155, v35, 1, v62
	v_cvt_f32_i32_e32 v154, v154
	v_cvt_f32_i32_e32 v155, v155
	v_mul_f32_e32 v154, v130, v154
	v_mul_f32_e32 v155, v146, v155
	v_mul_f32_e32 v154, v70, v154
	v_mul_f32_e32 v155, v70, v155
	v_mul_f32_e64 v156, |v154|, s82
	v_mul_f32_e64 v157, |v155|, s82
	v_fma_f32 v158, v156, s83, 1.0
	v_fma_f32 v159, v157, s83, 1.0
	v_rcp_f32_e32 v158, v158
	v_rcp_f32_e32 v159, v159
	v_mul_f32_e64 v156, v156, -v156
	v_mul_f32_e64 v157, v157, -v157
	v_mul_f32_e32 v156, 0x3fb8aa3b, v156
	v_mul_f32_e32 v157, 0x3fb8aa3b, v157
	v_fmamk_f32 v160, v158, 0x3f87dc22, v110
	v_fmamk_f32 v161, v159, 0x3f87dc22, v110
	v_exp_f32_e32 v156, v156
	v_exp_f32_e32 v157, v157
	v_fmaak_f32 v160, v158, v160, 0x3fb5f0e3
	v_fmaak_f32 v161, v159, v161, 0x3fb5f0e3
	v_fmaak_f32 v160, v158, v160, 0xbe91a98e
	v_fmaak_f32 v161, v159, v161, 0xbe91a98e
	v_fmaak_f32 v160, v158, v160, 0x3e827906
	v_fmaak_f32 v161, v159, v161, 0x3e827906
	v_mul_f32_e32 v158, v158, v160
	v_mul_f32_e32 v159, v159, v161
	v_fma_f32 v156, -v156, v158, 1.0
	v_fma_f32 v157, -v157, v159, 1.0
	v_mul_f32_e32 v162, 0.5, v154
	v_mul_f32_e32 v163, 0.5, v155
	v_bfi_b32 v154, s84, v156, v154
	v_bfi_b32 v155, s84, v157, v155
	v_add_f32_e32 v154, 1.0, v154
	v_add_f32_e32 v155, 1.0, v155
	v_mul_f32_e32 v154, v162, v154
	v_mul_f32_e32 v155, v163, v155
	v_mul_f32_e32 v154, v50, v154
	v_mul_f32_e32 v155, v51, v155
	v_mul_f32_e32 v154, v131, v154
	v_mul_f32_e32 v155, v147, v155
	v_max_f32_e64 v164, |v154|, |v155|
	s_nop 1
	v_max_f32_dpp v164, v164, v164 quad_perm:[1,0,3,2] row_mask:0xf bank_mask:0xf
	s_nop 1
	v_max_f32_dpp v164, v164, v164 quad_perm:[2,3,0,1] row_mask:0xf bank_mask:0xf
	s_nop 1
	v_max_f32_dpp v164, v164, v164 row_half_mirror row_mask:0xf bank_mask:0xf
	s_nop 1
	v_max_f32_dpp v164, v164, v164 row_mirror row_mask:0xf bank_mask:0xf
	s_nop 1
	v_readlane_b32 s46, v164, 32
	v_readlane_b32 s47, v164, 48
; #define LAS __attribute__((address_space(3)))
; __device__ __forceinline__ float gelu_as(float z) {
;     const float ax = fabsf(z) * 0.70710678118654752f, t = __builtin_amdgcn_rcpf(1.f + 0.3275911f * ax);
;     const float poly = t * (0.254829592f + t * (-0.284496736f + t * (1.421413741f + t * (-1.453152027f + t * 1.061405429f))));
;     const float er = 1.f - poly * __expf(-ax * ax);
;     return 0.5f * z * (1.f + copysignf(er, z));
; __global__ void __launch_bounds__(NTHR, 2) k_main(Args a) {
;     ...
;                 const unsigned ew = *(const LAS unsigned*)(EL + tl * 128 + 2 * lane); const int e0 = (int)(ew & 0xffffu), e1 = (int)(ew >> 16);
;                 typedef int i2v __attribute__((ext_vector_type(2))); const i2v si = *(const LAS i2v*)(ACC + tl * 128 + 2 * lane);
;                 typedef float f2v __attribute__((ext_vector_type(2))); const f2v gt = *(const LAS f2v*)(GL + tl * 128 + 2 * lane); const float xs = XS[t];
;                 const int sx = ((const int*)(XS + T))[t];
;                 const float z0 = (float)(2 * si.x + sx) * SU[e0] * xs, z1 = (float)(2 * si.y + sx) * SU[e1] * xs;
;                 const float a0 = gt.x * gelu_as(z0) * SV[e0], a1 = gt.y * gelu_as(z1) * SV[e1];
;                 const float mx = wave_max_dpp(fmaxf(fabsf(a0), fabsf(a1)));
;                 const float sc = mx > 0.f ? mx * (1.f / 119.f) : 1.f, inv = 1.f / sc;
;                 const int q0 = (int)rintf(a0 * inv), q1 = (int)rintf(a1 * inv);
;                 *(LAS unsigned short*)(AL + tl * 128 + 2 * lane) = (unsigned short)((q0 & 255) | ((q1 & 255) << 8));
;                 const int qs = wave_sum_dpp_i(q0 + q1);
;                 if (lane == 0) { ASC[tl] = sc; SAL[tl] = qs; }
	v_readlane_b32 s12, v164, 0
	v_readlane_b32 s13, v164, 16
	s_nop 1
	v_mov_b32_e32 v164, s47
	v_max_f32_e32 v164, s46, v164
	v_mov_b32_e32 v165, s13
	v_max3_f32 v164, s12, v165, v164
	v_mul_f32_e32 v165, 0x3c09ae41, v164
	v_cmp_lt_f32_e32 vcc, 0, v164
	s_nop 1
	v_cndmask_b32_e32 v164, 1.0, v165, vcc
	v_div_scale_f32 v166, s[12:13], v164, v164, 1.0
	v_rcp_f32_e32 v167, v166
	v_div_scale_f32 v168, vcc, 1.0, v164, 1.0
	v_fma_f32 v169, -v166, v167, 1.0
	v_fmac_f32_e32 v167, v169, v167
	v_mul_f32_e32 v169, v168, v167
	v_fma_f32 v170, -v166, v169, v168
	v_fmac_f32_e32 v169, v170, v167
	v_fma_f32 v166, -v166, v169, v168
	v_div_fmas_f32 v166, v166, v167, v169
	v_div_fixup_f32 v166, v166, v164, 1.0
	v_mul_f32_e32 v154, v166, v154
	v_mul_f32_e32 v155, v166, v155
	v_rndne_f32_e32 v154, v154
	v_rndne_f32_e32 v155, v155
	v_cvt_i32_f32_e32 v154, v154
	v_cvt_i32_f32_e32 v155, v155
	v_perm_b32 v167, v155, v154, s85
	v_add_u32_e32 v154, v154, v155
	ds_write_b16 v90, v167 offset:4096
	s_nop 1
	v_add_u32_dpp v154, v154, v154 quad_perm:[1,0,3,2] row_mask:0xf bank_mask:0xf bound_ctrl:1
	s_nop 1
	v_add_u32_dpp v154, v154, v154 quad_perm:[2,3,0,1] row_mask:0xf bank_mask:0xf bound_ctrl:1
	s_nop 1
	v_add_u32_dpp v154, v154, v154 row_half_mirror row_mask:0xf bank_mask:0xf bound_ctrl:1
	s_nop 1
	v_add_u32_dpp v154, v154, v154 row_mirror row_mask:0xf bank_mask:0xf bound_ctrl:1
	s_nop 1
	v_readlane_b32 s46, v154, 0
	v_readlane_b32 s47, v154, 16
	v_readlane_b32 s12, v154, 32
	v_readlane_b32 s13, v154, 48
	s_nop 1
	s_add_i32 s46, s47, s46
	s_add_i32 s46, s46, s12
	s_add_i32 s46, s46, s13
	s_add_i32 s47, s67, 128
	s_and_saveexec_b64 s[12:13], s[8:9]
	v_mov_b32_e32 v154, s47
	v_mov_b32_e32 v155, s46
	ds_write2st64_b32 v154, v164, v155 offset1:1
	s_or_b64 exec, exec, s[12:13]
	s_waitcnt vmcnt(4)
	v_lshl_add_u32 v154, v36, 1, v63
	v_lshl_add_u32 v155, v37, 1, v63
	v_cvt_f32_i32_e32 v154, v154
	v_cvt_f32_i32_e32 v155, v155
	v_mul_f32_e32 v154, v132, v154
	v_mul_f32_e32 v155, v148, v155
	v_mul_f32_e32 v154, v71, v154
	v_mul_f32_e32 v155, v71, v155
	v_mul_f32_e64 v156, |v154|, s82
	v_mul_f32_e64 v157, |v155|, s82
	v_fma_f32 v158, v156, s83, 1.0
	v_fma_f32 v159, v157, s83, 1.0
	v_rcp_f32_e32 v158, v158
	v_rcp_f32_e32 v159, v159
	v_mul_f32_e64 v156, v156, -v156
	v_mul_f32_e64 v157, v157, -v157
	v_mul_f32_e32 v156, 0x3fb8aa3b, v156
	v_mul_f32_e32 v157, 0x3fb8aa3b, v157
	v_fmamk_f32 v160, v158, 0x3f87dc22, v110
	v_fmamk_f32 v161, v159, 0x3f87dc22, v110
	v_exp_f32_e32 v156, v156
	v_exp_f32_e32 v157, v157
	v_fmaak_f32 v160, v158, v160, 0x3fb5f0e3
	v_fmaak_f32 v161, v159, v161, 0x3fb5f0e3
	v_fmaak_f32 v160, v158, v160, 0xbe91a98e
	v_fmaak_f32 v161, v159, v161, 0xbe91a98e
	v_fmaak_f32 v160, v158, v160, 0x3e827906
	v_fmaak_f32 v161, v159, v161, 0x3e827906
	v_mul_f32_e32 v158, v158, v160
	v_mul_f32_e32 v159, v159, v161
	v_fma_f32 v156, -v156, v158, 1.0
	v_fma_f32 v157, -v157, v159, 1.0
	v_mul_f32_e32 v162, 0.5, v154
	v_mul_f32_e32 v163, 0.5, v155
	v_bfi_b32 v154, s84, v156, v154
	v_bfi_b32 v155, s84, v157, v155
	v_add_f32_e32 v154, 1.0, v154
	v_add_f32_e32 v155, 1.0, v155
	v_mul_f32_e32 v154, v162, v154
	v_mul_f32_e32 v155, v163, v155
	v_mul_f32_e32 v154, v52, v154
	v_mul_f32_e32 v155, v53, v155
	v_mul_f32_e32 v154, v133, v154
	v_mul_f32_e32 v155, v149, v155
	v_max_f32_e64 v164, |v154|, |v155|
	s_nop 1
	v_max_f32_dpp v164, v164, v164 quad_perm:[1,0,3,2] row_mask:0xf bank_mask:0xf
	s_nop 1
	v_max_f32_dpp v164, v164, v164 quad_perm:[2,3,0,1] row_mask:0xf bank_mask:0xf
	s_nop 1
	v_max_f32_dpp v164, v164, v164 row_half_mirror row_mask:0xf bank_mask:0xf
	s_nop 1
	v_max_f32_dpp v164, v164, v164 row_mirror row_mask:0xf bank_mask:0xf
	s_nop 1
	v_readlane_b32 s46, v164, 32
	v_readlane_b32 s47, v164, 48
	v_readlane_b32 s12, v164, 0
	v_readlane_b32 s13, v164, 16
	s_nop 1
	v_mov_b32_e32 v164, s47
	v_max_f32_e32 v164, s46, v164
	v_mov_b32_e32 v165, s13
	v_max3_f32 v164, s12, v165, v164
	v_mul_f32_e32 v165, 0x3c09ae41, v164
	v_cmp_lt_f32_e32 vcc, 0, v164
	s_nop 1
	v_cndmask_b32_e32 v164, 1.0, v165, vcc
	v_div_scale_f32 v166, s[12:13], v164, v164, 1.0
	v_rcp_f32_e32 v167, v166
	v_div_scale_f32 v168, vcc, 1.0, v164, 1.0
	v_fma_f32 v169, -v166, v167, 1.0
	v_fmac_f32_e32 v167, v169, v167
	v_mul_f32_e32 v169, v168, v167
	v_fma_f32 v170, -v166, v169, v168
	v_fmac_f32_e32 v169, v170, v167
	v_fma_f32 v166, -v166, v169, v168
	v_div_fmas_f32 v166, v166, v167, v169
	v_div_fixup_f32 v166, v166, v164, 1.0
	v_mul_f32_e32 v154, v166, v154
	v_mul_f32_e32 v155, v166, v155
	v_rndne_f32_e32 v154, v154
	v_rndne_f32_e32 v155, v155
	v_cvt_i32_f32_e32 v154, v154
	v_cvt_i32_f32_e32 v155, v155
	v_perm_b32 v167, v155, v154, s85
	v_add_u32_e32 v154, v154, v155
	ds_write_b16 v90, v167 offset:5120
	s_nop 1
	v_add_u32_dpp v154, v154, v154 quad_perm:[1,0,3,2] row_mask:0xf bank_mask:0xf bound_ctrl:1
	s_nop 1
	v_add_u32_dpp v154, v154, v154 quad_perm:[2,3,0,1] row_mask:0xf bank_mask:0xf bound_ctrl:1
	s_nop 1
	v_add_u32_dpp v154, v154, v154 row_half_mirror row_mask:0xf bank_mask:0xf bound_ctrl:1
	s_nop 1
	v_add_u32_dpp v154, v154, v154 row_mirror row_mask:0xf bank_mask:0xf bound_ctrl:1
	s_nop 1
	v_readlane_b32 s46, v154, 0
	v_readlane_b32 s47, v154, 16
	v_readlane_b32 s12, v154, 32
	v_readlane_b32 s13, v154, 48
	s_nop 1
	s_add_i32 s46, s47, s46
	s_add_i32 s46, s46, s12
	s_add_i32 s46, s46, s13
	s_add_i32 s47, s67, 160
	s_and_saveexec_b64 s[12:13], s[8:9]
	v_mov_b32_e32 v154, s47
	v_mov_b32_e32 v155, s46
	ds_write2st64_b32 v154, v164, v155 offset1:1
	s_or_b64 exec, exec, s[12:13]
	s_waitcnt vmcnt(2)
; #define LAS __attribute__((address_space(3)))
; __device__ __forceinline__ float gelu_as(float z) {
;     const float ax = fabsf(z) * 0.70710678118654752f, t = __builtin_amdgcn_rcpf(1.f + 0.3275911f * ax);
;     const float poly = t * (0.254829592f + t * (-0.284496736f + t * (1.421413741f + t * (-1.453152027f + t * 1.061405429f))));
;     const float er = 1.f - poly * __expf(-ax * ax);
;     return 0.5f * z * (1.f + copysignf(er, z));
; __global__ void __launch_bounds__(NTHR, 2) k_main(Args a) {
;     ...
;                 const unsigned ew = *(const LAS unsigned*)(EL + tl * 128 + 2 * lane); const int e0 = (int)(ew & 0xffffu), e1 = (int)(ew >> 16);
;                 typedef int i2v __attribute__((ext_vector_type(2))); const i2v si = *(const LAS i2v*)(ACC + tl * 128 + 2 * lane);
;                 typedef float f2v __attribute__((ext_vector_type(2))); const f2v gt = *(const LAS f2v*)(GL + tl * 128 + 2 * lane); const float xs = XS[t];
;                 const int sx = ((const int*)(XS + T))[t];
;                 const float z0 = (float)(2 * si.x + sx) * SU[e0] * xs, z1 = (float)(2 * si.y + sx) * SU[e1] * xs;
;                 const float a0 = gt.x * gelu_as(z0) * SV[e0], a1 = gt.y * gelu_as(z1) * SV[e1];
;                 const float mx = wave_max_dpp(fmaxf(fabsf(a0), fabsf(a1)));
;                 const float sc = mx > 0.f ? mx * (1.f / 119.f) : 1.f, inv = 1.f / sc;
;                 const int q0 = (int)rintf(a0 * inv), q1 = (int)rintf(a1 * inv);
;                 *(LAS unsigned short*)(AL + tl * 128 + 2 * lane) = (unsigned short)((q0 & 255) | ((q1 & 255) << 8));
;                 const int qs = wave_sum_dpp_i(q0 + q1);
;                 if (lane == 0) { ASC[tl] = sc; SAL[tl] = qs; }
	v_lshl_add_u32 v154, v38, 1, v64
	v_lshl_add_u32 v155, v39, 1, v64
	v_cvt_f32_i32_e32 v154, v154
	v_cvt_f32_i32_e32 v155, v155
	v_mul_f32_e32 v154, v134, v154
	v_mul_f32_e32 v155, v150, v155
	v_mul_f32_e32 v154, v72, v154
	v_mul_f32_e32 v155, v72, v155
	v_mul_f32_e64 v156, |v154|, s82
	v_mul_f32_e64 v157, |v155|, s82
	v_fma_f32 v158, v156, s83, 1.0
	v_fma_f32 v159, v157, s83, 1.0
	v_rcp_f32_e32 v158, v158
	v_rcp_f32_e32 v159, v159
	v_mul_f32_e64 v156, v156, -v156
	v_mul_f32_e64 v157, v157, -v157
	v_mul_f32_e32 v156, 0x3fb8aa3b, v156
	v_mul_f32_e32 v157, 0x3fb8aa3b, v157
	v_fmamk_f32 v160, v158, 0x3f87dc22, v110
	v_fmamk_f32 v161, v159, 0x3f87dc22, v110
	v_exp_f32_e32 v156, v156
	v_exp_f32_e32 v157, v157
	v_fmaak_f32 v160, v158, v160, 0x3fb5f0e3
	v_fmaak_f32 v161, v159, v161, 0x3fb5f0e3
	v_fmaak_f32 v160, v158, v160, 0xbe91a98e
	v_fmaak_f32 v161, v159, v161, 0xbe91a98e
	v_fmaak_f32 v160, v158, v160, 0x3e827906
	v_fmaak_f32 v161, v159, v161, 0x3e827906
	v_mul_f32_e32 v158, v158, v160
	v_mul_f32_e32 v159, v159, v161
	v_fma_f32 v156, -v156, v158, 1.0
	v_fma_f32 v157, -v157, v159, 1.0
	v_mul_f32_e32 v162, 0.5, v154
	v_mul_f32_e32 v163, 0.5, v155
	v_bfi_b32 v154, s84, v156, v154
	v_bfi_b32 v155, s84, v157, v155
	v_add_f32_e32 v154, 1.0, v154
	v_add_f32_e32 v155, 1.0, v155
	v_mul_f32_e32 v154, v162, v154
	v_mul_f32_e32 v155, v163, v155
	v_mul_f32_e32 v154, v54, v154
	v_mul_f32_e32 v155, v55, v155
	v_mul_f32_e32 v154, v135, v154
	v_mul_f32_e32 v155, v151, v155
	v_max_f32_e64 v164, |v154|, |v155|
	s_nop 1
	v_max_f32_dpp v164, v164, v164 quad_perm:[1,0,3,2] row_mask:0xf bank_mask:0xf
	s_nop 1
	v_max_f32_dpp v164, v164, v164 quad_perm:[2,3,0,1] row_mask:0xf bank_mask:0xf
	s_nop 1
	v_max_f32_dpp v164, v164, v164 row_half_mirror row_mask:0xf bank_mask:0xf
	s_nop 1
	v_max_f32_dpp v164, v164, v164 row_mirror row_mask:0xf bank_mask:0xf
	s_nop 1
	v_readlane_b32 s46, v164, 32
	v_readlane_b32 s47, v164, 48
	v_readlane_b32 s12, v164, 0
	v_readlane_b32 s13, v164, 16
	s_nop 1
	v_mov_b32_e32 v164, s47
	v_max_f32_e32 v164, s46, v164
	v_mov_b32_e32 v165, s13
	v_max3_f32 v164, s12, v165, v164
	v_mul_f32_e32 v165, 0x3c09ae41, v164
	v_cmp_lt_f32_e32 vcc, 0, v164
	s_nop 1
	v_cndmask_b32_e32 v164, 1.0, v165, vcc
	v_div_scale_f32 v166, s[12:13], v164, v164, 1.0
	v_rcp_f32_e32 v167, v166
	v_div_scale_f32 v168, vcc, 1.0, v164, 1.0
	v_fma_f32 v169, -v166, v167, 1.0
	v_fmac_f32_e32 v167, v169, v167
	v_mul_f32_e32 v169, v168, v167
	v_fma_f32 v170, -v166, v169, v168
	v_fmac_f32_e32 v169, v170, v167
	v_fma_f32 v166, -v166, v169, v168
	v_div_fmas_f32 v166, v166, v167, v169
	v_div_fixup_f32 v166, v166, v164, 1.0
	v_mul_f32_e32 v154, v166, v154
	v_mul_f32_e32 v155, v166, v155
	v_rndne_f32_e32 v154, v154
	v_rndne_f32_e32 v155, v155
	v_cvt_i32_f32_e32 v154, v154
	v_cvt_i32_f32_e32 v155, v155
	v_perm_b32 v167, v155, v154, s85
	v_add_u32_e32 v154, v154, v155
	ds_write_b16 v90, v167 offset:6144
	s_nop 1
	v_add_u32_dpp v154, v154, v154 quad_perm:[1,0,3,2] row_mask:0xf bank_mask:0xf bound_ctrl:1
	s_nop 1
	v_add_u32_dpp v154, v154, v154 quad_perm:[2,3,0,1] row_mask:0xf bank_mask:0xf bound_ctrl:1
	s_nop 1
	v_add_u32_dpp v154, v154, v154 row_half_mirror row_mask:0xf bank_mask:0xf bound_ctrl:1
	s_nop 1
	v_add_u32_dpp v154, v154, v154 row_mirror row_mask:0xf bank_mask:0xf bound_ctrl:1
	s_nop 1
	v_readlane_b32 s46, v154, 0
	v_readlane_b32 s47, v154, 16
	v_readlane_b32 s12, v154, 32
	v_readlane_b32 s13, v154, 48
	s_nop 1
	s_add_i32 s46, s47, s46
	s_add_i32 s46, s46, s12
	s_add_i32 s46, s46, s13
	s_add_i32 s47, s67, 192
	s_and_saveexec_b64 s[12:13], s[8:9]
	v_mov_b32_e32 v154, s47
	v_mov_b32_e32 v155, s46
	ds_write2st64_b32 v154, v164, v155 offset1:1
	s_or_b64 exec, exec, s[12:13]
	s_waitcnt vmcnt(0)
; #define LAS __attribute__((address_space(3)))
; __device__ __forceinline__ unsigned xb_ld(unsigned* p)              { return __hip_atomic_load(p, __ATOMIC_RELAXED, __HIP_MEMORY_SCOPE_AGENT); }
; #define XB_SPIN(cond, bar) do { unsigned _sp = 0; while (cond) { __builtin_amdgcn_s_sleep(1); \
;     if ((++_sp & 255u) == 0u) { if (xb_ld(&(bar)[XB_TMO])) break; if (_sp > XB_SPIN_CAP) { atomicAdd(&(bar)[XB_TMO], 1u); break; } } } } while (0)
; __global__ void __launch_bounds__(NTHR, 2) k_main(Args a) {
;     ...
;                 const unsigned ew = *(const LAS unsigned*)(EL + tl * 128 + 2 * lane); const int e0 = (int)(ew & 0xffffu), e1 = (int)(ew >> 16);
;                 typedef int i2v __attribute__((ext_vector_type(2))); const i2v si = *(const LAS i2v*)(ACC + tl * 128 + 2 * lane);
;                 typedef float f2v __attribute__((ext_vector_type(2))); const f2v gt = *(const LAS f2v*)(GL + tl * 128 + 2 * lane); const float xs = XS[t];
;                 const int sx = ((const int*)(XS + T))[t];
;                 const float z0 = (float)(2 * si.x + sx) * SU[e0] * xs, z1 = (float)(2 * si.y + sx) * SU[e1] * xs;
;                 const float a0 = gt.x * gelu_as(z0) * SV[e0], a1 = gt.y * gelu_as(z1) * SV[e1];
;                 const float mx = wave_max_dpp(fmaxf(fabsf(a0), fabsf(a1)));
;                 const float sc = mx > 0.f ? mx * (1.f / 119.f) : 1.f, inv = 1.f / sc;
;                 const int q0 = (int)rintf(a0 * inv), q1 = (int)rintf(a1 * inv);
;                 *(LAS unsigned short*)(AL + tl * 128 + 2 * lane) = (unsigned short)((q0 & 255) | ((q1 & 255) << 8));
;                 const int qs = wave_sum_dpp_i(q0 + q1);
;                 if (lane == 0) { ASC[tl] = sc; SAL[tl] = qs; }
;             }
;             if (tid == 0) XB_SPIN(xb_ld(&((unsigned*)ws)[14400]) < (unsigned)((T / 256) * (D / 256)), (unsigned*)ws);
	v_lshl_add_u32 v154, v40, 1, v65
	v_lshl_add_u32 v155, v41, 1, v65
	v_cvt_f32_i32_e32 v154, v154
	v_cvt_f32_i32_e32 v155, v155
	v_mul_f32_e32 v154, v136, v154
	v_mul_f32_e32 v155, v152, v155
	v_mul_f32_e32 v154, v73, v154
	v_mul_f32_e32 v155, v73, v155
	v_mul_f32_e64 v156, |v154|, s82
	v_mul_f32_e64 v157, |v155|, s82
	v_fma_f32 v158, v156, s83, 1.0
	v_fma_f32 v159, v157, s83, 1.0
	v_rcp_f32_e32 v158, v158
	v_rcp_f32_e32 v159, v159
	v_mul_f32_e64 v156, v156, -v156
	v_mul_f32_e64 v157, v157, -v157
	v_mul_f32_e32 v156, 0x3fb8aa3b, v156
	v_mul_f32_e32 v157, 0x3fb8aa3b, v157
	v_fmamk_f32 v160, v158, 0x3f87dc22, v110
	v_fmamk_f32 v161, v159, 0x3f87dc22, v110
	v_exp_f32_e32 v156, v156
	v_exp_f32_e32 v157, v157
	v_fmaak_f32 v160, v158, v160, 0x3fb5f0e3
	v_fmaak_f32 v161, v159, v161, 0x3fb5f0e3
	v_fmaak_f32 v160, v158, v160, 0xbe91a98e
	v_fmaak_f32 v161, v159, v161, 0xbe91a98e
	v_fmaak_f32 v160, v158, v160, 0x3e827906
	v_fmaak_f32 v161, v159, v161, 0x3e827906
	v_mul_f32_e32 v158, v158, v160
	v_mul_f32_e32 v159, v159, v161
	v_fma_f32 v156, -v156, v158, 1.0
	v_fma_f32 v157, -v157, v159, 1.0
	v_mul_f32_e32 v162, 0.5, v154
	v_mul_f32_e32 v163, 0.5, v155
	v_bfi_b32 v154, s84, v156, v154
	v_bfi_b32 v155, s84, v157, v155
	v_add_f32_e32 v154, 1.0, v154
	v_add_f32_e32 v155, 1.0, v155
	v_mul_f32_e32 v154, v162, v154
	v_mul_f32_e32 v155, v163, v155
	v_mul_f32_e32 v154, v56, v154
	v_mul_f32_e32 v155, v57, v155
	v_mul_f32_e32 v154, v137, v154
	v_mul_f32_e32 v155, v153, v155
	v_max_f32_e64 v164, |v154|, |v155|
	s_nop 1
	v_max_f32_dpp v164, v164, v164 quad_perm:[1,0,3,2] row_mask:0xf bank_mask:0xf
	s_nop 1
	v_max_f32_dpp v164, v164, v164 quad_perm:[2,3,0,1] row_mask:0xf bank_mask:0xf
	s_nop 1
	v_max_f32_dpp v164, v164, v164 row_half_mirror row_mask:0xf bank_mask:0xf
	s_nop 1
	v_max_f32_dpp v164, v164, v164 row_mirror row_mask:0xf bank_mask:0xf
	s_nop 1
	v_readlane_b32 s46, v164, 32
	v_readlane_b32 s47, v164, 48
	v_readlane_b32 s12, v164, 0
	v_readlane_b32 s13, v164, 16
	s_nop 1
	v_mov_b32_e32 v164, s47
	v_max_f32_e32 v164, s46, v164
	v_mov_b32_e32 v165, s13
	v_max3_f32 v164, s12, v165, v164
	v_mul_f32_e32 v165, 0x3c09ae41, v164
	v_cmp_lt_f32_e32 vcc, 0, v164
	s_nop 1
	v_cndmask_b32_e32 v164, 1.0, v165, vcc
	v_div_scale_f32 v166, s[12:13], v164, v164, 1.0
	v_rcp_f32_e32 v167, v166
	v_div_scale_f32 v168, vcc, 1.0, v164, 1.0
	v_fma_f32 v169, -v166, v167, 1.0
	v_fmac_f32_e32 v167, v169, v167
	v_mul_f32_e32 v169, v168, v167
	v_fma_f32 v170, -v166, v169, v168
	v_fmac_f32_e32 v169, v170, v167
	v_fma_f32 v166, -v166, v169, v168
	v_div_fmas_f32 v166, v166, v167, v169
	v_div_fixup_f32 v166, v166, v164, 1.0
	v_mul_f32_e32 v154, v166, v154
	v_mul_f32_e32 v155, v166, v155
	v_rndne_f32_e32 v154, v154
	v_rndne_f32_e32 v155, v155
	v_cvt_i32_f32_e32 v154, v154
	v_cvt_i32_f32_e32 v155, v155
	v_perm_b32 v167, v155, v154, s85
	v_add_u32_e32 v154, v154, v155
	ds_write_b16 v90, v167 offset:7168
	s_nop 1
	v_add_u32_dpp v154, v154, v154 quad_perm:[1,0,3,2] row_mask:0xf bank_mask:0xf bound_ctrl:1
	s_nop 1
	v_add_u32_dpp v154, v154, v154 quad_perm:[2,3,0,1] row_mask:0xf bank_mask:0xf bound_ctrl:1
	s_nop 1
	v_add_u32_dpp v154, v154, v154 row_half_mirror row_mask:0xf bank_mask:0xf bound_ctrl:1
	s_nop 1
	v_add_u32_dpp v154, v154, v154 row_mirror row_mask:0xf bank_mask:0xf bound_ctrl:1
	s_nop 1
	v_readlane_b32 s46, v154, 0
	v_readlane_b32 s47, v154, 16
	v_readlane_b32 s12, v154, 32
	v_readlane_b32 s13, v154, 48
	s_nop 1
	s_add_i32 s46, s47, s46
	s_add_i32 s46, s46, s12
	s_add_i32 s46, s46, s13
	s_add_i32 s47, s67, 224
	s_and_saveexec_b64 s[12:13], s[8:9]
	v_mov_b32_e32 v154, s47
	v_mov_b32_e32 v155, s46
	ds_write2st64_b32 v154, v164, v155 offset1:1
	s_or_b64 exec, exec, s[12:13]
.LBB0_678:
	s_and_saveexec_b64 s[10:11], s[0:1]
	s_cbranch_execz .LBB0_691
	v_mov_b32_e32 v18, v78
	v_cmp_lt_u32_e32 vcc, s3, v18
	s_cbranch_vccnz .LBB0_691
	s_mov_b32 s41, 1
	s_branch .LBB0_682
